# GEMM loops: per-phase s_setprio flips and duplicate lgkmcnt waits removed (on top of P3 scan rework)
# speedup vs baseline: 1.0853x; 1.0136x over previous
; #define PG8_STAGE(bufoff, gbase, voff) do { _Pragma("unroll") for (int _i = 0; _i < 2; ++_i) \
;         __builtin_amdgcn_global_load_lds((const unsigned*)((const char*)(gbase) + (voff)[_i]), (PG8_LAS unsigned*)(lds + (bufoff) + ldsw + _i * 8192), 16, 0, 0); } while (0)
; #define PG8_LDA(dst, b, h) do { _Pragma("unroll") for (int m = 0; m < 4; ++m) _Pragma("unroll") for (int k = 0; k < 2; ++k) dst[m][k] = *(const PG8_LAS bf16x8*)(lds + PG8_SA(b, h) + aoff + m * 2048 + k * 1024); } while (0)
; #define PG8_LDB(dst, b, h) do { _Pragma("unroll") for (int n = 0; n < 2; ++n) _Pragma("unroll") for (int k = 0; k < 2; ++k) dst[n][k] = *(const PG8_LAS bf16x8*)(lds + PG8_SB(b, h) + boff + n * 2048 + k * 1024); } while (0)
; #define PG8_MMA(ai, bj, At, Bt) do { __builtin_amdgcn_s_setprio(1); _Pragma("unroll") for (int m = 0; m < 4; ++m) _Pragma("unroll") for (int n = 0; n < 2; ++n) _Pragma("unroll") for (int k = 0; k < 2; ++k) \
;         acc[ai][bj][m][n] = __builtin_amdgcn_mfma_f32_16x16x32_bf16(Bt[n][k], At[m][k], acc[ai][bj][m][n], 0, 0, 0); __builtin_amdgcn_s_setprio(0); } while (0)
; #define PG8_WAIT_L(n) asm volatile("s_waitcnt lgkmcnt(" #n ")" ::: "memory")
; #define PG8_BAR __builtin_amdgcn_s_barrier()
; #define PG8_SCHED __builtin_amdgcn_sched_barrier(0)
; template <class Epi, class Sched>
; __device__ __forceinline__ void gemm_phase(PG8_LAS unsigned char* lds, const Gemm g, const Sched& S, const Epi& E) {
;     ...
;             PG8_LDB(B0, 0, 0); PG8_SCHED; PG8_LDA(At, 0, 0); PG8_STAGE(PG8_SA(1, 1), a1 + hstep, voffA);
;             PG8_WAIT_L(8); PG8_BAR; PG8_WAIT_L(0); PG8_MMA(0, 0, At, B0); PG8_BAR; PG8_SCHED;
;             PG8_LDB(B1, 0, 1); PG8_STAGE(PG8_SB(0, 0), b2, voffB);
;             PG8_BAR; PG8_WAIT_L(0); PG8_MMA(0, 1, At, B1); PG8_BAR;
;             PG8_LDA(At, 0, 1); PG8_STAGE(PG8_SA(0, 0), a2, voffA);
;             PG8_BAR; PG8_WAIT_L(0); PG8_MMA(1, 0, At, B0); PG8_BAR; PG8_SCHED;
.LBB0_166:
	ds_read_b128 v[144:147], v151
	ds_read_b128 v[154:157], v151 offset:1024
	ds_read_b128 v[158:161], v151 offset:2048
	ds_read_b128 v[162:165], v151 offset:3072
	s_add_u32 s24, s20, 0xfffc0080
	s_addc_u32 s25, s21, -1
	s_cmp_eq_u32 s67, 12
	s_cselect_b32 s27, s9, s25
	s_cselect_b32 s26, s63, s24
	s_cselect_b32 s25, s7, s66
	s_cselect_b32 s24, s64, s65
	v_lshl_add_u64 v[198:199], s[20:21], 0, v[136:137]
	s_add_i32 m0, s15, 0xc000
	ds_read_b128 v[166:169], v152
	ds_read_b128 v[170:173], v152 offset:1024
	ds_read_b128 v[174:177], v152 offset:2048
	ds_read_b128 v[178:181], v152 offset:3072
	ds_read_b128 v[182:185], v152 offset:4096
	ds_read_b128 v[186:189], v152 offset:5120
	ds_read_b128 v[190:193], v152 offset:6144
	ds_read_b128 v[194:197], v152 offset:7168
	global_load_lds_dwordx4 v[198:199], off
	v_lshl_add_u64 v[198:199], s[20:21], 0, v[138:139]
	s_add_i32 m0, s15, 0xe000
	s_nop 0
	global_load_lds_dwordx4 v[198:199], off
	s_waitcnt lgkmcnt(8)
	s_barrier
	s_waitcnt lgkmcnt(0)
	v_mfma_f32_16x16x32_bf16 v[124:127], v[144:147], v[166:169], v[124:127]
	v_mfma_f32_16x16x32_bf16 v[120:123], v[158:161], v[166:169], v[120:123]
	v_mfma_f32_16x16x32_bf16 v[116:119], v[144:147], v[174:177], v[116:119]
	v_mfma_f32_16x16x32_bf16 v[108:111], v[158:161], v[174:177], v[108:111]
	v_mfma_f32_16x16x32_bf16 v[100:103], v[144:147], v[182:185], v[100:103]
	v_mfma_f32_16x16x32_bf16 v[92:95], v[158:161], v[182:185], v[92:95]
	v_mfma_f32_16x16x32_bf16 v[84:87], v[144:147], v[190:193], v[84:87]
	v_mfma_f32_16x16x32_bf16 v[76:79], v[158:161], v[190:193], v[76:79]
	v_mfma_f32_16x16x32_bf16 v[124:127], v[154:157], v[170:173], v[124:127]
	v_mfma_f32_16x16x32_bf16 v[120:123], v[162:165], v[170:173], v[120:123]
	v_mfma_f32_16x16x32_bf16 v[116:119], v[154:157], v[178:181], v[116:119]
	v_mfma_f32_16x16x32_bf16 v[108:111], v[162:165], v[178:181], v[108:111]
	v_mfma_f32_16x16x32_bf16 v[100:103], v[154:157], v[186:189], v[100:103]
	v_mfma_f32_16x16x32_bf16 v[92:95], v[162:165], v[186:189], v[92:95]
	v_mfma_f32_16x16x32_bf16 v[84:87], v[154:157], v[194:197], v[84:87]
	v_mfma_f32_16x16x32_bf16 v[76:79], v[162:165], v[194:197], v[76:79]
	s_barrier
	s_add_i32 s68, s53, s36
	v_lshl_add_u64 v[214:215], s[24:25], 0, v[132:133]
	s_mov_b32 m0, s68
	ds_read_b128 v[198:201], v153
	ds_read_b128 v[202:205], v153 offset:1024
	ds_read_b128 v[206:209], v153 offset:2048
	ds_read_b128 v[210:213], v153 offset:3072
	global_load_lds_dwordx4 v[214:215], off
	v_lshl_add_u64 v[216:217], s[24:25], 0, v[128:129]
	s_add_i32 m0, s68, 0x2000
	s_nop 0
	global_load_lds_dwordx4 v[216:217], off
	s_barrier
	s_waitcnt lgkmcnt(0)
	v_mfma_f32_16x16x32_bf16 v[112:115], v[198:201], v[166:169], v[112:115]
	v_mfma_f32_16x16x32_bf16 v[104:107], v[206:209], v[166:169], v[104:107]
	v_mfma_f32_16x16x32_bf16 v[96:99], v[198:201], v[174:177], v[96:99]
	v_mfma_f32_16x16x32_bf16 v[88:91], v[206:209], v[174:177], v[88:91]
	v_mfma_f32_16x16x32_bf16 v[80:83], v[198:201], v[182:185], v[80:83]
	v_mfma_f32_16x16x32_bf16 v[72:75], v[206:209], v[182:185], v[72:75]
	v_mfma_f32_16x16x32_bf16 v[68:71], v[198:201], v[190:193], v[68:71]
	v_mfma_f32_16x16x32_bf16 v[64:67], v[206:209], v[190:193], v[64:67]
	v_mfma_f32_16x16x32_bf16 v[112:115], v[202:205], v[170:173], v[112:115]
	v_mfma_f32_16x16x32_bf16 v[104:107], v[210:213], v[170:173], v[104:107]
	v_mfma_f32_16x16x32_bf16 v[96:99], v[202:205], v[178:181], v[96:99]
	v_mfma_f32_16x16x32_bf16 v[88:91], v[210:213], v[178:181], v[88:91]
	v_mfma_f32_16x16x32_bf16 v[80:83], v[202:205], v[186:189], v[80:83]
	v_mfma_f32_16x16x32_bf16 v[72:75], v[210:213], v[186:189], v[72:75]
	v_mfma_f32_16x16x32_bf16 v[68:71], v[202:205], v[194:197], v[68:71]
	v_mfma_f32_16x16x32_bf16 v[64:67], v[210:213], v[194:197], v[64:67]
	s_mov_b32 m0, s15
	v_lshl_add_u64 v[218:219], s[26:27], 0, v[134:135]
	s_barrier
	ds_read_b128 v[166:169], v152 offset:16384
	ds_read_b128 v[170:173], v152 offset:17408
	ds_read_b128 v[174:177], v152 offset:18432
	ds_read_b128 v[178:181], v152 offset:19456
	ds_read_b128 v[182:185], v152 offset:20480
	ds_read_b128 v[186:189], v152 offset:21504
	ds_read_b128 v[190:193], v152 offset:22528
	ds_read_b128 v[194:197], v152 offset:23552
	global_load_lds_dwordx4 v[218:219], off
	v_lshl_add_u64 v[220:221], s[26:27], 0, v[130:131]
	s_mov_b32 m0, s39
	s_nop 0
	global_load_lds_dwordx4 v[220:221], off
	s_barrier
	s_waitcnt lgkmcnt(0)
	v_mfma_f32_16x16x32_bf16 v[60:63], v[144:147], v[166:169], v[60:63]
	v_mfma_f32_16x16x32_bf16 v[56:59], v[158:161], v[166:169], v[56:59]
	v_mfma_f32_16x16x32_bf16 v[52:55], v[144:147], v[174:177], v[52:55]
	v_mfma_f32_16x16x32_bf16 v[44:47], v[158:161], v[174:177], v[44:47]
	v_mfma_f32_16x16x32_bf16 v[36:39], v[144:147], v[182:185], v[36:39]
	v_mfma_f32_16x16x32_bf16 v[28:31], v[158:161], v[182:185], v[28:31]
	v_mfma_f32_16x16x32_bf16 v[20:23], v[144:147], v[190:193], v[20:23]
	v_mfma_f32_16x16x32_bf16 v[12:15], v[158:161], v[190:193], v[12:15]
	v_mfma_f32_16x16x32_bf16 v[60:63], v[154:157], v[170:173], v[60:63]
	v_mfma_f32_16x16x32_bf16 v[56:59], v[162:165], v[170:173], v[56:59]
	v_mfma_f32_16x16x32_bf16 v[52:55], v[154:157], v[178:181], v[52:55]
	v_mfma_f32_16x16x32_bf16 v[44:47], v[162:165], v[178:181], v[44:47]
	v_mfma_f32_16x16x32_bf16 v[36:39], v[154:157], v[186:189], v[36:39]
	v_mfma_f32_16x16x32_bf16 v[28:31], v[162:165], v[186:189], v[28:31]
	v_mfma_f32_16x16x32_bf16 v[20:23], v[154:157], v[194:197], v[20:23]
	v_mfma_f32_16x16x32_bf16 v[12:15], v[162:165], v[194:197], v[12:15]
	s_barrier
; #define PG8_STAGE(bufoff, gbase, voff) do { _Pragma("unroll") for (int _i = 0; _i < 2; ++_i) \
;         __builtin_amdgcn_global_load_lds((const unsigned*)((const char*)(gbase) + (voff)[_i]), (PG8_LAS unsigned*)(lds + (bufoff) + ldsw + _i * 8192), 16, 0, 0); } while (0)
; #define PG8_LDA(dst, b, h) do { _Pragma("unroll") for (int m = 0; m < 4; ++m) _Pragma("unroll") for (int k = 0; k < 2; ++k) dst[m][k] = *(const PG8_LAS bf16x8*)(lds + PG8_SA(b, h) + aoff + m * 2048 + k * 1024); } while (0)
; #define PG8_LDB(dst, b, h) do { _Pragma("unroll") for (int n = 0; n < 2; ++n) _Pragma("unroll") for (int k = 0; k < 2; ++k) dst[n][k] = *(const PG8_LAS bf16x8*)(lds + PG8_SB(b, h) + boff + n * 2048 + k * 1024); } while (0)
; #define PG8_MMA(ai, bj, At, Bt) do { __builtin_amdgcn_s_setprio(1); _Pragma("unroll") for (int m = 0; m < 4; ++m) _Pragma("unroll") for (int n = 0; n < 2; ++n) _Pragma("unroll") for (int k = 0; k < 2; ++k) \
;         acc[ai][bj][m][n] = __builtin_amdgcn_mfma_f32_16x16x32_bf16(Bt[n][k], At[m][k], acc[ai][bj][m][n], 0, 0, 0); __builtin_amdgcn_s_setprio(0); } while (0)
; #define PG8_WAIT_V(n) asm volatile("s_waitcnt vmcnt(" #n ")" ::: "memory")
; #define PG8_WAIT_L(n) asm volatile("s_waitcnt lgkmcnt(" #n ")" ::: "memory")
; #define PG8_BAR __builtin_amdgcn_s_barrier()
; #define PG8_SCHED __builtin_amdgcn_sched_barrier(0)
; template <class Epi, class Sched>
; __device__ __forceinline__ void gemm_phase(PG8_LAS unsigned char* lds, const Gemm g, const Sched& S, const Epi& E) {
;     ...
;             PG8_STAGE(PG8_SB(0, 1), b2 + hstep, voffB);
;             PG8_WAIT_V(6); PG8_BAR; PG8_MMA(1, 1, At, B1); PG8_BAR;
;             PG8_LDB(B0, 1, 0); PG8_SCHED; PG8_LDA(At, 1, 0); PG8_STAGE(PG8_SA(0, 1), a2 + hstep, voffA);
;             PG8_WAIT_L(8); PG8_BAR; PG8_WAIT_L(0); PG8_MMA(0, 0, At, B0); PG8_BAR; PG8_SCHED;
;             PG8_LDB(B1, 1, 1); PG8_STAGE(PG8_SB(1, 0), b3, voffB);
;             PG8_BAR; PG8_WAIT_L(0); PG8_MMA(0, 1, At, B1); PG8_BAR;
;             PG8_LDA(At, 1, 1); PG8_STAGE(PG8_SA(1, 0), a3, voffA);
	s_add_u32 s68, s24, 0x40000
	s_addc_u32 s69, s25, 0
	s_add_i32 s70, s60, s36
	v_lshl_add_u64 v[144:145], s[68:69], 0, v[132:133]
	s_mov_b32 m0, s70
	s_nop 0
	global_load_lds_dwordx4 v[144:145], off
	v_lshl_add_u64 v[144:145], s[68:69], 0, v[128:129]
	s_add_i32 m0, s70, 0x2000
	s_nop 0
	global_load_lds_dwordx4 v[144:145], off
	s_waitcnt vmcnt(6)
	s_barrier
	v_mfma_f32_16x16x32_bf16 v[48:51], v[198:201], v[166:169], v[48:51]
	v_mfma_f32_16x16x32_bf16 v[40:43], v[206:209], v[166:169], v[40:43]
	v_mfma_f32_16x16x32_bf16 v[32:35], v[198:201], v[174:177], v[32:35]
	v_mfma_f32_16x16x32_bf16 v[24:27], v[206:209], v[174:177], v[24:27]
	v_mfma_f32_16x16x32_bf16 v[16:19], v[198:201], v[182:185], v[16:19]
	v_mfma_f32_16x16x32_bf16 v[8:11], v[206:209], v[182:185], v[8:11]
	v_mfma_f32_16x16x32_bf16 v[4:7], v[198:201], v[190:193], v[4:7]
	v_mfma_f32_16x16x32_bf16 v[0:3], v[206:209], v[190:193], v[0:3]
	v_mfma_f32_16x16x32_bf16 v[48:51], v[202:205], v[170:173], v[48:51]
	v_mfma_f32_16x16x32_bf16 v[40:43], v[210:213], v[170:173], v[40:43]
	v_mfma_f32_16x16x32_bf16 v[32:35], v[202:205], v[178:181], v[32:35]
	v_mfma_f32_16x16x32_bf16 v[24:27], v[210:213], v[178:181], v[24:27]
	v_mfma_f32_16x16x32_bf16 v[16:19], v[202:205], v[186:189], v[16:19]
	v_mfma_f32_16x16x32_bf16 v[8:11], v[210:213], v[186:189], v[8:11]
	v_mfma_f32_16x16x32_bf16 v[4:7], v[202:205], v[194:197], v[4:7]
	v_mfma_f32_16x16x32_bf16 v[0:3], v[210:213], v[194:197], v[0:3]
	s_add_i32 s68, 0, 0x18000
	v_add_u32_e32 v162, s68, v149
	s_barrier
	ds_read_b128 v[144:147], v162
	ds_read_b128 v[154:157], v162 offset:1024
	ds_read_b128 v[158:161], v162 offset:2048
	ds_read_b128 v[162:165], v162 offset:3072
	s_add_u32 s26, s26, 0x40000
	s_addc_u32 s27, s27, 0
	s_mov_b32 m0, s40
	v_lshl_add_u64 v[198:199], s[26:27], 0, v[134:135]
	ds_read_b128 v[166:169], v152 offset:32768
	ds_read_b128 v[170:173], v152 offset:33792
	ds_read_b128 v[174:177], v152 offset:34816
	ds_read_b128 v[178:181], v152 offset:35840
	ds_read_b128 v[182:185], v152 offset:36864
	ds_read_b128 v[186:189], v152 offset:37888
	ds_read_b128 v[190:193], v152 offset:38912
	ds_read_b128 v[194:197], v152 offset:39936
	global_load_lds_dwordx4 v[198:199], off
	v_lshl_add_u64 v[198:199], s[26:27], 0, v[130:131]
	s_mov_b32 m0, s41
	s_nop 0
	global_load_lds_dwordx4 v[198:199], off
	s_waitcnt lgkmcnt(8)
	s_barrier
	s_waitcnt lgkmcnt(0)
	v_mfma_f32_16x16x32_bf16 v[124:127], v[144:147], v[166:169], v[124:127]
	v_mfma_f32_16x16x32_bf16 v[120:123], v[158:161], v[166:169], v[120:123]
	v_mfma_f32_16x16x32_bf16 v[116:119], v[144:147], v[174:177], v[116:119]
	v_mfma_f32_16x16x32_bf16 v[108:111], v[158:161], v[174:177], v[108:111]
	v_mfma_f32_16x16x32_bf16 v[100:103], v[144:147], v[182:185], v[100:103]
	v_mfma_f32_16x16x32_bf16 v[92:95], v[158:161], v[182:185], v[92:95]
	v_mfma_f32_16x16x32_bf16 v[84:87], v[144:147], v[190:193], v[84:87]
	v_mfma_f32_16x16x32_bf16 v[76:79], v[158:161], v[190:193], v[76:79]
	v_mfma_f32_16x16x32_bf16 v[124:127], v[154:157], v[170:173], v[124:127]
	v_mfma_f32_16x16x32_bf16 v[120:123], v[162:165], v[170:173], v[120:123]
	v_mfma_f32_16x16x32_bf16 v[116:119], v[154:157], v[178:181], v[116:119]
	v_mfma_f32_16x16x32_bf16 v[108:111], v[162:165], v[178:181], v[108:111]
	v_mfma_f32_16x16x32_bf16 v[100:103], v[154:157], v[186:189], v[100:103]
	v_mfma_f32_16x16x32_bf16 v[92:95], v[162:165], v[186:189], v[92:95]
	v_mfma_f32_16x16x32_bf16 v[84:87], v[154:157], v[194:197], v[84:87]
	v_mfma_f32_16x16x32_bf16 v[76:79], v[162:165], v[194:197], v[76:79]
	s_barrier
	s_add_i32 s26, 0, 0x1c000
	s_add_i32 s27, s68, s36
	v_add_u32_e32 v210, s26, v149
	v_lshl_add_u64 v[214:215], v[214:215], 0, s[4:5]
	s_mov_b32 m0, s27
	ds_read_b128 v[198:201], v210
	ds_read_b128 v[202:205], v210 offset:1024
	ds_read_b128 v[206:209], v210 offset:2048
	ds_read_b128 v[210:213], v210 offset:3072
	global_load_lds_dwordx4 v[214:215], off
	v_lshl_add_u64 v[214:215], v[216:217], 0, s[4:5]
	s_add_i32 m0, s27, 0x2000
	s_nop 0
	global_load_lds_dwordx4 v[214:215], off
	s_barrier
	s_waitcnt lgkmcnt(0)
	v_mfma_f32_16x16x32_bf16 v[112:115], v[198:201], v[166:169], v[112:115]
	v_mfma_f32_16x16x32_bf16 v[104:107], v[206:209], v[166:169], v[104:107]
	v_mfma_f32_16x16x32_bf16 v[96:99], v[198:201], v[174:177], v[96:99]
	v_mfma_f32_16x16x32_bf16 v[88:91], v[206:209], v[174:177], v[88:91]
	v_mfma_f32_16x16x32_bf16 v[80:83], v[198:201], v[182:185], v[80:83]
	v_mfma_f32_16x16x32_bf16 v[72:75], v[206:209], v[182:185], v[72:75]
	v_mfma_f32_16x16x32_bf16 v[68:71], v[198:201], v[190:193], v[68:71]
	v_mfma_f32_16x16x32_bf16 v[64:67], v[206:209], v[190:193], v[64:67]
	v_mfma_f32_16x16x32_bf16 v[112:115], v[202:205], v[170:173], v[112:115]
	v_mfma_f32_16x16x32_bf16 v[104:107], v[210:213], v[170:173], v[104:107]
	v_mfma_f32_16x16x32_bf16 v[96:99], v[202:205], v[178:181], v[96:99]
	v_mfma_f32_16x16x32_bf16 v[88:91], v[210:213], v[178:181], v[88:91]
	v_mfma_f32_16x16x32_bf16 v[80:83], v[202:205], v[186:189], v[80:83]
	v_mfma_f32_16x16x32_bf16 v[72:75], v[210:213], v[186:189], v[72:75]
	v_mfma_f32_16x16x32_bf16 v[68:71], v[202:205], v[194:197], v[68:71]
	v_mfma_f32_16x16x32_bf16 v[64:67], v[210:213], v[194:197], v[64:67]
	s_mov_b32 m0, s43
	v_lshl_add_u64 v[214:215], v[218:219], 0, s[4:5]
	s_barrier
	ds_read_b128 v[166:169], v152 offset:49152
	ds_read_b128 v[170:173], v152 offset:50176
	ds_read_b128 v[174:177], v152 offset:51200
	ds_read_b128 v[178:181], v152 offset:52224
	ds_read_b128 v[182:185], v152 offset:53248
	ds_read_b128 v[186:189], v152 offset:54272
	ds_read_b128 v[190:193], v152 offset:55296
	ds_read_b128 v[194:197], v152 offset:56320
	global_load_lds_dwordx4 v[214:215], off
	v_lshl_add_u64 v[214:215], v[220:221], 0, s[4:5]
	s_mov_b32 m0, s48
	s_nop 0
	global_load_lds_dwordx4 v[214:215], off
	s_barrier
; #define PG8_STAGE(bufoff, gbase, voff) do { _Pragma("unroll") for (int _i = 0; _i < 2; ++_i) \
;         __builtin_amdgcn_global_load_lds((const unsigned*)((const char*)(gbase) + (voff)[_i]), (PG8_LAS unsigned*)(lds + (bufoff) + ldsw + _i * 8192), 16, 0, 0); } while (0)
; #define PG8_MMA(ai, bj, At, Bt) do { __builtin_amdgcn_s_setprio(1); _Pragma("unroll") for (int m = 0; m < 4; ++m) _Pragma("unroll") for (int n = 0; n < 2; ++n) _Pragma("unroll") for (int k = 0; k < 2; ++k) \
;         acc[ai][bj][m][n] = __builtin_amdgcn_mfma_f32_16x16x32_bf16(Bt[n][k], At[m][k], acc[ai][bj][m][n], 0, 0, 0); __builtin_amdgcn_s_setprio(0); } while (0)
; #define PG8_WAIT_V(n) asm volatile("s_waitcnt vmcnt(" #n ")" ::: "memory")
; #define PG8_WAIT_L(n) asm volatile("s_waitcnt lgkmcnt(" #n ")" ::: "memory")
; #define PG8_BAR __builtin_amdgcn_s_barrier()
; #define PG8_SCHED __builtin_amdgcn_sched_barrier(0)
; template <class Epi, class Sched>
; __device__ __forceinline__ void gemm_phase(PG8_LAS unsigned char* lds, const Gemm g, const Sched& S, const Epi& E) {
;     ...
;             PG8_BAR; PG8_WAIT_L(0); PG8_MMA(1, 0, At, B0); PG8_BAR; PG8_SCHED;
;             PG8_STAGE(PG8_SB(1, 1), b3 + hstep, voffB);
;             PG8_WAIT_V(6); PG8_BAR; PG8_MMA(1, 1, At, B1); PG8_BAR;
;         }
	s_waitcnt lgkmcnt(0)
	v_mfma_f32_16x16x32_bf16 v[60:63], v[144:147], v[166:169], v[60:63]
	v_mfma_f32_16x16x32_bf16 v[56:59], v[158:161], v[166:169], v[56:59]
	v_mfma_f32_16x16x32_bf16 v[52:55], v[144:147], v[174:177], v[52:55]
	v_mfma_f32_16x16x32_bf16 v[44:47], v[158:161], v[174:177], v[44:47]
	v_mfma_f32_16x16x32_bf16 v[36:39], v[144:147], v[182:185], v[36:39]
	v_mfma_f32_16x16x32_bf16 v[28:31], v[158:161], v[182:185], v[28:31]
	v_mfma_f32_16x16x32_bf16 v[20:23], v[144:147], v[190:193], v[20:23]
	v_mfma_f32_16x16x32_bf16 v[12:15], v[158:161], v[190:193], v[12:15]
	v_mfma_f32_16x16x32_bf16 v[60:63], v[154:157], v[170:173], v[60:63]
	v_mfma_f32_16x16x32_bf16 v[56:59], v[162:165], v[170:173], v[56:59]
	v_mfma_f32_16x16x32_bf16 v[52:55], v[154:157], v[178:181], v[52:55]
	v_mfma_f32_16x16x32_bf16 v[44:47], v[162:165], v[178:181], v[44:47]
	v_mfma_f32_16x16x32_bf16 v[36:39], v[154:157], v[186:189], v[36:39]
	v_mfma_f32_16x16x32_bf16 v[28:31], v[162:165], v[186:189], v[28:31]
	v_mfma_f32_16x16x32_bf16 v[20:23], v[154:157], v[194:197], v[20:23]
	v_mfma_f32_16x16x32_bf16 v[12:15], v[162:165], v[194:197], v[12:15]
	s_barrier
	s_add_u32 s24, s24, 0x40080
	s_addc_u32 s25, s25, 0
	s_add_i32 s26, s26, s36
	v_lshl_add_u64 v[144:145], s[24:25], 0, v[132:133]
	s_mov_b32 m0, s26
	s_nop 0
	global_load_lds_dwordx4 v[144:145], off
	v_lshl_add_u64 v[144:145], s[24:25], 0, v[128:129]
	s_add_i32 m0, s26, 0x2000
	s_nop 0
	global_load_lds_dwordx4 v[144:145], off
	s_waitcnt vmcnt(6)
	s_barrier
	v_mfma_f32_16x16x32_bf16 v[48:51], v[198:201], v[166:169], v[48:51]
	v_mfma_f32_16x16x32_bf16 v[40:43], v[206:209], v[166:169], v[40:43]
	v_mfma_f32_16x16x32_bf16 v[32:35], v[198:201], v[174:177], v[32:35]
	v_mfma_f32_16x16x32_bf16 v[24:27], v[206:209], v[174:177], v[24:27]
	v_mfma_f32_16x16x32_bf16 v[16:19], v[198:201], v[182:185], v[16:19]
	v_mfma_f32_16x16x32_bf16 v[8:11], v[206:209], v[182:185], v[8:11]
	v_mfma_f32_16x16x32_bf16 v[4:7], v[198:201], v[190:193], v[4:7]
	v_mfma_f32_16x16x32_bf16 v[0:3], v[206:209], v[190:193], v[0:3]
	v_mfma_f32_16x16x32_bf16 v[48:51], v[202:205], v[170:173], v[48:51]
	v_mfma_f32_16x16x32_bf16 v[40:43], v[210:213], v[170:173], v[40:43]
	v_mfma_f32_16x16x32_bf16 v[32:35], v[202:205], v[178:181], v[32:35]
	v_mfma_f32_16x16x32_bf16 v[24:27], v[210:213], v[178:181], v[24:27]
	v_mfma_f32_16x16x32_bf16 v[16:19], v[202:205], v[186:189], v[16:19]
	v_mfma_f32_16x16x32_bf16 v[8:11], v[210:213], v[186:189], v[8:11]
	v_mfma_f32_16x16x32_bf16 v[4:7], v[202:205], v[194:197], v[4:7]
	v_mfma_f32_16x16x32_bf16 v[0:3], v[210:213], v[194:197], v[0:3]
	s_add_i32 s67, s67, 2
	s_add_u32 s20, s20, 0x100
	s_addc_u32 s21, s21, 0
	s_add_u32 s65, s65, 0x100
	s_addc_u32 s66, s66, 0
	s_cmp_gt_u32 s67, 13
	s_barrier
	s_cbranch_scc0 .LBB0_166
; __device__ __forceinline__ unsigned pk2(float lo, float hi) { unsigned r; asm("v_cvt_pk_bf16_f32 %0, %1, %2" : "=v"(r) : "v"(lo), "v"(hi)); return r; }
;     __device__ __forceinline__ void operator()(const f32x4 (&acc)[2][2][4][2], const Unit& u, int wr, int wc, int fr, int fq) const {
;         const int row0 = u.pm * BM + wr * 64 + fr, col0 = u.pn * BM + wc * 32 + 8 * fq;
; #pragma unroll
;         for (int ai = 0; ai < 2; ++ai)
; #pragma unroll
;             for (int m = 0; m < 4; ++m) { bf16_t* rowp = O + (size_t)(row0 + ai * HALF + m * 16) * ldc + col0;
; #pragma unroll
;                 for (int bj = 0; bj < 2; ++bj) { const f32x4 v0 = acc[ai][bj][m][0], v1 = acc[ai][bj][m][1]; u32x4 w; w.x = pk2(v0[0], v0[1]); w.y = pk2(v0[2], v0[3]); w.z = pk2(v1[0], v1[1]); w.w = pk2(v1[2], v1[3]);
;                     __builtin_nontemporal_store(w, (u32x4*)(rowp + bj * HALF)); } }
;     }
	v_lshl_add_u32 v156, s14, 8, v148
	v_lshl_or_b32 v146, s62, 8, v150
	v_ashrrev_i32_e32 v147, 31, v146
	v_mov_b64_e32 v[144:145], s[50:51]
	v_cvt_pk_bf16_f32 v68, v68, v69
	v_cvt_pk_bf16_f32 v69, v70, v71
	v_cvt_pk_bf16_f32 v70, v64, v65
	v_add_u32_e32 v64, 0x80, v156
	v_mad_i64_i32 v[154:155], s[20:21], v156, s61, v[144:145]
	v_lshlrev_b64 v[146:147], 1, v[146:147]
	v_cvt_pk_bf16_f32 v112, v112, v113
	v_cvt_pk_bf16_f32 v113, v114, v115
	v_cvt_pk_bf16_f32 v114, v104, v105
	v_or_b32_e32 v104, 16, v156
	v_mad_i64_i32 v[64:65], s[20:21], v64, s61, v[144:145]
	v_cvt_pk_bf16_f32 v48, v48, v49
	v_cvt_pk_bf16_f32 v49, v50, v51
	v_cvt_pk_bf16_f32 v50, v40, v41
	v_add_u32_e32 v40, 0x90, v156
	v_lshl_add_u64 v[154:155], v[154:155], 0, v[146:147]
	v_mad_i64_i32 v[104:105], s[20:21], v104, s61, v[144:145]
	v_cvt_pk_bf16_f32 v96, v96, v97
	v_cvt_pk_bf16_f32 v97, v98, v99
	v_cvt_pk_bf16_f32 v98, v88, v89
	v_or_b32_e32 v88, 32, v156
	v_lshl_add_u64 v[64:65], v[64:65], 0, v[146:147]
	v_mad_i64_i32 v[40:41], s[20:21], v40, s61, v[144:145]
	v_cvt_pk_bf16_f32 v32, v32, v33
	v_cvt_pk_bf16_f32 v33, v34, v35
	v_cvt_pk_bf16_f32 v34, v24, v25
	v_add_u32_e32 v24, 0xa0, v156
	v_cvt_pk_bf16_f32 v115, v106, v107
	global_store_dwordx4 v[154:155], v[112:115], off offset:256 nt
	v_mad_i64_i32 v[88:89], s[20:21], v88, s61, v[144:145]
	s_nop 0
	v_lshl_add_u64 v[112:113], v[104:105], 0, v[146:147]
	v_cvt_pk_bf16_f32 v80, v80, v81
	v_cvt_pk_bf16_f32 v81, v82, v83
	v_cvt_pk_bf16_f32 v82, v72, v73
	v_or_b32_e32 v72, 48, v156
	v_cvt_pk_bf16_f32 v51, v42, v43
	global_store_dwordx4 v[64:65], v[48:51], off offset:256 nt
	v_mad_i64_i32 v[24:25], s[20:21], v24, s61, v[144:145]
	s_nop 0
	v_lshl_add_u64 v[48:49], v[40:41], 0, v[146:147]
	v_cvt_pk_bf16_f32 v16, v16, v17
	v_cvt_pk_bf16_f32 v17, v18, v19
	v_cvt_pk_bf16_f32 v18, v8, v9
	v_add_u32_e32 v8, 0xb0, v156
	v_cvt_pk_bf16_f32 v99, v90, v91
	global_store_dwordx4 v[112:113], v[96:99], off offset:256 nt
	v_mad_i64_i32 v[72:73], s[20:21], v72, s61, v[144:145]
	s_nop 0
	v_lshl_add_u64 v[96:97], v[88:89], 0, v[146:147]
	v_cvt_pk_bf16_f32 v35, v26, v27
	global_store_dwordx4 v[48:49], v[32:35], off offset:256 nt
	v_mad_i64_i32 v[8:9], s[20:21], v8, s61, v[144:145]
	s_nop 0
	v_lshl_add_u64 v[32:33], v[24:25], 0, v[146:147]
	v_cvt_pk_bf16_f32 v83, v74, v75
	global_store_dwordx4 v[96:97], v[80:83], off offset:256 nt
	v_cvt_pk_bf16_f32 v19, v10, v11
	global_store_dwordx4 v[32:33], v[16:19], off offset:256 nt
	s_and_b64 vcc, exec, s[0:1]
	v_lshl_add_u64 v[80:81], v[72:73], 0, v[146:147]
	v_lshl_add_u64 v[16:17], v[8:9], 0, v[146:147]
	s_mov_b32 s62, s6
	s_mov_b32 s14, s8
	s_mov_b64 s[24:25], s[12:13]
	s_mov_b64 s[20:21], s[10:11]
	v_cvt_pk_bf16_f32 v124, v124, v125
	v_cvt_pk_bf16_f32 v125, v126, v127
	v_cvt_pk_bf16_f32 v126, v120, v121
	v_cvt_pk_bf16_f32 v127, v122, v123
	global_store_dwordx4 v[154:155], v[124:127], off nt
	v_cvt_pk_bf16_f32 v104, v116, v117
	v_cvt_pk_bf16_f32 v105, v118, v119
	v_cvt_pk_bf16_f32 v106, v108, v109
	v_cvt_pk_bf16_f32 v107, v110, v111
	global_store_dwordx4 v[112:113], v[104:107], off nt
	v_cvt_pk_bf16_f32 v88, v100, v101
	v_cvt_pk_bf16_f32 v89, v102, v103
	v_cvt_pk_bf16_f32 v90, v92, v93
	v_cvt_pk_bf16_f32 v91, v94, v95
	global_store_dwordx4 v[96:97], v[88:91], off nt
	v_cvt_pk_bf16_f32 v72, v84, v85
	v_cvt_pk_bf16_f32 v73, v86, v87
	v_cvt_pk_bf16_f32 v74, v76, v77
	v_cvt_pk_bf16_f32 v75, v78, v79
	global_store_dwordx4 v[80:81], v[72:75], off nt
	v_cvt_pk_bf16_f32 v71, v66, v67
	global_store_dwordx4 v[80:81], v[68:71], off offset:256 nt
	v_cvt_pk_bf16_f32 v60, v60, v61
	v_cvt_pk_bf16_f32 v61, v62, v63
	v_cvt_pk_bf16_f32 v62, v56, v57
	v_cvt_pk_bf16_f32 v63, v58, v59
	global_store_dwordx4 v[64:65], v[60:63], off nt
	v_cvt_pk_bf16_f32 v40, v52, v53
	v_cvt_pk_bf16_f32 v41, v54, v55
	v_cvt_pk_bf16_f32 v42, v44, v45
	v_cvt_pk_bf16_f32 v43, v46, v47
	global_store_dwordx4 v[48:49], v[40:43], off nt
	v_cvt_pk_bf16_f32 v24, v36, v37
	v_cvt_pk_bf16_f32 v25, v38, v39
	v_cvt_pk_bf16_f32 v26, v28, v29
	v_cvt_pk_bf16_f32 v27, v30, v31
	global_store_dwordx4 v[32:33], v[24:27], off nt
	v_cvt_pk_bf16_f32 v8, v20, v21
	v_cvt_pk_bf16_f32 v9, v22, v23
	v_cvt_pk_bf16_f32 v10, v12, v13
	v_cvt_pk_bf16_f32 v11, v14, v15
	global_store_dwordx4 v[16:17], v[8:11], off nt
	v_cvt_pk_bf16_f32 v4, v4, v5
	v_cvt_pk_bf16_f32 v5, v6, v7
	v_cvt_pk_bf16_f32 v6, v0, v1
	v_cvt_pk_bf16_f32 v7, v2, v3
	global_store_dwordx4 v[16:17], v[4:7], off offset:256 nt
	s_cbranch_vccz .LBB0_163
	s_waitcnt vmcnt(0)
	s_cmpk_gt_u32 s3, 0xff
	s_cbranch_scc1 .LBB0_170
	s_barrier

; #define PG8_STAGE(bufoff, gbase, voff) do { _Pragma("unroll") for (int _i = 0; _i < 2; ++_i) \
;         __builtin_amdgcn_global_load_lds((const unsigned*)((const char*)(gbase) + (voff)[_i]), (PG8_LAS unsigned*)(lds + (bufoff) + ldsw + _i * 8192), 16, 0, 0); } while (0)
; #define PG8_LDA(dst, b, h) do { _Pragma("unroll") for (int m = 0; m < 4; ++m) _Pragma("unroll") for (int k = 0; k < 2; ++k) dst[m][k] = *(const PG8_LAS bf16x8*)(lds + PG8_SA(b, h) + aoff + m * 2048 + k * 1024); } while (0)
; #define PG8_LDB(dst, b, h) do { _Pragma("unroll") for (int n = 0; n < 2; ++n) _Pragma("unroll") for (int k = 0; k < 2; ++k) dst[n][k] = *(const PG8_LAS bf16x8*)(lds + PG8_SB(b, h) + boff + n * 2048 + k * 1024); } while (0)
; #define PG8_MMA(ai, bj, At, Bt) do { __builtin_amdgcn_s_setprio(1); _Pragma("unroll") for (int m = 0; m < 4; ++m) _Pragma("unroll") for (int n = 0; n < 2; ++n) _Pragma("unroll") for (int k = 0; k < 2; ++k) \
;         acc[ai][bj][m][n] = __builtin_amdgcn_mfma_f32_16x16x32_bf16(Bt[n][k], At[m][k], acc[ai][bj][m][n], 0, 0, 0); __builtin_amdgcn_s_setprio(0); } while (0)
; #define PG8_WAIT_L(n) asm volatile("s_waitcnt lgkmcnt(" #n ")" ::: "memory")
; #define PG8_BAR __builtin_amdgcn_s_barrier()
; #define PG8_SCHED __builtin_amdgcn_sched_barrier(0)
; template <class Epi, class Sched>
; __device__ __forceinline__ void gemm_phase(PG8_LAS unsigned char* lds, const Gemm g, const Sched& S, const Epi& E) {
;     ...
;             PG8_LDB(B0, 0, 0); PG8_SCHED; PG8_LDA(At, 0, 0); PG8_STAGE(PG8_SA(1, 1), a1 + hstep, voffA);
;             PG8_WAIT_L(8); PG8_BAR; PG8_WAIT_L(0); PG8_MMA(0, 0, At, B0); PG8_BAR; PG8_SCHED;
;             PG8_LDB(B1, 0, 1); PG8_STAGE(PG8_SB(0, 0), b2, voffB);
;             PG8_BAR; PG8_WAIT_L(0); PG8_MMA(0, 1, At, B1); PG8_BAR;
;             PG8_LDA(At, 0, 1); PG8_STAGE(PG8_SA(0, 0), a2, voffA);
;             PG8_BAR; PG8_WAIT_L(0); PG8_MMA(1, 0, At, B0); PG8_BAR; PG8_SCHED;
.LBB0_439:
	ds_read_b128 v[8:11], v154
	ds_read_b128 v[12:15], v154 offset:1024
	ds_read_b128 v[16:19], v154 offset:2048
	ds_read_b128 v[20:23], v154 offset:3072
	s_add_u32 s70, s38, 0x18080
	s_addc_u32 s71, s39, 0
	s_add_i32 s77, s48, 0xc000
	v_lshl_add_u64 v[0:1], s[70:71], 0, v[128:129]
	s_mov_b32 m0, s77
	ds_read_b128 v[4:7], v152
	ds_read_b128 v[24:27], v152 offset:1024
	ds_read_b128 v[28:31], v152 offset:2048
	ds_read_b128 v[32:35], v152 offset:3072
	ds_read_b128 v[36:39], v152 offset:4096
	ds_read_b128 v[40:43], v152 offset:5120
	ds_read_b128 v[44:47], v152 offset:6144
	ds_read_b128 v[48:51], v152 offset:7168
	global_load_lds_dwordx4 v[0:1], off
	v_lshl_add_u64 v[0:1], s[70:71], 0, v[132:133]
	s_add_i32 s70, s48, 0xe000
	s_mov_b32 m0, s70
	s_nop 0
	global_load_lds_dwordx4 v[0:1], off
	s_waitcnt lgkmcnt(8)
	s_barrier
	s_waitcnt lgkmcnt(0)
	v_mfma_f32_16x16x32_bf16 v[0:3], v[8:11], v[4:7], 0
	v_mfma_f32_16x16x32_bf16 v[52:55], v[12:15], v[24:27], v[0:3]
	v_mfma_f32_16x16x32_bf16 v[0:3], v[16:19], v[4:7], 0
	v_mfma_f32_16x16x32_bf16 v[56:59], v[20:23], v[24:27], v[0:3]
	v_mfma_f32_16x16x32_bf16 v[0:3], v[8:11], v[28:31], 0
	v_mfma_f32_16x16x32_bf16 v[60:63], v[12:15], v[32:35], v[0:3]
	v_mfma_f32_16x16x32_bf16 v[0:3], v[16:19], v[28:31], 0
	v_mfma_f32_16x16x32_bf16 v[64:67], v[20:23], v[32:35], v[0:3]
	v_mfma_f32_16x16x32_bf16 v[0:3], v[8:11], v[36:39], 0
	v_mfma_f32_16x16x32_bf16 v[68:71], v[12:15], v[40:43], v[0:3]
	v_mfma_f32_16x16x32_bf16 v[0:3], v[16:19], v[36:39], 0
	v_mfma_f32_16x16x32_bf16 v[72:75], v[20:23], v[40:43], v[0:3]
	v_mfma_f32_16x16x32_bf16 v[0:3], v[8:11], v[44:47], 0
	v_mfma_f32_16x16x32_bf16 v[76:79], v[12:15], v[48:51], v[0:3]
	v_mfma_f32_16x16x32_bf16 v[0:3], v[16:19], v[44:47], 0
	v_mfma_f32_16x16x32_bf16 v[80:83], v[20:23], v[48:51], v[0:3]
	s_barrier
	s_nop 4
	v_lshl_add_u64 v[0:1], s[40:41], 0, v[130:131]
	s_add_i32 s73, s65, s43
	v_lshl_add_u64 v[2:3], v[0:1], 0, s[20:21]
	s_mov_b32 m0, s73
	ds_read_b128 v[84:87], v155
	ds_read_b128 v[88:91], v155 offset:1024
	ds_read_b128 v[92:95], v155 offset:2048
	ds_read_b128 v[96:99], v155 offset:3072
	global_load_lds_dwordx4 v[2:3], off
	v_lshl_add_u64 v[2:3], s[40:41], 0, v[134:135]
	s_add_i32 s71, s73, 0x2000
	v_lshl_add_u64 v[100:101], v[2:3], 0, s[20:21]
	s_mov_b32 m0, s71
	s_nop 0
	global_load_lds_dwordx4 v[100:101], off
	s_barrier
	s_waitcnt lgkmcnt(0)
	v_mfma_f32_16x16x32_bf16 v[100:103], v[84:87], v[4:7], 0
	v_mfma_f32_16x16x32_bf16 v[4:7], v[92:95], v[4:7], 0
	v_mfma_f32_16x16x32_bf16 v[100:103], v[88:91], v[24:27], v[100:103]
	v_mfma_f32_16x16x32_bf16 v[24:27], v[96:99], v[24:27], v[4:7]
	v_mfma_f32_16x16x32_bf16 v[4:7], v[84:87], v[28:31], 0
	v_mfma_f32_16x16x32_bf16 v[104:107], v[88:91], v[32:35], v[4:7]
	v_mfma_f32_16x16x32_bf16 v[4:7], v[92:95], v[28:31], 0
	v_mfma_f32_16x16x32_bf16 v[28:31], v[96:99], v[32:35], v[4:7]
	v_mfma_f32_16x16x32_bf16 v[4:7], v[84:87], v[36:39], 0
	v_mfma_f32_16x16x32_bf16 v[32:35], v[88:91], v[40:43], v[4:7]
	v_mfma_f32_16x16x32_bf16 v[4:7], v[92:95], v[36:39], 0
	v_mfma_f32_16x16x32_bf16 v[36:39], v[96:99], v[40:43], v[4:7]
	v_mfma_f32_16x16x32_bf16 v[4:7], v[84:87], v[44:47], 0
	v_mfma_f32_16x16x32_bf16 v[40:43], v[88:91], v[48:51], v[4:7]
	v_mfma_f32_16x16x32_bf16 v[4:7], v[92:95], v[44:47], 0
	v_mfma_f32_16x16x32_bf16 v[44:47], v[96:99], v[48:51], v[4:7]
	s_nop 5
	v_lshl_add_u64 v[4:5], s[38:39], 0, v[128:129]
	s_mov_b32 m0, s48
	v_lshl_add_u64 v[6:7], v[4:5], 0, s[20:21]
	s_barrier
	ds_read_b128 v[48:51], v152 offset:16384
	ds_read_b128 v[108:111], v152 offset:17408
	ds_read_b128 v[112:115], v152 offset:18432
	ds_read_b128 v[116:119], v152 offset:19456
	ds_read_b128 v[120:123], v152 offset:20480
	ds_read_b128 v[124:127], v152 offset:21504
	ds_read_b128 v[140:143], v152 offset:22528
	ds_read_b128 v[144:147], v152 offset:23552
	global_load_lds_dwordx4 v[6:7], off
	v_lshl_add_u64 v[6:7], s[38:39], 0, v[132:133]
	v_lshl_add_u64 v[148:149], v[6:7], 0, s[20:21]
	s_mov_b32 m0, s49
	s_nop 0
	global_load_lds_dwordx4 v[148:149], off
	s_barrier
	s_waitcnt lgkmcnt(0)
	v_mfma_f32_16x16x32_bf16 v[156:159], v[8:11], v[48:51], 0
	v_mfma_f32_16x16x32_bf16 v[164:167], v[8:11], v[112:115], 0
	v_mfma_f32_16x16x32_bf16 v[172:175], v[8:11], v[120:123], 0
	v_mfma_f32_16x16x32_bf16 v[8:11], v[8:11], v[140:143], 0
	v_mfma_f32_16x16x32_bf16 v[156:159], v[12:15], v[108:111], v[156:159]
	v_mfma_f32_16x16x32_bf16 v[160:163], v[16:19], v[48:51], 0
	v_mfma_f32_16x16x32_bf16 v[164:167], v[12:15], v[116:119], v[164:167]
	v_mfma_f32_16x16x32_bf16 v[168:171], v[16:19], v[112:115], 0
	v_mfma_f32_16x16x32_bf16 v[172:175], v[12:15], v[124:127], v[172:175]
	v_mfma_f32_16x16x32_bf16 v[176:179], v[16:19], v[120:123], 0
	v_mfma_f32_16x16x32_bf16 v[10:13], v[12:15], v[144:147], v[8:11]
	v_mfma_f32_16x16x32_bf16 v[14:17], v[16:19], v[140:143], 0
	v_mfma_f32_16x16x32_bf16 v[160:163], v[20:23], v[108:111], v[160:163]
	v_mfma_f32_16x16x32_bf16 v[168:171], v[20:23], v[116:119], v[168:171]
	v_mfma_f32_16x16x32_bf16 v[176:179], v[20:23], v[124:127], v[176:179]
	v_mfma_f32_16x16x32_bf16 v[14:17], v[20:23], v[144:147], v[14:17]
	s_barrier
	s_add_u32 s78, s40, 0x18100
	s_addc_u32 s79, s41, 0
	s_add_i32 s74, s66, s43
	v_lshl_add_u64 v[8:9], s[78:79], 0, v[130:131]
	s_mov_b32 m0, s74
	s_add_i32 s72, s74, 0x2000
	global_load_lds_dwordx4 v[8:9], off
	v_lshl_add_u64 v[8:9], s[78:79], 0, v[134:135]
	s_mov_b32 m0, s72
	s_nop 0
	global_load_lds_dwordx4 v[8:9], off
	s_waitcnt vmcnt(6)
	s_barrier
; #define PG8_STAGE(bufoff, gbase, voff) do { _Pragma("unroll") for (int _i = 0; _i < 2; ++_i) \
;         __builtin_amdgcn_global_load_lds((const unsigned*)((const char*)(gbase) + (voff)[_i]), (PG8_LAS unsigned*)(lds + (bufoff) + ldsw + _i * 8192), 16, 0, 0); } while (0)
; #define PG8_LDA(dst, b, h) do { _Pragma("unroll") for (int m = 0; m < 4; ++m) _Pragma("unroll") for (int k = 0; k < 2; ++k) dst[m][k] = *(const PG8_LAS bf16x8*)(lds + PG8_SA(b, h) + aoff + m * 2048 + k * 1024); } while (0)
; #define PG8_LDB(dst, b, h) do { _Pragma("unroll") for (int n = 0; n < 2; ++n) _Pragma("unroll") for (int k = 0; k < 2; ++k) dst[n][k] = *(const PG8_LAS bf16x8*)(lds + PG8_SB(b, h) + boff + n * 2048 + k * 1024); } while (0)
; #define PG8_MMA(ai, bj, At, Bt) do { __builtin_amdgcn_s_setprio(1); _Pragma("unroll") for (int m = 0; m < 4; ++m) _Pragma("unroll") for (int n = 0; n < 2; ++n) _Pragma("unroll") for (int k = 0; k < 2; ++k) \
;         acc[ai][bj][m][n] = __builtin_amdgcn_mfma_f32_16x16x32_bf16(Bt[n][k], At[m][k], acc[ai][bj][m][n], 0, 0, 0); __builtin_amdgcn_s_setprio(0); } while (0)
; #define PG8_WAIT_V(n) asm volatile("s_waitcnt vmcnt(" #n ")" ::: "memory")
; #define PG8_WAIT_L(n) asm volatile("s_waitcnt lgkmcnt(" #n ")" ::: "memory")
; #define PG8_BAR __builtin_amdgcn_s_barrier()
; #define PG8_SCHED __builtin_amdgcn_sched_barrier(0)
; template <class Epi, class Sched>
; __device__ __forceinline__ void gemm_phase(PG8_LAS unsigned char* lds, const Gemm g, const Sched& S, const Epi& E) {
;     ...
;             PG8_STAGE(PG8_SB(0, 1), b2 + hstep, voffB);
;             PG8_WAIT_V(6); PG8_BAR; PG8_MMA(1, 1, At, B1); PG8_BAR;
;             PG8_LDB(B0, 1, 0); PG8_SCHED; PG8_LDA(At, 1, 0); PG8_STAGE(PG8_SA(0, 1), a2 + hstep, voffA);
;             PG8_WAIT_L(8); PG8_BAR; PG8_WAIT_L(0); PG8_MMA(0, 0, At, B0); PG8_BAR; PG8_SCHED;
;             PG8_LDB(B1, 1, 1); PG8_STAGE(PG8_SB(1, 0), b3, voffB);
;             PG8_BAR; PG8_WAIT_L(0); PG8_MMA(0, 1, At, B1); PG8_BAR;
;             PG8_LDA(At, 1, 1); PG8_STAGE(PG8_SA(1, 0), a3, voffA);
	v_mfma_f32_16x16x32_bf16 v[18:21], v[84:87], v[48:51], 0
	v_mfma_f32_16x16x32_bf16 v[48:51], v[92:95], v[48:51], 0
	v_mfma_f32_16x16x32_bf16 v[18:21], v[88:91], v[108:111], v[18:21]
	v_mfma_f32_16x16x32_bf16 v[48:51], v[96:99], v[108:111], v[48:51]
	v_mfma_f32_16x16x32_bf16 v[108:111], v[84:87], v[112:115], 0
	v_mfma_f32_16x16x32_bf16 v[112:115], v[92:95], v[112:115], 0
	v_mfma_f32_16x16x32_bf16 v[108:111], v[88:91], v[116:119], v[108:111]
	v_mfma_f32_16x16x32_bf16 v[112:115], v[96:99], v[116:119], v[112:115]
	v_mfma_f32_16x16x32_bf16 v[116:119], v[84:87], v[120:123], 0
	v_mfma_f32_16x16x32_bf16 v[84:87], v[84:87], v[140:143], 0
	v_mfma_f32_16x16x32_bf16 v[116:119], v[88:91], v[124:127], v[116:119]
	v_mfma_f32_16x16x32_bf16 v[120:123], v[92:95], v[120:123], 0
	v_mfma_f32_16x16x32_bf16 v[84:87], v[88:91], v[144:147], v[84:87]
	v_mfma_f32_16x16x32_bf16 v[88:91], v[92:95], v[140:143], 0
	v_mfma_f32_16x16x32_bf16 v[120:123], v[96:99], v[124:127], v[120:123]
	v_mfma_f32_16x16x32_bf16 v[88:91], v[96:99], v[144:147], v[88:91]
	s_add_i32 s75, 0, 0x18000
	v_add_u32_e32 v8, s75, v151
	s_barrier
	ds_read_b128 v[92:95], v8
	ds_read_b128 v[96:99], v8 offset:1024
	ds_read_b128 v[124:127], v8 offset:2048
	ds_read_b128 v[140:143], v8 offset:3072
	s_add_u32 s78, s38, 0x18100
	s_addc_u32 s79, s39, 0
	s_mov_b32 m0, s52
	v_lshl_add_u64 v[22:23], s[78:79], 0, v[128:129]
	ds_read_b128 v[144:147], v152 offset:32768
	ds_read_b128 v[180:183], v152 offset:33792
	ds_read_b128 v[184:187], v152 offset:34816
	ds_read_b128 v[188:191], v152 offset:35840
	ds_read_b128 v[192:195], v152 offset:36864
	ds_read_b128 v[196:199], v152 offset:37888
	ds_read_b128 v[200:203], v152 offset:38912
	ds_read_b128 v[204:207], v152 offset:39936
	global_load_lds_dwordx4 v[22:23], off
	v_lshl_add_u64 v[22:23], s[78:79], 0, v[132:133]
	s_mov_b32 m0, s53
	s_nop 0
	global_load_lds_dwordx4 v[22:23], off
	s_waitcnt lgkmcnt(8)
	s_barrier
	s_waitcnt lgkmcnt(0)
	v_mfma_f32_16x16x32_bf16 v[52:55], v[92:95], v[144:147], v[52:55]
	v_mfma_f32_16x16x32_bf16 v[56:59], v[124:127], v[144:147], v[56:59]
	v_mfma_f32_16x16x32_bf16 v[60:63], v[92:95], v[184:187], v[60:63]
	v_mfma_f32_16x16x32_bf16 v[64:67], v[124:127], v[184:187], v[64:67]
	v_mfma_f32_16x16x32_bf16 v[68:71], v[92:95], v[192:195], v[68:71]
	v_mfma_f32_16x16x32_bf16 v[72:75], v[124:127], v[192:195], v[72:75]
	v_mfma_f32_16x16x32_bf16 v[76:79], v[92:95], v[200:203], v[76:79]
	v_mfma_f32_16x16x32_bf16 v[80:83], v[124:127], v[200:203], v[80:83]
	v_mfma_f32_16x16x32_bf16 v[52:55], v[96:99], v[180:183], v[52:55]
	v_mfma_f32_16x16x32_bf16 v[56:59], v[140:143], v[180:183], v[56:59]
	v_mfma_f32_16x16x32_bf16 v[60:63], v[96:99], v[188:191], v[60:63]
	v_mfma_f32_16x16x32_bf16 v[64:67], v[140:143], v[188:191], v[64:67]
	v_mfma_f32_16x16x32_bf16 v[68:71], v[96:99], v[196:199], v[68:71]
	v_mfma_f32_16x16x32_bf16 v[72:75], v[140:143], v[196:199], v[72:75]
	v_mfma_f32_16x16x32_bf16 v[76:79], v[96:99], v[204:207], v[76:79]
	v_mfma_f32_16x16x32_bf16 v[80:83], v[140:143], v[204:207], v[80:83]
	s_barrier
	s_add_i32 s79, 0, 0x1c000
	s_add_i32 s78, s75, s43
	v_add_u32_e32 v9, s79, v151
	v_lshl_add_u64 v[22:23], v[0:1], 0, s[24:25]
	s_mov_b32 m0, s78
	s_add_i32 s75, s78, 0x2000
	ds_read_b128 v[208:211], v9
	ds_read_b128 v[216:219], v9 offset:1024
	ds_read_b128 v[220:223], v9 offset:2048
	ds_read_b128 v[224:227], v9 offset:3072
	global_load_lds_dwordx4 v[22:23], off
	v_lshl_add_u64 v[22:23], v[2:3], 0, s[24:25]
	s_mov_b32 m0, s75
	s_nop 0
	global_load_lds_dwordx4 v[22:23], off
	s_barrier
	s_waitcnt lgkmcnt(0)
	v_mfma_f32_16x16x32_bf16 v[100:103], v[208:211], v[144:147], v[100:103]
	v_mfma_f32_16x16x32_bf16 v[22:25], v[220:223], v[144:147], v[24:27]
	v_mfma_f32_16x16x32_bf16 v[104:107], v[208:211], v[184:187], v[104:107]
	v_mfma_f32_16x16x32_bf16 v[26:29], v[220:223], v[184:187], v[28:31]
	v_mfma_f32_16x16x32_bf16 v[30:33], v[208:211], v[192:195], v[32:35]
	v_mfma_f32_16x16x32_bf16 v[34:37], v[220:223], v[192:195], v[36:39]
	v_mfma_f32_16x16x32_bf16 v[38:41], v[208:211], v[200:203], v[40:43]
	v_mfma_f32_16x16x32_bf16 v[42:45], v[220:223], v[200:203], v[44:47]
	v_mfma_f32_16x16x32_bf16 v[100:103], v[216:219], v[180:183], v[100:103]
	v_mfma_f32_16x16x32_bf16 v[22:25], v[224:227], v[180:183], v[22:25]
	v_mfma_f32_16x16x32_bf16 v[104:107], v[216:219], v[188:191], v[104:107]
	v_mfma_f32_16x16x32_bf16 v[26:29], v[224:227], v[188:191], v[26:29]
	v_mfma_f32_16x16x32_bf16 v[30:33], v[216:219], v[196:199], v[30:33]
	v_mfma_f32_16x16x32_bf16 v[34:37], v[224:227], v[196:199], v[34:37]
	v_mfma_f32_16x16x32_bf16 v[38:41], v[216:219], v[204:207], v[38:41]
	v_mfma_f32_16x16x32_bf16 v[42:45], v[224:227], v[204:207], v[42:45]
	s_mov_b32 m0, s60
	v_lshl_add_u64 v[46:47], v[4:5], 0, s[24:25]
	s_barrier
	ds_read_b128 v[144:147], v152 offset:49152
	ds_read_b128 v[180:183], v152 offset:50176
	ds_read_b128 v[184:187], v152 offset:51200
	ds_read_b128 v[188:191], v152 offset:52224
	ds_read_b128 v[192:195], v152 offset:53248
	ds_read_b128 v[196:199], v152 offset:54272
	ds_read_b128 v[200:203], v152 offset:55296
	ds_read_b128 v[204:207], v152 offset:56320
	global_load_lds_dwordx4 v[46:47], off
	v_lshl_add_u64 v[46:47], v[6:7], 0, s[24:25]
	s_mov_b32 m0, s61
	s_nop 0
	global_load_lds_dwordx4 v[46:47], off
	s_barrier
; #define PG8_STAGE(bufoff, gbase, voff) do { _Pragma("unroll") for (int _i = 0; _i < 2; ++_i) \
;         __builtin_amdgcn_global_load_lds((const unsigned*)((const char*)(gbase) + (voff)[_i]), (PG8_LAS unsigned*)(lds + (bufoff) + ldsw + _i * 8192), 16, 0, 0); } while (0)
; #define PG8_LDA(dst, b, h) do { _Pragma("unroll") for (int m = 0; m < 4; ++m) _Pragma("unroll") for (int k = 0; k < 2; ++k) dst[m][k] = *(const PG8_LAS bf16x8*)(lds + PG8_SA(b, h) + aoff + m * 2048 + k * 1024); } while (0)
; #define PG8_LDB(dst, b, h) do { _Pragma("unroll") for (int n = 0; n < 2; ++n) _Pragma("unroll") for (int k = 0; k < 2; ++k) dst[n][k] = *(const PG8_LAS bf16x8*)(lds + PG8_SB(b, h) + boff + n * 2048 + k * 1024); } while (0)
; #define PG8_WAIT_V(n) asm volatile("s_waitcnt vmcnt(" #n ")" ::: "memory")
; #define PG8_WAIT_L(n) asm volatile("s_waitcnt lgkmcnt(" #n ")" ::: "memory")
; #define PG8_BAR __builtin_amdgcn_s_barrier()
; #define PG8_SCHED __builtin_amdgcn_sched_barrier(0)
; template <class Epi, class Sched>
; __device__ __forceinline__ void gemm_phase(PG8_LAS unsigned char* lds, const Gemm g, const Sched& S, const Epi& E) {
;     ...
;             PG8_LDB(B0, 0, 0); PG8_SCHED; PG8_LDA(At, 0, 0); PG8_STAGE(PG8_SA(1, 1), a1 + hstep, voffA);
;             PG8_WAIT_L(8); PG8_BAR; PG8_WAIT_L(0); PG8_MMA(0, 0, At, B0); PG8_BAR; PG8_SCHED;
;             PG8_LDB(B1, 0, 1); PG8_STAGE(PG8_SB(0, 0), b2, voffB);
;             PG8_BAR; PG8_WAIT_L(0); PG8_MMA(0, 1, At, B1); PG8_BAR;
;             PG8_LDA(At, 0, 1); PG8_STAGE(PG8_SA(0, 0), a2, voffA);
;             PG8_BAR; PG8_WAIT_L(0); PG8_MMA(1, 0, At, B0); PG8_BAR; PG8_SCHED;
;             PG8_STAGE(PG8_SB(0, 1), b2 + hstep, voffB);
;             PG8_WAIT_V(6); PG8_BAR; PG8_MMA(1, 1, At, B1); PG8_BAR;
;             PG8_LDB(B0, 1, 0); PG8_SCHED; PG8_LDA(At, 1, 0); PG8_STAGE(PG8_SA(0, 1), a2 + hstep, voffA);
;             PG8_WAIT_L(8); PG8_BAR; PG8_WAIT_L(0); PG8_MMA(0, 0, At, B0); PG8_BAR; PG8_SCHED;
;             PG8_LDB(B1, 1, 1); PG8_STAGE(PG8_SB(1, 0), b3, voffB);
;             PG8_BAR; PG8_WAIT_L(0); PG8_MMA(0, 1, At, B1); PG8_BAR;
;             PG8_LDA(At, 1, 1); PG8_STAGE(PG8_SA(1, 0), a3, voffA);
;             PG8_BAR; PG8_WAIT_L(0); PG8_MMA(1, 0, At, B0); PG8_BAR; PG8_SCHED;
;             PG8_STAGE(PG8_SB(1, 1), b3 + hstep, voffB);
;             PG8_WAIT_V(6); PG8_BAR; PG8_MMA(1, 1, At, B1); PG8_BAR;
	s_waitcnt lgkmcnt(0)
	v_mfma_f32_16x16x32_bf16 v[156:159], v[92:95], v[144:147], v[156:159]
	v_mfma_f32_16x16x32_bf16 v[160:163], v[124:127], v[144:147], v[160:163]
	v_mfma_f32_16x16x32_bf16 v[164:167], v[92:95], v[184:187], v[164:167]
	v_mfma_f32_16x16x32_bf16 v[168:171], v[124:127], v[184:187], v[168:171]
	v_mfma_f32_16x16x32_bf16 v[172:175], v[92:95], v[192:195], v[172:175]
	v_mfma_f32_16x16x32_bf16 v[176:179], v[124:127], v[192:195], v[176:179]
	v_mfma_f32_16x16x32_bf16 v[10:13], v[92:95], v[200:203], v[10:13]
	v_mfma_f32_16x16x32_bf16 v[14:17], v[124:127], v[200:203], v[14:17]
	v_mfma_f32_16x16x32_bf16 v[156:159], v[96:99], v[180:183], v[156:159]
	v_mfma_f32_16x16x32_bf16 v[160:163], v[140:143], v[180:183], v[160:163]
	v_mfma_f32_16x16x32_bf16 v[164:167], v[96:99], v[188:191], v[164:167]
	v_mfma_f32_16x16x32_bf16 v[168:171], v[140:143], v[188:191], v[168:171]
	v_mfma_f32_16x16x32_bf16 v[172:175], v[96:99], v[196:199], v[172:175]
	v_mfma_f32_16x16x32_bf16 v[176:179], v[140:143], v[196:199], v[176:179]
	v_mfma_f32_16x16x32_bf16 v[10:13], v[96:99], v[204:207], v[10:13]
	v_mfma_f32_16x16x32_bf16 v[14:17], v[140:143], v[204:207], v[14:17]
	s_barrier
	s_add_u32 s80, s40, 0x18180
	s_addc_u32 s81, s41, 0
	s_add_i32 s79, s79, s43
	v_lshl_add_u64 v[46:47], s[80:81], 0, v[130:131]
	s_mov_b32 m0, s79
	s_add_i32 s76, s79, 0x2000
	global_load_lds_dwordx4 v[46:47], off
	v_lshl_add_u64 v[46:47], s[80:81], 0, v[134:135]
	s_mov_b32 m0, s76
	s_nop 0
	global_load_lds_dwordx4 v[46:47], off
	s_waitcnt vmcnt(6)
	s_barrier
	v_mfma_f32_16x16x32_bf16 v[18:21], v[208:211], v[144:147], v[18:21]
	v_mfma_f32_16x16x32_bf16 v[46:49], v[220:223], v[144:147], v[48:51]
	v_mfma_f32_16x16x32_bf16 v[92:95], v[208:211], v[184:187], v[108:111]
	v_mfma_f32_16x16x32_bf16 v[96:99], v[220:223], v[184:187], v[112:115]
	v_mfma_f32_16x16x32_bf16 v[108:111], v[208:211], v[192:195], v[116:119]
	v_mfma_f32_16x16x32_bf16 v[112:115], v[220:223], v[192:195], v[120:123]
	v_mfma_f32_16x16x32_bf16 v[84:87], v[208:211], v[200:203], v[84:87]
	v_mfma_f32_16x16x32_bf16 v[88:91], v[220:223], v[200:203], v[88:91]
	v_mfma_f32_16x16x32_bf16 v[18:21], v[216:219], v[180:183], v[18:21]
	v_mfma_f32_16x16x32_bf16 v[46:49], v[224:227], v[180:183], v[46:49]
	v_mfma_f32_16x16x32_bf16 v[92:95], v[216:219], v[188:191], v[92:95]
	v_mfma_f32_16x16x32_bf16 v[96:99], v[224:227], v[188:191], v[96:99]
	v_mfma_f32_16x16x32_bf16 v[108:111], v[216:219], v[196:199], v[108:111]
	v_mfma_f32_16x16x32_bf16 v[112:115], v[224:227], v[196:199], v[112:115]
	v_mfma_f32_16x16x32_bf16 v[84:87], v[216:219], v[204:207], v[84:87]
	v_mfma_f32_16x16x32_bf16 v[88:91], v[224:227], v[204:207], v[88:91]
	s_barrier
	ds_read_b128 v[116:119], v154
	ds_read_b128 v[120:123], v154 offset:1024
	ds_read_b128 v[124:127], v154 offset:2048
	ds_read_b128 v[140:143], v154 offset:3072
	s_add_u32 s80, s38, 0x18180
	s_addc_u32 s81, s39, 0
	s_mov_b32 m0, s77
	v_lshl_add_u64 v[50:51], s[80:81], 0, v[128:129]
	ds_read_b128 v[144:147], v152
	ds_read_b128 v[180:183], v152 offset:1024
	ds_read_b128 v[184:187], v152 offset:2048
	ds_read_b128 v[188:191], v152 offset:3072
	ds_read_b128 v[192:195], v152 offset:4096
	ds_read_b128 v[196:199], v152 offset:5120
	ds_read_b128 v[200:203], v152 offset:6144
	ds_read_b128 v[204:207], v152 offset:7168
	global_load_lds_dwordx4 v[50:51], off
	v_lshl_add_u64 v[50:51], s[80:81], 0, v[132:133]
	s_mov_b32 m0, s70
	s_nop 0
	global_load_lds_dwordx4 v[50:51], off
	s_waitcnt lgkmcnt(8)
	s_barrier
	s_waitcnt lgkmcnt(0)
	v_mfma_f32_16x16x32_bf16 v[50:53], v[116:119], v[144:147], v[52:55]
	v_mfma_f32_16x16x32_bf16 v[54:57], v[124:127], v[144:147], v[56:59]
	v_mfma_f32_16x16x32_bf16 v[58:61], v[116:119], v[184:187], v[60:63]
	v_mfma_f32_16x16x32_bf16 v[62:65], v[124:127], v[184:187], v[64:67]
	v_mfma_f32_16x16x32_bf16 v[66:69], v[116:119], v[192:195], v[68:71]
	v_mfma_f32_16x16x32_bf16 v[70:73], v[124:127], v[192:195], v[72:75]
	v_mfma_f32_16x16x32_bf16 v[74:77], v[116:119], v[200:203], v[76:79]
	v_mfma_f32_16x16x32_bf16 v[78:81], v[124:127], v[200:203], v[80:83]
	v_mfma_f32_16x16x32_bf16 v[50:53], v[120:123], v[180:183], v[50:53]
	v_mfma_f32_16x16x32_bf16 v[54:57], v[140:143], v[180:183], v[54:57]
	v_mfma_f32_16x16x32_bf16 v[58:61], v[120:123], v[188:191], v[58:61]
	v_mfma_f32_16x16x32_bf16 v[62:65], v[140:143], v[188:191], v[62:65]
	v_mfma_f32_16x16x32_bf16 v[66:69], v[120:123], v[196:199], v[66:69]
	v_mfma_f32_16x16x32_bf16 v[70:73], v[140:143], v[196:199], v[70:73]
	v_mfma_f32_16x16x32_bf16 v[74:77], v[120:123], v[204:207], v[74:77]
	v_mfma_f32_16x16x32_bf16 v[78:81], v[140:143], v[204:207], v[78:81]
	s_barrier
	s_mov_b32 m0, s73
	v_lshl_add_u64 v[82:83], v[0:1], 0, s[16:17]
	ds_read_b128 v[208:211], v155
	ds_read_b128 v[216:219], v155 offset:1024
	ds_read_b128 v[220:223], v155 offset:2048
	ds_read_b128 v[224:227], v155 offset:3072
	global_load_lds_dwordx4 v[82:83], off
	v_lshl_add_u64 v[82:83], v[2:3], 0, s[16:17]
	s_mov_b32 m0, s71
	s_nop 0
	global_load_lds_dwordx4 v[82:83], off
	s_barrier
	s_waitcnt lgkmcnt(0)
	v_mfma_f32_16x16x32_bf16 v[100:103], v[208:211], v[144:147], v[100:103]
	v_mfma_f32_16x16x32_bf16 v[22:25], v[220:223], v[144:147], v[22:25]
	v_mfma_f32_16x16x32_bf16 v[104:107], v[208:211], v[184:187], v[104:107]
	v_mfma_f32_16x16x32_bf16 v[26:29], v[220:223], v[184:187], v[26:29]
	v_mfma_f32_16x16x32_bf16 v[30:33], v[208:211], v[192:195], v[30:33]
	v_mfma_f32_16x16x32_bf16 v[34:37], v[220:223], v[192:195], v[34:37]
	v_mfma_f32_16x16x32_bf16 v[38:41], v[208:211], v[200:203], v[38:41]
	v_mfma_f32_16x16x32_bf16 v[42:45], v[220:223], v[200:203], v[42:45]
	v_mfma_f32_16x16x32_bf16 v[100:103], v[216:219], v[180:183], v[100:103]
	v_mfma_f32_16x16x32_bf16 v[22:25], v[224:227], v[180:183], v[22:25]
	v_mfma_f32_16x16x32_bf16 v[104:107], v[216:219], v[188:191], v[104:107]
	v_mfma_f32_16x16x32_bf16 v[26:29], v[224:227], v[188:191], v[26:29]
	v_mfma_f32_16x16x32_bf16 v[30:33], v[216:219], v[196:199], v[30:33]
	v_mfma_f32_16x16x32_bf16 v[34:37], v[224:227], v[196:199], v[34:37]
	v_mfma_f32_16x16x32_bf16 v[38:41], v[216:219], v[204:207], v[38:41]
	v_mfma_f32_16x16x32_bf16 v[42:45], v[224:227], v[204:207], v[42:45]
	s_mov_b32 m0, s48
	v_lshl_add_u64 v[82:83], v[4:5], 0, s[16:17]
	s_barrier
; #define PG8_STAGE(bufoff, gbase, voff) do { _Pragma("unroll") for (int _i = 0; _i < 2; ++_i) \
;         __builtin_amdgcn_global_load_lds((const unsigned*)((const char*)(gbase) + (voff)[_i]), (PG8_LAS unsigned*)(lds + (bufoff) + ldsw + _i * 8192), 16, 0, 0); } while (0)
; #define PG8_LDA(dst, b, h) do { _Pragma("unroll") for (int m = 0; m < 4; ++m) _Pragma("unroll") for (int k = 0; k < 2; ++k) dst[m][k] = *(const PG8_LAS bf16x8*)(lds + PG8_SA(b, h) + aoff + m * 2048 + k * 1024); } while (0)
; #define PG8_LDB(dst, b, h) do { _Pragma("unroll") for (int n = 0; n < 2; ++n) _Pragma("unroll") for (int k = 0; k < 2; ++k) dst[n][k] = *(const PG8_LAS bf16x8*)(lds + PG8_SB(b, h) + boff + n * 2048 + k * 1024); } while (0)
; #define PG8_MMA(ai, bj, At, Bt) do { __builtin_amdgcn_s_setprio(1); _Pragma("unroll") for (int m = 0; m < 4; ++m) _Pragma("unroll") for (int n = 0; n < 2; ++n) _Pragma("unroll") for (int k = 0; k < 2; ++k) \
;         acc[ai][bj][m][n] = __builtin_amdgcn_mfma_f32_16x16x32_bf16(Bt[n][k], At[m][k], acc[ai][bj][m][n], 0, 0, 0); __builtin_amdgcn_s_setprio(0); } while (0)
; #define PG8_WAIT_V(n) asm volatile("s_waitcnt vmcnt(" #n ")" ::: "memory")
; #define PG8_WAIT_L(n) asm volatile("s_waitcnt lgkmcnt(" #n ")" ::: "memory")
; #define PG8_BAR __builtin_amdgcn_s_barrier()
; #define PG8_SCHED __builtin_amdgcn_sched_barrier(0)
; template <class Epi, class Sched>
; __device__ __forceinline__ void gemm_phase(PG8_LAS unsigned char* lds, const Gemm g, const Sched& S, const Epi& E) {
;     ...
;             PG8_LDA(At, 0, 1); PG8_STAGE(PG8_SA(0, 0), a2, voffA);
;             PG8_BAR; PG8_WAIT_L(0); PG8_MMA(1, 0, At, B0); PG8_BAR; PG8_SCHED;
;             PG8_STAGE(PG8_SB(0, 1), b2 + hstep, voffB);
;             PG8_WAIT_V(6); PG8_BAR; PG8_MMA(1, 1, At, B1); PG8_BAR;
;             PG8_LDB(B0, 1, 0); PG8_SCHED; PG8_LDA(At, 1, 0); PG8_STAGE(PG8_SA(0, 1), a2 + hstep, voffA);
;             PG8_WAIT_L(8); PG8_BAR; PG8_WAIT_L(0); PG8_MMA(0, 0, At, B0); PG8_BAR; PG8_SCHED;
;             PG8_LDB(B1, 1, 1); PG8_STAGE(PG8_SB(1, 0), b3, voffB);
	ds_read_b128 v[144:147], v152 offset:16384
	ds_read_b128 v[180:183], v152 offset:17408
	ds_read_b128 v[184:187], v152 offset:18432
	ds_read_b128 v[188:191], v152 offset:19456
	ds_read_b128 v[192:195], v152 offset:20480
	ds_read_b128 v[196:199], v152 offset:21504
	ds_read_b128 v[200:203], v152 offset:22528
	ds_read_b128 v[204:207], v152 offset:23552
	global_load_lds_dwordx4 v[82:83], off
	v_lshl_add_u64 v[82:83], v[6:7], 0, s[16:17]
	s_mov_b32 m0, s49
	s_nop 0
	global_load_lds_dwordx4 v[82:83], off
	s_barrier
	s_waitcnt lgkmcnt(0)
	v_mfma_f32_16x16x32_bf16 v[156:159], v[116:119], v[144:147], v[156:159]
	v_mfma_f32_16x16x32_bf16 v[160:163], v[124:127], v[144:147], v[160:163]
	v_mfma_f32_16x16x32_bf16 v[164:167], v[116:119], v[184:187], v[164:167]
	v_mfma_f32_16x16x32_bf16 v[168:171], v[124:127], v[184:187], v[168:171]
	v_mfma_f32_16x16x32_bf16 v[172:175], v[116:119], v[192:195], v[172:175]
	v_mfma_f32_16x16x32_bf16 v[176:179], v[124:127], v[192:195], v[176:179]
	v_mfma_f32_16x16x32_bf16 v[10:13], v[116:119], v[200:203], v[10:13]
	v_mfma_f32_16x16x32_bf16 v[14:17], v[124:127], v[200:203], v[14:17]
	v_mfma_f32_16x16x32_bf16 v[156:159], v[120:123], v[180:183], v[156:159]
	v_mfma_f32_16x16x32_bf16 v[160:163], v[140:143], v[180:183], v[160:163]
	v_mfma_f32_16x16x32_bf16 v[164:167], v[120:123], v[188:191], v[164:167]
	v_mfma_f32_16x16x32_bf16 v[168:171], v[140:143], v[188:191], v[168:171]
	v_mfma_f32_16x16x32_bf16 v[172:175], v[120:123], v[196:199], v[172:175]
	v_mfma_f32_16x16x32_bf16 v[176:179], v[140:143], v[196:199], v[176:179]
	v_mfma_f32_16x16x32_bf16 v[10:13], v[120:123], v[204:207], v[10:13]
	v_mfma_f32_16x16x32_bf16 v[14:17], v[140:143], v[204:207], v[14:17]
	s_barrier
	s_add_u32 s80, s40, 0x18200
	s_addc_u32 s81, s41, 0
	s_mov_b32 m0, s74
	v_lshl_add_u64 v[82:83], s[80:81], 0, v[130:131]
	global_load_lds_dwordx4 v[82:83], off
	v_lshl_add_u64 v[82:83], s[80:81], 0, v[134:135]
	s_mov_b32 m0, s72
	s_nop 0
	global_load_lds_dwordx4 v[82:83], off
	s_waitcnt vmcnt(6)
	s_barrier
	v_mfma_f32_16x16x32_bf16 v[18:21], v[208:211], v[144:147], v[18:21]
	v_mfma_f32_16x16x32_bf16 v[46:49], v[220:223], v[144:147], v[46:49]
	v_mfma_f32_16x16x32_bf16 v[92:95], v[208:211], v[184:187], v[92:95]
	v_mfma_f32_16x16x32_bf16 v[96:99], v[220:223], v[184:187], v[96:99]
	v_mfma_f32_16x16x32_bf16 v[108:111], v[208:211], v[192:195], v[108:111]
	v_mfma_f32_16x16x32_bf16 v[112:115], v[220:223], v[192:195], v[112:115]
	v_mfma_f32_16x16x32_bf16 v[82:85], v[208:211], v[200:203], v[84:87]
	v_mfma_f32_16x16x32_bf16 v[86:89], v[220:223], v[200:203], v[88:91]
	v_mfma_f32_16x16x32_bf16 v[18:21], v[216:219], v[180:183], v[18:21]
	v_mfma_f32_16x16x32_bf16 v[46:49], v[224:227], v[180:183], v[46:49]
	v_mfma_f32_16x16x32_bf16 v[92:95], v[216:219], v[188:191], v[92:95]
	v_mfma_f32_16x16x32_bf16 v[96:99], v[224:227], v[188:191], v[96:99]
	v_mfma_f32_16x16x32_bf16 v[108:111], v[216:219], v[196:199], v[108:111]
	v_mfma_f32_16x16x32_bf16 v[112:115], v[224:227], v[196:199], v[112:115]
	v_mfma_f32_16x16x32_bf16 v[82:85], v[216:219], v[204:207], v[82:85]
	v_mfma_f32_16x16x32_bf16 v[86:89], v[224:227], v[204:207], v[86:89]
	s_barrier
	ds_read_b128 v[116:119], v8
	ds_read_b128 v[120:123], v8 offset:1024
	ds_read_b128 v[124:127], v8 offset:2048
	ds_read_b128 v[140:143], v8 offset:3072
	s_add_u32 s80, s38, 0x18200
	s_addc_u32 s81, s39, 0
	s_mov_b32 m0, s52
	v_lshl_add_u64 v[90:91], s[80:81], 0, v[128:129]
	ds_read_b128 v[144:147], v152 offset:32768
	ds_read_b128 v[180:183], v152 offset:33792
	ds_read_b128 v[184:187], v152 offset:34816
	ds_read_b128 v[188:191], v152 offset:35840
	ds_read_b128 v[192:195], v152 offset:36864
	ds_read_b128 v[196:199], v152 offset:37888
	ds_read_b128 v[200:203], v152 offset:38912
	ds_read_b128 v[204:207], v152 offset:39936
	global_load_lds_dwordx4 v[90:91], off
	v_lshl_add_u64 v[90:91], s[80:81], 0, v[132:133]
	s_mov_b32 m0, s53
	s_nop 0
	global_load_lds_dwordx4 v[90:91], off
	s_waitcnt lgkmcnt(8)
	s_barrier
	s_waitcnt lgkmcnt(0)
	v_mfma_f32_16x16x32_bf16 v[50:53], v[116:119], v[144:147], v[50:53]
	v_mfma_f32_16x16x32_bf16 v[54:57], v[124:127], v[144:147], v[54:57]
	v_mfma_f32_16x16x32_bf16 v[58:61], v[116:119], v[184:187], v[58:61]
	v_mfma_f32_16x16x32_bf16 v[62:65], v[124:127], v[184:187], v[62:65]
	v_mfma_f32_16x16x32_bf16 v[66:69], v[116:119], v[192:195], v[66:69]
	v_mfma_f32_16x16x32_bf16 v[70:73], v[124:127], v[192:195], v[70:73]
	v_mfma_f32_16x16x32_bf16 v[74:77], v[116:119], v[200:203], v[74:77]
	v_mfma_f32_16x16x32_bf16 v[78:81], v[124:127], v[200:203], v[78:81]
	v_mfma_f32_16x16x32_bf16 v[50:53], v[120:123], v[180:183], v[50:53]
	v_mfma_f32_16x16x32_bf16 v[54:57], v[140:143], v[180:183], v[54:57]
	v_mfma_f32_16x16x32_bf16 v[58:61], v[120:123], v[188:191], v[58:61]
	v_mfma_f32_16x16x32_bf16 v[62:65], v[140:143], v[188:191], v[62:65]
	v_mfma_f32_16x16x32_bf16 v[66:69], v[120:123], v[196:199], v[66:69]
	v_mfma_f32_16x16x32_bf16 v[70:73], v[140:143], v[196:199], v[70:73]
	v_mfma_f32_16x16x32_bf16 v[74:77], v[120:123], v[204:207], v[74:77]
	v_mfma_f32_16x16x32_bf16 v[78:81], v[140:143], v[204:207], v[78:81]
	s_barrier
	s_mov_b32 m0, s78
	v_lshl_add_u64 v[0:1], v[0:1], 0, s[26:27]
	ds_read_b128 v[208:211], v9
	ds_read_b128 v[216:219], v9 offset:1024
	ds_read_b128 v[220:223], v9 offset:2048
	ds_read_b128 v[224:227], v9 offset:3072
	global_load_lds_dwordx4 v[0:1], off
	v_lshl_add_u64 v[0:1], v[2:3], 0, s[26:27]
	s_mov_b32 m0, s75
	s_nop 0
	global_load_lds_dwordx4 v[0:1], off
	s_barrier
; #define PG8_STAGE(bufoff, gbase, voff) do { _Pragma("unroll") for (int _i = 0; _i < 2; ++_i) \
;         __builtin_amdgcn_global_load_lds((const unsigned*)((const char*)(gbase) + (voff)[_i]), (PG8_LAS unsigned*)(lds + (bufoff) + ldsw + _i * 8192), 16, 0, 0); } while (0)
; #define PG8_LDA(dst, b, h) do { _Pragma("unroll") for (int m = 0; m < 4; ++m) _Pragma("unroll") for (int k = 0; k < 2; ++k) dst[m][k] = *(const PG8_LAS bf16x8*)(lds + PG8_SA(b, h) + aoff + m * 2048 + k * 1024); } while (0)
; #define PG8_LDB(dst, b, h) do { _Pragma("unroll") for (int n = 0; n < 2; ++n) _Pragma("unroll") for (int k = 0; k < 2; ++k) dst[n][k] = *(const PG8_LAS bf16x8*)(lds + PG8_SB(b, h) + boff + n * 2048 + k * 1024); } while (0)
; #define PG8_WAIT_V(n) asm volatile("s_waitcnt vmcnt(" #n ")" ::: "memory")
; #define PG8_WAIT_L(n) asm volatile("s_waitcnt lgkmcnt(" #n ")" ::: "memory")
; #define PG8_BAR __builtin_amdgcn_s_barrier()
; #define PG8_SCHED __builtin_amdgcn_sched_barrier(0)
; template <class Epi, class Sched>
; __device__ __forceinline__ void gemm_phase(PG8_LAS unsigned char* lds, const Gemm g, const Sched& S, const Epi& E) {
;     ...
;             PG8_LDB(B0, 0, 0); PG8_SCHED; PG8_LDA(At, 0, 0); PG8_STAGE(PG8_SA(1, 1), a1 + hstep, voffA);
;             PG8_WAIT_L(8); PG8_BAR; PG8_WAIT_L(0); PG8_MMA(0, 0, At, B0); PG8_BAR; PG8_SCHED;
;             PG8_LDB(B1, 0, 1); PG8_STAGE(PG8_SB(0, 0), b2, voffB);
;             PG8_BAR; PG8_WAIT_L(0); PG8_MMA(0, 1, At, B1); PG8_BAR;
;             PG8_LDA(At, 0, 1); PG8_STAGE(PG8_SA(0, 0), a2, voffA);
;             PG8_BAR; PG8_WAIT_L(0); PG8_MMA(1, 0, At, B0); PG8_BAR; PG8_SCHED;
;             PG8_STAGE(PG8_SB(0, 1), b2 + hstep, voffB);
;             PG8_WAIT_V(6); PG8_BAR; PG8_MMA(1, 1, At, B1); PG8_BAR;
;             PG8_LDB(B0, 1, 0); PG8_SCHED; PG8_LDA(At, 1, 0); PG8_STAGE(PG8_SA(0, 1), a2 + hstep, voffA);
;             PG8_WAIT_L(8); PG8_BAR; PG8_WAIT_L(0); PG8_MMA(0, 0, At, B0); PG8_BAR; PG8_SCHED;
;             PG8_LDB(B1, 1, 1); PG8_STAGE(PG8_SB(1, 0), b3, voffB);
;             PG8_BAR; PG8_WAIT_L(0); PG8_MMA(0, 1, At, B1); PG8_BAR;
;             PG8_LDA(At, 1, 1); PG8_STAGE(PG8_SA(1, 0), a3, voffA);
;             PG8_BAR; PG8_WAIT_L(0); PG8_MMA(1, 0, At, B0); PG8_BAR; PG8_SCHED;
;             PG8_STAGE(PG8_SB(1, 1), b3 + hstep, voffB);
;             PG8_WAIT_V(6); PG8_BAR; PG8_MMA(1, 1, At, B1); PG8_BAR;
	s_waitcnt lgkmcnt(0)
	v_mfma_f32_16x16x32_bf16 v[0:3], v[208:211], v[144:147], v[100:103]
	v_mfma_f32_16x16x32_bf16 v[22:25], v[220:223], v[144:147], v[22:25]
	v_mfma_f32_16x16x32_bf16 v[100:103], v[208:211], v[184:187], v[104:107]
	v_mfma_f32_16x16x32_bf16 v[26:29], v[220:223], v[184:187], v[26:29]
	v_mfma_f32_16x16x32_bf16 v[30:33], v[208:211], v[192:195], v[30:33]
	v_mfma_f32_16x16x32_bf16 v[34:37], v[220:223], v[192:195], v[34:37]
	v_mfma_f32_16x16x32_bf16 v[38:41], v[208:211], v[200:203], v[38:41]
	v_mfma_f32_16x16x32_bf16 v[42:45], v[220:223], v[200:203], v[42:45]
	v_mfma_f32_16x16x32_bf16 v[0:3], v[216:219], v[180:183], v[0:3]
	v_mfma_f32_16x16x32_bf16 v[22:25], v[224:227], v[180:183], v[22:25]
	v_mfma_f32_16x16x32_bf16 v[100:103], v[216:219], v[188:191], v[100:103]
	v_mfma_f32_16x16x32_bf16 v[26:29], v[224:227], v[188:191], v[26:29]
	v_mfma_f32_16x16x32_bf16 v[30:33], v[216:219], v[196:199], v[30:33]
	v_mfma_f32_16x16x32_bf16 v[34:37], v[224:227], v[196:199], v[34:37]
	v_mfma_f32_16x16x32_bf16 v[38:41], v[216:219], v[204:207], v[38:41]
	v_mfma_f32_16x16x32_bf16 v[42:45], v[224:227], v[204:207], v[42:45]
	s_mov_b32 m0, s60
	v_lshl_add_u64 v[4:5], v[4:5], 0, s[26:27]
	s_barrier
	ds_read_b128 v[104:107], v152 offset:49152
	ds_read_b128 v[144:147], v152 offset:50176
	ds_read_b128 v[180:183], v152 offset:51200
	ds_read_b128 v[184:187], v152 offset:52224
	ds_read_b128 v[188:191], v152 offset:53248
	ds_read_b128 v[192:195], v152 offset:54272
	ds_read_b128 v[196:199], v152 offset:55296
	ds_read_b128 v[200:203], v152 offset:56320
	global_load_lds_dwordx4 v[4:5], off
	v_lshl_add_u64 v[4:5], v[6:7], 0, s[26:27]
	s_mov_b32 m0, s61
	s_nop 0
	global_load_lds_dwordx4 v[4:5], off
	s_barrier
	s_waitcnt lgkmcnt(0)
	v_mfma_f32_16x16x32_bf16 v[4:7], v[116:119], v[104:107], v[156:159]
	v_mfma_f32_16x16x32_bf16 v[156:159], v[124:127], v[104:107], v[160:163]
	v_mfma_f32_16x16x32_bf16 v[160:163], v[116:119], v[180:183], v[164:167]
	v_mfma_f32_16x16x32_bf16 v[164:167], v[124:127], v[180:183], v[168:171]
	v_mfma_f32_16x16x32_bf16 v[168:171], v[116:119], v[188:191], v[172:175]
	v_mfma_f32_16x16x32_bf16 v[172:175], v[124:127], v[188:191], v[176:179]
	v_mfma_f32_16x16x32_bf16 v[10:13], v[116:119], v[196:199], v[10:13]
	v_mfma_f32_16x16x32_bf16 v[14:17], v[124:127], v[196:199], v[14:17]
	v_mfma_f32_16x16x32_bf16 v[4:7], v[120:123], v[144:147], v[4:7]
	v_mfma_f32_16x16x32_bf16 v[156:159], v[140:143], v[144:147], v[156:159]
	v_mfma_f32_16x16x32_bf16 v[160:163], v[120:123], v[184:187], v[160:163]
	v_mfma_f32_16x16x32_bf16 v[164:167], v[140:143], v[184:187], v[164:167]
	v_mfma_f32_16x16x32_bf16 v[168:171], v[120:123], v[192:195], v[168:171]
	v_mfma_f32_16x16x32_bf16 v[172:175], v[140:143], v[192:195], v[172:175]
	v_mfma_f32_16x16x32_bf16 v[10:13], v[120:123], v[200:203], v[10:13]
	v_mfma_f32_16x16x32_bf16 v[14:17], v[140:143], v[200:203], v[14:17]
	s_barrier
	s_add_u32 s40, s40, 0x18280
	s_addc_u32 s41, s41, 0
	s_mov_b32 m0, s79
	v_lshl_add_u64 v[90:91], s[40:41], 0, v[130:131]
	global_load_lds_dwordx4 v[90:91], off
	v_lshl_add_u64 v[90:91], s[40:41], 0, v[134:135]
	s_mov_b32 m0, s76
	s_nop 0
	global_load_lds_dwordx4 v[90:91], off
	s_waitcnt vmcnt(6)
	s_barrier
	v_mfma_f32_16x16x32_bf16 v[18:21], v[208:211], v[104:107], v[18:21]
	v_mfma_f32_16x16x32_bf16 v[46:49], v[220:223], v[104:107], v[46:49]
	v_mfma_f32_16x16x32_bf16 v[90:93], v[208:211], v[180:183], v[92:95]
	v_mfma_f32_16x16x32_bf16 v[94:97], v[220:223], v[180:183], v[96:99]
	v_mfma_f32_16x16x32_bf16 v[104:107], v[208:211], v[188:191], v[108:111]
	v_mfma_f32_16x16x32_bf16 v[108:111], v[220:223], v[188:191], v[112:115]
	v_mfma_f32_16x16x32_bf16 v[82:85], v[208:211], v[196:199], v[82:85]
	v_mfma_f32_16x16x32_bf16 v[86:89], v[220:223], v[196:199], v[86:89]
	v_mfma_f32_16x16x32_bf16 v[18:21], v[216:219], v[144:147], v[18:21]
	v_mfma_f32_16x16x32_bf16 v[46:49], v[224:227], v[144:147], v[46:49]
	v_mfma_f32_16x16x32_bf16 v[90:93], v[216:219], v[184:187], v[90:93]
	v_mfma_f32_16x16x32_bf16 v[94:97], v[224:227], v[184:187], v[94:97]
	v_mfma_f32_16x16x32_bf16 v[104:107], v[216:219], v[192:195], v[104:107]
	v_mfma_f32_16x16x32_bf16 v[108:111], v[224:227], v[192:195], v[108:111]
	v_mfma_f32_16x16x32_bf16 v[82:85], v[216:219], v[200:203], v[82:85]
	v_mfma_f32_16x16x32_bf16 v[86:89], v[224:227], v[200:203], v[86:89]
	s_barrier
	ds_read_b128 v[112:115], v154
	ds_read_b128 v[116:119], v154 offset:1024
	ds_read_b128 v[120:123], v154 offset:2048
	ds_read_b128 v[124:127], v154 offset:3072
	s_add_u32 s38, s38, 0x18280
	s_addc_u32 s39, s39, 0
	s_mov_b32 m0, s77
	v_lshl_add_u64 v[98:99], s[38:39], 0, v[128:129]
	ds_read_b128 v[140:143], v152
	ds_read_b128 v[144:147], v152 offset:1024
	ds_read_b128 v[176:179], v152 offset:2048
	ds_read_b128 v[180:183], v152 offset:3072
	ds_read_b128 v[184:187], v152 offset:4096
	ds_read_b128 v[188:191], v152 offset:5120
	ds_read_b128 v[192:195], v152 offset:6144
	ds_read_b128 v[196:199], v152 offset:7168
	global_load_lds_dwordx4 v[98:99], off
	v_lshl_add_u64 v[98:99], s[38:39], 0, v[132:133]
	s_mov_b32 m0, s70
	s_nop 0
	global_load_lds_dwordx4 v[98:99], off
	s_waitcnt lgkmcnt(8)
	s_barrier
; #define PG8_STAGE(bufoff, gbase, voff) do { _Pragma("unroll") for (int _i = 0; _i < 2; ++_i) \
;         __builtin_amdgcn_global_load_lds((const unsigned*)((const char*)(gbase) + (voff)[_i]), (PG8_LAS unsigned*)(lds + (bufoff) + ldsw + _i * 8192), 16, 0, 0); } while (0)
; #define PG8_LDA(dst, b, h) do { _Pragma("unroll") for (int m = 0; m < 4; ++m) _Pragma("unroll") for (int k = 0; k < 2; ++k) dst[m][k] = *(const PG8_LAS bf16x8*)(lds + PG8_SA(b, h) + aoff + m * 2048 + k * 1024); } while (0)
; #define PG8_LDB(dst, b, h) do { _Pragma("unroll") for (int n = 0; n < 2; ++n) _Pragma("unroll") for (int k = 0; k < 2; ++k) dst[n][k] = *(const PG8_LAS bf16x8*)(lds + PG8_SB(b, h) + boff + n * 2048 + k * 1024); } while (0)
; #define PG8_MMA(ai, bj, At, Bt) do { __builtin_amdgcn_s_setprio(1); _Pragma("unroll") for (int m = 0; m < 4; ++m) _Pragma("unroll") for (int n = 0; n < 2; ++n) _Pragma("unroll") for (int k = 0; k < 2; ++k) \
;         acc[ai][bj][m][n] = __builtin_amdgcn_mfma_f32_16x16x32_bf16(Bt[n][k], At[m][k], acc[ai][bj][m][n], 0, 0, 0); __builtin_amdgcn_s_setprio(0); } while (0)
; #define PG8_WAIT_V(n) asm volatile("s_waitcnt vmcnt(" #n ")" ::: "memory")
; #define PG8_WAIT_L(n) asm volatile("s_waitcnt lgkmcnt(" #n ")" ::: "memory")
; #define PG8_BAR __builtin_amdgcn_s_barrier()
; #define PG8_SCHED __builtin_amdgcn_sched_barrier(0)
; template <class Epi, class Sched>
; __device__ __forceinline__ void gemm_phase(PG8_LAS unsigned char* lds, const Gemm g, const Sched& S, const Epi& E) {
;     ...
;             PG8_LDB(B0, 0, 0); PG8_SCHED; PG8_LDA(At, 0, 0); PG8_STAGE(PG8_SA(1, 1), a1 + hstep, voffA);
;             PG8_WAIT_L(8); PG8_BAR; PG8_WAIT_L(0); PG8_MMA(0, 0, At, B0); PG8_BAR; PG8_SCHED;
;             PG8_LDB(B1, 0, 1); PG8_STAGE(PG8_SB(0, 0), b2, voffB);
;             PG8_BAR; PG8_WAIT_L(0); PG8_MMA(0, 1, At, B1); PG8_BAR;
;             PG8_LDA(At, 0, 1); PG8_STAGE(PG8_SA(0, 0), a2, voffA);
;             PG8_BAR; PG8_WAIT_L(0); PG8_MMA(1, 0, At, B0); PG8_BAR; PG8_SCHED;
;             PG8_STAGE(PG8_SB(0, 1), b2 + hstep, voffB);
;             PG8_WAIT_V(6); PG8_BAR; PG8_MMA(1, 1, At, B1); PG8_BAR;
	s_waitcnt lgkmcnt(0)
	v_mfma_f32_16x16x32_bf16 v[50:53], v[112:115], v[140:143], v[50:53]
	v_mfma_f32_16x16x32_bf16 v[54:57], v[120:123], v[140:143], v[54:57]
	v_mfma_f32_16x16x32_bf16 v[58:61], v[112:115], v[176:179], v[58:61]
	v_mfma_f32_16x16x32_bf16 v[62:65], v[120:123], v[176:179], v[62:65]
	v_mfma_f32_16x16x32_bf16 v[66:69], v[112:115], v[184:187], v[66:69]
	v_mfma_f32_16x16x32_bf16 v[70:73], v[120:123], v[184:187], v[70:73]
	v_mfma_f32_16x16x32_bf16 v[74:77], v[112:115], v[192:195], v[74:77]
	v_mfma_f32_16x16x32_bf16 v[78:81], v[120:123], v[192:195], v[78:81]
	v_mfma_f32_16x16x32_bf16 v[50:53], v[116:119], v[144:147], v[50:53]
	v_mfma_f32_16x16x32_bf16 v[54:57], v[124:127], v[144:147], v[54:57]
	v_mfma_f32_16x16x32_bf16 v[58:61], v[116:119], v[180:183], v[58:61]
	v_mfma_f32_16x16x32_bf16 v[62:65], v[124:127], v[180:183], v[62:65]
	v_mfma_f32_16x16x32_bf16 v[66:69], v[116:119], v[188:191], v[66:69]
	v_mfma_f32_16x16x32_bf16 v[70:73], v[124:127], v[188:191], v[70:73]
	v_mfma_f32_16x16x32_bf16 v[74:77], v[116:119], v[196:199], v[74:77]
	v_mfma_f32_16x16x32_bf16 v[78:81], v[124:127], v[196:199], v[78:81]
	s_barrier
	s_mov_b32 m0, s73
	v_lshl_add_u64 v[148:149], s[6:7], 0, v[130:131]
	ds_read_b128 v[200:203], v155
	ds_read_b128 v[204:207], v155 offset:1024
	ds_read_b128 v[208:211], v155 offset:2048
	ds_read_b128 v[216:219], v155 offset:3072
	global_load_lds_dwordx4 v[148:149], off
	v_lshl_add_u64 v[212:213], s[6:7], 0, v[134:135]
	s_mov_b32 m0, s71
	s_nop 0
	global_load_lds_dwordx4 v[212:213], off
	s_barrier
	s_waitcnt lgkmcnt(0)
	v_mfma_f32_16x16x32_bf16 v[38:41], v[200:203], v[192:195], v[38:41]
	v_mfma_f32_16x16x32_bf16 v[0:3], v[200:203], v[140:143], v[0:3]
	v_mfma_f32_16x16x32_bf16 v[22:25], v[208:211], v[140:143], v[22:25]
	v_mfma_f32_16x16x32_bf16 v[98:101], v[200:203], v[176:179], v[100:103]
	v_mfma_f32_16x16x32_bf16 v[26:29], v[208:211], v[176:179], v[26:29]
	v_mfma_f32_16x16x32_bf16 v[30:33], v[200:203], v[184:187], v[30:33]
	v_mfma_f32_16x16x32_bf16 v[34:37], v[208:211], v[184:187], v[34:37]
	v_mfma_f32_16x16x32_bf16 v[140:143], v[204:207], v[196:199], v[38:41]
	v_mfma_f32_16x16x32_bf16 v[38:41], v[208:211], v[192:195], v[42:45]
	v_mfma_f32_16x16x32_bf16 v[0:3], v[204:207], v[144:147], v[0:3]
	v_mfma_f32_16x16x32_bf16 v[22:25], v[216:219], v[144:147], v[22:25]
	v_mfma_f32_16x16x32_bf16 v[98:101], v[204:207], v[180:183], v[98:101]
	v_mfma_f32_16x16x32_bf16 v[26:29], v[216:219], v[180:183], v[26:29]
	v_mfma_f32_16x16x32_bf16 v[30:33], v[204:207], v[188:191], v[30:33]
	v_mfma_f32_16x16x32_bf16 v[34:37], v[216:219], v[188:191], v[34:37]
	v_mfma_f32_16x16x32_bf16 v[144:147], v[216:219], v[196:199], v[38:41]
	s_mov_b32 m0, s48
	v_lshl_add_u64 v[102:103], s[0:1], 0, v[128:129]
	s_barrier
	ds_read_b128 v[38:41], v152 offset:16384
	ds_read_b128 v[42:45], v152 offset:17408
	ds_read_b128 v[176:179], v152 offset:18432
	ds_read_b128 v[180:183], v152 offset:19456
	ds_read_b128 v[184:187], v152 offset:20480
	ds_read_b128 v[188:191], v152 offset:21504
	ds_read_b128 v[192:195], v152 offset:22528
	ds_read_b128 v[196:199], v152 offset:23552
	global_load_lds_dwordx4 v[102:103], off
	v_lshl_add_u64 v[252:253], s[0:1], 0, v[132:133]
	s_mov_b32 m0, s49
	s_nop 0
	global_load_lds_dwordx4 v[252:253], off
	s_barrier
	s_waitcnt lgkmcnt(0)
	v_mfma_f32_16x16x32_bf16 v[4:7], v[112:115], v[38:41], v[4:7]
	v_mfma_f32_16x16x32_bf16 v[156:159], v[120:123], v[38:41], v[156:159]
	v_mfma_f32_16x16x32_bf16 v[160:163], v[112:115], v[176:179], v[160:163]
	v_mfma_f32_16x16x32_bf16 v[164:167], v[120:123], v[176:179], v[164:167]
	v_mfma_f32_16x16x32_bf16 v[168:171], v[112:115], v[184:187], v[168:171]
	v_mfma_f32_16x16x32_bf16 v[172:175], v[120:123], v[184:187], v[172:175]
	v_mfma_f32_16x16x32_bf16 v[10:13], v[112:115], v[192:195], v[10:13]
	v_mfma_f32_16x16x32_bf16 v[14:17], v[120:123], v[192:195], v[14:17]
	v_mfma_f32_16x16x32_bf16 v[4:7], v[116:119], v[42:45], v[4:7]
	v_mfma_f32_16x16x32_bf16 v[156:159], v[124:127], v[42:45], v[156:159]
	v_mfma_f32_16x16x32_bf16 v[160:163], v[116:119], v[180:183], v[160:163]
	v_mfma_f32_16x16x32_bf16 v[164:167], v[124:127], v[180:183], v[164:167]
	v_mfma_f32_16x16x32_bf16 v[168:171], v[116:119], v[188:191], v[168:171]
	v_mfma_f32_16x16x32_bf16 v[172:175], v[124:127], v[188:191], v[172:175]
	v_mfma_f32_16x16x32_bf16 v[10:13], v[116:119], v[196:199], v[10:13]
	v_mfma_f32_16x16x32_bf16 v[14:17], v[124:127], v[196:199], v[14:17]
	s_barrier
	s_add_u32 s38, s6, 0x18000
	s_addc_u32 s39, s7, 0
	s_mov_b32 m0, s74
	v_lshl_add_u64 v[112:113], s[38:39], 0, v[130:131]
	global_load_lds_dwordx4 v[112:113], off
	v_lshl_add_u64 v[112:113], s[38:39], 0, v[134:135]
	s_mov_b32 m0, s72
	s_nop 0
	global_load_lds_dwordx4 v[112:113], off
	s_waitcnt vmcnt(6)
	s_barrier
	v_mfma_f32_16x16x32_bf16 v[18:21], v[200:203], v[38:41], v[18:21]
	v_mfma_f32_16x16x32_bf16 v[38:41], v[208:211], v[38:41], v[46:49]
	v_mfma_f32_16x16x32_bf16 v[220:223], v[216:219], v[42:45], v[38:41]
	v_mfma_f32_16x16x32_bf16 v[38:41], v[200:203], v[176:179], v[90:93]
	v_mfma_f32_16x16x32_bf16 v[224:227], v[204:207], v[180:183], v[38:41]
	v_mfma_f32_16x16x32_bf16 v[38:41], v[208:211], v[176:179], v[94:97]
	v_mfma_f32_16x16x32_bf16 v[176:179], v[216:219], v[180:183], v[38:41]
	v_mfma_f32_16x16x32_bf16 v[38:41], v[200:203], v[184:187], v[104:107]
	v_mfma_f32_16x16x32_bf16 v[180:183], v[204:207], v[188:191], v[38:41]
	v_mfma_f32_16x16x32_bf16 v[38:41], v[208:211], v[184:187], v[108:111]
	v_mfma_f32_16x16x32_bf16 v[184:187], v[216:219], v[188:191], v[38:41]
	v_mfma_f32_16x16x32_bf16 v[38:41], v[200:203], v[192:195], v[82:85]
	v_mfma_f32_16x16x32_bf16 v[188:191], v[204:207], v[196:199], v[38:41]
	v_mfma_f32_16x16x32_bf16 v[38:41], v[208:211], v[192:195], v[86:89]
	v_mfma_f32_16x16x32_bf16 v[18:21], v[204:207], v[42:45], v[18:21]
	v_mfma_f32_16x16x32_bf16 v[192:195], v[216:219], v[196:199], v[38:41]
	s_barrier
; #define PG8_STAGE(bufoff, gbase, voff) do { _Pragma("unroll") for (int _i = 0; _i < 2; ++_i) \
;         __builtin_amdgcn_global_load_lds((const unsigned*)((const char*)(gbase) + (voff)[_i]), (PG8_LAS unsigned*)(lds + (bufoff) + ldsw + _i * 8192), 16, 0, 0); } while (0)
; #define PG8_LDA(dst, b, h) do { _Pragma("unroll") for (int m = 0; m < 4; ++m) _Pragma("unroll") for (int k = 0; k < 2; ++k) dst[m][k] = *(const PG8_LAS bf16x8*)(lds + PG8_SA(b, h) + aoff + m * 2048 + k * 1024); } while (0)
; #define PG8_LDB(dst, b, h) do { _Pragma("unroll") for (int n = 0; n < 2; ++n) _Pragma("unroll") for (int k = 0; k < 2; ++k) dst[n][k] = *(const PG8_LAS bf16x8*)(lds + PG8_SB(b, h) + boff + n * 2048 + k * 1024); } while (0)
; #define PG8_MMA(ai, bj, At, Bt) do { __builtin_amdgcn_s_setprio(1); _Pragma("unroll") for (int m = 0; m < 4; ++m) _Pragma("unroll") for (int n = 0; n < 2; ++n) _Pragma("unroll") for (int k = 0; k < 2; ++k) \
;         acc[ai][bj][m][n] = __builtin_amdgcn_mfma_f32_16x16x32_bf16(Bt[n][k], At[m][k], acc[ai][bj][m][n], 0, 0, 0); __builtin_amdgcn_s_setprio(0); } while (0)
; #define PG8_WAIT_L(n) asm volatile("s_waitcnt lgkmcnt(" #n ")" ::: "memory")
; #define PG8_BAR __builtin_amdgcn_s_barrier()
; #define PG8_SCHED __builtin_amdgcn_sched_barrier(0)
; template <class Epi, class Sched>
; __device__ __forceinline__ void gemm_phase(PG8_LAS unsigned char* lds, const Gemm g, const Sched& S, const Epi& E) {
;     ...
;             PG8_LDB(B0, 1, 0); PG8_SCHED; PG8_LDA(At, 1, 0); PG8_STAGE(PG8_SA(0, 1), a2 + hstep, voffA);
;             PG8_WAIT_L(8); PG8_BAR; PG8_WAIT_L(0); PG8_MMA(0, 0, At, B0); PG8_BAR; PG8_SCHED;
;             PG8_LDB(B1, 1, 1); PG8_STAGE(PG8_SB(1, 0), b3, voffB);
;             PG8_BAR; PG8_WAIT_L(0); PG8_MMA(0, 1, At, B1); PG8_BAR;
;             PG8_LDA(At, 1, 1); PG8_STAGE(PG8_SA(1, 0), a3, voffA);
;             PG8_BAR; PG8_WAIT_L(0); PG8_MMA(1, 0, At, B0); PG8_BAR; PG8_SCHED;
;             PG8_STAGE(PG8_SB(1, 1), b3 + hstep, voffB);
	ds_read_b128 v[196:199], v8
	ds_read_b128 v[200:203], v8 offset:1024
	ds_read_b128 v[204:207], v8 offset:2048
	ds_read_b128 v[208:211], v8 offset:3072
	s_add_u32 s38, s0, 0x18000
	s_addc_u32 s39, s1, 0
	s_mov_b32 m0, s52
	v_lshl_add_u64 v[104:105], s[38:39], 0, v[128:129]
	ds_read_b128 v[38:41], v152 offset:32768
	ds_read_b128 v[42:45], v152 offset:33792
	ds_read_b128 v[46:49], v152 offset:34816
	ds_read_b128 v[82:85], v152 offset:35840
	ds_read_b128 v[86:89], v152 offset:36864
	ds_read_b128 v[90:93], v152 offset:37888
	ds_read_b128 v[94:97], v152 offset:38912
	ds_read_b128 v[216:219], v152 offset:39936
	global_load_lds_dwordx4 v[104:105], off
	v_lshl_add_u64 v[104:105], s[38:39], 0, v[132:133]
	s_mov_b32 m0, s53
	s_nop 0
	global_load_lds_dwordx4 v[104:105], off
	s_waitcnt lgkmcnt(8)
	s_barrier
	s_waitcnt lgkmcnt(0)
	v_mfma_f32_16x16x32_bf16 v[50:53], v[196:199], v[38:41], v[50:53]
	v_mfma_f32_16x16x32_bf16 v[228:231], v[200:203], v[42:45], v[50:53]
	v_mfma_f32_16x16x32_bf16 v[50:53], v[204:207], v[38:41], v[54:57]
	v_mfma_f32_16x16x32_bf16 v[232:235], v[208:211], v[42:45], v[50:53]
	v_mfma_f32_16x16x32_bf16 v[50:53], v[196:199], v[46:49], v[58:61]
	v_mfma_f32_16x16x32_bf16 v[124:127], v[200:203], v[82:85], v[50:53]
	v_mfma_f32_16x16x32_bf16 v[50:53], v[204:207], v[46:49], v[62:65]
	v_mfma_f32_16x16x32_bf16 v[120:123], v[208:211], v[82:85], v[50:53]
	v_mfma_f32_16x16x32_bf16 v[50:53], v[196:199], v[86:89], v[66:69]
	v_mfma_f32_16x16x32_bf16 v[116:119], v[200:203], v[90:93], v[50:53]
	v_mfma_f32_16x16x32_bf16 v[50:53], v[204:207], v[86:89], v[70:73]
	v_mfma_f32_16x16x32_bf16 v[112:115], v[208:211], v[90:93], v[50:53]
	v_mfma_f32_16x16x32_bf16 v[50:53], v[196:199], v[94:97], v[74:77]
	v_mfma_f32_16x16x32_bf16 v[108:111], v[200:203], v[216:219], v[50:53]
	v_mfma_f32_16x16x32_bf16 v[50:53], v[204:207], v[94:97], v[78:81]
	v_mfma_f32_16x16x32_bf16 v[104:107], v[208:211], v[216:219], v[50:53]
	s_barrier
	s_mov_b32 m0, s78
	ds_read_b128 v[72:75], v9
	ds_read_b128 v[76:79], v9 offset:1024
	ds_read_b128 v[236:239], v9 offset:2048
	ds_read_b128 v[240:243], v9 offset:3072
	v_lshl_add_u64 v[8:9], v[148:149], 0, s[14:15]
	global_load_lds_dwordx4 v[8:9], off
	v_lshl_add_u64 v[8:9], v[212:213], 0, s[14:15]
	s_mov_b32 m0, s75
	s_nop 0
	global_load_lds_dwordx4 v[8:9], off
	s_barrier
	s_waitcnt lgkmcnt(0)
	v_mfma_f32_16x16x32_bf16 v[0:3], v[72:75], v[38:41], v[0:3]
	v_mfma_f32_16x16x32_bf16 v[60:63], v[76:79], v[42:45], v[0:3]
	v_mfma_f32_16x16x32_bf16 v[0:3], v[236:239], v[38:41], v[22:25]
	v_mfma_f32_16x16x32_bf16 v[56:59], v[240:243], v[42:45], v[0:3]
	v_mfma_f32_16x16x32_bf16 v[0:3], v[72:75], v[46:49], v[98:101]
	v_mfma_f32_16x16x32_bf16 v[52:55], v[76:79], v[82:85], v[0:3]
	v_mfma_f32_16x16x32_bf16 v[0:3], v[236:239], v[46:49], v[26:29]
	v_mfma_f32_16x16x32_bf16 v[48:51], v[240:243], v[82:85], v[0:3]
	v_mfma_f32_16x16x32_bf16 v[0:3], v[72:75], v[86:89], v[30:33]
	v_mfma_f32_16x16x32_bf16 v[44:47], v[76:79], v[90:93], v[0:3]
	v_mfma_f32_16x16x32_bf16 v[0:3], v[236:239], v[86:89], v[34:37]
	v_mfma_f32_16x16x32_bf16 v[40:43], v[240:243], v[90:93], v[0:3]
	v_mfma_f32_16x16x32_bf16 v[0:3], v[72:75], v[94:97], v[140:143]
	v_mfma_f32_16x16x32_bf16 v[36:39], v[76:79], v[216:219], v[0:3]
	v_mfma_f32_16x16x32_bf16 v[0:3], v[236:239], v[94:97], v[144:147]
	v_mfma_f32_16x16x32_bf16 v[32:35], v[240:243], v[216:219], v[0:3]
	s_mov_b32 m0, s60
	v_lshl_add_u64 v[8:9], v[102:103], 0, s[14:15]
	s_barrier
	s_nop 2
	ds_read_b128 v[0:3], v152 offset:49152
	ds_read_b128 v[22:25], v152 offset:50176
	ds_read_b128 v[140:143], v152 offset:51200
	ds_read_b128 v[144:147], v152 offset:52224
	ds_read_b128 v[216:219], v152 offset:53248
	ds_read_b128 v[244:247], v152 offset:54272
	ds_read_b128 v[248:251], v152 offset:55296
	ds_read_b128 v[212:215], v152 offset:56320
	global_load_lds_dwordx4 v[8:9], off
	v_lshl_add_u64 v[8:9], v[252:253], 0, s[14:15]
	s_mov_b32 m0, s61
	s_nop 0
	global_load_lds_dwordx4 v[8:9], off
	s_barrier
	s_waitcnt lgkmcnt(0)
	v_mfma_f32_16x16x32_bf16 v[4:7], v[196:199], v[0:3], v[4:7]
	v_mfma_f32_16x16x32_bf16 v[100:103], v[200:203], v[22:25], v[4:7]
	v_mfma_f32_16x16x32_bf16 v[4:7], v[204:207], v[0:3], v[156:159]
	v_mfma_f32_16x16x32_bf16 v[96:99], v[208:211], v[22:25], v[4:7]
	v_mfma_f32_16x16x32_bf16 v[4:7], v[196:199], v[140:143], v[160:163]
	v_mfma_f32_16x16x32_bf16 v[92:95], v[200:203], v[144:147], v[4:7]
	v_mfma_f32_16x16x32_bf16 v[4:7], v[204:207], v[140:143], v[164:167]
	v_mfma_f32_16x16x32_bf16 v[88:91], v[208:211], v[144:147], v[4:7]
	v_mfma_f32_16x16x32_bf16 v[4:7], v[196:199], v[216:219], v[168:171]
	v_mfma_f32_16x16x32_bf16 v[84:87], v[200:203], v[244:247], v[4:7]
	v_mfma_f32_16x16x32_bf16 v[4:7], v[204:207], v[216:219], v[172:175]
	v_mfma_f32_16x16x32_bf16 v[80:83], v[208:211], v[244:247], v[4:7]
	v_mfma_f32_16x16x32_bf16 v[4:7], v[196:199], v[248:251], v[10:13]
	v_mfma_f32_16x16x32_bf16 v[68:71], v[200:203], v[212:215], v[4:7]
	v_mfma_f32_16x16x32_bf16 v[4:7], v[204:207], v[248:251], v[14:17]
	v_mfma_f32_16x16x32_bf16 v[64:67], v[208:211], v[212:215], v[4:7]
	s_barrier
	s_add_u32 s38, s6, 0x18080
	s_addc_u32 s39, s7, 0
	s_mov_b32 m0, s79
	s_nop 1
	v_lshl_add_u64 v[4:5], s[38:39], 0, v[130:131]
	global_load_lds_dwordx4 v[4:5], off
	v_lshl_add_u64 v[4:5], s[38:39], 0, v[134:135]
	s_mov_b32 m0, s76
	s_nop 0
	global_load_lds_dwordx4 v[4:5], off
	s_waitcnt vmcnt(6)
	s_barrier
; #define PG8_MMA(ai, bj, At, Bt) do { __builtin_amdgcn_s_setprio(1); _Pragma("unroll") for (int m = 0; m < 4; ++m) _Pragma("unroll") for (int n = 0; n < 2; ++n) _Pragma("unroll") for (int k = 0; k < 2; ++k) \
;         acc[ai][bj][m][n] = __builtin_amdgcn_mfma_f32_16x16x32_bf16(Bt[n][k], At[m][k], acc[ai][bj][m][n], 0, 0, 0); __builtin_amdgcn_s_setprio(0); } while (0)
; #define PG8_WAIT_V(n) asm volatile("s_waitcnt vmcnt(" #n ")" ::: "memory")
; #define PG8_BAR __builtin_amdgcn_s_barrier()
; __device__ __forceinline__ u32x4 pack8(const float (&f)[8]) { u32x4 o; o.x = pk2(f[0], f[1]); o.y = pk2(f[2], f[3]); o.z = pk2(f[4], f[5]); o.w = pk2(f[6], f[7]); return o; }
; __device__ __forceinline__ float sigmoidf_(float x) { return __builtin_amdgcn_rcpf(1.0f + __expf(-x)); }
; template <class Epi, class Sched>
; __device__ __forceinline__ void gemm_phase(PG8_LAS unsigned char* lds, const Gemm g, const Sched& S, const Epi& E) {
;     ...
;             PG8_WAIT_V(6); PG8_BAR; PG8_MMA(1, 1, At, B1); PG8_BAR;
;     __device__ __forceinline__ void operator()(const f32x4 (&acc)[2][2][4][2], const Unit& u, int wr, int wc, int fr, int fq) const {
;         const int row0 = u.pm * BM + wr * 64 + fr, cb = 128 * u.pn + wc * 32 + 8 * fq;
; #pragma unroll
;         for (int bj = 0; bj < 2; ++bj) {
;             const f32x4 w0a = *(const f32x4*)(w0 + 512 * bj + cb), w0b = *(const f32x4*)(w0 + 512 * bj + cb + 4); bf16_t* D = bj ? DBp : DFp;
; #pragma unroll
;             for (int ai = 0; ai < 2; ++ai)
; #pragma unroll
;                 for (int m = 0; m < 4; ++m) { const f32x4 a0 = acc[ai][bj][m][0], a1 = acc[ai][bj][m][1]; float d[8];
; #pragma unroll
;                     for (int j = 0; j < 4; ++j) { d[j] = 0.60653066f * sigmoidf_(w0a[j] + a0[j]); d[4 + j] = 0.60653066f * sigmoidf_(w0b[j] + a1[j]); }
;                     *(u32x4*)(D + (size_t)(row0 + ai * HALF + m * 16) * 512 + cb) = pack8(d); asm volatile("" ::: "memory"); }
	v_mfma_f32_16x16x32_bf16 v[4:7], v[72:75], v[0:3], v[18:21]
	v_mfma_f32_16x16x32_bf16 v[0:3], v[236:239], v[0:3], v[220:223]
	v_mfma_f32_16x16x32_bf16 v[28:31], v[76:79], v[22:25], v[4:7]
	v_mfma_f32_16x16x32_bf16 v[24:27], v[240:243], v[22:25], v[0:3]
	v_mfma_f32_16x16x32_bf16 v[0:3], v[72:75], v[140:143], v[224:227]
	v_mfma_f32_16x16x32_bf16 v[20:23], v[76:79], v[144:147], v[0:3]
	v_mfma_f32_16x16x32_bf16 v[0:3], v[236:239], v[140:143], v[176:179]
	v_mfma_f32_16x16x32_bf16 v[16:19], v[240:243], v[144:147], v[0:3]
	v_mfma_f32_16x16x32_bf16 v[0:3], v[72:75], v[216:219], v[180:183]
	v_mfma_f32_16x16x32_bf16 v[12:15], v[76:79], v[244:247], v[0:3]
	v_mfma_f32_16x16x32_bf16 v[0:3], v[236:239], v[216:219], v[184:187]
	v_mfma_f32_16x16x32_bf16 v[8:11], v[240:243], v[244:247], v[0:3]
	v_mfma_f32_16x16x32_bf16 v[0:3], v[72:75], v[248:251], v[188:191]
	v_mfma_f32_16x16x32_bf16 v[4:7], v[76:79], v[212:215], v[0:3]
	v_mfma_f32_16x16x32_bf16 v[0:3], v[236:239], v[248:251], v[192:195]
	v_mfma_f32_16x16x32_bf16 v[0:3], v[240:243], v[212:215], v[0:3]
	v_lshl_or_b32 v140, s69, 7, v153
	v_ashrrev_i32_e32 v141, 31, v140
	v_lshl_add_u64 v[142:143], v[140:141], 2, s[18:19]
	s_barrier
	global_load_dwordx4 v[76:79], v[142:143], off
	global_load_dwordx4 v[72:75], v[142:143], off offset:16
	v_lshl_add_u32 v148, s68, 8, v150
	v_ashrrev_i32_e32 v149, 31, v148
	v_lshlrev_b64 v[144:145], 1, v[140:141]
	v_lshlrev_b64 v[140:141], 10, v[148:149]
	v_lshl_add_u64 v[146:147], s[10:11], 0, v[144:145]
	v_lshl_add_u64 v[160:161], v[146:147], 0, v[140:141]
	s_mov_b64 s[38:39], 0x20000
	s_add_i32 s64, s64, s96
	s_andn2_b64 vcc, exec, s[4:5]
	s_mov_b32 s69, s3
	s_mov_b32 s68, s67
	s_mov_b64 s[40:41], s[6:7]
	v_mov_b32_e32 v244, v136
	s_waitcnt vmcnt(0)
	v_add_f32_e32 v149, v228, v76
	v_add_f32_e32 v156, v232, v72
	v_add_f32_e32 v157, v229, v77
	v_add_f32_e32 v124, v124, v76
	v_add_f32_e32 v120, v120, v72
	v_add_f32_e32 v64, v64, v72
	v_add_f32_e32 v69, v69, v77
	v_add_f32_e32 v125, v125, v77
	v_add_f32_e32 v121, v121, v73
	v_add_f32_e32 v122, v122, v74
	v_mul_f32_e32 v149, 0xbfb8aa3b, v149
	v_mul_f32_e32 v156, 0xbfb8aa3b, v156
	v_mul_f32_e32 v157, 0xbfb8aa3b, v157
	v_mul_f32_e32 v124, 0xbfb8aa3b, v124
	v_mul_f32_e32 v120, 0xbfb8aa3b, v120
	v_mul_f32_e32 v64, 0xbfb8aa3b, v64
	v_mul_f32_e32 v69, 0xbfb8aa3b, v69
	v_mul_f32_e32 v125, 0xbfb8aa3b, v125
	v_mul_f32_e32 v121, 0xbfb8aa3b, v121
	v_mul_f32_e32 v122, 0xbfb8aa3b, v122
	v_exp_f32_e32 v149, v149
	v_exp_f32_e32 v156, v156
	v_exp_f32_e32 v157, v157
	v_exp_f32_e32 v124, v124
	v_exp_f32_e32 v120, v120
	v_exp_f32_e32 v64, v64
	v_exp_f32_e32 v69, v69
	v_add_f32_e32 v158, v233, v73
	v_add_f32_e32 v159, v230, v78
	v_add_f32_e32 v162, v234, v74
	v_add_f32_e32 v126, v126, v78
	v_exp_f32_e32 v125, v125
	v_exp_f32_e32 v121, v121
	v_exp_f32_e32 v122, v122
	v_add_f32_e32 v127, v127, v79
	v_add_f32_e32 v163, v231, v79
	v_add_f32_e32 v164, v235, v75
	v_mul_f32_e32 v158, 0xbfb8aa3b, v158
	v_mul_f32_e32 v159, 0xbfb8aa3b, v159
	v_mul_f32_e32 v162, 0xbfb8aa3b, v162
	v_mul_f32_e32 v126, 0xbfb8aa3b, v126
	v_mul_f32_e32 v127, 0xbfb8aa3b, v127
	v_add_f32_e32 v123, v123, v75
	v_add_f32_e32 v116, v116, v76
	v_add_f32_e32 v112, v112, v72
	v_mul_f32_e32 v163, 0xbfb8aa3b, v163
	v_mul_f32_e32 v164, 0xbfb8aa3b, v164
	v_exp_f32_e32 v158, v158
	v_exp_f32_e32 v159, v159
	v_exp_f32_e32 v162, v162
	v_exp_f32_e32 v126, v126
	v_exp_f32_e32 v127, v127
	v_mul_f32_e32 v123, 0xbfb8aa3b, v123
	v_mul_f32_e32 v116, 0xbfb8aa3b, v116
	v_mul_f32_e32 v112, 0xbfb8aa3b, v112
	v_add_f32_e32 v117, v117, v77
	v_add_f32_e32 v113, v113, v73
	v_add_f32_e32 v114, v114, v74
	v_exp_f32_e32 v163, v163
	v_exp_f32_e32 v164, v164
	v_add_f32_e32 v149, 1.0, v149
	v_add_f32_e32 v156, 1.0, v156
	v_add_f32_e32 v157, 1.0, v157
	v_add_f32_e32 v124, 1.0, v124
	v_add_f32_e32 v120, 1.0, v120
	v_exp_f32_e32 v123, v123
	v_exp_f32_e32 v116, v116
	v_exp_f32_e32 v112, v112
	v_mul_f32_e32 v117, 0xbfb8aa3b, v117
	v_mul_f32_e32 v113, 0xbfb8aa3b, v113
	v_mul_f32_e32 v114, 0xbfb8aa3b, v114
	v_add_f32_e32 v64, 1.0, v64
	v_add_f32_e32 v69, 1.0, v69
	v_add_f32_e32 v65, v65, v73
	v_add_f32_e32 v125, 1.0, v125
	v_add_f32_e32 v121, 1.0, v121
	v_rcp_f32_e32 v149, v149
	v_rcp_f32_e32 v156, v156
	v_rcp_f32_e32 v157, v157
	v_rcp_f32_e32 v124, v124
	v_rcp_f32_e32 v120, v120
	v_add_f32_e32 v122, 1.0, v122
	v_exp_f32_e32 v117, v117
	v_exp_f32_e32 v113, v113
	v_add_f32_e32 v118, v118, v78
	v_exp_f32_e32 v114, v114
	v_add_f32_e32 v119, v119, v79
	v_rcp_f32_e32 v64, v64
	v_rcp_f32_e32 v69, v69
	v_mul_f32_e32 v65, 0xbfb8aa3b, v65
	v_rcp_f32_e32 v125, v125
	v_rcp_f32_e32 v121, v121
	v_rcp_f32_e32 v122, v122
	v_mul_f32_e32 v118, 0xbfb8aa3b, v118
	v_mul_f32_e32 v119, 0xbfb8aa3b, v119
	v_add_f32_e32 v115, v115, v75
	v_add_f32_e32 v108, v108, v76
	v_add_f32_e32 v104, v104, v72
	v_exp_f32_e32 v65, v65
	v_add_f32_e32 v158, 1.0, v158
	v_add_f32_e32 v159, 1.0, v159
	v_add_f32_e32 v162, 1.0, v162
	v_add_f32_e32 v126, 1.0, v126
	v_add_f32_e32 v127, 1.0, v127
	v_exp_f32_e32 v118, v118
	v_exp_f32_e32 v119, v119
	v_mul_f32_e32 v115, 0xbfb8aa3b, v115
	v_mul_f32_e32 v108, 0xbfb8aa3b, v108
	v_mul_f32_e32 v104, 0xbfb8aa3b, v104
	v_add_f32_e32 v109, v109, v77
	v_add_f32_e32 v105, v105, v73
	v_add_f32_e32 v106, v106, v74
	v_add_f32_e32 v163, 1.0, v163
	v_add_f32_e32 v164, 1.0, v164
	v_rcp_f32_e32 v158, v158
	v_rcp_f32_e32 v159, v159
	v_rcp_f32_e32 v162, v162
	v_rcp_f32_e32 v126, v126
	v_rcp_f32_e32 v127, v127
	v_add_f32_e32 v123, 1.0, v123
	v_add_f32_e32 v116, 1.0, v116
	v_add_f32_e32 v112, 1.0, v112
	v_exp_f32_e32 v115, v115
	v_exp_f32_e32 v108, v108
	v_exp_f32_e32 v104, v104
	v_mul_f32_e32 v109, 0xbfb8aa3b, v109
	v_mul_f32_e32 v105, 0xbfb8aa3b, v105
; __device__ __forceinline__ u32x4 pack8(const float (&f)[8]) { u32x4 o; o.x = pk2(f[0], f[1]); o.y = pk2(f[2], f[3]); o.z = pk2(f[4], f[5]); o.w = pk2(f[6], f[7]); return o; }
; __device__ __forceinline__ float sigmoidf_(float x) { return __builtin_amdgcn_rcpf(1.0f + __expf(-x)); }
;     __device__ __forceinline__ void operator()(const f32x4 (&acc)[2][2][4][2], const Unit& u, int wr, int wc, int fr, int fq) const {
;     ...
;             const f32x4 w0a = *(const f32x4*)(w0 + 512 * bj + cb), w0b = *(const f32x4*)(w0 + 512 * bj + cb + 4); bf16_t* D = bj ? DBp : DFp;
; #pragma unroll
;             for (int ai = 0; ai < 2; ++ai)
; #pragma unroll
;                 for (int m = 0; m < 4; ++m) { const f32x4 a0 = acc[ai][bj][m][0], a1 = acc[ai][bj][m][1]; float d[8];
; #pragma unroll
;                     for (int j = 0; j < 4; ++j) { d[j] = 0.60653066f * sigmoidf_(w0a[j] + a0[j]); d[4 + j] = 0.60653066f * sigmoidf_(w0b[j] + a1[j]); }
;                     *(u32x4*)(D + (size_t)(row0 + ai * HALF + m * 16) * 512 + cb) = pack8(d); asm volatile("" ::: "memory"); }
	v_mul_f32_e32 v106, 0xbfb8aa3b, v106
	v_rcp_f32_e32 v163, v163
	v_rcp_f32_e32 v164, v164
	v_mul_f32_e32 v149, 0x3f1b4598, v149
	v_mul_f32_e32 v165, 0x3f1b4598, v156
	v_mul_f32_e32 v156, 0x3f1b4598, v157
	v_mul_f32_e32 v124, 0x3f1b4598, v124
	v_mul_f32_e32 v120, 0x3f1b4598, v120
	v_rcp_f32_e32 v123, v123
	v_rcp_f32_e32 v116, v116
	v_rcp_f32_e32 v112, v112
	v_add_f32_e32 v117, 1.0, v117
	v_add_f32_e32 v113, 1.0, v113
	v_add_f32_e32 v114, 1.0, v114
	v_exp_f32_e32 v109, v109
	v_exp_f32_e32 v105, v105
	v_add_f32_e32 v110, v110, v78
	v_exp_f32_e32 v106, v106
	v_add_f32_e32 v111, v111, v79
	v_add_f32_e32 v96, v96, v72
	v_add_f32_e32 v88, v88, v72
	v_add_f32_e32 v80, v80, v72
	v_mul_f32_e32 v72, 0x3f1b4598, v64
	v_mul_f32_e32 v64, 0x3f1b4598, v69
	v_add_f32_e32 v69, v70, v78
	v_mul_f32_e32 v125, 0x3f1b4598, v125
	v_mul_f32_e32 v121, 0x3f1b4598, v121
	v_cvt_pk_bf16_f32 v156, v149, v156
	v_mul_f32_e32 v149, 0x3f1b4598, v122
	v_cvt_pk_bf16_f32 v122, v124, v125
	v_cvt_pk_bf16_f32 v124, v120, v121
	v_or_b32_e32 v120, 16, v148
	v_rcp_f32_e32 v117, v117
	v_rcp_f32_e32 v113, v113
	v_rcp_f32_e32 v114, v114
	v_mul_f32_e32 v110, 0xbfb8aa3b, v110
	v_mul_f32_e32 v111, 0xbfb8aa3b, v111
	v_add_f32_e32 v107, v107, v75
	v_add_f32_e32 v100, v100, v76
	v_add_f32_e32 v97, v97, v73
	v_add_f32_e32 v65, 1.0, v65
	v_mul_f32_e32 v69, 0xbfb8aa3b, v69
	v_ashrrev_i32_e32 v121, 31, v120
	v_add_f32_e32 v118, 1.0, v118
	v_add_f32_e32 v119, 1.0, v119
	v_exp_f32_e32 v110, v110
	v_exp_f32_e32 v111, v111
	v_mul_f32_e32 v107, 0xbfb8aa3b, v107
	v_mul_f32_e32 v100, 0xbfb8aa3b, v100
	v_mul_f32_e32 v96, 0xbfb8aa3b, v96
	v_add_f32_e32 v101, v101, v77
	v_mul_f32_e32 v97, 0xbfb8aa3b, v97
	v_add_f32_e32 v102, v102, v78
	v_add_f32_e32 v98, v98, v74
	v_add_f32_e32 v103, v103, v79
	v_rcp_f32_e32 v65, v65
	v_exp_f32_e32 v69, v69
	v_mul_f32_e32 v158, 0x3f1b4598, v158
	v_mul_f32_e32 v157, 0x3f1b4598, v159
	v_mul_f32_e32 v159, 0x3f1b4598, v162
	v_mul_f32_e32 v126, 0x3f1b4598, v126
	v_mul_f32_e32 v127, 0x3f1b4598, v127
	v_lshlrev_b64 v[120:121], 10, v[120:121]
	v_rcp_f32_e32 v118, v118
	v_rcp_f32_e32 v119, v119
	v_add_f32_e32 v115, 1.0, v115
	v_add_f32_e32 v108, 1.0, v108
	v_add_f32_e32 v104, 1.0, v104
	v_exp_f32_e32 v107, v107
	v_exp_f32_e32 v100, v100
	v_exp_f32_e32 v96, v96
	v_mul_f32_e32 v101, 0xbfb8aa3b, v101
	v_exp_f32_e32 v97, v97
	v_mul_f32_e32 v102, 0xbfb8aa3b, v102
	v_mul_f32_e32 v98, 0xbfb8aa3b, v98
	v_mul_f32_e32 v103, 0xbfb8aa3b, v103
	v_add_f32_e32 v99, v99, v75
	v_add_f32_e32 v92, v92, v76
	v_add_f32_e32 v89, v89, v73
	v_mul_f32_e32 v162, 0x3f1b4598, v163
	v_mul_f32_e32 v163, 0x3f1b4598, v164
	v_cvt_pk_bf16_f32 v157, v157, v162
	v_cvt_pk_bf16_f32 v158, v165, v158
	v_cvt_pk_bf16_f32 v159, v159, v163
	global_store_dwordx4 v[160:161], v[156:159], off
	v_mul_f32_e32 v116, 0x3f1b4598, v116
	v_mul_f32_e32 v112, 0x3f1b4598, v112
	v_mul_f32_e32 v156, 0x3f1b4598, v123
	v_cvt_pk_bf16_f32 v123, v126, v127
	v_lshl_add_u64 v[126:127], v[146:147], 0, v[120:121]
	v_rcp_f32_e32 v115, v115
	v_rcp_f32_e32 v108, v108
	v_rcp_f32_e32 v104, v104
	v_add_f32_e32 v109, 1.0, v109
	v_add_f32_e32 v105, 1.0, v105
	v_add_f32_e32 v106, 1.0, v106
	v_exp_f32_e32 v101, v101
	v_exp_f32_e32 v102, v102
	v_exp_f32_e32 v98, v98
	v_exp_f32_e32 v103, v103
	v_mul_f32_e32 v99, 0xbfb8aa3b, v99
	v_mul_f32_e32 v92, 0xbfb8aa3b, v92
	v_mul_f32_e32 v88, 0xbfb8aa3b, v88
	v_add_f32_e32 v93, v93, v77
	v_mul_f32_e32 v89, 0xbfb8aa3b, v89
	v_add_f32_e32 v94, v94, v78
	v_add_f32_e32 v90, v90, v74
	v_add_f32_e32 v95, v95, v79
	v_cvt_pk_bf16_f32 v125, v149, v156
	global_store_dwordx4 v[126:127], v[122:125], off
	v_mul_f32_e32 v117, 0x3f1b4598, v117
	v_mul_f32_e32 v113, 0x3f1b4598, v113
	v_mul_f32_e32 v122, 0x3f1b4598, v114
	v_cvt_pk_bf16_f32 v114, v116, v117
	v_cvt_pk_bf16_f32 v116, v112, v113
	v_or_b32_e32 v112, 32, v148
	v_rcp_f32_e32 v109, v109
	v_rcp_f32_e32 v105, v105
	v_rcp_f32_e32 v106, v106
	v_exp_f32_e32 v99, v99
	v_exp_f32_e32 v92, v92
	v_exp_f32_e32 v88, v88
	v_mul_f32_e32 v93, 0xbfb8aa3b, v93
	v_exp_f32_e32 v89, v89
	v_mul_f32_e32 v94, 0xbfb8aa3b, v94
	v_mul_f32_e32 v90, 0xbfb8aa3b, v90
	v_mul_f32_e32 v95, 0xbfb8aa3b, v95
	v_add_f32_e32 v91, v91, v75
	v_add_f32_e32 v84, v84, v76
	v_add_f32_e32 v81, v81, v73
	v_ashrrev_i32_e32 v113, 31, v112
	v_add_f32_e32 v110, 1.0, v110
	v_add_f32_e32 v111, 1.0, v111
	v_exp_f32_e32 v93, v93
	v_exp_f32_e32 v94, v94
	v_exp_f32_e32 v90, v90
	v_exp_f32_e32 v95, v95
	v_mul_f32_e32 v91, 0xbfb8aa3b, v91
	v_mul_f32_e32 v84, 0xbfb8aa3b, v84
	v_mul_f32_e32 v80, 0xbfb8aa3b, v80
	v_add_f32_e32 v85, v85, v77
	v_mul_f32_e32 v81, 0xbfb8aa3b, v81
	v_add_f32_e32 v86, v86, v78
	v_add_f32_e32 v82, v82, v74
	v_add_f32_e32 v87, v87, v79
	v_add_f32_e32 v66, v66, v74
	v_mul_f32_e32 v70, 0x3f1b4598, v65
	v_add_f32_e32 v65, 1.0, v69
	v_add_f32_e32 v69, v71, v79
	v_mul_f32_e32 v118, 0x3f1b4598, v118
	v_mul_f32_e32 v119, 0x3f1b4598, v119
	v_lshlrev_b64 v[112:113], 10, v[112:113]
	v_rcp_f32_e32 v110, v110
	v_rcp_f32_e32 v111, v111
	v_add_f32_e32 v107, 1.0, v107
	v_add_f32_e32 v100, 1.0, v100
	v_add_f32_e32 v96, 1.0, v96
	v_add_f32_e32 v97, 1.0, v97
	v_exp_f32_e32 v91, v91
	v_exp_f32_e32 v84, v84
	v_exp_f32_e32 v80, v80
	v_mul_f32_e32 v85, 0xbfb8aa3b, v85
	v_exp_f32_e32 v81, v81
	v_mul_f32_e32 v86, 0xbfb8aa3b, v86
	v_mul_f32_e32 v82, 0xbfb8aa3b, v82
	v_mul_f32_e32 v87, 0xbfb8aa3b, v87
	v_add_f32_e32 v83, v83, v75
	v_add_f32_e32 v68, v68, v76
	v_mul_f32_e32 v66, 0xbfb8aa3b, v66
	v_mul_f32_e32 v69, 0xbfb8aa3b, v69
	v_mul_f32_e32 v123, 0x3f1b4598, v115
	v_cvt_pk_bf16_f32 v115, v118, v119
	v_lshl_add_u64 v[118:119], v[146:147], 0, v[112:113]
	v_mul_f32_e32 v108, 0x3f1b4598, v108
	v_mul_f32_e32 v104, 0x3f1b4598, v104
; __device__ __forceinline__ u32x4 pack8(const float (&f)[8]) { u32x4 o; o.x = pk2(f[0], f[1]); o.y = pk2(f[2], f[3]); o.z = pk2(f[4], f[5]); o.w = pk2(f[6], f[7]); return o; }
; __device__ __forceinline__ float sigmoidf_(float x) { return __builtin_amdgcn_rcpf(1.0f + __expf(-x)); }
;     __device__ __forceinline__ void operator()(const f32x4 (&acc)[2][2][4][2], const Unit& u, int wr, int wc, int fr, int fq) const {
;     ...
;         for (int bj = 0; bj < 2; ++bj) {
;             const f32x4 w0a = *(const f32x4*)(w0 + 512 * bj + cb), w0b = *(const f32x4*)(w0 + 512 * bj + cb + 4); bf16_t* D = bj ? DBp : DFp;
; #pragma unroll
;             for (int ai = 0; ai < 2; ++ai)
; #pragma unroll
;                 for (int m = 0; m < 4; ++m) { const f32x4 a0 = acc[ai][bj][m][0], a1 = acc[ai][bj][m][1]; float d[8];
; #pragma unroll
;                     for (int j = 0; j < 4; ++j) { d[j] = 0.60653066f * sigmoidf_(w0a[j] + a0[j]); d[4 + j] = 0.60653066f * sigmoidf_(w0b[j] + a1[j]); }
;                     *(u32x4*)(D + (size_t)(row0 + ai * HALF + m * 16) * 512 + cb) = pack8(d); asm volatile("" ::: "memory"); }
	v_rcp_f32_e32 v107, v107
	v_rcp_f32_e32 v100, v100
	v_rcp_f32_e32 v96, v96
	v_add_f32_e32 v101, 1.0, v101
	v_rcp_f32_e32 v97, v97
	v_add_f32_e32 v102, 1.0, v102
	v_add_f32_e32 v98, 1.0, v98
	v_add_f32_e32 v103, 1.0, v103
	v_exp_f32_e32 v85, v85
	v_exp_f32_e32 v86, v86
	v_exp_f32_e32 v82, v82
	v_exp_f32_e32 v87, v87
	v_mul_f32_e32 v83, 0xbfb8aa3b, v83
	v_mul_f32_e32 v68, 0xbfb8aa3b, v68
	v_exp_f32_e32 v66, v66
	v_exp_f32_e32 v69, v69
	v_add_f32_e32 v67, v67, v75
	v_cvt_pk_bf16_f32 v117, v122, v123
	global_store_dwordx4 v[118:119], v[114:117], off
	v_mul_f32_e32 v109, 0x3f1b4598, v109
	v_mul_f32_e32 v105, 0x3f1b4598, v105
	v_mul_f32_e32 v114, 0x3f1b4598, v106
	v_cvt_pk_bf16_f32 v106, v108, v109
	v_cvt_pk_bf16_f32 v108, v104, v105
	v_or_b32_e32 v104, 48, v148
	v_rcp_f32_e32 v101, v101
	v_rcp_f32_e32 v102, v102
	v_rcp_f32_e32 v98, v98
	v_rcp_f32_e32 v103, v103
	v_add_f32_e32 v99, 1.0, v99
	v_add_f32_e32 v92, 1.0, v92
	v_add_f32_e32 v88, 1.0, v88
	v_add_f32_e32 v89, 1.0, v89
	v_exp_f32_e32 v83, v83
	v_exp_f32_e32 v68, v68
	v_mul_f32_e32 v67, 0xbfb8aa3b, v67
	v_ashrrev_i32_e32 v105, 31, v104
	v_rcp_f32_e32 v99, v99
	v_rcp_f32_e32 v92, v92
	v_rcp_f32_e32 v88, v88
	v_add_f32_e32 v93, 1.0, v93
	v_rcp_f32_e32 v89, v89
	v_add_f32_e32 v94, 1.0, v94
	v_add_f32_e32 v90, 1.0, v90
	v_add_f32_e32 v95, 1.0, v95
	v_exp_f32_e32 v67, v67
	v_mul_f32_e32 v110, 0x3f1b4598, v110
	v_mul_f32_e32 v111, 0x3f1b4598, v111
	v_lshlrev_b64 v[104:105], 10, v[104:105]
	v_rcp_f32_e32 v93, v93
	v_rcp_f32_e32 v94, v94
	v_rcp_f32_e32 v90, v90
	v_rcp_f32_e32 v95, v95
	v_add_f32_e32 v91, 1.0, v91
	v_add_f32_e32 v84, 1.0, v84
	v_add_f32_e32 v80, 1.0, v80
	v_add_f32_e32 v81, 1.0, v81
	v_mul_f32_e32 v115, 0x3f1b4598, v107
	v_cvt_pk_bf16_f32 v107, v110, v111
	v_lshl_add_u64 v[110:111], v[146:147], 0, v[104:105]
	v_mul_f32_e32 v100, 0x3f1b4598, v100
	v_mul_f32_e32 v96, 0x3f1b4598, v96
	v_mul_f32_e32 v97, 0x3f1b4598, v97
	v_rcp_f32_e32 v91, v91
	v_rcp_f32_e32 v84, v84
	v_rcp_f32_e32 v80, v80
	v_add_f32_e32 v85, 1.0, v85
	v_rcp_f32_e32 v81, v81
	v_add_f32_e32 v86, 1.0, v86
	v_add_f32_e32 v82, 1.0, v82
	v_add_f32_e32 v87, 1.0, v87
	v_add_f32_e32 v66, 1.0, v66
	v_add_f32_e32 v69, 1.0, v69
	v_cvt_pk_bf16_f32 v109, v114, v115
	global_store_dwordx4 v[110:111], v[106:109], off
	v_mul_f32_e32 v101, 0x3f1b4598, v101
	v_mul_f32_e32 v102, 0x3f1b4598, v102
	v_mul_f32_e32 v106, 0x3f1b4598, v98
	v_mul_f32_e32 v103, 0x3f1b4598, v103
	v_cvt_pk_bf16_f32 v98, v100, v101
	v_cvt_pk_bf16_f32 v100, v96, v97
	v_lshl_add_u64 v[96:97], v[140:141], 0, s[38:39]
	v_rcp_f32_e32 v85, v85
	v_rcp_f32_e32 v86, v86
	v_rcp_f32_e32 v82, v82
	v_rcp_f32_e32 v87, v87
	v_add_f32_e32 v83, 1.0, v83
	v_add_f32_e32 v68, 1.0, v68
	v_rcp_f32_e32 v65, v65
	v_rcp_f32_e32 v66, v66
	v_rcp_f32_e32 v69, v69
	v_mul_f32_e32 v107, 0x3f1b4598, v99
	v_cvt_pk_bf16_f32 v99, v102, v103
	v_lshl_add_u64 v[102:103], v[146:147], 0, v[96:97]
	v_mul_f32_e32 v92, 0x3f1b4598, v92
	v_mul_f32_e32 v88, 0x3f1b4598, v88
	v_mul_f32_e32 v89, 0x3f1b4598, v89
	s_mov_b64 s[38:39], 0x24000
	v_rcp_f32_e32 v83, v83
	v_rcp_f32_e32 v68, v68
	v_add_f32_e32 v67, 1.0, v67
	v_cvt_pk_bf16_f32 v101, v106, v107
	global_store_dwordx4 v[102:103], v[98:101], off
	v_mul_f32_e32 v93, 0x3f1b4598, v93
	v_mul_f32_e32 v94, 0x3f1b4598, v94
	v_mul_f32_e32 v98, 0x3f1b4598, v90
	v_mul_f32_e32 v95, 0x3f1b4598, v95
	v_cvt_pk_bf16_f32 v90, v92, v93
	v_cvt_pk_bf16_f32 v92, v88, v89
	v_lshl_add_u64 v[88:89], v[140:141], 0, s[38:39]
	v_rcp_f32_e32 v67, v67
	v_mul_f32_e32 v99, 0x3f1b4598, v91
	v_cvt_pk_bf16_f32 v91, v94, v95
	v_lshl_add_u64 v[94:95], v[146:147], 0, v[88:89]
	v_mul_f32_e32 v84, 0x3f1b4598, v84
	v_mul_f32_e32 v80, 0x3f1b4598, v80
	v_mul_f32_e32 v81, 0x3f1b4598, v81
	s_mov_b64 s[38:39], 0x28000
	v_cvt_pk_bf16_f32 v93, v98, v99
	global_store_dwordx4 v[94:95], v[90:93], off
	v_mul_f32_e32 v85, 0x3f1b4598, v85
	v_mul_f32_e32 v86, 0x3f1b4598, v86
	v_mul_f32_e32 v90, 0x3f1b4598, v82
	v_mul_f32_e32 v87, 0x3f1b4598, v87
	v_cvt_pk_bf16_f32 v82, v84, v85
	v_cvt_pk_bf16_f32 v84, v80, v81
	v_lshl_add_u64 v[80:81], v[140:141], 0, s[38:39]
	v_mul_f32_e32 v65, 0x3f1b4598, v65
	v_mul_f32_e32 v71, 0x3f1b4598, v66
	v_mul_f32_e32 v66, 0x3f1b4598, v69
	s_mov_b64 s[38:39], 0x2c000
	v_mul_f32_e32 v91, 0x3f1b4598, v83
	v_cvt_pk_bf16_f32 v83, v86, v87
	v_lshl_add_u64 v[86:87], v[146:147], 0, v[80:81]
	v_mul_f32_e32 v68, 0x3f1b4598, v68
	v_cvt_pk_bf16_f32 v65, v65, v66
	v_cvt_pk_bf16_f32 v66, v72, v70
	v_lshl_add_u64 v[72:73], v[140:141], 0, s[38:39]
	v_cvt_pk_bf16_f32 v85, v90, v91
	global_store_dwordx4 v[86:87], v[82:85], off
	v_mul_f32_e32 v67, 0x3f1b4598, v67
	v_cvt_pk_bf16_f32 v64, v68, v64
	v_lshl_add_u64 v[68:69], v[146:147], 0, v[72:73]
	v_cvt_pk_bf16_f32 v67, v71, v67
	global_store_dwordx4 v[68:69], v[64:67], off
	global_load_dwordx4 v[68:71], v[142:143], off offset:2048
	global_load_dwordx4 v[64:67], v[142:143], off offset:2064
	v_lshl_add_u64 v[74:75], s[12:13], 0, v[144:145]
	s_mov_b64 s[38:39], s[0:1]
	s_waitcnt vmcnt(0)
; __device__ __forceinline__ u32x4 pack8(const float (&f)[8]) { u32x4 o; o.x = pk2(f[0], f[1]); o.y = pk2(f[2], f[3]); o.z = pk2(f[4], f[5]); o.w = pk2(f[6], f[7]); return o; }
; __device__ __forceinline__ float sigmoidf_(float x) { return __builtin_amdgcn_rcpf(1.0f + __expf(-x)); }
;     __device__ __forceinline__ void operator()(const f32x4 (&acc)[2][2][4][2], const Unit& u, int wr, int wc, int fr, int fq) const {
;     ...
;         for (int bj = 0; bj < 2; ++bj) {
;             const f32x4 w0a = *(const f32x4*)(w0 + 512 * bj + cb), w0b = *(const f32x4*)(w0 + 512 * bj + cb + 4); bf16_t* D = bj ? DBp : DFp;
; #pragma unroll
;             for (int ai = 0; ai < 2; ++ai)
; #pragma unroll
;                 for (int m = 0; m < 4; ++m) { const f32x4 a0 = acc[ai][bj][m][0], a1 = acc[ai][bj][m][1]; float d[8];
; #pragma unroll
;                     for (int j = 0; j < 4; ++j) { d[j] = 0.60653066f * sigmoidf_(w0a[j] + a0[j]); d[4 + j] = 0.60653066f * sigmoidf_(w0b[j] + a1[j]); }
;                     *(u32x4*)(D + (size_t)(row0 + ai * HALF + m * 16) * 512 + cb) = pack8(d); asm volatile("" ::: "memory"); }
	v_add_f32_e32 v61, v61, v69
	v_add_f32_e32 v56, v56, v64
	v_mul_f32_e32 v56, 0xbfb8aa3b, v56
	v_mul_f32_e32 v61, 0xbfb8aa3b, v61
	v_exp_f32_e32 v56, v56
	v_exp_f32_e32 v61, v61
	v_add_f32_e32 v57, v57, v65
	v_mul_f32_e32 v57, 0xbfb8aa3b, v57
	v_add_f32_e32 v56, 1.0, v56
	v_add_f32_e32 v61, 1.0, v61
	v_rcp_f32_e32 v56, v56
	v_rcp_f32_e32 v61, v61
	v_exp_f32_e32 v57, v57
	v_add_f32_e32 v60, v60, v68
	v_mul_f32_e32 v76, 0x3f1b4598, v56
	v_mul_f32_e32 v56, 0x3f1b4598, v61
	v_add_f32_e32 v61, v62, v70
	v_add_f32_e32 v57, 1.0, v57
	v_mul_f32_e32 v61, 0xbfb8aa3b, v61
	v_rcp_f32_e32 v57, v57
	v_exp_f32_e32 v61, v61
	v_mul_f32_e32 v60, 0xbfb8aa3b, v60
	v_add_f32_e32 v58, v58, v66
	v_mul_f32_e32 v62, 0x3f1b4598, v57
	v_add_f32_e32 v57, 1.0, v61
	v_add_f32_e32 v61, v63, v71
	v_add_f32_e32 v59, v59, v67
	v_exp_f32_e32 v60, v60
	v_mul_f32_e32 v58, 0xbfb8aa3b, v58
	v_mul_f32_e32 v61, 0xbfb8aa3b, v61
	v_mul_f32_e32 v59, 0xbfb8aa3b, v59
	v_add_f32_e32 v48, v48, v64
	v_add_f32_e32 v53, v53, v69
	v_exp_f32_e32 v58, v58
	v_exp_f32_e32 v61, v61
	v_exp_f32_e32 v59, v59
	v_mul_f32_e32 v48, 0xbfb8aa3b, v48
	v_mul_f32_e32 v53, 0xbfb8aa3b, v53
	v_exp_f32_e32 v48, v48
	v_exp_f32_e32 v53, v53
	v_add_f32_e32 v60, 1.0, v60
	v_rcp_f32_e32 v60, v60
	v_add_f32_e32 v58, 1.0, v58
	v_add_f32_e32 v61, 1.0, v61
	v_add_f32_e32 v59, 1.0, v59
	v_rcp_f32_e32 v57, v57
	v_rcp_f32_e32 v58, v58
	v_rcp_f32_e32 v61, v61
	v_rcp_f32_e32 v59, v59
	v_add_f32_e32 v48, 1.0, v48
	v_add_f32_e32 v53, 1.0, v53
	v_add_f32_e32 v49, v49, v65
	v_rcp_f32_e32 v48, v48
	v_rcp_f32_e32 v53, v53
	v_mul_f32_e32 v49, 0xbfb8aa3b, v49
	v_exp_f32_e32 v49, v49
	v_mul_f32_e32 v60, 0x3f1b4598, v60
	v_mul_f32_e32 v57, 0x3f1b4598, v57
	v_mul_f32_e32 v63, 0x3f1b4598, v58
	v_mul_f32_e32 v58, 0x3f1b4598, v61
	v_mul_f32_e32 v59, 0x3f1b4598, v59
	v_cvt_pk_bf16_f32 v56, v60, v56
	v_lshl_add_u64 v[60:61], v[74:75], 0, v[140:141]
	v_cvt_pk_bf16_f32 v57, v57, v58
	v_cvt_pk_bf16_f32 v58, v76, v62
	v_cvt_pk_bf16_f32 v59, v63, v59
	global_store_dwordx4 v[60:61], v[56:59], off
	v_add_f32_e32 v49, 1.0, v49
	v_rcp_f32_e32 v49, v49
	v_mul_f32_e32 v56, 0x3f1b4598, v48
	v_mul_f32_e32 v48, 0x3f1b4598, v53
	v_add_f32_e32 v53, v54, v70
	v_mul_f32_e32 v53, 0xbfb8aa3b, v53
	v_exp_f32_e32 v53, v53
	v_add_f32_e32 v52, v52, v68
	v_mul_f32_e32 v52, 0xbfb8aa3b, v52
	v_add_f32_e32 v50, v50, v66
	v_mul_f32_e32 v54, 0x3f1b4598, v49
	v_add_f32_e32 v49, 1.0, v53
	v_add_f32_e32 v53, v55, v71
	v_add_f32_e32 v51, v51, v67
	v_exp_f32_e32 v52, v52
	v_mul_f32_e32 v50, 0xbfb8aa3b, v50
	v_mul_f32_e32 v53, 0xbfb8aa3b, v53
	v_mul_f32_e32 v51, 0xbfb8aa3b, v51
	v_add_f32_e32 v40, v40, v64
	v_add_f32_e32 v45, v45, v69
	v_exp_f32_e32 v50, v50
	v_exp_f32_e32 v53, v53
	v_exp_f32_e32 v51, v51
	v_mul_f32_e32 v40, 0xbfb8aa3b, v40
	v_mul_f32_e32 v45, 0xbfb8aa3b, v45
	v_exp_f32_e32 v40, v40
	v_exp_f32_e32 v45, v45
	v_add_f32_e32 v52, 1.0, v52
	v_rcp_f32_e32 v52, v52
	v_add_f32_e32 v50, 1.0, v50
	v_add_f32_e32 v53, 1.0, v53
	v_add_f32_e32 v51, 1.0, v51
	v_rcp_f32_e32 v49, v49
	v_rcp_f32_e32 v50, v50
	v_rcp_f32_e32 v53, v53
	v_rcp_f32_e32 v51, v51
	v_add_f32_e32 v40, 1.0, v40
	v_add_f32_e32 v45, 1.0, v45
	v_add_f32_e32 v41, v41, v65
	v_rcp_f32_e32 v40, v40
	v_rcp_f32_e32 v45, v45
	v_mul_f32_e32 v41, 0xbfb8aa3b, v41
	v_exp_f32_e32 v41, v41
	v_mul_f32_e32 v52, 0x3f1b4598, v52
	v_mul_f32_e32 v49, 0x3f1b4598, v49
	v_mul_f32_e32 v55, 0x3f1b4598, v50
	v_mul_f32_e32 v50, 0x3f1b4598, v53
	v_mul_f32_e32 v51, 0x3f1b4598, v51
	v_cvt_pk_bf16_f32 v48, v52, v48
	v_lshl_add_u64 v[52:53], v[74:75], 0, v[120:121]
	v_cvt_pk_bf16_f32 v49, v49, v50
	v_cvt_pk_bf16_f32 v50, v56, v54
	v_cvt_pk_bf16_f32 v51, v55, v51
	global_store_dwordx4 v[52:53], v[48:51], off
	v_add_f32_e32 v41, 1.0, v41
	v_rcp_f32_e32 v41, v41
	v_mul_f32_e32 v48, 0x3f1b4598, v40
	v_mul_f32_e32 v40, 0x3f1b4598, v45
	v_add_f32_e32 v45, v46, v70
	v_mul_f32_e32 v45, 0xbfb8aa3b, v45
	v_exp_f32_e32 v45, v45
	v_add_f32_e32 v44, v44, v68
	v_mul_f32_e32 v44, 0xbfb8aa3b, v44
	v_add_f32_e32 v42, v42, v66
	v_mul_f32_e32 v46, 0x3f1b4598, v41
	v_add_f32_e32 v41, 1.0, v45
	v_add_f32_e32 v45, v47, v71
	v_add_f32_e32 v43, v43, v67
	v_exp_f32_e32 v44, v44
	v_mul_f32_e32 v42, 0xbfb8aa3b, v42
	v_mul_f32_e32 v45, 0xbfb8aa3b, v45
	v_mul_f32_e32 v43, 0xbfb8aa3b, v43
	v_add_f32_e32 v32, v32, v64
	v_add_f32_e32 v37, v37, v69
	v_exp_f32_e32 v42, v42
	v_exp_f32_e32 v45, v45
	v_exp_f32_e32 v43, v43
	v_mul_f32_e32 v32, 0xbfb8aa3b, v32
	v_mul_f32_e32 v37, 0xbfb8aa3b, v37
	v_exp_f32_e32 v32, v32
	v_exp_f32_e32 v37, v37
	v_add_f32_e32 v44, 1.0, v44
	v_rcp_f32_e32 v44, v44
	v_add_f32_e32 v42, 1.0, v42
	v_add_f32_e32 v45, 1.0, v45
	v_add_f32_e32 v43, 1.0, v43
	v_rcp_f32_e32 v41, v41
	v_rcp_f32_e32 v42, v42
	v_rcp_f32_e32 v45, v45
	v_rcp_f32_e32 v43, v43
	v_add_f32_e32 v32, 1.0, v32
	v_add_f32_e32 v37, 1.0, v37
	v_add_f32_e32 v33, v33, v65
	v_rcp_f32_e32 v32, v32
	v_rcp_f32_e32 v37, v37
	v_mul_f32_e32 v33, 0xbfb8aa3b, v33
	v_exp_f32_e32 v33, v33
	v_mul_f32_e32 v44, 0x3f1b4598, v44
	v_mul_f32_e32 v41, 0x3f1b4598, v41
	v_mul_f32_e32 v47, 0x3f1b4598, v42
	v_mul_f32_e32 v42, 0x3f1b4598, v45
	v_mul_f32_e32 v43, 0x3f1b4598, v43
	v_cvt_pk_bf16_f32 v40, v44, v40
	v_lshl_add_u64 v[44:45], v[74:75], 0, v[112:113]
	v_cvt_pk_bf16_f32 v41, v41, v42
	v_cvt_pk_bf16_f32 v42, v48, v46
	v_cvt_pk_bf16_f32 v43, v47, v43
	global_store_dwordx4 v[44:45], v[40:43], off
	v_add_f32_e32 v33, 1.0, v33
	v_rcp_f32_e32 v33, v33
	v_mul_f32_e32 v40, 0x3f1b4598, v32
	v_mul_f32_e32 v32, 0x3f1b4598, v37
	v_add_f32_e32 v37, v38, v70
	v_mul_f32_e32 v37, 0xbfb8aa3b, v37
	v_exp_f32_e32 v37, v37
	v_add_f32_e32 v36, v36, v68
	v_mul_f32_e32 v36, 0xbfb8aa3b, v36
	v_add_f32_e32 v34, v34, v66
; __device__ __forceinline__ u32x4 pack8(const float (&f)[8]) { u32x4 o; o.x = pk2(f[0], f[1]); o.y = pk2(f[2], f[3]); o.z = pk2(f[4], f[5]); o.w = pk2(f[6], f[7]); return o; }
; __device__ __forceinline__ float sigmoidf_(float x) { return __builtin_amdgcn_rcpf(1.0f + __expf(-x)); }
;     __device__ __forceinline__ void operator()(const f32x4 (&acc)[2][2][4][2], const Unit& u, int wr, int wc, int fr, int fq) const {
;     ...
;         for (int bj = 0; bj < 2; ++bj) {
;             const f32x4 w0a = *(const f32x4*)(w0 + 512 * bj + cb), w0b = *(const f32x4*)(w0 + 512 * bj + cb + 4); bf16_t* D = bj ? DBp : DFp;
; #pragma unroll
;             for (int ai = 0; ai < 2; ++ai)
; #pragma unroll
;                 for (int m = 0; m < 4; ++m) { const f32x4 a0 = acc[ai][bj][m][0], a1 = acc[ai][bj][m][1]; float d[8];
; #pragma unroll
;                     for (int j = 0; j < 4; ++j) { d[j] = 0.60653066f * sigmoidf_(w0a[j] + a0[j]); d[4 + j] = 0.60653066f * sigmoidf_(w0b[j] + a1[j]); }
;                     *(u32x4*)(D + (size_t)(row0 + ai * HALF + m * 16) * 512 + cb) = pack8(d); asm volatile("" ::: "memory"); }
	v_mul_f32_e32 v38, 0x3f1b4598, v33
	v_add_f32_e32 v33, 1.0, v37
	v_add_f32_e32 v37, v39, v71
	v_add_f32_e32 v35, v35, v67
	v_exp_f32_e32 v36, v36
	v_mul_f32_e32 v34, 0xbfb8aa3b, v34
	v_mul_f32_e32 v37, 0xbfb8aa3b, v37
	v_mul_f32_e32 v35, 0xbfb8aa3b, v35
	v_add_f32_e32 v24, v24, v64
	v_add_f32_e32 v29, v29, v69
	v_exp_f32_e32 v34, v34
	v_exp_f32_e32 v37, v37
	v_exp_f32_e32 v35, v35
	v_mul_f32_e32 v24, 0xbfb8aa3b, v24
	v_mul_f32_e32 v29, 0xbfb8aa3b, v29
	v_exp_f32_e32 v24, v24
	v_exp_f32_e32 v29, v29
	v_add_f32_e32 v36, 1.0, v36
	v_rcp_f32_e32 v36, v36
	v_add_f32_e32 v34, 1.0, v34
	v_add_f32_e32 v37, 1.0, v37
	v_add_f32_e32 v35, 1.0, v35
	v_rcp_f32_e32 v33, v33
	v_rcp_f32_e32 v34, v34
	v_rcp_f32_e32 v37, v37
	v_rcp_f32_e32 v35, v35
	v_add_f32_e32 v24, 1.0, v24
	v_add_f32_e32 v29, 1.0, v29
	v_add_f32_e32 v25, v25, v65
	v_rcp_f32_e32 v24, v24
	v_rcp_f32_e32 v29, v29
	v_mul_f32_e32 v25, 0xbfb8aa3b, v25
	v_exp_f32_e32 v25, v25
	v_mul_f32_e32 v36, 0x3f1b4598, v36
	v_mul_f32_e32 v33, 0x3f1b4598, v33
	v_mul_f32_e32 v39, 0x3f1b4598, v34
	v_mul_f32_e32 v34, 0x3f1b4598, v37
	v_mul_f32_e32 v35, 0x3f1b4598, v35
	v_cvt_pk_bf16_f32 v32, v36, v32
	v_lshl_add_u64 v[36:37], v[74:75], 0, v[104:105]
	v_cvt_pk_bf16_f32 v33, v33, v34
	v_cvt_pk_bf16_f32 v34, v40, v38
	v_cvt_pk_bf16_f32 v35, v39, v35
	global_store_dwordx4 v[36:37], v[32:35], off
	v_add_f32_e32 v25, 1.0, v25
	v_rcp_f32_e32 v25, v25
	v_mul_f32_e32 v32, 0x3f1b4598, v24
	v_mul_f32_e32 v24, 0x3f1b4598, v29
	v_add_f32_e32 v29, v30, v70
	v_mul_f32_e32 v29, 0xbfb8aa3b, v29
	v_exp_f32_e32 v29, v29
	v_add_f32_e32 v28, v28, v68
	v_mul_f32_e32 v28, 0xbfb8aa3b, v28
	v_add_f32_e32 v26, v26, v66
	v_mul_f32_e32 v30, 0x3f1b4598, v25
	v_add_f32_e32 v25, 1.0, v29
	v_add_f32_e32 v29, v31, v71
	v_add_f32_e32 v27, v27, v67
	v_exp_f32_e32 v28, v28
	v_mul_f32_e32 v26, 0xbfb8aa3b, v26
	v_mul_f32_e32 v29, 0xbfb8aa3b, v29
	v_mul_f32_e32 v27, 0xbfb8aa3b, v27
	v_add_f32_e32 v16, v16, v64
	v_add_f32_e32 v21, v21, v69
	v_exp_f32_e32 v26, v26
	v_exp_f32_e32 v29, v29
	v_exp_f32_e32 v27, v27
	v_mul_f32_e32 v16, 0xbfb8aa3b, v16
	v_mul_f32_e32 v21, 0xbfb8aa3b, v21
	v_exp_f32_e32 v16, v16
	v_exp_f32_e32 v21, v21
	v_add_f32_e32 v28, 1.0, v28
	v_rcp_f32_e32 v28, v28
	v_add_f32_e32 v26, 1.0, v26
	v_add_f32_e32 v29, 1.0, v29
	v_add_f32_e32 v27, 1.0, v27
	v_rcp_f32_e32 v25, v25
	v_rcp_f32_e32 v26, v26
	v_rcp_f32_e32 v29, v29
	v_rcp_f32_e32 v27, v27
	v_add_f32_e32 v16, 1.0, v16
	v_add_f32_e32 v21, 1.0, v21
	v_add_f32_e32 v17, v17, v65
	v_rcp_f32_e32 v16, v16
	v_rcp_f32_e32 v21, v21
	v_mul_f32_e32 v17, 0xbfb8aa3b, v17
	v_exp_f32_e32 v17, v17
	v_mul_f32_e32 v28, 0x3f1b4598, v28
	v_mul_f32_e32 v25, 0x3f1b4598, v25
	v_mul_f32_e32 v31, 0x3f1b4598, v26
	v_mul_f32_e32 v26, 0x3f1b4598, v29
	v_mul_f32_e32 v27, 0x3f1b4598, v27
	v_cvt_pk_bf16_f32 v24, v28, v24
	v_lshl_add_u64 v[28:29], v[74:75], 0, v[96:97]
	v_cvt_pk_bf16_f32 v25, v25, v26
	v_cvt_pk_bf16_f32 v26, v32, v30
	v_cvt_pk_bf16_f32 v27, v31, v27
	global_store_dwordx4 v[28:29], v[24:27], off
	v_add_f32_e32 v17, 1.0, v17
	v_rcp_f32_e32 v17, v17
	v_mul_f32_e32 v24, 0x3f1b4598, v16
	v_mul_f32_e32 v16, 0x3f1b4598, v21
	v_add_f32_e32 v21, v22, v70
	v_mul_f32_e32 v21, 0xbfb8aa3b, v21
	v_exp_f32_e32 v21, v21
	v_add_f32_e32 v20, v20, v68
	v_mul_f32_e32 v20, 0xbfb8aa3b, v20
	v_add_f32_e32 v18, v18, v66
	v_mul_f32_e32 v22, 0x3f1b4598, v17
	v_add_f32_e32 v17, 1.0, v21
	v_add_f32_e32 v21, v23, v71
	v_add_f32_e32 v19, v19, v67
	v_exp_f32_e32 v20, v20
	v_mul_f32_e32 v18, 0xbfb8aa3b, v18
	v_mul_f32_e32 v21, 0xbfb8aa3b, v21
	v_mul_f32_e32 v19, 0xbfb8aa3b, v19
	v_add_f32_e32 v8, v8, v64
	v_add_f32_e32 v13, v13, v69
	v_exp_f32_e32 v18, v18
	v_exp_f32_e32 v21, v21
	v_exp_f32_e32 v19, v19
	v_mul_f32_e32 v8, 0xbfb8aa3b, v8
; __device__ __forceinline__ u32x4 pack8(const float (&f)[8]) { u32x4 o; o.x = pk2(f[0], f[1]); o.y = pk2(f[2], f[3]); o.z = pk2(f[4], f[5]); o.w = pk2(f[6], f[7]); return o; }
; __device__ __forceinline__ float sigmoidf_(float x) { return __builtin_amdgcn_rcpf(1.0f + __expf(-x)); }
;     __device__ __forceinline__ void operator()(const f32x4 (&acc)[2][2][4][2], const Unit& u, int wr, int wc, int fr, int fq) const {
;     ...
;         for (int bj = 0; bj < 2; ++bj) {
;             const f32x4 w0a = *(const f32x4*)(w0 + 512 * bj + cb), w0b = *(const f32x4*)(w0 + 512 * bj + cb + 4); bf16_t* D = bj ? DBp : DFp;
; #pragma unroll
;             for (int ai = 0; ai < 2; ++ai)
; #pragma unroll
;                 for (int m = 0; m < 4; ++m) { const f32x4 a0 = acc[ai][bj][m][0], a1 = acc[ai][bj][m][1]; float d[8];
; #pragma unroll
;                     for (int j = 0; j < 4; ++j) { d[j] = 0.60653066f * sigmoidf_(w0a[j] + a0[j]); d[4 + j] = 0.60653066f * sigmoidf_(w0b[j] + a1[j]); }
;                     *(u32x4*)(D + (size_t)(row0 + ai * HALF + m * 16) * 512 + cb) = pack8(d); asm volatile("" ::: "memory"); }
	v_mul_f32_e32 v13, 0xbfb8aa3b, v13
	v_exp_f32_e32 v8, v8
	v_exp_f32_e32 v13, v13
	v_add_f32_e32 v20, 1.0, v20
	v_rcp_f32_e32 v20, v20
	v_add_f32_e32 v18, 1.0, v18
	v_add_f32_e32 v21, 1.0, v21
	v_add_f32_e32 v19, 1.0, v19
	v_rcp_f32_e32 v17, v17
	v_rcp_f32_e32 v18, v18
	v_rcp_f32_e32 v21, v21
	v_rcp_f32_e32 v19, v19
	v_add_f32_e32 v8, 1.0, v8
	v_add_f32_e32 v13, 1.0, v13
	v_add_f32_e32 v9, v9, v65
	v_rcp_f32_e32 v8, v8
	v_rcp_f32_e32 v13, v13
	v_mul_f32_e32 v9, 0xbfb8aa3b, v9
	v_exp_f32_e32 v9, v9
	v_mul_f32_e32 v20, 0x3f1b4598, v20
	v_mul_f32_e32 v17, 0x3f1b4598, v17
	v_mul_f32_e32 v23, 0x3f1b4598, v18
	v_mul_f32_e32 v18, 0x3f1b4598, v21
	v_mul_f32_e32 v19, 0x3f1b4598, v19
	v_cvt_pk_bf16_f32 v16, v20, v16
	v_lshl_add_u64 v[20:21], v[74:75], 0, v[88:89]
	v_cvt_pk_bf16_f32 v17, v17, v18
	v_cvt_pk_bf16_f32 v18, v24, v22
	v_cvt_pk_bf16_f32 v19, v23, v19
	global_store_dwordx4 v[20:21], v[16:19], off
	v_add_f32_e32 v9, 1.0, v9
	v_rcp_f32_e32 v9, v9
	v_mul_f32_e32 v16, 0x3f1b4598, v8
	v_mul_f32_e32 v8, 0x3f1b4598, v13
	v_add_f32_e32 v13, v14, v70
	v_mul_f32_e32 v13, 0xbfb8aa3b, v13
	v_exp_f32_e32 v13, v13
	v_add_f32_e32 v12, v12, v68
	v_mul_f32_e32 v12, 0xbfb8aa3b, v12
	v_add_f32_e32 v10, v10, v66
	v_mul_f32_e32 v14, 0x3f1b4598, v9
	v_add_f32_e32 v9, 1.0, v13
	v_add_f32_e32 v13, v15, v71
	v_add_f32_e32 v11, v11, v67
	v_exp_f32_e32 v12, v12
	v_mul_f32_e32 v10, 0xbfb8aa3b, v10
	v_mul_f32_e32 v13, 0xbfb8aa3b, v13
	v_mul_f32_e32 v11, 0xbfb8aa3b, v11
	v_add_f32_e32 v0, v0, v64
	v_add_f32_e32 v5, v5, v69
	v_exp_f32_e32 v10, v10
	v_exp_f32_e32 v13, v13
	v_exp_f32_e32 v11, v11
	v_mul_f32_e32 v0, 0xbfb8aa3b, v0
	v_mul_f32_e32 v5, 0xbfb8aa3b, v5
	v_exp_f32_e32 v0, v0
	v_exp_f32_e32 v5, v5
	v_add_f32_e32 v12, 1.0, v12
	v_rcp_f32_e32 v12, v12
	v_add_f32_e32 v10, 1.0, v10
	v_add_f32_e32 v13, 1.0, v13
	v_add_f32_e32 v11, 1.0, v11
	v_rcp_f32_e32 v9, v9
	v_rcp_f32_e32 v10, v10
	v_rcp_f32_e32 v13, v13
	v_rcp_f32_e32 v11, v11
	v_add_f32_e32 v0, 1.0, v0
	v_add_f32_e32 v5, 1.0, v5
	v_add_f32_e32 v1, v1, v65
	v_rcp_f32_e32 v0, v0
	v_rcp_f32_e32 v5, v5
	v_mul_f32_e32 v1, 0xbfb8aa3b, v1
	v_exp_f32_e32 v1, v1
	v_mul_f32_e32 v12, 0x3f1b4598, v12
	v_mul_f32_e32 v9, 0x3f1b4598, v9
	v_mul_f32_e32 v15, 0x3f1b4598, v10
	v_mul_f32_e32 v10, 0x3f1b4598, v13
	v_mul_f32_e32 v11, 0x3f1b4598, v11
	v_cvt_pk_bf16_f32 v8, v12, v8
	v_lshl_add_u64 v[12:13], v[74:75], 0, v[80:81]
	v_cvt_pk_bf16_f32 v9, v9, v10
	v_cvt_pk_bf16_f32 v10, v16, v14
	v_cvt_pk_bf16_f32 v11, v15, v11
	global_store_dwordx4 v[12:13], v[8:11], off
	v_add_f32_e32 v1, 1.0, v1
	v_rcp_f32_e32 v1, v1
	v_mul_f32_e32 v8, 0x3f1b4598, v0
	v_mul_f32_e32 v0, 0x3f1b4598, v5
	v_add_f32_e32 v5, v6, v70
	v_mul_f32_e32 v5, 0xbfb8aa3b, v5
	v_exp_f32_e32 v5, v5
	v_add_f32_e32 v4, v4, v68
	v_mul_f32_e32 v4, 0xbfb8aa3b, v4
	v_add_f32_e32 v2, v2, v66
	v_mul_f32_e32 v6, 0x3f1b4598, v1
	v_add_f32_e32 v1, 1.0, v5
	v_add_f32_e32 v5, v7, v71
	v_add_f32_e32 v3, v3, v67
	v_exp_f32_e32 v4, v4
	v_mul_f32_e32 v2, 0xbfb8aa3b, v2
	v_mul_f32_e32 v5, 0xbfb8aa3b, v5
	v_mul_f32_e32 v3, 0xbfb8aa3b, v3
	v_exp_f32_e32 v2, v2
	v_exp_f32_e32 v5, v5
	v_exp_f32_e32 v3, v3
	v_add_f32_e32 v4, 1.0, v4
	v_rcp_f32_e32 v4, v4
	v_add_f32_e32 v2, 1.0, v2
	v_add_f32_e32 v5, 1.0, v5
	v_add_f32_e32 v3, 1.0, v3
	v_rcp_f32_e32 v1, v1
	v_rcp_f32_e32 v2, v2
	v_rcp_f32_e32 v5, v5
	v_rcp_f32_e32 v3, v3
	v_mul_f32_e32 v4, 0x3f1b4598, v4
	v_mul_f32_e32 v1, 0x3f1b4598, v1
	v_mul_f32_e32 v7, 0x3f1b4598, v2
	v_mul_f32_e32 v2, 0x3f1b4598, v5
	v_mul_f32_e32 v3, 0x3f1b4598, v3
	v_cvt_pk_bf16_f32 v0, v4, v0
	v_lshl_add_u64 v[4:5], v[74:75], 0, v[72:73]
	v_cvt_pk_bf16_f32 v1, v1, v2
	v_cvt_pk_bf16_f32 v2, v8, v6
	v_cvt_pk_bf16_f32 v3, v7, v3
	global_store_dwordx4 v[4:5], v[0:3], off
	s_cbranch_vccz .LBB0_450

; #define PG8_STAGE(bufoff, gbase, voff) do { _Pragma("unroll") for (int _i = 0; _i < 2; ++_i) \
;         __builtin_amdgcn_global_load_lds((const unsigned*)((const char*)(gbase) + (voff)[_i]), (PG8_LAS unsigned*)(lds + (bufoff) + ldsw + _i * 8192), 16, 0, 0); } while (0)
; #define PG8_LDA(dst, b, h) do { _Pragma("unroll") for (int m = 0; m < 4; ++m) _Pragma("unroll") for (int k = 0; k < 2; ++k) dst[m][k] = *(const PG8_LAS bf16x8*)(lds + PG8_SA(b, h) + aoff + m * 2048 + k * 1024); } while (0)
; #define PG8_LDB(dst, b, h) do { _Pragma("unroll") for (int n = 0; n < 2; ++n) _Pragma("unroll") for (int k = 0; k < 2; ++k) dst[n][k] = *(const PG8_LAS bf16x8*)(lds + PG8_SB(b, h) + boff + n * 2048 + k * 1024); } while (0)
; #define PG8_MMA(ai, bj, At, Bt) do { __builtin_amdgcn_s_setprio(1); _Pragma("unroll") for (int m = 0; m < 4; ++m) _Pragma("unroll") for (int n = 0; n < 2; ++n) _Pragma("unroll") for (int k = 0; k < 2; ++k) \
;         acc[ai][bj][m][n] = __builtin_amdgcn_mfma_f32_16x16x32_bf16(Bt[n][k], At[m][k], acc[ai][bj][m][n], 0, 0, 0); __builtin_amdgcn_s_setprio(0); } while (0)
; #define PG8_WAIT_L(n) asm volatile("s_waitcnt lgkmcnt(" #n ")" ::: "memory")
; #define PG8_BAR __builtin_amdgcn_s_barrier()
; #define PG8_SCHED __builtin_amdgcn_sched_barrier(0)
; template <class Epi, class Sched>
; __device__ __forceinline__ void gemm_phase(PG8_LAS unsigned char* lds, const Gemm g, const Sched& S, const Epi& E) {
;     ...
;             PG8_LDB(B0, 0, 0); PG8_SCHED; PG8_LDA(At, 0, 0); PG8_STAGE(PG8_SA(1, 1), a1 + hstep, voffA);
;             PG8_WAIT_L(8); PG8_BAR; PG8_WAIT_L(0); PG8_MMA(0, 0, At, B0); PG8_BAR; PG8_SCHED;
;             PG8_LDB(B1, 0, 1); PG8_STAGE(PG8_SB(0, 0), b2, voffB);
;             PG8_BAR; PG8_WAIT_L(0); PG8_MMA(0, 1, At, B1); PG8_BAR;
;             PG8_LDA(At, 0, 1); PG8_STAGE(PG8_SA(0, 0), a2, voffA);
;             PG8_BAR; PG8_WAIT_L(0); PG8_MMA(1, 0, At, B0); PG8_BAR; PG8_SCHED;
.LBB0_461:
	ds_read_b128 v[8:11], v106
	ds_read_b128 v[12:15], v106 offset:1024
	ds_read_b128 v[16:19], v106 offset:2048
	ds_read_b128 v[20:23], v106 offset:3072
	s_add_u32 s72, s24, 0x18080
	s_addc_u32 s73, s25, 0
	s_add_i32 s79, s38, 0xc000
	v_lshl_add_u64 v[0:1], s[72:73], 0, v[64:65]
	s_mov_b32 m0, s79
	ds_read_b128 v[4:7], v105
	ds_read_b128 v[24:27], v105 offset:1024
	ds_read_b128 v[28:31], v105 offset:2048
	ds_read_b128 v[32:35], v105 offset:3072
	ds_read_b128 v[36:39], v105 offset:4096
	ds_read_b128 v[40:43], v105 offset:5120
	ds_read_b128 v[44:47], v105 offset:6144
	ds_read_b128 v[48:51], v105 offset:7168
	global_load_lds_dwordx4 v[0:1], off
	v_lshl_add_u64 v[0:1], s[72:73], 0, v[68:69]
	s_add_i32 s72, s38, 0xe000
	s_mov_b32 m0, s72
	s_nop 0
	global_load_lds_dwordx4 v[0:1], off
	s_waitcnt lgkmcnt(8)
	s_barrier
	s_waitcnt lgkmcnt(0)
	v_mfma_f32_16x16x32_bf16 v[0:3], v[8:11], v[4:7], 0
	v_mfma_f32_16x16x32_bf16 v[52:55], v[12:15], v[24:27], v[0:3]
	v_mfma_f32_16x16x32_bf16 v[0:3], v[16:19], v[4:7], 0
	v_mfma_f32_16x16x32_bf16 v[56:59], v[20:23], v[24:27], v[0:3]
	v_mfma_f32_16x16x32_bf16 v[0:3], v[8:11], v[28:31], 0
	v_mfma_f32_16x16x32_bf16 v[60:63], v[12:15], v[32:35], v[0:3]
	v_mfma_f32_16x16x32_bf16 v[0:3], v[16:19], v[28:31], 0
	v_mfma_f32_16x16x32_bf16 v[78:81], v[20:23], v[32:35], v[0:3]
	v_mfma_f32_16x16x32_bf16 v[0:3], v[8:11], v[36:39], 0
	v_mfma_f32_16x16x32_bf16 v[82:85], v[12:15], v[40:43], v[0:3]
	v_mfma_f32_16x16x32_bf16 v[0:3], v[16:19], v[36:39], 0
	v_mfma_f32_16x16x32_bf16 v[86:89], v[20:23], v[40:43], v[0:3]
	v_mfma_f32_16x16x32_bf16 v[0:3], v[8:11], v[44:47], 0
	v_mfma_f32_16x16x32_bf16 v[90:93], v[12:15], v[48:51], v[0:3]
	v_mfma_f32_16x16x32_bf16 v[0:3], v[16:19], v[44:47], 0
	v_mfma_f32_16x16x32_bf16 v[94:97], v[20:23], v[48:51], v[0:3]
	s_barrier
	s_nop 4
	v_lshl_add_u64 v[0:1], s[26:27], 0, v[66:67]
	s_add_i32 s75, s66, s37
	v_lshl_add_u64 v[2:3], v[0:1], 0, s[14:15]
	s_mov_b32 m0, s75
	ds_read_b128 v[98:101], v107
	ds_read_b128 v[108:111], v107 offset:1024
	ds_read_b128 v[112:115], v107 offset:2048
	ds_read_b128 v[116:119], v107 offset:3072
	global_load_lds_dwordx4 v[2:3], off
	v_lshl_add_u64 v[2:3], s[26:27], 0, v[70:71]
	s_add_i32 s73, s75, 0x2000
	v_lshl_add_u64 v[120:121], v[2:3], 0, s[14:15]
	s_mov_b32 m0, s73
	s_nop 0
	global_load_lds_dwordx4 v[120:121], off
	s_barrier
	s_waitcnt lgkmcnt(0)
	v_mfma_f32_16x16x32_bf16 v[120:123], v[98:101], v[4:7], 0
	v_mfma_f32_16x16x32_bf16 v[4:7], v[112:115], v[4:7], 0
	v_mfma_f32_16x16x32_bf16 v[120:123], v[108:111], v[24:27], v[120:123]
	v_mfma_f32_16x16x32_bf16 v[24:27], v[116:119], v[24:27], v[4:7]
	v_mfma_f32_16x16x32_bf16 v[4:7], v[98:101], v[28:31], 0
	v_mfma_f32_16x16x32_bf16 v[124:127], v[108:111], v[32:35], v[4:7]
	v_mfma_f32_16x16x32_bf16 v[4:7], v[112:115], v[28:31], 0
	v_mfma_f32_16x16x32_bf16 v[28:31], v[116:119], v[32:35], v[4:7]
	v_mfma_f32_16x16x32_bf16 v[4:7], v[98:101], v[36:39], 0
	v_mfma_f32_16x16x32_bf16 v[32:35], v[108:111], v[40:43], v[4:7]
	v_mfma_f32_16x16x32_bf16 v[4:7], v[112:115], v[36:39], 0
	v_mfma_f32_16x16x32_bf16 v[36:39], v[116:119], v[40:43], v[4:7]
	v_mfma_f32_16x16x32_bf16 v[4:7], v[98:101], v[44:47], 0
	v_mfma_f32_16x16x32_bf16 v[40:43], v[108:111], v[48:51], v[4:7]
	v_mfma_f32_16x16x32_bf16 v[4:7], v[112:115], v[44:47], 0
	v_mfma_f32_16x16x32_bf16 v[44:47], v[116:119], v[48:51], v[4:7]
	s_nop 5
	v_lshl_add_u64 v[4:5], s[24:25], 0, v[64:65]
	s_mov_b32 m0, s38
	v_lshl_add_u64 v[6:7], v[4:5], 0, s[14:15]
	s_barrier
	ds_read_b128 v[48:51], v105 offset:16384
	ds_read_b128 v[128:131], v105 offset:17408
	ds_read_b128 v[132:135], v105 offset:18432
	ds_read_b128 v[136:139], v105 offset:19456
	ds_read_b128 v[140:143], v105 offset:20480
	ds_read_b128 v[144:147], v105 offset:21504
	ds_read_b128 v[148:151], v105 offset:22528
	ds_read_b128 v[152:155], v105 offset:23552
	global_load_lds_dwordx4 v[6:7], off
	v_lshl_add_u64 v[6:7], s[24:25], 0, v[68:69]
	v_lshl_add_u64 v[156:157], v[6:7], 0, s[14:15]
	s_mov_b32 m0, s39
	s_nop 0
	global_load_lds_dwordx4 v[156:157], off
	s_barrier
	s_waitcnt lgkmcnt(0)
	v_mfma_f32_16x16x32_bf16 v[156:159], v[8:11], v[48:51], 0
	v_mfma_f32_16x16x32_bf16 v[164:167], v[8:11], v[132:135], 0
	v_mfma_f32_16x16x32_bf16 v[172:175], v[8:11], v[140:143], 0
	v_mfma_f32_16x16x32_bf16 v[8:11], v[8:11], v[148:151], 0
	v_mfma_f32_16x16x32_bf16 v[156:159], v[12:15], v[128:131], v[156:159]
	v_mfma_f32_16x16x32_bf16 v[160:163], v[16:19], v[48:51], 0
	v_mfma_f32_16x16x32_bf16 v[164:167], v[12:15], v[136:139], v[164:167]
	v_mfma_f32_16x16x32_bf16 v[168:171], v[16:19], v[132:135], 0
	v_mfma_f32_16x16x32_bf16 v[172:175], v[12:15], v[144:147], v[172:175]
	v_mfma_f32_16x16x32_bf16 v[176:179], v[16:19], v[140:143], 0
	v_mfma_f32_16x16x32_bf16 v[10:13], v[12:15], v[152:155], v[8:11]
	v_mfma_f32_16x16x32_bf16 v[14:17], v[16:19], v[148:151], 0
	v_mfma_f32_16x16x32_bf16 v[160:163], v[20:23], v[128:131], v[160:163]
	v_mfma_f32_16x16x32_bf16 v[168:171], v[20:23], v[136:139], v[168:171]
	v_mfma_f32_16x16x32_bf16 v[176:179], v[20:23], v[144:147], v[176:179]
	v_mfma_f32_16x16x32_bf16 v[14:17], v[20:23], v[152:155], v[14:17]
	s_barrier
	s_add_u32 s80, s26, 0x18100
	s_addc_u32 s81, s27, 0
	s_add_i32 s76, s67, s37
	v_lshl_add_u64 v[8:9], s[80:81], 0, v[66:67]
	s_mov_b32 m0, s76
	s_add_i32 s74, s76, 0x2000
	global_load_lds_dwordx4 v[8:9], off
	v_lshl_add_u64 v[8:9], s[80:81], 0, v[70:71]
	s_mov_b32 m0, s74
	s_nop 0
	global_load_lds_dwordx4 v[8:9], off
	s_waitcnt vmcnt(6)
	s_barrier
; #define PG8_STAGE(bufoff, gbase, voff) do { _Pragma("unroll") for (int _i = 0; _i < 2; ++_i) \
;         __builtin_amdgcn_global_load_lds((const unsigned*)((const char*)(gbase) + (voff)[_i]), (PG8_LAS unsigned*)(lds + (bufoff) + ldsw + _i * 8192), 16, 0, 0); } while (0)
; #define PG8_LDA(dst, b, h) do { _Pragma("unroll") for (int m = 0; m < 4; ++m) _Pragma("unroll") for (int k = 0; k < 2; ++k) dst[m][k] = *(const PG8_LAS bf16x8*)(lds + PG8_SA(b, h) + aoff + m * 2048 + k * 1024); } while (0)
; #define PG8_LDB(dst, b, h) do { _Pragma("unroll") for (int n = 0; n < 2; ++n) _Pragma("unroll") for (int k = 0; k < 2; ++k) dst[n][k] = *(const PG8_LAS bf16x8*)(lds + PG8_SB(b, h) + boff + n * 2048 + k * 1024); } while (0)
; #define PG8_MMA(ai, bj, At, Bt) do { __builtin_amdgcn_s_setprio(1); _Pragma("unroll") for (int m = 0; m < 4; ++m) _Pragma("unroll") for (int n = 0; n < 2; ++n) _Pragma("unroll") for (int k = 0; k < 2; ++k) \
;         acc[ai][bj][m][n] = __builtin_amdgcn_mfma_f32_16x16x32_bf16(Bt[n][k], At[m][k], acc[ai][bj][m][n], 0, 0, 0); __builtin_amdgcn_s_setprio(0); } while (0)
; #define PG8_WAIT_V(n) asm volatile("s_waitcnt vmcnt(" #n ")" ::: "memory")
; #define PG8_WAIT_L(n) asm volatile("s_waitcnt lgkmcnt(" #n ")" ::: "memory")
; #define PG8_BAR __builtin_amdgcn_s_barrier()
; #define PG8_SCHED __builtin_amdgcn_sched_barrier(0)
; template <class Epi, class Sched>
; __device__ __forceinline__ void gemm_phase(PG8_LAS unsigned char* lds, const Gemm g, const Sched& S, const Epi& E) {
;     ...
;             PG8_STAGE(PG8_SB(0, 1), b2 + hstep, voffB);
;             PG8_WAIT_V(6); PG8_BAR; PG8_MMA(1, 1, At, B1); PG8_BAR;
;             PG8_LDB(B0, 1, 0); PG8_SCHED; PG8_LDA(At, 1, 0); PG8_STAGE(PG8_SA(0, 1), a2 + hstep, voffA);
;             PG8_WAIT_L(8); PG8_BAR; PG8_WAIT_L(0); PG8_MMA(0, 0, At, B0); PG8_BAR; PG8_SCHED;
;             PG8_LDB(B1, 1, 1); PG8_STAGE(PG8_SB(1, 0), b3, voffB);
;             PG8_BAR; PG8_WAIT_L(0); PG8_MMA(0, 1, At, B1); PG8_BAR;
;             PG8_LDA(At, 1, 1); PG8_STAGE(PG8_SA(1, 0), a3, voffA);
	v_mfma_f32_16x16x32_bf16 v[18:21], v[98:101], v[48:51], 0
	v_mfma_f32_16x16x32_bf16 v[48:51], v[112:115], v[48:51], 0
	v_mfma_f32_16x16x32_bf16 v[18:21], v[108:111], v[128:131], v[18:21]
	v_mfma_f32_16x16x32_bf16 v[48:51], v[116:119], v[128:131], v[48:51]
	v_mfma_f32_16x16x32_bf16 v[128:131], v[98:101], v[132:135], 0
	v_mfma_f32_16x16x32_bf16 v[132:135], v[112:115], v[132:135], 0
	v_mfma_f32_16x16x32_bf16 v[128:131], v[108:111], v[136:139], v[128:131]
	v_mfma_f32_16x16x32_bf16 v[132:135], v[116:119], v[136:139], v[132:135]
	v_mfma_f32_16x16x32_bf16 v[136:139], v[98:101], v[140:143], 0
	v_mfma_f32_16x16x32_bf16 v[98:101], v[98:101], v[148:151], 0
	v_mfma_f32_16x16x32_bf16 v[136:139], v[108:111], v[144:147], v[136:139]
	v_mfma_f32_16x16x32_bf16 v[140:143], v[112:115], v[140:143], 0
	v_mfma_f32_16x16x32_bf16 v[98:101], v[108:111], v[152:155], v[98:101]
	v_mfma_f32_16x16x32_bf16 v[108:111], v[112:115], v[148:151], 0
	v_mfma_f32_16x16x32_bf16 v[140:143], v[116:119], v[144:147], v[140:143]
	v_mfma_f32_16x16x32_bf16 v[108:111], v[116:119], v[152:155], v[108:111]
	s_add_i32 s77, 0, 0x18000
	v_add_u32_e32 v8, s77, v104
	s_barrier
	ds_read_b128 v[112:115], v8
	ds_read_b128 v[116:119], v8 offset:1024
	ds_read_b128 v[144:147], v8 offset:2048
	ds_read_b128 v[148:151], v8 offset:3072
	s_add_u32 s80, s24, 0x18100
	s_addc_u32 s81, s25, 0
	s_mov_b32 m0, s40
	v_lshl_add_u64 v[22:23], s[80:81], 0, v[64:65]
	ds_read_b128 v[152:155], v105 offset:32768
	ds_read_b128 v[180:183], v105 offset:33792
	ds_read_b128 v[184:187], v105 offset:34816
	ds_read_b128 v[188:191], v105 offset:35840
	ds_read_b128 v[192:195], v105 offset:36864
	ds_read_b128 v[196:199], v105 offset:37888
	ds_read_b128 v[200:203], v105 offset:38912
	ds_read_b128 v[204:207], v105 offset:39936
	global_load_lds_dwordx4 v[22:23], off
	v_lshl_add_u64 v[22:23], s[80:81], 0, v[68:69]
	s_mov_b32 m0, s41
	s_nop 0
	global_load_lds_dwordx4 v[22:23], off
	s_waitcnt lgkmcnt(8)
	s_barrier
	s_waitcnt lgkmcnt(0)
	v_mfma_f32_16x16x32_bf16 v[52:55], v[112:115], v[152:155], v[52:55]
	v_mfma_f32_16x16x32_bf16 v[56:59], v[144:147], v[152:155], v[56:59]
	v_mfma_f32_16x16x32_bf16 v[60:63], v[112:115], v[184:187], v[60:63]
	v_mfma_f32_16x16x32_bf16 v[78:81], v[144:147], v[184:187], v[78:81]
	v_mfma_f32_16x16x32_bf16 v[82:85], v[112:115], v[192:195], v[82:85]
	v_mfma_f32_16x16x32_bf16 v[86:89], v[144:147], v[192:195], v[86:89]
	v_mfma_f32_16x16x32_bf16 v[90:93], v[112:115], v[200:203], v[90:93]
	v_mfma_f32_16x16x32_bf16 v[94:97], v[144:147], v[200:203], v[94:97]
	v_mfma_f32_16x16x32_bf16 v[52:55], v[116:119], v[180:183], v[52:55]
	v_mfma_f32_16x16x32_bf16 v[56:59], v[148:151], v[180:183], v[56:59]
	v_mfma_f32_16x16x32_bf16 v[60:63], v[116:119], v[188:191], v[60:63]
	v_mfma_f32_16x16x32_bf16 v[78:81], v[148:151], v[188:191], v[78:81]
	v_mfma_f32_16x16x32_bf16 v[82:85], v[116:119], v[196:199], v[82:85]
	v_mfma_f32_16x16x32_bf16 v[86:89], v[148:151], v[196:199], v[86:89]
	v_mfma_f32_16x16x32_bf16 v[90:93], v[116:119], v[204:207], v[90:93]
	v_mfma_f32_16x16x32_bf16 v[94:97], v[148:151], v[204:207], v[94:97]
	s_barrier
	s_add_i32 s81, 0, 0x1c000
	s_add_i32 s80, s77, s37
	v_add_u32_e32 v9, s81, v104
	v_lshl_add_u64 v[22:23], v[0:1], 0, s[16:17]
	s_mov_b32 m0, s80
	s_add_i32 s77, s80, 0x2000
	ds_read_b128 v[208:211], v9
	ds_read_b128 v[212:215], v9 offset:1024
	ds_read_b128 v[216:219], v9 offset:2048
	ds_read_b128 v[220:223], v9 offset:3072
	global_load_lds_dwordx4 v[22:23], off
	v_lshl_add_u64 v[22:23], v[2:3], 0, s[16:17]
	s_mov_b32 m0, s77
	s_nop 0
	global_load_lds_dwordx4 v[22:23], off
	s_barrier
	s_waitcnt lgkmcnt(0)
	v_mfma_f32_16x16x32_bf16 v[120:123], v[208:211], v[152:155], v[120:123]
	v_mfma_f32_16x16x32_bf16 v[22:25], v[216:219], v[152:155], v[24:27]
	v_mfma_f32_16x16x32_bf16 v[124:127], v[208:211], v[184:187], v[124:127]
	v_mfma_f32_16x16x32_bf16 v[26:29], v[216:219], v[184:187], v[28:31]
	v_mfma_f32_16x16x32_bf16 v[30:33], v[208:211], v[192:195], v[32:35]
	v_mfma_f32_16x16x32_bf16 v[34:37], v[216:219], v[192:195], v[36:39]
	v_mfma_f32_16x16x32_bf16 v[38:41], v[208:211], v[200:203], v[40:43]
	v_mfma_f32_16x16x32_bf16 v[42:45], v[216:219], v[200:203], v[44:47]
	v_mfma_f32_16x16x32_bf16 v[120:123], v[212:215], v[180:183], v[120:123]
	v_mfma_f32_16x16x32_bf16 v[22:25], v[220:223], v[180:183], v[22:25]
	v_mfma_f32_16x16x32_bf16 v[124:127], v[212:215], v[188:191], v[124:127]
	v_mfma_f32_16x16x32_bf16 v[26:29], v[220:223], v[188:191], v[26:29]
	v_mfma_f32_16x16x32_bf16 v[30:33], v[212:215], v[196:199], v[30:33]
	v_mfma_f32_16x16x32_bf16 v[34:37], v[220:223], v[196:199], v[34:37]
	v_mfma_f32_16x16x32_bf16 v[38:41], v[212:215], v[204:207], v[38:41]
	v_mfma_f32_16x16x32_bf16 v[42:45], v[220:223], v[204:207], v[42:45]
	s_mov_b32 m0, s43
	v_lshl_add_u64 v[46:47], v[4:5], 0, s[16:17]
	s_barrier
	ds_read_b128 v[152:155], v105 offset:49152
	ds_read_b128 v[180:183], v105 offset:50176
	ds_read_b128 v[184:187], v105 offset:51200
	ds_read_b128 v[188:191], v105 offset:52224
	ds_read_b128 v[192:195], v105 offset:53248
	ds_read_b128 v[196:199], v105 offset:54272
	ds_read_b128 v[200:203], v105 offset:55296
	ds_read_b128 v[204:207], v105 offset:56320
	global_load_lds_dwordx4 v[46:47], off
	v_lshl_add_u64 v[46:47], v[6:7], 0, s[16:17]
	s_mov_b32 m0, s60
	s_nop 0
	global_load_lds_dwordx4 v[46:47], off
	s_barrier
; #define PG8_STAGE(bufoff, gbase, voff) do { _Pragma("unroll") for (int _i = 0; _i < 2; ++_i) \
;         __builtin_amdgcn_global_load_lds((const unsigned*)((const char*)(gbase) + (voff)[_i]), (PG8_LAS unsigned*)(lds + (bufoff) + ldsw + _i * 8192), 16, 0, 0); } while (0)
; #define PG8_LDA(dst, b, h) do { _Pragma("unroll") for (int m = 0; m < 4; ++m) _Pragma("unroll") for (int k = 0; k < 2; ++k) dst[m][k] = *(const PG8_LAS bf16x8*)(lds + PG8_SA(b, h) + aoff + m * 2048 + k * 1024); } while (0)
; #define PG8_LDB(dst, b, h) do { _Pragma("unroll") for (int n = 0; n < 2; ++n) _Pragma("unroll") for (int k = 0; k < 2; ++k) dst[n][k] = *(const PG8_LAS bf16x8*)(lds + PG8_SB(b, h) + boff + n * 2048 + k * 1024); } while (0)
; #define PG8_WAIT_V(n) asm volatile("s_waitcnt vmcnt(" #n ")" ::: "memory")
; #define PG8_WAIT_L(n) asm volatile("s_waitcnt lgkmcnt(" #n ")" ::: "memory")
; #define PG8_BAR __builtin_amdgcn_s_barrier()
; #define PG8_SCHED __builtin_amdgcn_sched_barrier(0)
; template <class Epi, class Sched>
; __device__ __forceinline__ void gemm_phase(PG8_LAS unsigned char* lds, const Gemm g, const Sched& S, const Epi& E) {
;     ...
;             PG8_LDB(B0, 0, 0); PG8_SCHED; PG8_LDA(At, 0, 0); PG8_STAGE(PG8_SA(1, 1), a1 + hstep, voffA);
;             PG8_WAIT_L(8); PG8_BAR; PG8_WAIT_L(0); PG8_MMA(0, 0, At, B0); PG8_BAR; PG8_SCHED;
;             PG8_LDB(B1, 0, 1); PG8_STAGE(PG8_SB(0, 0), b2, voffB);
;             PG8_BAR; PG8_WAIT_L(0); PG8_MMA(0, 1, At, B1); PG8_BAR;
;             PG8_LDA(At, 0, 1); PG8_STAGE(PG8_SA(0, 0), a2, voffA);
;             PG8_BAR; PG8_WAIT_L(0); PG8_MMA(1, 0, At, B0); PG8_BAR; PG8_SCHED;
;             PG8_STAGE(PG8_SB(0, 1), b2 + hstep, voffB);
;             PG8_WAIT_V(6); PG8_BAR; PG8_MMA(1, 1, At, B1); PG8_BAR;
;             PG8_LDB(B0, 1, 0); PG8_SCHED; PG8_LDA(At, 1, 0); PG8_STAGE(PG8_SA(0, 1), a2 + hstep, voffA);
;             PG8_WAIT_L(8); PG8_BAR; PG8_WAIT_L(0); PG8_MMA(0, 0, At, B0); PG8_BAR; PG8_SCHED;
;             PG8_LDB(B1, 1, 1); PG8_STAGE(PG8_SB(1, 0), b3, voffB);
;             PG8_BAR; PG8_WAIT_L(0); PG8_MMA(0, 1, At, B1); PG8_BAR;
;             PG8_LDA(At, 1, 1); PG8_STAGE(PG8_SA(1, 0), a3, voffA);
;             PG8_BAR; PG8_WAIT_L(0); PG8_MMA(1, 0, At, B0); PG8_BAR; PG8_SCHED;
;             PG8_STAGE(PG8_SB(1, 1), b3 + hstep, voffB);
;             PG8_WAIT_V(6); PG8_BAR; PG8_MMA(1, 1, At, B1); PG8_BAR;
	s_waitcnt lgkmcnt(0)
	v_mfma_f32_16x16x32_bf16 v[156:159], v[112:115], v[152:155], v[156:159]
	v_mfma_f32_16x16x32_bf16 v[160:163], v[144:147], v[152:155], v[160:163]
	v_mfma_f32_16x16x32_bf16 v[164:167], v[112:115], v[184:187], v[164:167]
	v_mfma_f32_16x16x32_bf16 v[168:171], v[144:147], v[184:187], v[168:171]
	v_mfma_f32_16x16x32_bf16 v[172:175], v[112:115], v[192:195], v[172:175]
	v_mfma_f32_16x16x32_bf16 v[176:179], v[144:147], v[192:195], v[176:179]
	v_mfma_f32_16x16x32_bf16 v[10:13], v[112:115], v[200:203], v[10:13]
	v_mfma_f32_16x16x32_bf16 v[14:17], v[144:147], v[200:203], v[14:17]
	v_mfma_f32_16x16x32_bf16 v[156:159], v[116:119], v[180:183], v[156:159]
	v_mfma_f32_16x16x32_bf16 v[160:163], v[148:151], v[180:183], v[160:163]
	v_mfma_f32_16x16x32_bf16 v[164:167], v[116:119], v[188:191], v[164:167]
	v_mfma_f32_16x16x32_bf16 v[168:171], v[148:151], v[188:191], v[168:171]
	v_mfma_f32_16x16x32_bf16 v[172:175], v[116:119], v[196:199], v[172:175]
	v_mfma_f32_16x16x32_bf16 v[176:179], v[148:151], v[196:199], v[176:179]
	v_mfma_f32_16x16x32_bf16 v[10:13], v[116:119], v[204:207], v[10:13]
	v_mfma_f32_16x16x32_bf16 v[14:17], v[148:151], v[204:207], v[14:17]
	s_barrier
	s_add_u32 s82, s26, 0x18180
	s_addc_u32 s83, s27, 0
	s_add_i32 s81, s81, s37
	v_lshl_add_u64 v[46:47], s[82:83], 0, v[66:67]
	s_mov_b32 m0, s81
	s_add_i32 s78, s81, 0x2000
	global_load_lds_dwordx4 v[46:47], off
	v_lshl_add_u64 v[46:47], s[82:83], 0, v[70:71]
	s_mov_b32 m0, s78
	s_nop 0
	global_load_lds_dwordx4 v[46:47], off
	s_waitcnt vmcnt(6)
	s_barrier
	v_mfma_f32_16x16x32_bf16 v[18:21], v[208:211], v[152:155], v[18:21]
	v_mfma_f32_16x16x32_bf16 v[46:49], v[216:219], v[152:155], v[48:51]
	v_mfma_f32_16x16x32_bf16 v[112:115], v[208:211], v[184:187], v[128:131]
	v_mfma_f32_16x16x32_bf16 v[116:119], v[216:219], v[184:187], v[132:135]
	v_mfma_f32_16x16x32_bf16 v[128:131], v[208:211], v[192:195], v[136:139]
	v_mfma_f32_16x16x32_bf16 v[132:135], v[216:219], v[192:195], v[140:143]
	v_mfma_f32_16x16x32_bf16 v[98:101], v[208:211], v[200:203], v[98:101]
	v_mfma_f32_16x16x32_bf16 v[108:111], v[216:219], v[200:203], v[108:111]
	v_mfma_f32_16x16x32_bf16 v[18:21], v[212:215], v[180:183], v[18:21]
	v_mfma_f32_16x16x32_bf16 v[46:49], v[220:223], v[180:183], v[46:49]
	v_mfma_f32_16x16x32_bf16 v[112:115], v[212:215], v[188:191], v[112:115]
	v_mfma_f32_16x16x32_bf16 v[116:119], v[220:223], v[188:191], v[116:119]
	v_mfma_f32_16x16x32_bf16 v[128:131], v[212:215], v[196:199], v[128:131]
	v_mfma_f32_16x16x32_bf16 v[132:135], v[220:223], v[196:199], v[132:135]
	v_mfma_f32_16x16x32_bf16 v[98:101], v[212:215], v[204:207], v[98:101]
	v_mfma_f32_16x16x32_bf16 v[108:111], v[220:223], v[204:207], v[108:111]
	s_barrier
	ds_read_b128 v[136:139], v106
	ds_read_b128 v[140:143], v106 offset:1024
	ds_read_b128 v[144:147], v106 offset:2048
	ds_read_b128 v[148:151], v106 offset:3072
	s_add_u32 s82, s24, 0x18180
	s_addc_u32 s83, s25, 0
	s_mov_b32 m0, s79
	v_lshl_add_u64 v[50:51], s[82:83], 0, v[64:65]
	ds_read_b128 v[152:155], v105
	ds_read_b128 v[180:183], v105 offset:1024
	ds_read_b128 v[184:187], v105 offset:2048
	ds_read_b128 v[188:191], v105 offset:3072
	ds_read_b128 v[192:195], v105 offset:4096
	ds_read_b128 v[196:199], v105 offset:5120
	ds_read_b128 v[200:203], v105 offset:6144
	ds_read_b128 v[204:207], v105 offset:7168
	global_load_lds_dwordx4 v[50:51], off
	v_lshl_add_u64 v[50:51], s[82:83], 0, v[68:69]
	s_mov_b32 m0, s72
	s_nop 0
	global_load_lds_dwordx4 v[50:51], off
	s_waitcnt lgkmcnt(8)
	s_barrier
	s_waitcnt lgkmcnt(0)
	v_mfma_f32_16x16x32_bf16 v[50:53], v[136:139], v[152:155], v[52:55]
	v_mfma_f32_16x16x32_bf16 v[54:57], v[144:147], v[152:155], v[56:59]
	v_mfma_f32_16x16x32_bf16 v[58:61], v[136:139], v[184:187], v[60:63]
	v_mfma_f32_16x16x32_bf16 v[78:81], v[144:147], v[184:187], v[78:81]
	v_mfma_f32_16x16x32_bf16 v[82:85], v[136:139], v[192:195], v[82:85]
	v_mfma_f32_16x16x32_bf16 v[86:89], v[144:147], v[192:195], v[86:89]
	v_mfma_f32_16x16x32_bf16 v[90:93], v[136:139], v[200:203], v[90:93]
	v_mfma_f32_16x16x32_bf16 v[94:97], v[144:147], v[200:203], v[94:97]
	v_mfma_f32_16x16x32_bf16 v[50:53], v[140:143], v[180:183], v[50:53]
	v_mfma_f32_16x16x32_bf16 v[54:57], v[148:151], v[180:183], v[54:57]
	v_mfma_f32_16x16x32_bf16 v[58:61], v[140:143], v[188:191], v[58:61]
	v_mfma_f32_16x16x32_bf16 v[78:81], v[148:151], v[188:191], v[78:81]
	v_mfma_f32_16x16x32_bf16 v[82:85], v[140:143], v[196:199], v[82:85]
	v_mfma_f32_16x16x32_bf16 v[86:89], v[148:151], v[196:199], v[86:89]
	v_mfma_f32_16x16x32_bf16 v[90:93], v[140:143], v[204:207], v[90:93]
	v_mfma_f32_16x16x32_bf16 v[94:97], v[148:151], v[204:207], v[94:97]
	s_barrier
	s_mov_b32 m0, s75
	v_lshl_add_u64 v[62:63], v[0:1], 0, s[12:13]
	ds_read_b128 v[208:211], v107
	ds_read_b128 v[212:215], v107 offset:1024
	ds_read_b128 v[216:219], v107 offset:2048
	ds_read_b128 v[220:223], v107 offset:3072
	global_load_lds_dwordx4 v[62:63], off
	v_lshl_add_u64 v[62:63], v[2:3], 0, s[12:13]
	s_mov_b32 m0, s73
	s_nop 0
	global_load_lds_dwordx4 v[62:63], off
	s_barrier
	s_waitcnt lgkmcnt(0)
	v_mfma_f32_16x16x32_bf16 v[120:123], v[208:211], v[152:155], v[120:123]
	v_mfma_f32_16x16x32_bf16 v[22:25], v[216:219], v[152:155], v[22:25]
	v_mfma_f32_16x16x32_bf16 v[124:127], v[208:211], v[184:187], v[124:127]
	v_mfma_f32_16x16x32_bf16 v[26:29], v[216:219], v[184:187], v[26:29]
	v_mfma_f32_16x16x32_bf16 v[30:33], v[208:211], v[192:195], v[30:33]
	v_mfma_f32_16x16x32_bf16 v[34:37], v[216:219], v[192:195], v[34:37]
	v_mfma_f32_16x16x32_bf16 v[38:41], v[208:211], v[200:203], v[38:41]
	v_mfma_f32_16x16x32_bf16 v[42:45], v[216:219], v[200:203], v[42:45]
	v_mfma_f32_16x16x32_bf16 v[120:123], v[212:215], v[180:183], v[120:123]
	v_mfma_f32_16x16x32_bf16 v[22:25], v[220:223], v[180:183], v[22:25]
	v_mfma_f32_16x16x32_bf16 v[124:127], v[212:215], v[188:191], v[124:127]
	v_mfma_f32_16x16x32_bf16 v[26:29], v[220:223], v[188:191], v[26:29]
	v_mfma_f32_16x16x32_bf16 v[30:33], v[212:215], v[196:199], v[30:33]
	v_mfma_f32_16x16x32_bf16 v[34:37], v[220:223], v[196:199], v[34:37]
	v_mfma_f32_16x16x32_bf16 v[38:41], v[212:215], v[204:207], v[38:41]
	v_mfma_f32_16x16x32_bf16 v[42:45], v[220:223], v[204:207], v[42:45]
	s_mov_b32 m0, s38
	v_lshl_add_u64 v[62:63], v[4:5], 0, s[12:13]
	s_barrier
; #define PG8_STAGE(bufoff, gbase, voff) do { _Pragma("unroll") for (int _i = 0; _i < 2; ++_i) \
;         __builtin_amdgcn_global_load_lds((const unsigned*)((const char*)(gbase) + (voff)[_i]), (PG8_LAS unsigned*)(lds + (bufoff) + ldsw + _i * 8192), 16, 0, 0); } while (0)
; #define PG8_LDA(dst, b, h) do { _Pragma("unroll") for (int m = 0; m < 4; ++m) _Pragma("unroll") for (int k = 0; k < 2; ++k) dst[m][k] = *(const PG8_LAS bf16x8*)(lds + PG8_SA(b, h) + aoff + m * 2048 + k * 1024); } while (0)
; #define PG8_LDB(dst, b, h) do { _Pragma("unroll") for (int n = 0; n < 2; ++n) _Pragma("unroll") for (int k = 0; k < 2; ++k) dst[n][k] = *(const PG8_LAS bf16x8*)(lds + PG8_SB(b, h) + boff + n * 2048 + k * 1024); } while (0)
; #define PG8_WAIT_V(n) asm volatile("s_waitcnt vmcnt(" #n ")" ::: "memory")
; #define PG8_WAIT_L(n) asm volatile("s_waitcnt lgkmcnt(" #n ")" ::: "memory")
; #define PG8_BAR __builtin_amdgcn_s_barrier()
; #define PG8_SCHED __builtin_amdgcn_sched_barrier(0)
; template <class Epi, class Sched>
; __device__ __forceinline__ void gemm_phase(PG8_LAS unsigned char* lds, const Gemm g, const Sched& S, const Epi& E) {
;     ...
;             PG8_LDB(B0, 0, 0); PG8_SCHED; PG8_LDA(At, 0, 0); PG8_STAGE(PG8_SA(1, 1), a1 + hstep, voffA);
;             PG8_WAIT_L(8); PG8_BAR; PG8_WAIT_L(0); PG8_MMA(0, 0, At, B0); PG8_BAR; PG8_SCHED;
;             PG8_LDB(B1, 0, 1); PG8_STAGE(PG8_SB(0, 0), b2, voffB);
;             PG8_BAR; PG8_WAIT_L(0); PG8_MMA(0, 1, At, B1); PG8_BAR;
;             PG8_LDA(At, 0, 1); PG8_STAGE(PG8_SA(0, 0), a2, voffA);
;             PG8_BAR; PG8_WAIT_L(0); PG8_MMA(1, 0, At, B0); PG8_BAR; PG8_SCHED;
;             PG8_STAGE(PG8_SB(0, 1), b2 + hstep, voffB);
;             PG8_WAIT_V(6); PG8_BAR; PG8_MMA(1, 1, At, B1); PG8_BAR;
;             PG8_LDB(B0, 1, 0); PG8_SCHED; PG8_LDA(At, 1, 0); PG8_STAGE(PG8_SA(0, 1), a2 + hstep, voffA);
;             PG8_WAIT_L(8); PG8_BAR; PG8_WAIT_L(0); PG8_MMA(0, 0, At, B0); PG8_BAR; PG8_SCHED;
;             PG8_LDB(B1, 1, 1); PG8_STAGE(PG8_SB(1, 0), b3, voffB);
;             PG8_BAR; PG8_WAIT_L(0); PG8_MMA(0, 1, At, B1); PG8_BAR;
;             PG8_LDA(At, 1, 1); PG8_STAGE(PG8_SA(1, 0), a3, voffA);
;             PG8_BAR; PG8_WAIT_L(0); PG8_MMA(1, 0, At, B0); PG8_BAR; PG8_SCHED;
;             PG8_STAGE(PG8_SB(1, 1), b3 + hstep, voffB);
;             PG8_WAIT_V(6); PG8_BAR; PG8_MMA(1, 1, At, B1); PG8_BAR;
	ds_read_b128 v[152:155], v105 offset:16384
	ds_read_b128 v[180:183], v105 offset:17408
	ds_read_b128 v[184:187], v105 offset:18432
	ds_read_b128 v[188:191], v105 offset:19456
	ds_read_b128 v[192:195], v105 offset:20480
	ds_read_b128 v[196:199], v105 offset:21504
	ds_read_b128 v[200:203], v105 offset:22528
	ds_read_b128 v[204:207], v105 offset:23552
	global_load_lds_dwordx4 v[62:63], off
	v_lshl_add_u64 v[62:63], v[6:7], 0, s[12:13]
	s_mov_b32 m0, s39
	s_nop 0
	global_load_lds_dwordx4 v[62:63], off
	s_barrier
	s_waitcnt lgkmcnt(0)
	v_mfma_f32_16x16x32_bf16 v[156:159], v[136:139], v[152:155], v[156:159]
	v_mfma_f32_16x16x32_bf16 v[160:163], v[144:147], v[152:155], v[160:163]
	v_mfma_f32_16x16x32_bf16 v[164:167], v[136:139], v[184:187], v[164:167]
	v_mfma_f32_16x16x32_bf16 v[168:171], v[144:147], v[184:187], v[168:171]
	v_mfma_f32_16x16x32_bf16 v[172:175], v[136:139], v[192:195], v[172:175]
	v_mfma_f32_16x16x32_bf16 v[176:179], v[144:147], v[192:195], v[176:179]
	v_mfma_f32_16x16x32_bf16 v[10:13], v[136:139], v[200:203], v[10:13]
	v_mfma_f32_16x16x32_bf16 v[14:17], v[144:147], v[200:203], v[14:17]
	v_mfma_f32_16x16x32_bf16 v[156:159], v[140:143], v[180:183], v[156:159]
	v_mfma_f32_16x16x32_bf16 v[160:163], v[148:151], v[180:183], v[160:163]
	v_mfma_f32_16x16x32_bf16 v[164:167], v[140:143], v[188:191], v[164:167]
	v_mfma_f32_16x16x32_bf16 v[168:171], v[148:151], v[188:191], v[168:171]
	v_mfma_f32_16x16x32_bf16 v[172:175], v[140:143], v[196:199], v[172:175]
	v_mfma_f32_16x16x32_bf16 v[176:179], v[148:151], v[196:199], v[176:179]
	v_mfma_f32_16x16x32_bf16 v[10:13], v[140:143], v[204:207], v[10:13]
	v_mfma_f32_16x16x32_bf16 v[14:17], v[148:151], v[204:207], v[14:17]
	s_barrier
	s_add_u32 s82, s26, 0x18200
	s_addc_u32 s83, s27, 0
	s_mov_b32 m0, s76
	v_lshl_add_u64 v[62:63], s[82:83], 0, v[66:67]
	global_load_lds_dwordx4 v[62:63], off
	v_lshl_add_u64 v[62:63], s[82:83], 0, v[70:71]
	s_mov_b32 m0, s74
	s_nop 0
	global_load_lds_dwordx4 v[62:63], off
	s_waitcnt vmcnt(6)
	s_barrier
	v_mfma_f32_16x16x32_bf16 v[18:21], v[208:211], v[152:155], v[18:21]
	v_mfma_f32_16x16x32_bf16 v[46:49], v[216:219], v[152:155], v[46:49]
	v_mfma_f32_16x16x32_bf16 v[112:115], v[208:211], v[184:187], v[112:115]
	v_mfma_f32_16x16x32_bf16 v[116:119], v[216:219], v[184:187], v[116:119]
	v_mfma_f32_16x16x32_bf16 v[128:131], v[208:211], v[192:195], v[128:131]
	v_mfma_f32_16x16x32_bf16 v[132:135], v[216:219], v[192:195], v[132:135]
	v_mfma_f32_16x16x32_bf16 v[98:101], v[208:211], v[200:203], v[98:101]
	v_mfma_f32_16x16x32_bf16 v[108:111], v[216:219], v[200:203], v[108:111]
	v_mfma_f32_16x16x32_bf16 v[18:21], v[212:215], v[180:183], v[18:21]
	v_mfma_f32_16x16x32_bf16 v[46:49], v[220:223], v[180:183], v[46:49]
	v_mfma_f32_16x16x32_bf16 v[112:115], v[212:215], v[188:191], v[112:115]
	v_mfma_f32_16x16x32_bf16 v[116:119], v[220:223], v[188:191], v[116:119]
	v_mfma_f32_16x16x32_bf16 v[128:131], v[212:215], v[196:199], v[128:131]
	v_mfma_f32_16x16x32_bf16 v[132:135], v[220:223], v[196:199], v[132:135]
	v_mfma_f32_16x16x32_bf16 v[98:101], v[212:215], v[204:207], v[98:101]
	v_mfma_f32_16x16x32_bf16 v[108:111], v[220:223], v[204:207], v[108:111]
	s_barrier
	ds_read_b128 v[136:139], v8
	ds_read_b128 v[140:143], v8 offset:1024
	ds_read_b128 v[144:147], v8 offset:2048
	ds_read_b128 v[148:151], v8 offset:3072
	s_add_u32 s82, s24, 0x18200
	s_addc_u32 s83, s25, 0
	s_mov_b32 m0, s40
	v_lshl_add_u64 v[62:63], s[82:83], 0, v[64:65]
	ds_read_b128 v[152:155], v105 offset:32768
	ds_read_b128 v[180:183], v105 offset:33792
	ds_read_b128 v[184:187], v105 offset:34816
	ds_read_b128 v[188:191], v105 offset:35840
	ds_read_b128 v[192:195], v105 offset:36864
	ds_read_b128 v[196:199], v105 offset:37888
	ds_read_b128 v[200:203], v105 offset:38912
	ds_read_b128 v[204:207], v105 offset:39936
	global_load_lds_dwordx4 v[62:63], off
	v_lshl_add_u64 v[62:63], s[82:83], 0, v[68:69]
	s_mov_b32 m0, s41
	s_nop 0
	global_load_lds_dwordx4 v[62:63], off
	s_waitcnt lgkmcnt(8)
	s_barrier
	s_waitcnt lgkmcnt(0)
	v_mfma_f32_16x16x32_bf16 v[50:53], v[136:139], v[152:155], v[50:53]
	v_mfma_f32_16x16x32_bf16 v[54:57], v[144:147], v[152:155], v[54:57]
	v_mfma_f32_16x16x32_bf16 v[58:61], v[136:139], v[184:187], v[58:61]
	v_mfma_f32_16x16x32_bf16 v[78:81], v[144:147], v[184:187], v[78:81]
	v_mfma_f32_16x16x32_bf16 v[82:85], v[136:139], v[192:195], v[82:85]
	v_mfma_f32_16x16x32_bf16 v[86:89], v[144:147], v[192:195], v[86:89]
	v_mfma_f32_16x16x32_bf16 v[90:93], v[136:139], v[200:203], v[90:93]
	v_mfma_f32_16x16x32_bf16 v[94:97], v[144:147], v[200:203], v[94:97]
	v_mfma_f32_16x16x32_bf16 v[50:53], v[140:143], v[180:183], v[50:53]
	v_mfma_f32_16x16x32_bf16 v[54:57], v[148:151], v[180:183], v[54:57]
	v_mfma_f32_16x16x32_bf16 v[58:61], v[140:143], v[188:191], v[58:61]
	v_mfma_f32_16x16x32_bf16 v[78:81], v[148:151], v[188:191], v[78:81]
	v_mfma_f32_16x16x32_bf16 v[82:85], v[140:143], v[196:199], v[82:85]
	v_mfma_f32_16x16x32_bf16 v[86:89], v[148:151], v[196:199], v[86:89]
	v_mfma_f32_16x16x32_bf16 v[90:93], v[140:143], v[204:207], v[90:93]
	v_mfma_f32_16x16x32_bf16 v[94:97], v[148:151], v[204:207], v[94:97]
	s_barrier
	s_mov_b32 m0, s80
	v_lshl_add_u64 v[0:1], v[0:1], 0, s[18:19]
	ds_read_b128 v[208:211], v9
	ds_read_b128 v[212:215], v9 offset:1024
	ds_read_b128 v[216:219], v9 offset:2048
	ds_read_b128 v[220:223], v9 offset:3072
	global_load_lds_dwordx4 v[0:1], off
	v_lshl_add_u64 v[0:1], v[2:3], 0, s[18:19]
	s_mov_b32 m0, s77
	s_nop 0
	global_load_lds_dwordx4 v[0:1], off
	s_barrier
; #define PG8_STAGE(bufoff, gbase, voff) do { _Pragma("unroll") for (int _i = 0; _i < 2; ++_i) \
;         __builtin_amdgcn_global_load_lds((const unsigned*)((const char*)(gbase) + (voff)[_i]), (PG8_LAS unsigned*)(lds + (bufoff) + ldsw + _i * 8192), 16, 0, 0); } while (0)
; #define PG8_LDA(dst, b, h) do { _Pragma("unroll") for (int m = 0; m < 4; ++m) _Pragma("unroll") for (int k = 0; k < 2; ++k) dst[m][k] = *(const PG8_LAS bf16x8*)(lds + PG8_SA(b, h) + aoff + m * 2048 + k * 1024); } while (0)
; #define PG8_LDB(dst, b, h) do { _Pragma("unroll") for (int n = 0; n < 2; ++n) _Pragma("unroll") for (int k = 0; k < 2; ++k) dst[n][k] = *(const PG8_LAS bf16x8*)(lds + PG8_SB(b, h) + boff + n * 2048 + k * 1024); } while (0)
; #define PG8_WAIT_V(n) asm volatile("s_waitcnt vmcnt(" #n ")" ::: "memory")
; #define PG8_WAIT_L(n) asm volatile("s_waitcnt lgkmcnt(" #n ")" ::: "memory")
; #define PG8_BAR __builtin_amdgcn_s_barrier()
; #define PG8_SCHED __builtin_amdgcn_sched_barrier(0)
; template <class Epi, class Sched>
; __device__ __forceinline__ void gemm_phase(PG8_LAS unsigned char* lds, const Gemm g, const Sched& S, const Epi& E) {
;     ...
;             PG8_LDB(B0, 0, 0); PG8_SCHED; PG8_LDA(At, 0, 0); PG8_STAGE(PG8_SA(1, 1), a1 + hstep, voffA);
;             PG8_WAIT_L(8); PG8_BAR; PG8_WAIT_L(0); PG8_MMA(0, 0, At, B0); PG8_BAR; PG8_SCHED;
;             PG8_LDB(B1, 0, 1); PG8_STAGE(PG8_SB(0, 0), b2, voffB);
;             PG8_BAR; PG8_WAIT_L(0); PG8_MMA(0, 1, At, B1); PG8_BAR;
;             PG8_LDA(At, 0, 1); PG8_STAGE(PG8_SA(0, 0), a2, voffA);
;             PG8_BAR; PG8_WAIT_L(0); PG8_MMA(1, 0, At, B0); PG8_BAR; PG8_SCHED;
;             PG8_STAGE(PG8_SB(0, 1), b2 + hstep, voffB);
;             PG8_WAIT_V(6); PG8_BAR; PG8_MMA(1, 1, At, B1); PG8_BAR;
;             PG8_LDB(B0, 1, 0); PG8_SCHED; PG8_LDA(At, 1, 0); PG8_STAGE(PG8_SA(0, 1), a2 + hstep, voffA);
;             PG8_WAIT_L(8); PG8_BAR; PG8_WAIT_L(0); PG8_MMA(0, 0, At, B0); PG8_BAR; PG8_SCHED;
;             PG8_LDB(B1, 1, 1); PG8_STAGE(PG8_SB(1, 0), b3, voffB);
;             PG8_BAR; PG8_WAIT_L(0); PG8_MMA(0, 1, At, B1); PG8_BAR;
;             PG8_LDA(At, 1, 1); PG8_STAGE(PG8_SA(1, 0), a3, voffA);
;             PG8_BAR; PG8_WAIT_L(0); PG8_MMA(1, 0, At, B0); PG8_BAR; PG8_SCHED;
;             PG8_STAGE(PG8_SB(1, 1), b3 + hstep, voffB);
;             PG8_WAIT_V(6); PG8_BAR; PG8_MMA(1, 1, At, B1); PG8_BAR;
	s_waitcnt lgkmcnt(0)
	v_mfma_f32_16x16x32_bf16 v[0:3], v[208:211], v[152:155], v[120:123]
	v_mfma_f32_16x16x32_bf16 v[22:25], v[216:219], v[152:155], v[22:25]
	v_mfma_f32_16x16x32_bf16 v[120:123], v[208:211], v[184:187], v[124:127]
	v_mfma_f32_16x16x32_bf16 v[26:29], v[216:219], v[184:187], v[26:29]
	v_mfma_f32_16x16x32_bf16 v[30:33], v[208:211], v[192:195], v[30:33]
	v_mfma_f32_16x16x32_bf16 v[34:37], v[216:219], v[192:195], v[34:37]
	v_mfma_f32_16x16x32_bf16 v[38:41], v[208:211], v[200:203], v[38:41]
	v_mfma_f32_16x16x32_bf16 v[42:45], v[216:219], v[200:203], v[42:45]
	v_mfma_f32_16x16x32_bf16 v[0:3], v[212:215], v[180:183], v[0:3]
	v_mfma_f32_16x16x32_bf16 v[22:25], v[220:223], v[180:183], v[22:25]
	v_mfma_f32_16x16x32_bf16 v[120:123], v[212:215], v[188:191], v[120:123]
	v_mfma_f32_16x16x32_bf16 v[26:29], v[220:223], v[188:191], v[26:29]
	v_mfma_f32_16x16x32_bf16 v[30:33], v[212:215], v[196:199], v[30:33]
	v_mfma_f32_16x16x32_bf16 v[34:37], v[220:223], v[196:199], v[34:37]
	v_mfma_f32_16x16x32_bf16 v[38:41], v[212:215], v[204:207], v[38:41]
	v_mfma_f32_16x16x32_bf16 v[42:45], v[220:223], v[204:207], v[42:45]
	s_mov_b32 m0, s43
	v_lshl_add_u64 v[4:5], v[4:5], 0, s[18:19]
	s_barrier
	ds_read_b128 v[124:127], v105 offset:49152
	ds_read_b128 v[152:155], v105 offset:50176
	ds_read_b128 v[180:183], v105 offset:51200
	ds_read_b128 v[184:187], v105 offset:52224
	ds_read_b128 v[188:191], v105 offset:53248
	ds_read_b128 v[192:195], v105 offset:54272
	ds_read_b128 v[196:199], v105 offset:55296
	ds_read_b128 v[200:203], v105 offset:56320
	global_load_lds_dwordx4 v[4:5], off
	v_lshl_add_u64 v[4:5], v[6:7], 0, s[18:19]
	s_mov_b32 m0, s60
	s_nop 0
	global_load_lds_dwordx4 v[4:5], off
	s_barrier
	s_waitcnt lgkmcnt(0)
	v_mfma_f32_16x16x32_bf16 v[4:7], v[136:139], v[124:127], v[156:159]
	v_mfma_f32_16x16x32_bf16 v[156:159], v[144:147], v[124:127], v[160:163]
	v_mfma_f32_16x16x32_bf16 v[160:163], v[136:139], v[180:183], v[164:167]
	v_mfma_f32_16x16x32_bf16 v[164:167], v[144:147], v[180:183], v[168:171]
	v_mfma_f32_16x16x32_bf16 v[168:171], v[136:139], v[188:191], v[172:175]
	v_mfma_f32_16x16x32_bf16 v[172:175], v[144:147], v[188:191], v[176:179]
	v_mfma_f32_16x16x32_bf16 v[10:13], v[136:139], v[196:199], v[10:13]
	v_mfma_f32_16x16x32_bf16 v[14:17], v[144:147], v[196:199], v[14:17]
	v_mfma_f32_16x16x32_bf16 v[4:7], v[140:143], v[152:155], v[4:7]
	v_mfma_f32_16x16x32_bf16 v[156:159], v[148:151], v[152:155], v[156:159]
	v_mfma_f32_16x16x32_bf16 v[160:163], v[140:143], v[184:187], v[160:163]
	v_mfma_f32_16x16x32_bf16 v[164:167], v[148:151], v[184:187], v[164:167]
	v_mfma_f32_16x16x32_bf16 v[168:171], v[140:143], v[192:195], v[168:171]
	v_mfma_f32_16x16x32_bf16 v[172:175], v[148:151], v[192:195], v[172:175]
	v_mfma_f32_16x16x32_bf16 v[10:13], v[140:143], v[200:203], v[10:13]
	v_mfma_f32_16x16x32_bf16 v[14:17], v[148:151], v[200:203], v[14:17]
	s_barrier
	s_add_u32 s26, s26, 0x18280
	s_addc_u32 s27, s27, 0
	s_mov_b32 m0, s81
	v_lshl_add_u64 v[62:63], s[26:27], 0, v[66:67]
	global_load_lds_dwordx4 v[62:63], off
	v_lshl_add_u64 v[62:63], s[26:27], 0, v[70:71]
	s_mov_b32 m0, s78
	s_nop 0
	global_load_lds_dwordx4 v[62:63], off
	s_waitcnt vmcnt(6)
	s_barrier
	v_mfma_f32_16x16x32_bf16 v[18:21], v[208:211], v[124:127], v[18:21]
	v_mfma_f32_16x16x32_bf16 v[46:49], v[216:219], v[124:127], v[46:49]
	v_mfma_f32_16x16x32_bf16 v[112:115], v[208:211], v[180:183], v[112:115]
	v_mfma_f32_16x16x32_bf16 v[116:119], v[216:219], v[180:183], v[116:119]
	v_mfma_f32_16x16x32_bf16 v[124:127], v[208:211], v[188:191], v[128:131]
	v_mfma_f32_16x16x32_bf16 v[128:131], v[216:219], v[188:191], v[132:135]
	v_mfma_f32_16x16x32_bf16 v[98:101], v[208:211], v[196:199], v[98:101]
	v_mfma_f32_16x16x32_bf16 v[108:111], v[216:219], v[196:199], v[108:111]
	v_mfma_f32_16x16x32_bf16 v[18:21], v[212:215], v[152:155], v[18:21]
	v_mfma_f32_16x16x32_bf16 v[46:49], v[220:223], v[152:155], v[46:49]
	v_mfma_f32_16x16x32_bf16 v[112:115], v[212:215], v[184:187], v[112:115]
	v_mfma_f32_16x16x32_bf16 v[116:119], v[220:223], v[184:187], v[116:119]
	v_mfma_f32_16x16x32_bf16 v[124:127], v[212:215], v[192:195], v[124:127]
	v_mfma_f32_16x16x32_bf16 v[128:131], v[220:223], v[192:195], v[128:131]
	v_mfma_f32_16x16x32_bf16 v[98:101], v[212:215], v[200:203], v[98:101]
	v_mfma_f32_16x16x32_bf16 v[108:111], v[220:223], v[200:203], v[108:111]
	s_barrier
	ds_read_b128 v[132:135], v106
	ds_read_b128 v[136:139], v106 offset:1024
	ds_read_b128 v[140:143], v106 offset:2048
	ds_read_b128 v[144:147], v106 offset:3072
	s_add_u32 s24, s24, 0x18280
	s_addc_u32 s25, s25, 0
	s_mov_b32 m0, s79
	v_lshl_add_u64 v[62:63], s[24:25], 0, v[64:65]
	ds_read_b128 v[148:151], v105
	ds_read_b128 v[152:155], v105 offset:1024
	ds_read_b128 v[176:179], v105 offset:2048
	ds_read_b128 v[180:183], v105 offset:3072
	ds_read_b128 v[184:187], v105 offset:4096
	ds_read_b128 v[188:191], v105 offset:5120
	ds_read_b128 v[192:195], v105 offset:6144
	ds_read_b128 v[196:199], v105 offset:7168
	global_load_lds_dwordx4 v[62:63], off
	v_lshl_add_u64 v[62:63], s[24:25], 0, v[68:69]
	s_mov_b32 m0, s72
	s_nop 0
	global_load_lds_dwordx4 v[62:63], off
	s_waitcnt lgkmcnt(8)
	s_barrier
; #define PG8_STAGE(bufoff, gbase, voff) do { _Pragma("unroll") for (int _i = 0; _i < 2; ++_i) \
;         __builtin_amdgcn_global_load_lds((const unsigned*)((const char*)(gbase) + (voff)[_i]), (PG8_LAS unsigned*)(lds + (bufoff) + ldsw + _i * 8192), 16, 0, 0); } while (0)
; #define PG8_LDA(dst, b, h) do { _Pragma("unroll") for (int m = 0; m < 4; ++m) _Pragma("unroll") for (int k = 0; k < 2; ++k) dst[m][k] = *(const PG8_LAS bf16x8*)(lds + PG8_SA(b, h) + aoff + m * 2048 + k * 1024); } while (0)
; #define PG8_LDB(dst, b, h) do { _Pragma("unroll") for (int n = 0; n < 2; ++n) _Pragma("unroll") for (int k = 0; k < 2; ++k) dst[n][k] = *(const PG8_LAS bf16x8*)(lds + PG8_SB(b, h) + boff + n * 2048 + k * 1024); } while (0)
; #define PG8_WAIT_V(n) asm volatile("s_waitcnt vmcnt(" #n ")" ::: "memory")
; #define PG8_WAIT_L(n) asm volatile("s_waitcnt lgkmcnt(" #n ")" ::: "memory")
; #define PG8_BAR __builtin_amdgcn_s_barrier()
; #define PG8_SCHED __builtin_amdgcn_sched_barrier(0)
; template <class Epi, class Sched>
; __device__ __forceinline__ void gemm_phase(PG8_LAS unsigned char* lds, const Gemm g, const Sched& S, const Epi& E) {
;     ...
;             PG8_LDB(B0, 0, 0); PG8_SCHED; PG8_LDA(At, 0, 0); PG8_STAGE(PG8_SA(1, 1), a1 + hstep, voffA);
;             PG8_WAIT_L(8); PG8_BAR; PG8_WAIT_L(0); PG8_MMA(0, 0, At, B0); PG8_BAR; PG8_SCHED;
;             PG8_LDB(B1, 0, 1); PG8_STAGE(PG8_SB(0, 0), b2, voffB);
;             PG8_BAR; PG8_WAIT_L(0); PG8_MMA(0, 1, At, B1); PG8_BAR;
;             PG8_LDA(At, 0, 1); PG8_STAGE(PG8_SA(0, 0), a2, voffA);
;             PG8_BAR; PG8_WAIT_L(0); PG8_MMA(1, 0, At, B0); PG8_BAR; PG8_SCHED;
;             PG8_STAGE(PG8_SB(0, 1), b2 + hstep, voffB);
;             PG8_WAIT_V(6); PG8_BAR; PG8_MMA(1, 1, At, B1); PG8_BAR;
;             PG8_LDB(B0, 1, 0); PG8_SCHED; PG8_LDA(At, 1, 0); PG8_STAGE(PG8_SA(0, 1), a2 + hstep, voffA);
;             PG8_WAIT_L(8); PG8_BAR; PG8_WAIT_L(0); PG8_MMA(0, 0, At, B0); PG8_BAR; PG8_SCHED;
;             PG8_LDB(B1, 1, 1); PG8_STAGE(PG8_SB(1, 0), b3, voffB);
;             PG8_BAR; PG8_WAIT_L(0); PG8_MMA(0, 1, At, B1); PG8_BAR;
;             PG8_LDA(At, 1, 1); PG8_STAGE(PG8_SA(1, 0), a3, voffA);
;             PG8_BAR; PG8_WAIT_L(0); PG8_MMA(1, 0, At, B0); PG8_BAR; PG8_SCHED;
;             PG8_STAGE(PG8_SB(1, 1), b3 + hstep, voffB);
;             PG8_WAIT_V(6); PG8_BAR; PG8_MMA(1, 1, At, B1); PG8_BAR;
	s_waitcnt lgkmcnt(0)
	v_mfma_f32_16x16x32_bf16 v[58:61], v[132:135], v[176:179], v[58:61]
	v_mfma_f32_16x16x32_bf16 v[200:203], v[136:139], v[180:183], v[58:61]
	v_mfma_f32_16x16x32_bf16 v[58:61], v[140:143], v[176:179], v[78:81]
	v_mfma_f32_16x16x32_bf16 v[78:81], v[144:147], v[180:183], v[58:61]
	v_mfma_f32_16x16x32_bf16 v[58:61], v[132:135], v[184:187], v[82:85]
	v_mfma_f32_16x16x32_bf16 v[82:85], v[136:139], v[188:191], v[58:61]
	v_mfma_f32_16x16x32_bf16 v[58:61], v[140:143], v[184:187], v[86:89]
	v_mfma_f32_16x16x32_bf16 v[86:89], v[144:147], v[188:191], v[58:61]
	v_mfma_f32_16x16x32_bf16 v[58:61], v[132:135], v[192:195], v[90:93]
	v_mfma_f32_16x16x32_bf16 v[50:53], v[132:135], v[148:151], v[50:53]
	v_mfma_f32_16x16x32_bf16 v[54:57], v[140:143], v[148:151], v[54:57]
	v_mfma_f32_16x16x32_bf16 v[90:93], v[136:139], v[196:199], v[58:61]
	v_mfma_f32_16x16x32_bf16 v[58:61], v[140:143], v[192:195], v[94:97]
	v_mfma_f32_16x16x32_bf16 v[50:53], v[136:139], v[152:155], v[50:53]
	v_mfma_f32_16x16x32_bf16 v[54:57], v[144:147], v[152:155], v[54:57]
	v_mfma_f32_16x16x32_bf16 v[94:97], v[144:147], v[196:199], v[58:61]
	s_barrier
	s_mov_b32 m0, s75
	v_lshl_add_u64 v[224:225], s[8:9], 0, v[66:67]
	s_nop 0
	ds_read_b128 v[58:61], v107
	ds_read_b128 v[204:207], v107 offset:1024
	ds_read_b128 v[208:211], v107 offset:2048
	ds_read_b128 v[212:215], v107 offset:3072
	global_load_lds_dwordx4 v[224:225], off
	v_lshl_add_u64 v[226:227], s[8:9], 0, v[70:71]
	s_mov_b32 m0, s73
	s_nop 0
	global_load_lds_dwordx4 v[226:227], off
	s_barrier
	s_waitcnt lgkmcnt(0)
	v_mfma_f32_16x16x32_bf16 v[30:33], v[58:61], v[184:187], v[30:33]
	v_mfma_f32_16x16x32_bf16 v[0:3], v[58:61], v[148:151], v[0:3]
	v_mfma_f32_16x16x32_bf16 v[22:25], v[208:211], v[148:151], v[22:25]
	v_mfma_f32_16x16x32_bf16 v[148:151], v[204:207], v[188:191], v[30:33]
	v_mfma_f32_16x16x32_bf16 v[30:33], v[208:211], v[184:187], v[34:37]
	v_mfma_f32_16x16x32_bf16 v[0:3], v[204:207], v[152:155], v[0:3]
	v_mfma_f32_16x16x32_bf16 v[22:25], v[212:215], v[152:155], v[22:25]
	v_mfma_f32_16x16x32_bf16 v[152:155], v[212:215], v[188:191], v[30:33]
	v_mfma_f32_16x16x32_bf16 v[30:33], v[58:61], v[192:195], v[38:41]
	v_mfma_f32_16x16x32_bf16 v[120:123], v[58:61], v[176:179], v[120:123]
	v_mfma_f32_16x16x32_bf16 v[26:29], v[208:211], v[176:179], v[26:29]
	v_mfma_f32_16x16x32_bf16 v[176:179], v[204:207], v[196:199], v[30:33]
	v_mfma_f32_16x16x32_bf16 v[30:33], v[208:211], v[192:195], v[42:45]
	v_mfma_f32_16x16x32_bf16 v[120:123], v[204:207], v[180:183], v[120:123]
	v_mfma_f32_16x16x32_bf16 v[26:29], v[212:215], v[180:183], v[26:29]
	v_mfma_f32_16x16x32_bf16 v[180:183], v[212:215], v[196:199], v[30:33]
	s_mov_b32 m0, s38
	v_lshl_add_u64 v[240:241], s[0:1], 0, v[64:65]
	s_barrier
	s_nop 0
	ds_read_b128 v[30:33], v105 offset:16384
	ds_read_b128 v[34:37], v105 offset:17408
	ds_read_b128 v[38:41], v105 offset:18432
	ds_read_b128 v[42:45], v105 offset:19456
	ds_read_b128 v[184:187], v105 offset:20480
	ds_read_b128 v[188:191], v105 offset:21504
	ds_read_b128 v[192:195], v105 offset:22528
	ds_read_b128 v[196:199], v105 offset:23552
	global_load_lds_dwordx4 v[240:241], off
	v_lshl_add_u64 v[242:243], s[0:1], 0, v[68:69]
	s_mov_b32 m0, s39
	s_nop 0
	global_load_lds_dwordx4 v[242:243], off
	s_barrier
	s_waitcnt lgkmcnt(0)
	v_mfma_f32_16x16x32_bf16 v[10:13], v[132:135], v[192:195], v[10:13]
	v_mfma_f32_16x16x32_bf16 v[4:7], v[132:135], v[30:33], v[4:7]
	v_mfma_f32_16x16x32_bf16 v[156:159], v[140:143], v[30:33], v[156:159]
	v_mfma_f32_16x16x32_bf16 v[160:163], v[132:135], v[38:41], v[160:163]
	v_mfma_f32_16x16x32_bf16 v[164:167], v[140:143], v[38:41], v[164:167]
	v_mfma_f32_16x16x32_bf16 v[168:171], v[132:135], v[184:187], v[168:171]
	v_mfma_f32_16x16x32_bf16 v[172:175], v[140:143], v[184:187], v[172:175]
	v_mfma_f32_16x16x32_bf16 v[132:135], v[136:139], v[196:199], v[10:13]
	v_mfma_f32_16x16x32_bf16 v[10:13], v[140:143], v[192:195], v[14:17]
	v_mfma_f32_16x16x32_bf16 v[4:7], v[136:139], v[34:37], v[4:7]
	v_mfma_f32_16x16x32_bf16 v[156:159], v[144:147], v[34:37], v[156:159]
	v_mfma_f32_16x16x32_bf16 v[160:163], v[136:139], v[42:45], v[160:163]
	v_mfma_f32_16x16x32_bf16 v[164:167], v[144:147], v[42:45], v[164:167]
	v_mfma_f32_16x16x32_bf16 v[168:171], v[136:139], v[188:191], v[168:171]
	v_mfma_f32_16x16x32_bf16 v[172:175], v[144:147], v[188:191], v[172:175]
	v_mfma_f32_16x16x32_bf16 v[136:139], v[144:147], v[196:199], v[10:13]
	s_barrier
	s_add_u32 s24, s8, 0x18000
	s_addc_u32 s25, s9, 0
	s_mov_b32 m0, s76
	v_lshl_add_u64 v[10:11], s[24:25], 0, v[66:67]
	global_load_lds_dwordx4 v[10:11], off
	v_lshl_add_u64 v[10:11], s[24:25], 0, v[70:71]
	s_mov_b32 m0, s74
	s_nop 0
	global_load_lds_dwordx4 v[10:11], off
	s_waitcnt vmcnt(6)
	s_barrier
	v_mfma_f32_16x16x32_bf16 v[10:13], v[58:61], v[30:33], v[18:21]
	v_mfma_f32_16x16x32_bf16 v[140:143], v[204:207], v[34:37], v[10:13]
	v_mfma_f32_16x16x32_bf16 v[10:13], v[208:211], v[30:33], v[46:49]
	v_mfma_f32_16x16x32_bf16 v[144:147], v[212:215], v[34:37], v[10:13]
	v_mfma_f32_16x16x32_bf16 v[10:13], v[58:61], v[38:41], v[112:115]
	v_mfma_f32_16x16x32_bf16 v[112:115], v[204:207], v[42:45], v[10:13]
	v_mfma_f32_16x16x32_bf16 v[10:13], v[208:211], v[38:41], v[116:119]
	v_mfma_f32_16x16x32_bf16 v[116:119], v[212:215], v[42:45], v[10:13]
	v_mfma_f32_16x16x32_bf16 v[10:13], v[58:61], v[184:187], v[124:127]
	v_mfma_f32_16x16x32_bf16 v[124:127], v[204:207], v[188:191], v[10:13]
	v_mfma_f32_16x16x32_bf16 v[10:13], v[208:211], v[184:187], v[128:131]
	v_mfma_f32_16x16x32_bf16 v[128:131], v[212:215], v[188:191], v[10:13]
	v_mfma_f32_16x16x32_bf16 v[10:13], v[58:61], v[192:195], v[98:101]
	v_mfma_f32_16x16x32_bf16 v[98:101], v[204:207], v[196:199], v[10:13]
	v_mfma_f32_16x16x32_bf16 v[10:13], v[208:211], v[192:195], v[108:111]
	v_mfma_f32_16x16x32_bf16 v[108:111], v[212:215], v[196:199], v[10:13]
	s_barrier
; #define PG8_STAGE(bufoff, gbase, voff) do { _Pragma("unroll") for (int _i = 0; _i < 2; ++_i) \
;         __builtin_amdgcn_global_load_lds((const unsigned*)((const char*)(gbase) + (voff)[_i]), (PG8_LAS unsigned*)(lds + (bufoff) + ldsw + _i * 8192), 16, 0, 0); } while (0)
; #define PG8_LDA(dst, b, h) do { _Pragma("unroll") for (int m = 0; m < 4; ++m) _Pragma("unroll") for (int k = 0; k < 2; ++k) dst[m][k] = *(const PG8_LAS bf16x8*)(lds + PG8_SA(b, h) + aoff + m * 2048 + k * 1024); } while (0)
; #define PG8_LDB(dst, b, h) do { _Pragma("unroll") for (int n = 0; n < 2; ++n) _Pragma("unroll") for (int k = 0; k < 2; ++k) dst[n][k] = *(const PG8_LAS bf16x8*)(lds + PG8_SB(b, h) + boff + n * 2048 + k * 1024); } while (0)
; #define PG8_WAIT_V(n) asm volatile("s_waitcnt vmcnt(" #n ")" ::: "memory")
; #define PG8_WAIT_L(n) asm volatile("s_waitcnt lgkmcnt(" #n ")" ::: "memory")
; #define PG8_BAR __builtin_amdgcn_s_barrier()
; #define PG8_SCHED __builtin_amdgcn_sched_barrier(0)
; template <class Epi, class Sched>
; __device__ __forceinline__ void gemm_phase(PG8_LAS unsigned char* lds, const Gemm g, const Sched& S, const Epi& E) {
;     ...
;             PG8_LDB(B0, 0, 0); PG8_SCHED; PG8_LDA(At, 0, 0); PG8_STAGE(PG8_SA(1, 1), a1 + hstep, voffA);
;             PG8_WAIT_L(8); PG8_BAR; PG8_WAIT_L(0); PG8_MMA(0, 0, At, B0); PG8_BAR; PG8_SCHED;
;             PG8_LDB(B1, 0, 1); PG8_STAGE(PG8_SB(0, 0), b2, voffB);
;             PG8_BAR; PG8_WAIT_L(0); PG8_MMA(0, 1, At, B1); PG8_BAR;
;             PG8_LDA(At, 0, 1); PG8_STAGE(PG8_SA(0, 0), a2, voffA);
;             PG8_BAR; PG8_WAIT_L(0); PG8_MMA(1, 0, At, B0); PG8_BAR; PG8_SCHED;
;             PG8_STAGE(PG8_SB(0, 1), b2 + hstep, voffB);
;             PG8_WAIT_V(6); PG8_BAR; PG8_MMA(1, 1, At, B1); PG8_BAR;
;             PG8_LDB(B0, 1, 0); PG8_SCHED; PG8_LDA(At, 1, 0); PG8_STAGE(PG8_SA(0, 1), a2 + hstep, voffA);
;             PG8_WAIT_L(8); PG8_BAR; PG8_WAIT_L(0); PG8_MMA(0, 0, At, B0); PG8_BAR; PG8_SCHED;
;             PG8_LDB(B1, 1, 1); PG8_STAGE(PG8_SB(1, 0), b3, voffB);
;             PG8_BAR; PG8_WAIT_L(0); PG8_MMA(0, 1, At, B1); PG8_BAR;
;             PG8_LDA(At, 1, 1); PG8_STAGE(PG8_SA(1, 0), a3, voffA);
;             PG8_BAR; PG8_WAIT_L(0); PG8_MMA(1, 0, At, B0); PG8_BAR; PG8_SCHED;
;             PG8_STAGE(PG8_SB(1, 1), b3 + hstep, voffB);
;             PG8_WAIT_V(6); PG8_BAR; PG8_MMA(1, 1, At, B1); PG8_BAR;
	ds_read_b128 v[184:187], v8
	ds_read_b128 v[188:191], v8 offset:1024
	ds_read_b128 v[192:195], v8 offset:2048
	ds_read_b128 v[196:199], v8 offset:3072
	s_add_u32 s24, s0, 0x18000
	s_addc_u32 s25, s1, 0
	s_mov_b32 m0, s40
	v_lshl_add_u64 v[30:31], s[24:25], 0, v[64:65]
	ds_read_b128 v[10:13], v105 offset:32768
	ds_read_b128 v[14:17], v105 offset:33792
	ds_read_b128 v[18:21], v105 offset:34816
	ds_read_b128 v[204:207], v105 offset:35840
	ds_read_b128 v[208:211], v105 offset:36864
	ds_read_b128 v[212:215], v105 offset:37888
	ds_read_b128 v[216:219], v105 offset:38912
	ds_read_b128 v[220:223], v105 offset:39936
	global_load_lds_dwordx4 v[30:31], off
	v_lshl_add_u64 v[30:31], s[24:25], 0, v[68:69]
	s_mov_b32 m0, s41
	s_nop 0
	global_load_lds_dwordx4 v[30:31], off
	s_waitcnt lgkmcnt(8)
	s_barrier
	s_waitcnt lgkmcnt(0)
	v_mfma_f32_16x16x32_bf16 v[30:33], v[184:187], v[10:13], v[50:53]
	v_mfma_f32_16x16x32_bf16 v[60:63], v[188:191], v[14:17], v[30:33]
	v_mfma_f32_16x16x32_bf16 v[30:33], v[192:195], v[10:13], v[54:57]
	v_mfma_f32_16x16x32_bf16 v[56:59], v[196:199], v[14:17], v[30:33]
	v_mfma_f32_16x16x32_bf16 v[30:33], v[184:187], v[18:21], v[200:203]
	v_mfma_f32_16x16x32_bf16 v[48:51], v[188:191], v[204:207], v[30:33]
	v_mfma_f32_16x16x32_bf16 v[30:33], v[192:195], v[18:21], v[78:81]
	v_mfma_f32_16x16x32_bf16 v[52:55], v[196:199], v[204:207], v[30:33]
	v_mfma_f32_16x16x32_bf16 v[30:33], v[184:187], v[208:211], v[82:85]
	v_mfma_f32_16x16x32_bf16 v[40:43], v[188:191], v[212:215], v[30:33]
	v_mfma_f32_16x16x32_bf16 v[30:33], v[192:195], v[208:211], v[86:89]
	v_mfma_f32_16x16x32_bf16 v[44:47], v[196:199], v[212:215], v[30:33]
	v_mfma_f32_16x16x32_bf16 v[30:33], v[184:187], v[216:219], v[90:93]
	v_mfma_f32_16x16x32_bf16 v[36:39], v[192:195], v[216:219], v[94:97]
	v_mfma_f32_16x16x32_bf16 v[32:35], v[188:191], v[220:223], v[30:33]
	v_mfma_f32_16x16x32_bf16 v[36:39], v[196:199], v[220:223], v[36:39]
	s_barrier
	s_mov_b32 m0, s80
	ds_read_b128 v[78:81], v9
	ds_read_b128 v[82:85], v9 offset:1024
	ds_read_b128 v[86:89], v9 offset:2048
	ds_read_b128 v[90:93], v9 offset:3072
	v_lshl_add_u64 v[8:9], v[224:225], 0, s[10:11]
	global_load_lds_dwordx4 v[8:9], off
	v_lshl_add_u64 v[8:9], v[226:227], 0, s[10:11]
	s_mov_b32 m0, s77
	s_nop 0
	global_load_lds_dwordx4 v[8:9], off
	s_barrier
	s_waitcnt lgkmcnt(0)
	v_mfma_f32_16x16x32_bf16 v[0:3], v[78:81], v[10:13], v[0:3]
	v_mfma_f32_16x16x32_bf16 v[94:97], v[82:85], v[14:17], v[0:3]
	v_mfma_f32_16x16x32_bf16 v[0:3], v[86:89], v[10:13], v[22:25]
	v_mfma_f32_16x16x32_bf16 v[200:203], v[90:93], v[14:17], v[0:3]
	v_mfma_f32_16x16x32_bf16 v[0:3], v[78:81], v[18:21], v[120:123]
	v_mfma_f32_16x16x32_bf16 v[120:123], v[82:85], v[204:207], v[0:3]
	v_mfma_f32_16x16x32_bf16 v[0:3], v[86:89], v[18:21], v[26:29]
	v_mfma_f32_16x16x32_bf16 v[204:207], v[90:93], v[204:207], v[0:3]
	v_mfma_f32_16x16x32_bf16 v[0:3], v[78:81], v[208:211], v[148:151]
	v_mfma_f32_16x16x32_bf16 v[148:151], v[82:85], v[212:215], v[0:3]
	v_mfma_f32_16x16x32_bf16 v[0:3], v[86:89], v[208:211], v[152:155]
	v_mfma_f32_16x16x32_bf16 v[152:155], v[90:93], v[212:215], v[0:3]
	v_mfma_f32_16x16x32_bf16 v[0:3], v[78:81], v[216:219], v[176:179]
	v_mfma_f32_16x16x32_bf16 v[176:179], v[82:85], v[220:223], v[0:3]
	v_mfma_f32_16x16x32_bf16 v[0:3], v[86:89], v[216:219], v[180:183]
	v_mfma_f32_16x16x32_bf16 v[180:183], v[90:93], v[220:223], v[0:3]
	s_mov_b32 m0, s43
	s_nop 4
	v_lshl_add_u64 v[0:1], v[240:241], 0, s[10:11]
	s_barrier
	ds_read_b128 v[208:211], v105 offset:49152
	ds_read_b128 v[212:215], v105 offset:50176
	ds_read_b128 v[216:219], v105 offset:51200
	ds_read_b128 v[220:223], v105 offset:52224
	ds_read_b128 v[224:227], v105 offset:53248
	ds_read_b128 v[228:231], v105 offset:54272
	ds_read_b128 v[232:235], v105 offset:55296
	ds_read_b128 v[236:239], v105 offset:56320
	global_load_lds_dwordx4 v[0:1], off
	v_lshl_add_u64 v[0:1], v[242:243], 0, s[10:11]
	s_mov_b32 m0, s60
	s_nop 0
	global_load_lds_dwordx4 v[0:1], off
	s_barrier
	s_waitcnt lgkmcnt(0)
	v_mfma_f32_16x16x32_bf16 v[0:3], v[184:187], v[208:211], v[4:7]
	v_mfma_f32_16x16x32_bf16 v[24:27], v[188:191], v[212:215], v[0:3]
	v_mfma_f32_16x16x32_bf16 v[0:3], v[192:195], v[208:211], v[156:159]
	v_mfma_f32_16x16x32_bf16 v[28:31], v[196:199], v[212:215], v[0:3]
	v_mfma_f32_16x16x32_bf16 v[0:3], v[184:187], v[216:219], v[160:163]
	v_mfma_f32_16x16x32_bf16 v[16:19], v[188:191], v[220:223], v[0:3]
	v_mfma_f32_16x16x32_bf16 v[0:3], v[192:195], v[216:219], v[164:167]
	v_mfma_f32_16x16x32_bf16 v[20:23], v[196:199], v[220:223], v[0:3]
	v_mfma_f32_16x16x32_bf16 v[0:3], v[184:187], v[224:227], v[168:171]
	v_mfma_f32_16x16x32_bf16 v[8:11], v[188:191], v[228:231], v[0:3]
	v_mfma_f32_16x16x32_bf16 v[0:3], v[192:195], v[224:227], v[172:175]
	v_mfma_f32_16x16x32_bf16 v[12:15], v[196:199], v[228:231], v[0:3]
	v_mfma_f32_16x16x32_bf16 v[0:3], v[184:187], v[232:235], v[132:135]
	v_mfma_f32_16x16x32_bf16 v[4:7], v[192:195], v[232:235], v[136:139]
	v_mfma_f32_16x16x32_bf16 v[0:3], v[188:191], v[236:239], v[0:3]
	v_mfma_f32_16x16x32_bf16 v[4:7], v[196:199], v[236:239], v[4:7]
	s_barrier
	s_add_u32 s24, s8, 0x18080
	s_addc_u32 s25, s9, 0
	s_mov_b32 m0, s81
	v_lshl_add_u64 v[132:133], s[24:25], 0, v[66:67]
	global_load_lds_dwordx4 v[132:133], off
	v_lshl_add_u64 v[132:133], s[24:25], 0, v[70:71]
	s_mov_b32 m0, s78
	s_nop 0
	global_load_lds_dwordx4 v[132:133], off
	s_waitcnt vmcnt(6)
	s_barrier
; #define PG8_STAGE(bufoff, gbase, voff) do { _Pragma("unroll") for (int _i = 0; _i < 2; ++_i) \
;         __builtin_amdgcn_global_load_lds((const unsigned*)((const char*)(gbase) + (voff)[_i]), (PG8_LAS unsigned*)(lds + (bufoff) + ldsw + _i * 8192), 16, 0, 0); } while (0)
; #define PG8_WAIT_V(n) asm volatile("s_waitcnt vmcnt(" #n ")" ::: "memory")
; template <class Epi, class Sched>
; __device__ __forceinline__ void gemm_phase(PG8_LAS unsigned char* lds, const Gemm g, const Sched& S, const Epi& E) {
;     ...
;             PG8_WAIT_V(6); PG8_BAR; PG8_MMA(1, 1, At, B1); PG8_BAR;
;             PG8_LDB(B0, 1, 0); PG8_SCHED; PG8_LDA(At, 1, 0); PG8_STAGE(PG8_SA(0, 1), a2 + hstep, voffA);
;             PG8_WAIT_L(8); PG8_BAR; PG8_WAIT_L(0); PG8_MMA(0, 0, At, B0); PG8_BAR; PG8_SCHED;
;             PG8_LDB(B1, 1, 1); PG8_STAGE(PG8_SB(1, 0), b3, voffB);
;             PG8_BAR; PG8_WAIT_L(0); PG8_MMA(0, 1, At, B1); PG8_BAR;
;             PG8_LDA(At, 1, 1); PG8_STAGE(PG8_SA(1, 0), a3, voffA);
;             PG8_BAR; PG8_WAIT_L(0); PG8_MMA(1, 0, At, B0); PG8_BAR; PG8_SCHED;
;             PG8_STAGE(PG8_SB(1, 1), b3 + hstep, voffB);
;             PG8_WAIT_V(6); PG8_BAR; PG8_MMA(1, 1, At, B1); PG8_BAR;
;     __device__ __forceinline__ void operator()(const f32x4 (&acc)[2][2][4][2], const Unit& u, int wr, int wc, int fr, int fq) const {
;     ...
;         for (int ai = 0; ai < 2; ++ai)
; #pragma unroll
;             for (int m = 0; m < 4; ++m) { const f32x4 g0 = acc[ai][1][m][0], g1 = acc[ai][1][m][1]; u32x4 w; w.x = pk2(g0[0], g0[1]); w.y = pk2(g0[2], g0[3]); w.z = pk2(g1[0], g1[1]); w.w = pk2(g1[2], g1[3]);
;                 *(u32x4*)(G + (size_t)(row0 + ai * HALF + m * 16) * 512 + cb) = w; }
;         asm volatile("" ::: "memory");
; #pragma unroll
;         for (int ai = 0; ai < 2; ++ai)
; #pragma unroll
;             for (int m = 0; m < 4; ++m) { const int row = row0 + ai * HALF + m * 16; const size_t off = (size_t)row * 512 + cb; bf16_t* kp = RKV + (size_t)row * 1536 + 512 + cb;
;                 float ks[8], av[8], t[8]; unpack8(*(const u32x4*)kp, ks);
;                 { const f32x4 c0 = *(const f32x4*)(a0 + cb), c1 = *(const f32x4*)(a0 + cb + 4); const f32x4 x0 = acc[ai][0][m][0], x1 = acc[ai][0][m][1];
; #pragma unroll
;                   for (int j = 0; j < 4; ++j) { av[j] = sigmoidf_(c0[j] + x0[j]); av[4 + j] = sigmoidf_(c1[j] + x1[j]); } }
	v_mfma_f32_16x16x32_bf16 v[132:135], v[78:81], v[208:211], v[140:143]
	v_mfma_f32_16x16x32_bf16 v[112:115], v[78:81], v[216:219], v[112:115]
	v_mfma_f32_16x16x32_bf16 v[124:127], v[78:81], v[224:227], v[124:127]
	v_mfma_f32_16x16x32_bf16 v[78:81], v[78:81], v[232:235], v[98:101]
	v_mfma_f32_16x16x32_bf16 v[136:139], v[86:89], v[208:211], v[144:147]
	v_mfma_f32_16x16x32_bf16 v[116:119], v[86:89], v[216:219], v[116:119]
	v_mfma_f32_16x16x32_bf16 v[128:131], v[86:89], v[224:227], v[128:131]
	v_mfma_f32_16x16x32_bf16 v[140:143], v[82:85], v[236:239], v[78:81]
	v_mfma_f32_16x16x32_bf16 v[78:81], v[86:89], v[232:235], v[108:111]
	v_mfma_f32_16x16x32_bf16 v[132:135], v[82:85], v[212:215], v[132:135]
	v_mfma_f32_16x16x32_bf16 v[136:139], v[90:93], v[212:215], v[136:139]
	v_mfma_f32_16x16x32_bf16 v[112:115], v[82:85], v[220:223], v[112:115]
	v_mfma_f32_16x16x32_bf16 v[116:119], v[90:93], v[220:223], v[116:119]
	v_mfma_f32_16x16x32_bf16 v[124:127], v[82:85], v[228:231], v[124:127]
	v_mfma_f32_16x16x32_bf16 v[128:131], v[90:93], v[228:231], v[128:131]
	v_mfma_f32_16x16x32_bf16 v[84:87], v[90:93], v[236:239], v[78:81]
	s_lshl_b32 s24, s71, 7
	v_lshl_add_u32 v100, s70, 8, v102
	s_or_b32 s24, s24, s42
	v_or_b32_e32 v78, s24, v103
	v_ashrrev_i32_e32 v101, 31, v100
	v_ashrrev_i32_e32 v79, 31, v78
	v_lshlrev_b64 v[80:81], 10, v[100:101]
	v_lshl_add_u64 v[80:81], s[52:53], 0, v[80:81]
	v_lshlrev_b64 v[82:83], 1, v[78:79]
	v_or_b32_e32 v98, 16, v100
	v_lshl_add_u64 v[80:81], v[80:81], 0, v[82:83]
	v_ashrrev_i32_e32 v99, 31, v98
	s_barrier
	v_cvt_pk_bf16_f32 v88, v94, v95
	v_cvt_pk_bf16_f32 v89, v96, v97
	v_cvt_pk_bf16_f32 v90, v200, v201
	v_cvt_pk_bf16_f32 v91, v202, v203
	global_store_dwordx4 v[80:81], v[88:91], off
	v_lshlrev_b64 v[80:81], 10, v[98:99]
	v_lshl_add_u64 v[80:81], s[52:53], 0, v[80:81]
	v_or_b32_e32 v96, 32, v100
	v_lshl_add_u64 v[80:81], v[80:81], 0, v[82:83]
	v_ashrrev_i32_e32 v97, 31, v96
	v_cvt_pk_bf16_f32 v88, v120, v121
	v_cvt_pk_bf16_f32 v89, v122, v123
	v_cvt_pk_bf16_f32 v90, v204, v205
	v_cvt_pk_bf16_f32 v91, v206, v207
	global_store_dwordx4 v[80:81], v[88:91], off
	v_lshlrev_b64 v[80:81], 10, v[96:97]
	v_lshl_add_u64 v[80:81], s[52:53], 0, v[80:81]
	v_or_b32_e32 v94, 48, v100
	v_lshl_add_u64 v[80:81], v[80:81], 0, v[82:83]
	v_ashrrev_i32_e32 v95, 31, v94
	v_cvt_pk_bf16_f32 v88, v148, v149
	v_cvt_pk_bf16_f32 v89, v150, v151
	v_cvt_pk_bf16_f32 v90, v152, v153
	v_cvt_pk_bf16_f32 v91, v154, v155
	global_store_dwordx4 v[80:81], v[88:91], off
	v_lshlrev_b64 v[80:81], 10, v[94:95]
	v_lshl_add_u64 v[80:81], s[52:53], 0, v[80:81]
	v_add_u32_e32 v92, 0x80, v100
	v_lshl_add_u64 v[80:81], v[80:81], 0, v[82:83]
	v_ashrrev_i32_e32 v93, 31, v92
	v_cvt_pk_bf16_f32 v88, v176, v177
	v_cvt_pk_bf16_f32 v89, v178, v179
	v_cvt_pk_bf16_f32 v90, v180, v181
	v_cvt_pk_bf16_f32 v91, v182, v183
	global_store_dwordx4 v[80:81], v[88:91], off
	v_lshlrev_b64 v[80:81], 10, v[92:93]
	v_lshl_add_u64 v[80:81], s[52:53], 0, v[80:81]
	v_cvt_pk_bf16_f32 v90, v136, v137
	v_lshl_add_u64 v[80:81], v[80:81], 0, v[82:83]
	v_cvt_pk_bf16_f32 v88, v132, v133
	v_cvt_pk_bf16_f32 v89, v134, v135
	v_cvt_pk_bf16_f32 v91, v138, v139
	global_store_dwordx4 v[80:81], v[88:91], off
	v_cvt_pk_bf16_f32 v108, v112, v113
	v_cvt_pk_bf16_f32 v109, v114, v115
	v_cvt_pk_bf16_f32 v110, v116, v117
	v_cvt_pk_bf16_f32 v111, v118, v119
	s_ashr_i32 s24, s24, 6
	s_nop 0
	v_add_u32_e32 v90, 0x90, v100
	v_ashrrev_i32_e32 v91, 31, v90
	v_lshlrev_b64 v[80:81], 10, v[90:91]
	v_lshl_add_u64 v[80:81], s[52:53], 0, v[80:81]
	v_add_u32_e32 v88, 0xa0, v100
	v_lshl_add_u64 v[80:81], v[80:81], 0, v[82:83]
	v_ashrrev_i32_e32 v89, 31, v88
	global_store_dwordx4 v[80:81], v[108:111], off
	v_lshlrev_b64 v[80:81], 10, v[88:89]
	v_lshl_add_u64 v[80:81], s[52:53], 0, v[80:81]
	v_lshl_add_u64 v[80:81], v[80:81], 0, v[82:83]
	v_cvt_pk_bf16_f32 v108, v124, v125
	v_cvt_pk_bf16_f32 v109, v126, v127
	v_cvt_pk_bf16_f32 v110, v128, v129
	v_cvt_pk_bf16_f32 v111, v130, v131
	global_store_dwordx4 v[80:81], v[108:111], off
	v_add_u32_e32 v80, 0xb0, v100
	v_ashrrev_i32_e32 v81, 31, v80
	v_cvt_pk_bf16_f32 v110, v84, v85
	v_lshlrev_b64 v[84:85], 10, v[80:81]
	v_lshl_add_u64 v[84:85], s[52:53], 0, v[84:85]
	v_lshl_add_u64 v[84:85], v[84:85], 0, v[82:83]
	v_cvt_pk_bf16_f32 v108, v140, v141
	v_cvt_pk_bf16_f32 v109, v142, v143
	v_cvt_pk_bf16_f32 v111, v86, v87
	global_store_dwordx4 v[84:85], v[108:111], off
	v_mad_i64_i32 v[84:85], s[26:27], v100, s68, v[76:77]
	v_lshlrev_b64 v[130:131], 2, v[78:79]
	v_lshl_add_u64 v[128:129], v[84:85], 0, v[82:83]
	v_lshl_add_u64 v[84:85], s[22:23], 0, v[130:131]
	global_load_dwordx4 v[108:111], v[128:129], off offset:1024
	global_load_dwordx4 v[112:115], v[84:85], off
	global_load_dwordx4 v[116:119], v[84:85], off offset:16
	v_lshl_add_u64 v[86:87], s[30:31], 0, v[130:131]
	global_load_dwordx4 v[120:123], v[86:87], off
	global_load_dwordx4 v[124:127], v[86:87], off offset:16
	s_add_i32 s65, s65, s96
	s_andn2_b64 vcc, exec, s[6:7]
	s_mov_b32 s71, s3
	s_mov_b32 s70, s69
	s_waitcnt vmcnt(0)
; __device__ __forceinline__ void unpack8(const u32x4 w, float (&f)[8]) { f[0] = bflo(w.x); f[1] = bfhi(w.x); f[2] = bflo(w.y); f[3] = bfhi(w.y); f[4] = bflo(w.z); f[5] = bfhi(w.z); f[6] = bflo(w.w); f[7] = bfhi(w.w); }
; __device__ __forceinline__ u32x4 pack8(const float (&f)[8]) { u32x4 o; o.x = pk2(f[0], f[1]); o.y = pk2(f[2], f[3]); o.z = pk2(f[4], f[5]); o.w = pk2(f[6], f[7]); return o; }
; __device__ __forceinline__ float sigmoidf_(float x) { return __builtin_amdgcn_rcpf(1.0f + __expf(-x)); }
;     __device__ __forceinline__ void operator()(const f32x4 (&acc)[2][2][4][2], const Unit& u, int wr, int wc, int fr, int fq) const {
;     ...
;             for (int m = 0; m < 4; ++m) { const int row = row0 + ai * HALF + m * 16; const size_t off = (size_t)row * 512 + cb; bf16_t* kp = RKV + (size_t)row * 1536 + 512 + cb;
;                 float ks[8], av[8], t[8]; unpack8(*(const u32x4*)kp, ks);
;                 { const f32x4 c0 = *(const f32x4*)(a0 + cb), c1 = *(const f32x4*)(a0 + cb + 4); const f32x4 x0 = acc[ai][0][m][0], x1 = acc[ai][0][m][1];
; #pragma unroll
;                   for (int j = 0; j < 4; ++j) { av[j] = sigmoidf_(c0[j] + x0[j]); av[4 + j] = sigmoidf_(c1[j] + x1[j]); } }
;                 { const f32x4 c0 = *(const f32x4*)(k_a + cb), c1 = *(const f32x4*)(k_a + cb + 4);
; #pragma unroll
;                   for (int j = 0; j < 4; ++j) { t[j] = ks[j] * (1.0f + (av[j] - 1.0f) * c0[j]); t[4 + j] = ks[4 + j] * (1.0f + (av[4 + j] - 1.0f) * c1[j]); } }
;                 *(u32x4*)kp = pack8(t);
;                 { const f32x4 c0 = *(const f32x4*)(k_k + cb), c1 = *(const f32x4*)(k_k + cb + 4); const float ri = rinv[row * 8 + (cb >> 6)];
; #pragma unroll
;                   for (int j = 0; j < 4; ++j) { t[j] = ks[j] * c0[j] * ri; t[4 + j] = ks[4 + j] * c1[j] * ri; } }
;                 *(u32x4*)(KK + off) = pack8(t);
; #pragma unroll
;                 for (int e = 0; e < 8; ++e) t[e] = -t[e] * av[e];
;                 *(u32x4*)(NB + off) = pack8(t);
;                 asm volatile("" ::: "memory"); }
	v_add_f32_e32 v60, v60, v112
	v_mul_f32_e32 v60, 0xbfb8aa3b, v60
	v_exp_f32_e32 v60, v60
	v_add_f32_e32 v56, v56, v116
	v_mul_f32_e32 v56, 0xbfb8aa3b, v56
	v_exp_f32_e32 v56, v56
	v_add_f32_e32 v60, 1.0, v60
	v_rcp_f32_e32 v116, v60
	v_add_f32_e32 v60, v61, v113
	v_mul_f32_e32 v60, 0xbfb8aa3b, v60
	v_add_f32_e32 v57, v57, v117
	v_exp_f32_e32 v60, v60
	v_mul_f32_e32 v57, 0xbfb8aa3b, v57
	v_exp_f32_e32 v57, v57
	v_add_f32_e32 v56, 1.0, v56
	v_rcp_f32_e32 v113, v56
	v_add_f32_e32 v56, 1.0, v60
	v_rcp_f32_e32 v117, v56
	v_add_f32_e32 v56, 1.0, v57
	v_add_f32_e32 v57, v62, v114
	v_mul_f32_e32 v57, 0xbfb8aa3b, v57
	v_add_f32_e32 v58, v58, v118
	v_exp_f32_e32 v57, v57
	v_mul_f32_e32 v58, 0xbfb8aa3b, v58
	v_exp_f32_e32 v58, v58
	v_rcp_f32_e32 v114, v56
	v_add_f32_e32 v56, 1.0, v57
	v_add_f32_e32 v57, v63, v115
	v_rcp_f32_e32 v118, v56
	v_add_f32_e32 v56, 1.0, v58
	v_mul_f32_e32 v57, 0xbfb8aa3b, v57
	v_add_f32_e32 v58, v59, v119
	v_exp_f32_e32 v57, v57
	v_mul_f32_e32 v58, 0xbfb8aa3b, v58
	v_exp_f32_e32 v58, v58
	v_rcp_f32_e32 v115, v56
	v_add_f32_e32 v56, 1.0, v57
	v_rcp_f32_e32 v119, v56
	v_add_f32_e32 v56, 1.0, v58
	v_rcp_f32_e32 v139, v56
	v_add_f32_e32 v57, -1.0, v113
	v_lshlrev_b32_e32 v136, 16, v110
	v_fma_f32 v57, v124, v57, 1.0
	v_add_f32_e32 v56, -1.0, v116
	v_mul_f32_e32 v58, v57, v136
	v_add_f32_e32 v57, -1.0, v117
	v_add_f32_e32 v62, -1.0, v119
	v_lshlrev_b32_e32 v132, 16, v108
	v_and_b32_e32 v133, 0xffff0000, v108
	v_and_b32_e32 v135, 0xffff0000, v109
	v_fma_f32 v56, v120, v56, 1.0
	v_fma_f32 v57, v121, v57, 1.0
	v_add_f32_e32 v59, -1.0, v114
	v_add_f32_e32 v60, -1.0, v118
	v_fma_f32 v62, v123, v62, 1.0
	v_add_f32_e32 v63, -1.0, v139
	v_lshlrev_b32_e32 v134, 16, v109
	v_and_b32_e32 v137, 0xffff0000, v110
	v_and_b32_e32 v112, 0xffff0000, v111
	v_mul_f32_e32 v56, v56, v132
	v_mul_f32_e32 v57, v57, v133
	v_fma_f32 v59, v125, v59, 1.0
	v_fma_f32 v60, v122, v60, 1.0
	v_add_f32_e32 v61, -1.0, v115
	v_mul_f32_e32 v62, v62, v135
	v_fma_f32 v63, v127, v63, 1.0
	v_lshlrev_b32_e32 v138, 16, v111
	v_mul_f32_e32 v59, v59, v137
	v_mul_f32_e32 v60, v60, v134
	v_fma_f32 v61, v126, v61, 1.0
	v_mul_f32_e32 v63, v63, v112
	v_cvt_pk_bf16_f32 v56, v56, v57
	v_cvt_pk_bf16_f32 v57, v60, v62
	v_lshl_add_u32 v62, v100, 3, s24
	v_mul_f32_e32 v61, v61, v138
	v_cvt_pk_bf16_f32 v58, v58, v59
	v_cvt_pk_bf16_f32 v59, v61, v63
	global_store_dwordx4 v[128:129], v[56:59], off offset:1024
	v_ashrrev_i32_e32 v63, 31, v62
	v_lshl_add_u64 v[62:63], v[62:63], 2, s[4:5]
	v_lshl_add_u64 v[56:57], s[28:29], 0, v[130:131]
	global_load_dwordx4 v[58:61], v[56:57], off
	global_load_dword v120, v[62:63], off
	global_load_dwordx4 v[108:111], v[56:57], off offset:16
	v_lshlrev_b64 v[62:63], 9, v[100:101]
	v_lshl_add_u64 v[62:63], v[62:63], 0, v[78:79]
	v_lshlrev_b64 v[62:63], 1, v[62:63]
	v_lshl_add_u64 v[100:101], s[50:51], 0, v[62:63]
	v_lshl_add_u64 v[62:63], s[62:63], 0, v[62:63]
	s_waitcnt vmcnt(0)
	v_mul_f32_e32 v58, v58, v132
	v_mul_f32_e32 v121, v58, v120
	v_mul_f32_e32 v58, v108, v136
	v_mul_f32_e32 v108, v120, v58
	v_mul_f32_e32 v58, v59, v133
	v_mul_f32_e32 v122, v58, v120
	v_mul_f32_e32 v58, v109, v137
	v_mul_f32_e32 v109, v120, v58
	v_mul_f32_e32 v58, v60, v134
	v_mul_f32_e32 v123, v58, v120
	v_mul_f32_e32 v58, v110, v138
	v_mul_f32_e32 v110, v120, v58
	v_mul_f32_e32 v58, v61, v135
	v_mul_f32_e32 v124, v58, v120
	v_mul_f32_e32 v58, v111, v112
	v_mul_f32_e32 v111, v120, v58
	v_cvt_pk_bf16_f32 v58, v121, v122
	v_cvt_pk_bf16_f32 v59, v123, v124
	v_cvt_pk_bf16_f32 v60, v108, v109
	v_cvt_pk_bf16_f32 v61, v110, v111
	global_store_dwordx4 v[100:101], v[58:61], off
	v_mul_f32_e64 v100, v113, -v108
	v_mul_f32_e64 v101, v114, -v109
	v_mul_f32_e64 v58, v116, -v121
	v_mul_f32_e64 v59, v117, -v122
	v_mul_f32_e64 v60, v118, -v123
	v_mul_f32_e64 v61, v119, -v124
	v_cvt_pk_bf16_f32 v58, v58, v59
	v_cvt_pk_bf16_f32 v59, v60, v61
	v_mul_f32_e64 v108, v115, -v110
	v_mul_f32_e64 v109, v139, -v111
	v_cvt_pk_bf16_f32 v60, v100, v101
	v_cvt_pk_bf16_f32 v61, v108, v109
	global_store_dwordx4 v[62:63], v[58:61], off
	s_nop 1
	v_mad_i64_i32 v[58:59], s[26:27], v98, s68, v[76:77]
	v_lshl_add_u64 v[62:63], v[58:59], 0, v[82:83]
	global_load_dwordx4 v[58:61], v[62:63], off offset:1024
	global_load_dwordx4 v[108:111], v[84:85], off
	global_load_dwordx4 v[112:115], v[84:85], off offset:16
	global_load_dwordx4 v[116:119], v[86:87], off
	global_load_dwordx4 v[120:123], v[86:87], off offset:16
	s_waitcnt vmcnt(0)
; __device__ __forceinline__ void unpack8(const u32x4 w, float (&f)[8]) { f[0] = bflo(w.x); f[1] = bfhi(w.x); f[2] = bflo(w.y); f[3] = bfhi(w.y); f[4] = bflo(w.z); f[5] = bfhi(w.z); f[6] = bflo(w.w); f[7] = bfhi(w.w); }
; __device__ __forceinline__ u32x4 pack8(const float (&f)[8]) { u32x4 o; o.x = pk2(f[0], f[1]); o.y = pk2(f[2], f[3]); o.z = pk2(f[4], f[5]); o.w = pk2(f[6], f[7]); return o; }
; __device__ __forceinline__ float sigmoidf_(float x) { return __builtin_amdgcn_rcpf(1.0f + __expf(-x)); }
;     __device__ __forceinline__ void operator()(const f32x4 (&acc)[2][2][4][2], const Unit& u, int wr, int wc, int fr, int fq) const {
;     ...
;             for (int m = 0; m < 4; ++m) { const int row = row0 + ai * HALF + m * 16; const size_t off = (size_t)row * 512 + cb; bf16_t* kp = RKV + (size_t)row * 1536 + 512 + cb;
;                 float ks[8], av[8], t[8]; unpack8(*(const u32x4*)kp, ks);
;                 { const f32x4 c0 = *(const f32x4*)(a0 + cb), c1 = *(const f32x4*)(a0 + cb + 4); const f32x4 x0 = acc[ai][0][m][0], x1 = acc[ai][0][m][1];
; #pragma unroll
;                   for (int j = 0; j < 4; ++j) { av[j] = sigmoidf_(c0[j] + x0[j]); av[4 + j] = sigmoidf_(c1[j] + x1[j]); } }
;                 { const f32x4 c0 = *(const f32x4*)(k_a + cb), c1 = *(const f32x4*)(k_a + cb + 4);
; #pragma unroll
;                   for (int j = 0; j < 4; ++j) { t[j] = ks[j] * (1.0f + (av[j] - 1.0f) * c0[j]); t[4 + j] = ks[4 + j] * (1.0f + (av[4 + j] - 1.0f) * c1[j]); } }
;                 *(u32x4*)kp = pack8(t);
;                 { const f32x4 c0 = *(const f32x4*)(k_k + cb), c1 = *(const f32x4*)(k_k + cb + 4); const float ri = rinv[row * 8 + (cb >> 6)];
; #pragma unroll
;                   for (int j = 0; j < 4; ++j) { t[j] = ks[j] * c0[j] * ri; t[4 + j] = ks[4 + j] * c1[j] * ri; } }
;                 *(u32x4*)(KK + off) = pack8(t);
; #pragma unroll
;                 for (int e = 0; e < 8; ++e) t[e] = -t[e] * av[e];
;                 *(u32x4*)(NB + off) = pack8(t);
;                 asm volatile("" ::: "memory"); }
	v_lshlrev_b32_e32 v126, 16, v60
	v_add_f32_e32 v48, v48, v108
	v_add_f32_e32 v52, v52, v112
	v_mul_f32_e32 v52, 0xbfb8aa3b, v52
	v_add_f32_e32 v49, v49, v109
	v_add_f32_e32 v53, v53, v113
	v_exp_f32_e32 v52, v52
	v_add_f32_e32 v50, v50, v110
	v_add_f32_e32 v54, v54, v114
	v_add_f32_e32 v51, v51, v111
	v_add_f32_e32 v55, v55, v115
	v_mul_f32_e32 v48, 0xbfb8aa3b, v48
	v_mul_f32_e32 v49, 0xbfb8aa3b, v49
	v_mul_f32_e32 v53, 0xbfb8aa3b, v53
	v_mul_f32_e32 v50, 0xbfb8aa3b, v50
	v_mul_f32_e32 v54, 0xbfb8aa3b, v54
	v_mul_f32_e32 v51, 0xbfb8aa3b, v51
	v_mul_f32_e32 v55, 0xbfb8aa3b, v55
	v_exp_f32_e32 v48, v48
	v_exp_f32_e32 v49, v49
	v_exp_f32_e32 v53, v53
	v_exp_f32_e32 v50, v50
	v_exp_f32_e32 v54, v54
	v_exp_f32_e32 v51, v51
	v_exp_f32_e32 v55, v55
	v_add_f32_e32 v52, 1.0, v52
	v_rcp_f32_e32 v109, v52
	v_add_f32_e32 v48, 1.0, v48
	v_add_f32_e32 v49, 1.0, v49
	v_add_f32_e32 v53, 1.0, v53
	v_add_f32_e32 v50, 1.0, v50
	v_add_f32_e32 v54, 1.0, v54
	v_add_f32_e32 v51, 1.0, v51
	v_add_f32_e32 v55, 1.0, v55
	v_rcp_f32_e32 v108, v48
	v_rcp_f32_e32 v110, v49
	v_rcp_f32_e32 v111, v53
	v_rcp_f32_e32 v112, v50
	v_rcp_f32_e32 v113, v54
	v_rcp_f32_e32 v114, v51
	v_rcp_f32_e32 v115, v55
	v_add_f32_e32 v49, -1.0, v109
	v_fma_f32 v49, v120, v49, 1.0
	v_add_f32_e32 v48, -1.0, v108
	v_mul_f32_e32 v50, v49, v126
	v_add_f32_e32 v49, -1.0, v110
	v_add_f32_e32 v51, -1.0, v111
	v_lshlrev_b32_e32 v100, 16, v58
	v_and_b32_e32 v101, 0xffff0000, v58
	v_and_b32_e32 v127, 0xffff0000, v60
	v_fma_f32 v48, v116, v48, 1.0
	v_fma_f32 v49, v117, v49, 1.0
	v_fma_f32 v51, v121, v51, 1.0
	v_add_f32_e32 v52, -1.0, v112
	v_add_f32_e32 v53, -1.0, v113
	v_add_f32_e32 v54, -1.0, v114
	v_add_f32_e32 v55, -1.0, v115
	v_lshlrev_b32_e32 v124, 16, v59
	v_and_b32_e32 v125, 0xffff0000, v59
	v_lshlrev_b32_e32 v128, 16, v61
	v_and_b32_e32 v129, 0xffff0000, v61
	v_mul_f32_e32 v48, v48, v100
	v_mul_f32_e32 v49, v49, v101
	v_mul_f32_e32 v51, v51, v127
	v_fma_f32 v52, v118, v52, 1.0
	v_fma_f32 v53, v122, v53, 1.0
	v_fma_f32 v54, v119, v54, 1.0
	v_fma_f32 v55, v123, v55, 1.0
	v_lshl_add_u32 v58, v98, 3, s24
	v_mul_f32_e32 v52, v52, v124
	v_mul_f32_e32 v53, v53, v128
	v_mul_f32_e32 v54, v54, v125
	v_mul_f32_e32 v55, v55, v129
	v_cvt_pk_bf16_f32 v48, v48, v49
	v_cvt_pk_bf16_f32 v49, v52, v54
	v_cvt_pk_bf16_f32 v50, v50, v51
	v_cvt_pk_bf16_f32 v51, v53, v55
	global_store_dwordx4 v[62:63], v[48:51], off offset:1024
	v_ashrrev_i32_e32 v59, 31, v58
	global_load_dwordx4 v[48:51], v[56:57], off
	global_load_dwordx4 v[52:55], v[56:57], off offset:16
	v_lshl_add_u64 v[58:59], v[58:59], 2, s[4:5]
	global_load_dword v116, v[58:59], off
	v_lshlrev_b64 v[60:61], 9, v[98:99]
	v_lshl_add_u64 v[60:61], v[60:61], 0, v[78:79]
	v_mad_i64_i32 v[58:59], s[26:27], v96, s68, v[76:77]
	v_lshlrev_b64 v[60:61], 1, v[60:61]
	v_lshl_add_u64 v[62:63], v[58:59], 0, v[82:83]
	v_lshl_add_u64 v[58:59], s[50:51], 0, v[60:61]
	v_lshl_add_u64 v[60:61], s[62:63], 0, v[60:61]
	s_waitcnt vmcnt(0)
	v_mul_f32_e32 v48, v48, v100
	v_mul_f32_e32 v52, v52, v126
	v_mul_f32_e32 v49, v49, v101
	v_mul_f32_e32 v53, v53, v127
	v_mul_f32_e32 v50, v50, v124
	v_mul_f32_e32 v54, v54, v128
	v_mul_f32_e32 v51, v51, v125
	v_mul_f32_e32 v55, v55, v129
	v_mul_f32_e32 v98, v48, v116
	v_mul_f32_e32 v52, v116, v52
	v_mul_f32_e32 v99, v49, v116
	v_mul_f32_e32 v53, v116, v53
	v_mul_f32_e32 v100, v50, v116
	v_mul_f32_e32 v54, v116, v54
	v_mul_f32_e32 v101, v51, v116
	v_mul_f32_e32 v55, v116, v55
	v_cvt_pk_bf16_f32 v48, v98, v99
	v_cvt_pk_bf16_f32 v49, v100, v101
	v_cvt_pk_bf16_f32 v50, v52, v53
	v_cvt_pk_bf16_f32 v51, v54, v55
	v_mul_f32_e64 v98, v108, -v98
	v_mul_f32_e64 v99, v110, -v99
	v_mul_f32_e64 v100, v112, -v100
	v_mul_f32_e64 v101, v114, -v101
	v_mul_f32_e64 v52, v109, -v52
	v_mul_f32_e64 v53, v111, -v53
	v_mul_f32_e64 v54, v113, -v54
	v_mul_f32_e64 v55, v115, -v55
	global_store_dwordx4 v[58:59], v[48:51], off
	s_nop 1
	v_cvt_pk_bf16_f32 v48, v98, v99
	v_cvt_pk_bf16_f32 v49, v100, v101
	v_cvt_pk_bf16_f32 v50, v52, v53
	v_cvt_pk_bf16_f32 v51, v54, v55
	global_store_dwordx4 v[60:61], v[48:51], off
	global_load_dwordx4 v[48:51], v[62:63], off offset:1024
	global_load_dwordx4 v[52:55], v[84:85], off
	global_load_dwordx4 v[58:61], v[84:85], off offset:16
	global_load_dwordx4 v[98:101], v[86:87], off
	global_load_dwordx4 v[108:111], v[86:87], off offset:16
	s_waitcnt vmcnt(0)
; __device__ __forceinline__ void unpack8(const u32x4 w, float (&f)[8]) { f[0] = bflo(w.x); f[1] = bfhi(w.x); f[2] = bflo(w.y); f[3] = bfhi(w.y); f[4] = bflo(w.z); f[5] = bfhi(w.z); f[6] = bflo(w.w); f[7] = bfhi(w.w); }
; __device__ __forceinline__ u32x4 pack8(const float (&f)[8]) { u32x4 o; o.x = pk2(f[0], f[1]); o.y = pk2(f[2], f[3]); o.z = pk2(f[4], f[5]); o.w = pk2(f[6], f[7]); return o; }
; __device__ __forceinline__ float sigmoidf_(float x) { return __builtin_amdgcn_rcpf(1.0f + __expf(-x)); }
;     __device__ __forceinline__ void operator()(const f32x4 (&acc)[2][2][4][2], const Unit& u, int wr, int wc, int fr, int fq) const {
;     ...
;             for (int m = 0; m < 4; ++m) { const int row = row0 + ai * HALF + m * 16; const size_t off = (size_t)row * 512 + cb; bf16_t* kp = RKV + (size_t)row * 1536 + 512 + cb;
;                 float ks[8], av[8], t[8]; unpack8(*(const u32x4*)kp, ks);
;                 { const f32x4 c0 = *(const f32x4*)(a0 + cb), c1 = *(const f32x4*)(a0 + cb + 4); const f32x4 x0 = acc[ai][0][m][0], x1 = acc[ai][0][m][1];
; #pragma unroll
;                   for (int j = 0; j < 4; ++j) { av[j] = sigmoidf_(c0[j] + x0[j]); av[4 + j] = sigmoidf_(c1[j] + x1[j]); } }
;                 { const f32x4 c0 = *(const f32x4*)(k_a + cb), c1 = *(const f32x4*)(k_a + cb + 4);
; #pragma unroll
;                   for (int j = 0; j < 4; ++j) { t[j] = ks[j] * (1.0f + (av[j] - 1.0f) * c0[j]); t[4 + j] = ks[4 + j] * (1.0f + (av[4 + j] - 1.0f) * c1[j]); } }
;                 *(u32x4*)kp = pack8(t);
;                 { const f32x4 c0 = *(const f32x4*)(k_k + cb), c1 = *(const f32x4*)(k_k + cb + 4); const float ri = rinv[row * 8 + (cb >> 6)];
; #pragma unroll
;                   for (int j = 0; j < 4; ++j) { t[j] = ks[j] * c0[j] * ri; t[4 + j] = ks[4 + j] * c1[j] * ri; } }
;                 *(u32x4*)(KK + off) = pack8(t);
; #pragma unroll
;                 for (int e = 0; e < 8; ++e) t[e] = -t[e] * av[e];
;                 *(u32x4*)(NB + off) = pack8(t);
;                 asm volatile("" ::: "memory"); }
	v_and_b32_e32 v113, 0xffff0000, v48
	v_add_f32_e32 v41, v41, v53
	v_add_f32_e32 v44, v44, v58
	v_add_f32_e32 v45, v45, v59
	v_add_f32_e32 v40, v40, v52
	v_add_f32_e32 v42, v42, v54
	v_mul_f32_e32 v44, 0xbfb8aa3b, v44
	v_mul_f32_e32 v41, 0xbfb8aa3b, v41
	v_mul_f32_e32 v45, 0xbfb8aa3b, v45
	v_add_f32_e32 v46, v46, v60
	v_add_f32_e32 v43, v43, v55
	v_add_f32_e32 v47, v47, v61
	v_mul_f32_e32 v40, 0xbfb8aa3b, v40
	v_mul_f32_e32 v42, 0xbfb8aa3b, v42
	v_exp_f32_e32 v44, v44
	v_exp_f32_e32 v41, v41
	v_exp_f32_e32 v45, v45
	v_mul_f32_e32 v46, 0xbfb8aa3b, v46
	v_mul_f32_e32 v43, 0xbfb8aa3b, v43
	v_mul_f32_e32 v47, 0xbfb8aa3b, v47
	v_exp_f32_e32 v40, v40
	v_exp_f32_e32 v42, v42
	v_exp_f32_e32 v46, v46
	v_exp_f32_e32 v43, v43
	v_exp_f32_e32 v47, v47
	v_add_f32_e32 v44, 1.0, v44
	v_add_f32_e32 v41, 1.0, v41
	v_add_f32_e32 v45, 1.0, v45
	v_add_f32_e32 v40, 1.0, v40
	v_add_f32_e32 v42, 1.0, v42
	v_rcp_f32_e32 v53, v44
	v_rcp_f32_e32 v54, v41
	v_rcp_f32_e32 v55, v45
	v_add_f32_e32 v46, 1.0, v46
	v_add_f32_e32 v43, 1.0, v43
	v_add_f32_e32 v47, 1.0, v47
	v_rcp_f32_e32 v52, v40
	v_rcp_f32_e32 v58, v42
	v_rcp_f32_e32 v59, v46
	v_rcp_f32_e32 v60, v43
	v_rcp_f32_e32 v61, v47
	v_add_f32_e32 v41, -1.0, v53
	v_add_f32_e32 v42, -1.0, v54
	v_add_f32_e32 v43, -1.0, v55
	v_lshlrev_b32_e32 v116, 16, v50
	v_and_b32_e32 v117, 0xffff0000, v50
	v_add_f32_e32 v40, -1.0, v52
	v_add_f32_e32 v44, -1.0, v58
	v_fma_f32 v41, v108, v41, 1.0
	v_fma_f32 v42, v99, v42, 1.0
	v_fma_f32 v43, v109, v43, 1.0
	v_lshlrev_b32_e32 v112, 16, v48
	v_lshlrev_b32_e32 v114, 16, v49
	v_add_f32_e32 v45, -1.0, v59
	v_add_f32_e32 v46, -1.0, v60
	v_add_f32_e32 v47, -1.0, v61
	v_fma_f32 v40, v98, v40, 1.0
	v_fma_f32 v44, v100, v44, 1.0
	v_mul_f32_e32 v48, v41, v116
	v_mul_f32_e32 v41, v42, v113
	v_mul_f32_e32 v42, v43, v117
	v_and_b32_e32 v115, 0xffff0000, v49
	v_lshlrev_b32_e32 v118, 16, v51
	v_and_b32_e32 v119, 0xffff0000, v51
	v_fma_f32 v45, v110, v45, 1.0
	v_fma_f32 v46, v101, v46, 1.0
	v_fma_f32 v47, v111, v47, 1.0
	v_mul_f32_e32 v40, v40, v112
	v_mul_f32_e32 v43, v44, v114
	v_cvt_pk_bf16_f32 v42, v48, v42
	v_lshl_add_u32 v48, v96, 3, s24
	v_mul_f32_e32 v44, v45, v118
	v_mul_f32_e32 v45, v46, v115
	v_mul_f32_e32 v46, v47, v119
	v_cvt_pk_bf16_f32 v40, v40, v41
	v_cvt_pk_bf16_f32 v41, v43, v45
	v_cvt_pk_bf16_f32 v43, v44, v46
	global_store_dwordx4 v[62:63], v[40:43], off offset:1024
	v_ashrrev_i32_e32 v49, 31, v48
	global_load_dwordx4 v[40:43], v[56:57], off
	global_load_dwordx4 v[44:47], v[56:57], off offset:16
	v_lshl_add_u64 v[48:49], v[48:49], 2, s[4:5]
	global_load_dword v98, v[48:49], off
	v_lshlrev_b64 v[50:51], 9, v[96:97]
	v_lshl_add_u64 v[50:51], v[50:51], 0, v[78:79]
	v_mad_i64_i32 v[48:49], s[26:27], v94, s68, v[76:77]
	v_lshlrev_b64 v[50:51], 1, v[50:51]
	v_lshl_add_u64 v[62:63], v[48:49], 0, v[82:83]
	v_lshl_add_u64 v[48:49], s[50:51], 0, v[50:51]
	v_lshl_add_u64 v[50:51], s[62:63], 0, v[50:51]
	s_waitcnt vmcnt(0)
	v_mul_f32_e32 v40, v40, v112
	v_mul_f32_e32 v44, v44, v116
	v_mul_f32_e32 v41, v41, v113
	v_mul_f32_e32 v45, v45, v117
	v_mul_f32_e32 v42, v42, v114
	v_mul_f32_e32 v46, v46, v118
	v_mul_f32_e32 v43, v43, v115
	v_mul_f32_e32 v47, v47, v119
	v_mul_f32_e32 v96, v40, v98
	v_mul_f32_e32 v44, v98, v44
	v_mul_f32_e32 v97, v41, v98
	v_mul_f32_e32 v45, v98, v45
	v_mul_f32_e32 v99, v42, v98
	v_mul_f32_e32 v46, v98, v46
	v_mul_f32_e32 v100, v43, v98
	v_mul_f32_e32 v47, v98, v47
	v_cvt_pk_bf16_f32 v40, v96, v97
	v_cvt_pk_bf16_f32 v41, v99, v100
	v_cvt_pk_bf16_f32 v42, v44, v45
	v_cvt_pk_bf16_f32 v43, v46, v47
	v_mul_f32_e64 v52, v52, -v96
	v_mul_f32_e64 v54, v54, -v97
	v_mul_f32_e64 v58, v58, -v99
	v_mul_f32_e64 v60, v60, -v100
	v_mul_f32_e64 v44, v53, -v44
	v_mul_f32_e64 v45, v55, -v45
	v_mul_f32_e64 v46, v59, -v46
	v_mul_f32_e64 v47, v61, -v47
	global_store_dwordx4 v[48:49], v[40:43], off
	s_nop 1
	v_cvt_pk_bf16_f32 v40, v52, v54
	v_cvt_pk_bf16_f32 v41, v58, v60
	v_cvt_pk_bf16_f32 v42, v44, v45
	v_cvt_pk_bf16_f32 v43, v46, v47
	global_store_dwordx4 v[50:51], v[40:43], off
	global_load_dwordx4 v[40:43], v[62:63], off offset:1024
	global_load_dwordx4 v[44:47], v[84:85], off
	global_load_dwordx4 v[48:51], v[84:85], off offset:16
	global_load_dwordx4 v[52:55], v[86:87], off
	global_load_dwordx4 v[58:61], v[86:87], off offset:16
	s_waitcnt vmcnt(0)
; __device__ __forceinline__ void unpack8(const u32x4 w, float (&f)[8]) { f[0] = bflo(w.x); f[1] = bfhi(w.x); f[2] = bflo(w.y); f[3] = bfhi(w.y); f[4] = bflo(w.z); f[5] = bfhi(w.z); f[6] = bflo(w.w); f[7] = bfhi(w.w); }
; __device__ __forceinline__ u32x4 pack8(const float (&f)[8]) { u32x4 o; o.x = pk2(f[0], f[1]); o.y = pk2(f[2], f[3]); o.z = pk2(f[4], f[5]); o.w = pk2(f[6], f[7]); return o; }
; __device__ __forceinline__ float sigmoidf_(float x) { return __builtin_amdgcn_rcpf(1.0f + __expf(-x)); }
;     __device__ __forceinline__ void operator()(const f32x4 (&acc)[2][2][4][2], const Unit& u, int wr, int wc, int fr, int fq) const {
;     ...
;             for (int m = 0; m < 4; ++m) { const int row = row0 + ai * HALF + m * 16; const size_t off = (size_t)row * 512 + cb; bf16_t* kp = RKV + (size_t)row * 1536 + 512 + cb;
;                 float ks[8], av[8], t[8]; unpack8(*(const u32x4*)kp, ks);
;                 { const f32x4 c0 = *(const f32x4*)(a0 + cb), c1 = *(const f32x4*)(a0 + cb + 4); const f32x4 x0 = acc[ai][0][m][0], x1 = acc[ai][0][m][1];
; #pragma unroll
;                   for (int j = 0; j < 4; ++j) { av[j] = sigmoidf_(c0[j] + x0[j]); av[4 + j] = sigmoidf_(c1[j] + x1[j]); } }
;                 { const f32x4 c0 = *(const f32x4*)(k_a + cb), c1 = *(const f32x4*)(k_a + cb + 4);
; #pragma unroll
;                   for (int j = 0; j < 4; ++j) { t[j] = ks[j] * (1.0f + (av[j] - 1.0f) * c0[j]); t[4 + j] = ks[4 + j] * (1.0f + (av[4 + j] - 1.0f) * c1[j]); } }
;                 *(u32x4*)kp = pack8(t);
;                 { const f32x4 c0 = *(const f32x4*)(k_k + cb), c1 = *(const f32x4*)(k_k + cb + 4); const float ri = rinv[row * 8 + (cb >> 6)];
; #pragma unroll
;                   for (int j = 0; j < 4; ++j) { t[j] = ks[j] * c0[j] * ri; t[4 + j] = ks[4 + j] * c1[j] * ri; } }
;                 *(u32x4*)(KK + off) = pack8(t);
; #pragma unroll
;                 for (int e = 0; e < 8; ++e) t[e] = -t[e] * av[e];
;                 *(u32x4*)(NB + off) = pack8(t);
;                 asm volatile("" ::: "memory"); }
	v_and_b32_e32 v97, 0xffff0000, v40
	v_add_f32_e32 v33, v33, v45
	v_add_f32_e32 v36, v36, v48
	v_add_f32_e32 v37, v37, v49
	v_add_f32_e32 v32, v32, v44
	v_add_f32_e32 v34, v34, v46
	v_mul_f32_e32 v36, 0xbfb8aa3b, v36
	v_mul_f32_e32 v33, 0xbfb8aa3b, v33
	v_mul_f32_e32 v37, 0xbfb8aa3b, v37
	v_add_f32_e32 v38, v38, v50
	v_add_f32_e32 v35, v35, v47
	v_add_f32_e32 v39, v39, v51
	v_mul_f32_e32 v32, 0xbfb8aa3b, v32
	v_mul_f32_e32 v34, 0xbfb8aa3b, v34
	v_exp_f32_e32 v36, v36
	v_exp_f32_e32 v33, v33
	v_exp_f32_e32 v37, v37
	v_mul_f32_e32 v38, 0xbfb8aa3b, v38
	v_mul_f32_e32 v35, 0xbfb8aa3b, v35
	v_mul_f32_e32 v39, 0xbfb8aa3b, v39
	v_exp_f32_e32 v32, v32
	v_exp_f32_e32 v34, v34
	v_exp_f32_e32 v38, v38
	v_exp_f32_e32 v35, v35
	v_exp_f32_e32 v39, v39
	v_add_f32_e32 v36, 1.0, v36
	v_add_f32_e32 v33, 1.0, v33
	v_add_f32_e32 v37, 1.0, v37
	v_add_f32_e32 v32, 1.0, v32
	v_add_f32_e32 v34, 1.0, v34
	v_rcp_f32_e32 v45, v36
	v_rcp_f32_e32 v46, v33
	v_rcp_f32_e32 v47, v37
	v_add_f32_e32 v38, 1.0, v38
	v_add_f32_e32 v35, 1.0, v35
	v_add_f32_e32 v39, 1.0, v39
	v_rcp_f32_e32 v44, v32
	v_rcp_f32_e32 v48, v34
	v_rcp_f32_e32 v49, v38
	v_rcp_f32_e32 v50, v35
	v_rcp_f32_e32 v51, v39
	v_add_f32_e32 v33, -1.0, v45
	v_add_f32_e32 v34, -1.0, v46
	v_add_f32_e32 v35, -1.0, v47
	v_lshlrev_b32_e32 v100, 16, v42
	v_and_b32_e32 v101, 0xffff0000, v42
	v_add_f32_e32 v32, -1.0, v44
	v_add_f32_e32 v36, -1.0, v48
	v_fma_f32 v33, v58, v33, 1.0
	v_fma_f32 v34, v53, v34, 1.0
	v_fma_f32 v35, v59, v35, 1.0
	v_lshlrev_b32_e32 v96, 16, v40
	v_lshlrev_b32_e32 v98, 16, v41
	v_add_f32_e32 v37, -1.0, v49
	v_add_f32_e32 v38, -1.0, v50
	v_add_f32_e32 v39, -1.0, v51
	v_fma_f32 v32, v52, v32, 1.0
	v_fma_f32 v36, v54, v36, 1.0
	v_mul_f32_e32 v40, v33, v100
	v_mul_f32_e32 v33, v34, v97
	v_mul_f32_e32 v34, v35, v101
	v_and_b32_e32 v99, 0xffff0000, v41
	v_lshlrev_b32_e32 v108, 16, v43
	v_and_b32_e32 v109, 0xffff0000, v43
	v_fma_f32 v37, v60, v37, 1.0
	v_fma_f32 v38, v55, v38, 1.0
	v_fma_f32 v39, v61, v39, 1.0
	v_mul_f32_e32 v32, v32, v96
	v_mul_f32_e32 v35, v36, v98
	v_cvt_pk_bf16_f32 v34, v40, v34
	v_lshl_add_u32 v40, v94, 3, s24
	v_mul_f32_e32 v36, v37, v108
	v_mul_f32_e32 v37, v38, v99
	v_mul_f32_e32 v38, v39, v109
	v_cvt_pk_bf16_f32 v32, v32, v33
	v_cvt_pk_bf16_f32 v33, v35, v37
	v_cvt_pk_bf16_f32 v35, v36, v38
	global_store_dwordx4 v[62:63], v[32:35], off offset:1024
	v_ashrrev_i32_e32 v41, 31, v40
	global_load_dwordx4 v[32:35], v[56:57], off
	global_load_dwordx4 v[36:39], v[56:57], off offset:16
	v_lshl_add_u64 v[40:41], v[40:41], 2, s[4:5]
	global_load_dword v54, v[40:41], off
	v_lshlrev_b64 v[42:43], 9, v[94:95]
	v_lshl_add_u64 v[42:43], v[42:43], 0, v[78:79]
	v_mad_i64_i32 v[40:41], s[26:27], v92, s68, v[76:77]
	v_lshlrev_b64 v[42:43], 1, v[42:43]
	v_lshl_add_u64 v[52:53], v[40:41], 0, v[82:83]
	v_lshl_add_u64 v[40:41], s[50:51], 0, v[42:43]
	v_lshl_add_u64 v[42:43], s[62:63], 0, v[42:43]
	s_waitcnt vmcnt(0)
	v_mul_f32_e32 v32, v32, v96
	v_mul_f32_e32 v36, v36, v100
	v_mul_f32_e32 v33, v33, v97
	v_mul_f32_e32 v37, v37, v101
	v_mul_f32_e32 v34, v34, v98
	v_mul_f32_e32 v38, v38, v108
	v_mul_f32_e32 v35, v35, v99
	v_mul_f32_e32 v39, v39, v109
	v_mul_f32_e32 v55, v32, v54
	v_mul_f32_e32 v36, v54, v36
	v_mul_f32_e32 v58, v33, v54
	v_mul_f32_e32 v37, v54, v37
	v_mul_f32_e32 v59, v34, v54
	v_mul_f32_e32 v38, v54, v38
	v_mul_f32_e32 v60, v35, v54
	v_mul_f32_e32 v39, v54, v39
	v_cvt_pk_bf16_f32 v32, v55, v58
	v_cvt_pk_bf16_f32 v33, v59, v60
	v_cvt_pk_bf16_f32 v34, v36, v37
	v_cvt_pk_bf16_f32 v35, v38, v39
	v_mul_f32_e64 v44, v44, -v55
	v_mul_f32_e64 v46, v46, -v58
	v_mul_f32_e64 v48, v48, -v59
	v_mul_f32_e64 v50, v50, -v60
	v_mul_f32_e64 v36, v45, -v36
	v_mul_f32_e64 v37, v47, -v37
	v_mul_f32_e64 v38, v49, -v38
	v_mul_f32_e64 v39, v51, -v39
	global_store_dwordx4 v[40:41], v[32:35], off
	s_nop 1
	v_cvt_pk_bf16_f32 v32, v44, v46
	v_cvt_pk_bf16_f32 v33, v48, v50
	v_cvt_pk_bf16_f32 v34, v36, v37
	v_cvt_pk_bf16_f32 v35, v38, v39
	global_store_dwordx4 v[42:43], v[32:35], off
	global_load_dwordx4 v[32:35], v[52:53], off offset:1024
	global_load_dwordx4 v[36:39], v[84:85], off
	global_load_dwordx4 v[40:43], v[84:85], off offset:16
	global_load_dwordx4 v[44:47], v[86:87], off
	global_load_dwordx4 v[48:51], v[86:87], off offset:16
	s_waitcnt vmcnt(0)
; __device__ __forceinline__ void unpack8(const u32x4 w, float (&f)[8]) { f[0] = bflo(w.x); f[1] = bfhi(w.x); f[2] = bflo(w.y); f[3] = bfhi(w.y); f[4] = bflo(w.z); f[5] = bfhi(w.z); f[6] = bflo(w.w); f[7] = bfhi(w.w); }
; __device__ __forceinline__ u32x4 pack8(const float (&f)[8]) { u32x4 o; o.x = pk2(f[0], f[1]); o.y = pk2(f[2], f[3]); o.z = pk2(f[4], f[5]); o.w = pk2(f[6], f[7]); return o; }
; __device__ __forceinline__ float sigmoidf_(float x) { return __builtin_amdgcn_rcpf(1.0f + __expf(-x)); }
;     __device__ __forceinline__ void operator()(const f32x4 (&acc)[2][2][4][2], const Unit& u, int wr, int wc, int fr, int fq) const {
;     ...
;             for (int m = 0; m < 4; ++m) { const int row = row0 + ai * HALF + m * 16; const size_t off = (size_t)row * 512 + cb; bf16_t* kp = RKV + (size_t)row * 1536 + 512 + cb;
;                 float ks[8], av[8], t[8]; unpack8(*(const u32x4*)kp, ks);
;                 { const f32x4 c0 = *(const f32x4*)(a0 + cb), c1 = *(const f32x4*)(a0 + cb + 4); const f32x4 x0 = acc[ai][0][m][0], x1 = acc[ai][0][m][1];
; #pragma unroll
;                   for (int j = 0; j < 4; ++j) { av[j] = sigmoidf_(c0[j] + x0[j]); av[4 + j] = sigmoidf_(c1[j] + x1[j]); } }
;                 { const f32x4 c0 = *(const f32x4*)(k_a + cb), c1 = *(const f32x4*)(k_a + cb + 4);
; #pragma unroll
;                   for (int j = 0; j < 4; ++j) { t[j] = ks[j] * (1.0f + (av[j] - 1.0f) * c0[j]); t[4 + j] = ks[4 + j] * (1.0f + (av[4 + j] - 1.0f) * c1[j]); } }
;                 *(u32x4*)kp = pack8(t);
;                 { const f32x4 c0 = *(const f32x4*)(k_k + cb), c1 = *(const f32x4*)(k_k + cb + 4); const float ri = rinv[row * 8 + (cb >> 6)];
; #pragma unroll
;                   for (int j = 0; j < 4; ++j) { t[j] = ks[j] * c0[j] * ri; t[4 + j] = ks[4 + j] * c1[j] * ri; } }
;                 *(u32x4*)(KK + off) = pack8(t);
; #pragma unroll
;                 for (int e = 0; e < 8; ++e) t[e] = -t[e] * av[e];
;                 *(u32x4*)(NB + off) = pack8(t);
;                 asm volatile("" ::: "memory"); }
	v_and_b32_e32 v55, 0xffff0000, v32
	v_add_f32_e32 v25, v25, v37
	v_add_f32_e32 v28, v28, v40
	v_add_f32_e32 v29, v29, v41
	v_add_f32_e32 v24, v24, v36
	v_add_f32_e32 v26, v26, v38
	v_mul_f32_e32 v28, 0xbfb8aa3b, v28
	v_mul_f32_e32 v25, 0xbfb8aa3b, v25
	v_mul_f32_e32 v29, 0xbfb8aa3b, v29
	v_add_f32_e32 v30, v30, v42
	v_add_f32_e32 v27, v27, v39
	v_add_f32_e32 v31, v31, v43
	v_mul_f32_e32 v24, 0xbfb8aa3b, v24
	v_mul_f32_e32 v26, 0xbfb8aa3b, v26
	v_exp_f32_e32 v28, v28
	v_exp_f32_e32 v25, v25
	v_exp_f32_e32 v29, v29
	v_mul_f32_e32 v30, 0xbfb8aa3b, v30
	v_mul_f32_e32 v27, 0xbfb8aa3b, v27
	v_mul_f32_e32 v31, 0xbfb8aa3b, v31
	v_exp_f32_e32 v24, v24
	v_exp_f32_e32 v26, v26
	v_exp_f32_e32 v30, v30
	v_exp_f32_e32 v27, v27
	v_exp_f32_e32 v31, v31
	v_add_f32_e32 v28, 1.0, v28
	v_add_f32_e32 v25, 1.0, v25
	v_add_f32_e32 v29, 1.0, v29
	v_add_f32_e32 v24, 1.0, v24
	v_add_f32_e32 v26, 1.0, v26
	v_rcp_f32_e32 v37, v28
	v_rcp_f32_e32 v38, v25
	v_rcp_f32_e32 v39, v29
	v_add_f32_e32 v30, 1.0, v30
	v_add_f32_e32 v27, 1.0, v27
	v_add_f32_e32 v31, 1.0, v31
	v_rcp_f32_e32 v36, v24
	v_rcp_f32_e32 v40, v26
	v_rcp_f32_e32 v41, v30
	v_rcp_f32_e32 v42, v27
	v_rcp_f32_e32 v43, v31
	v_add_f32_e32 v25, -1.0, v37
	v_add_f32_e32 v26, -1.0, v38
	v_add_f32_e32 v27, -1.0, v39
	v_lshlrev_b32_e32 v60, 16, v34
	v_and_b32_e32 v61, 0xffff0000, v34
	v_add_f32_e32 v24, -1.0, v36
	v_add_f32_e32 v28, -1.0, v40
	v_fma_f32 v25, v48, v25, 1.0
	v_fma_f32 v26, v45, v26, 1.0
	v_fma_f32 v27, v49, v27, 1.0
	v_lshlrev_b32_e32 v54, 16, v32
	v_lshlrev_b32_e32 v58, 16, v33
	v_add_f32_e32 v29, -1.0, v41
	v_add_f32_e32 v30, -1.0, v42
	v_add_f32_e32 v31, -1.0, v43
	v_fma_f32 v24, v44, v24, 1.0
	v_fma_f32 v28, v46, v28, 1.0
	v_mul_f32_e32 v32, v25, v60
	v_mul_f32_e32 v25, v26, v55
	v_mul_f32_e32 v26, v27, v61
	v_and_b32_e32 v59, 0xffff0000, v33
	v_lshlrev_b32_e32 v62, 16, v35
	v_and_b32_e32 v63, 0xffff0000, v35
	v_fma_f32 v29, v50, v29, 1.0
	v_fma_f32 v30, v47, v30, 1.0
	v_fma_f32 v31, v51, v31, 1.0
	v_mul_f32_e32 v24, v24, v54
	v_mul_f32_e32 v27, v28, v58
	v_cvt_pk_bf16_f32 v26, v32, v26
	v_lshl_add_u32 v32, v92, 3, s24
	v_mul_f32_e32 v28, v29, v62
	v_mul_f32_e32 v29, v30, v59
	v_mul_f32_e32 v30, v31, v63
	v_cvt_pk_bf16_f32 v24, v24, v25
	v_cvt_pk_bf16_f32 v25, v27, v29
	v_cvt_pk_bf16_f32 v27, v28, v30
	global_store_dwordx4 v[52:53], v[24:27], off offset:1024
	v_ashrrev_i32_e32 v33, 31, v32
	global_load_dwordx4 v[24:27], v[56:57], off
	global_load_dwordx4 v[28:31], v[56:57], off offset:16
	v_lshl_add_u64 v[32:33], v[32:33], 2, s[4:5]
	global_load_dword v46, v[32:33], off
	v_lshlrev_b64 v[34:35], 9, v[92:93]
	v_lshl_add_u64 v[34:35], v[34:35], 0, v[78:79]
	v_mad_i64_i32 v[32:33], s[26:27], v90, s68, v[76:77]
	v_lshlrev_b64 v[34:35], 1, v[34:35]
	v_lshl_add_u64 v[44:45], v[32:33], 0, v[82:83]
	v_lshl_add_u64 v[32:33], s[50:51], 0, v[34:35]
	v_lshl_add_u64 v[34:35], s[62:63], 0, v[34:35]
	s_waitcnt vmcnt(0)
	v_mul_f32_e32 v24, v24, v54
	v_mul_f32_e32 v28, v28, v60
	v_mul_f32_e32 v25, v25, v55
	v_mul_f32_e32 v29, v29, v61
	v_mul_f32_e32 v26, v26, v58
	v_mul_f32_e32 v30, v30, v62
	v_mul_f32_e32 v27, v27, v59
	v_mul_f32_e32 v31, v31, v63
	v_mul_f32_e32 v47, v24, v46
	v_mul_f32_e32 v28, v46, v28
	v_mul_f32_e32 v48, v25, v46
	v_mul_f32_e32 v29, v46, v29
	v_mul_f32_e32 v49, v26, v46
	v_mul_f32_e32 v30, v46, v30
	v_mul_f32_e32 v50, v27, v46
	v_mul_f32_e32 v31, v46, v31
	v_cvt_pk_bf16_f32 v24, v47, v48
	v_cvt_pk_bf16_f32 v25, v49, v50
	v_cvt_pk_bf16_f32 v26, v28, v29
	v_cvt_pk_bf16_f32 v27, v30, v31
	v_mul_f32_e64 v36, v36, -v47
	v_mul_f32_e64 v38, v38, -v48
	v_mul_f32_e64 v40, v40, -v49
	v_mul_f32_e64 v42, v42, -v50
	v_mul_f32_e64 v28, v37, -v28
	v_mul_f32_e64 v29, v39, -v29
	v_mul_f32_e64 v30, v41, -v30
	v_mul_f32_e64 v31, v43, -v31
	global_store_dwordx4 v[32:33], v[24:27], off
	s_nop 1
	v_cvt_pk_bf16_f32 v24, v36, v38
	v_cvt_pk_bf16_f32 v25, v40, v42
	v_cvt_pk_bf16_f32 v26, v28, v29
	v_cvt_pk_bf16_f32 v27, v30, v31
	global_store_dwordx4 v[34:35], v[24:27], off
	global_load_dwordx4 v[24:27], v[44:45], off offset:1024
	global_load_dwordx4 v[28:31], v[84:85], off
	global_load_dwordx4 v[32:35], v[84:85], off offset:16
	global_load_dwordx4 v[36:39], v[86:87], off
	global_load_dwordx4 v[40:43], v[86:87], off offset:16
	s_waitcnt vmcnt(0)
; __device__ __forceinline__ void unpack8(const u32x4 w, float (&f)[8]) { f[0] = bflo(w.x); f[1] = bfhi(w.x); f[2] = bflo(w.y); f[3] = bfhi(w.y); f[4] = bflo(w.z); f[5] = bfhi(w.z); f[6] = bflo(w.w); f[7] = bfhi(w.w); }
; __device__ __forceinline__ u32x4 pack8(const float (&f)[8]) { u32x4 o; o.x = pk2(f[0], f[1]); o.y = pk2(f[2], f[3]); o.z = pk2(f[4], f[5]); o.w = pk2(f[6], f[7]); return o; }
; __device__ __forceinline__ float sigmoidf_(float x) { return __builtin_amdgcn_rcpf(1.0f + __expf(-x)); }
;     __device__ __forceinline__ void operator()(const f32x4 (&acc)[2][2][4][2], const Unit& u, int wr, int wc, int fr, int fq) const {
;     ...
;             for (int m = 0; m < 4; ++m) { const int row = row0 + ai * HALF + m * 16; const size_t off = (size_t)row * 512 + cb; bf16_t* kp = RKV + (size_t)row * 1536 + 512 + cb;
;                 float ks[8], av[8], t[8]; unpack8(*(const u32x4*)kp, ks);
;                 { const f32x4 c0 = *(const f32x4*)(a0 + cb), c1 = *(const f32x4*)(a0 + cb + 4); const f32x4 x0 = acc[ai][0][m][0], x1 = acc[ai][0][m][1];
; #pragma unroll
;                   for (int j = 0; j < 4; ++j) { av[j] = sigmoidf_(c0[j] + x0[j]); av[4 + j] = sigmoidf_(c1[j] + x1[j]); } }
;                 { const f32x4 c0 = *(const f32x4*)(k_a + cb), c1 = *(const f32x4*)(k_a + cb + 4);
; #pragma unroll
;                   for (int j = 0; j < 4; ++j) { t[j] = ks[j] * (1.0f + (av[j] - 1.0f) * c0[j]); t[4 + j] = ks[4 + j] * (1.0f + (av[4 + j] - 1.0f) * c1[j]); } }
;                 *(u32x4*)kp = pack8(t);
;                 { const f32x4 c0 = *(const f32x4*)(k_k + cb), c1 = *(const f32x4*)(k_k + cb + 4); const float ri = rinv[row * 8 + (cb >> 6)];
; #pragma unroll
;                   for (int j = 0; j < 4; ++j) { t[j] = ks[j] * c0[j] * ri; t[4 + j] = ks[4 + j] * c1[j] * ri; } }
;                 *(u32x4*)(KK + off) = pack8(t);
; #pragma unroll
;                 for (int e = 0; e < 8; ++e) t[e] = -t[e] * av[e];
;                 *(u32x4*)(NB + off) = pack8(t);
;                 asm volatile("" ::: "memory"); }
	v_and_b32_e32 v47, 0xffff0000, v24
	v_add_f32_e32 v17, v17, v29
	v_add_f32_e32 v20, v20, v32
	v_add_f32_e32 v21, v21, v33
	v_add_f32_e32 v16, v16, v28
	v_add_f32_e32 v18, v18, v30
	v_mul_f32_e32 v20, 0xbfb8aa3b, v20
	v_mul_f32_e32 v17, 0xbfb8aa3b, v17
	v_mul_f32_e32 v21, 0xbfb8aa3b, v21
	v_add_f32_e32 v22, v22, v34
	v_add_f32_e32 v19, v19, v31
	v_add_f32_e32 v23, v23, v35
	v_mul_f32_e32 v16, 0xbfb8aa3b, v16
	v_mul_f32_e32 v18, 0xbfb8aa3b, v18
	v_exp_f32_e32 v20, v20
	v_exp_f32_e32 v17, v17
	v_exp_f32_e32 v21, v21
	v_mul_f32_e32 v22, 0xbfb8aa3b, v22
	v_mul_f32_e32 v19, 0xbfb8aa3b, v19
	v_mul_f32_e32 v23, 0xbfb8aa3b, v23
	v_exp_f32_e32 v16, v16
	v_exp_f32_e32 v18, v18
	v_exp_f32_e32 v22, v22
	v_exp_f32_e32 v19, v19
	v_exp_f32_e32 v23, v23
	v_add_f32_e32 v20, 1.0, v20
	v_add_f32_e32 v17, 1.0, v17
	v_add_f32_e32 v21, 1.0, v21
	v_add_f32_e32 v16, 1.0, v16
	v_add_f32_e32 v18, 1.0, v18
	v_rcp_f32_e32 v29, v20
	v_rcp_f32_e32 v30, v17
	v_rcp_f32_e32 v31, v21
	v_add_f32_e32 v22, 1.0, v22
	v_add_f32_e32 v19, 1.0, v19
	v_add_f32_e32 v23, 1.0, v23
	v_rcp_f32_e32 v28, v16
	v_rcp_f32_e32 v32, v18
	v_rcp_f32_e32 v33, v22
	v_rcp_f32_e32 v34, v19
	v_rcp_f32_e32 v35, v23
	v_add_f32_e32 v17, -1.0, v29
	v_add_f32_e32 v18, -1.0, v30
	v_add_f32_e32 v19, -1.0, v31
	v_lshlrev_b32_e32 v50, 16, v26
	v_and_b32_e32 v51, 0xffff0000, v26
	v_add_f32_e32 v16, -1.0, v28
	v_add_f32_e32 v20, -1.0, v32
	v_fma_f32 v17, v40, v17, 1.0
	v_fma_f32 v18, v37, v18, 1.0
	v_fma_f32 v19, v41, v19, 1.0
	v_lshlrev_b32_e32 v46, 16, v24
	v_lshlrev_b32_e32 v48, 16, v25
	v_add_f32_e32 v21, -1.0, v33
	v_add_f32_e32 v22, -1.0, v34
	v_add_f32_e32 v23, -1.0, v35
	v_fma_f32 v16, v36, v16, 1.0
	v_fma_f32 v20, v38, v20, 1.0
	v_mul_f32_e32 v24, v17, v50
	v_mul_f32_e32 v17, v18, v47
	v_mul_f32_e32 v18, v19, v51
	v_and_b32_e32 v49, 0xffff0000, v25
	v_lshlrev_b32_e32 v52, 16, v27
	v_and_b32_e32 v53, 0xffff0000, v27
	v_fma_f32 v21, v42, v21, 1.0
	v_fma_f32 v22, v39, v22, 1.0
	v_fma_f32 v23, v43, v23, 1.0
	v_mul_f32_e32 v16, v16, v46
	v_mul_f32_e32 v19, v20, v48
	v_cvt_pk_bf16_f32 v18, v24, v18
	v_lshl_add_u32 v24, v90, 3, s24
	v_mul_f32_e32 v20, v21, v52
	v_mul_f32_e32 v21, v22, v49
	v_mul_f32_e32 v22, v23, v53
	v_cvt_pk_bf16_f32 v16, v16, v17
	v_cvt_pk_bf16_f32 v17, v19, v21
	v_cvt_pk_bf16_f32 v19, v20, v22
	global_store_dwordx4 v[44:45], v[16:19], off offset:1024
	v_ashrrev_i32_e32 v25, 31, v24
	global_load_dwordx4 v[16:19], v[56:57], off
	global_load_dwordx4 v[20:23], v[56:57], off offset:16
	v_lshl_add_u64 v[24:25], v[24:25], 2, s[4:5]
	global_load_dword v38, v[24:25], off
	v_lshlrev_b64 v[26:27], 9, v[90:91]
	v_lshl_add_u64 v[26:27], v[26:27], 0, v[78:79]
	v_mad_i64_i32 v[24:25], s[26:27], v88, s68, v[76:77]
	v_lshlrev_b64 v[26:27], 1, v[26:27]
	v_lshl_add_u64 v[36:37], v[24:25], 0, v[82:83]
	v_lshl_add_u64 v[24:25], s[50:51], 0, v[26:27]
	v_lshl_add_u64 v[26:27], s[62:63], 0, v[26:27]
	s_waitcnt vmcnt(0)
	v_mul_f32_e32 v16, v16, v46
	v_mul_f32_e32 v20, v20, v50
	v_mul_f32_e32 v17, v17, v47
	v_mul_f32_e32 v21, v21, v51
	v_mul_f32_e32 v18, v18, v48
	v_mul_f32_e32 v22, v22, v52
	v_mul_f32_e32 v19, v19, v49
	v_mul_f32_e32 v23, v23, v53
	v_mul_f32_e32 v39, v16, v38
	v_mul_f32_e32 v20, v38, v20
	v_mul_f32_e32 v40, v17, v38
	v_mul_f32_e32 v21, v38, v21
	v_mul_f32_e32 v41, v18, v38
	v_mul_f32_e32 v22, v38, v22
	v_mul_f32_e32 v42, v19, v38
	v_mul_f32_e32 v23, v38, v23
	v_cvt_pk_bf16_f32 v16, v39, v40
	v_cvt_pk_bf16_f32 v17, v41, v42
	v_cvt_pk_bf16_f32 v18, v20, v21
	v_cvt_pk_bf16_f32 v19, v22, v23
	v_mul_f32_e64 v28, v28, -v39
	v_mul_f32_e64 v30, v30, -v40
	v_mul_f32_e64 v32, v32, -v41
	v_mul_f32_e64 v34, v34, -v42
	v_mul_f32_e64 v20, v29, -v20
	v_mul_f32_e64 v21, v31, -v21
	v_mul_f32_e64 v22, v33, -v22
	v_mul_f32_e64 v23, v35, -v23
	global_store_dwordx4 v[24:25], v[16:19], off
	s_nop 1
	v_cvt_pk_bf16_f32 v16, v28, v30
	v_cvt_pk_bf16_f32 v17, v32, v34
	v_cvt_pk_bf16_f32 v18, v20, v21
	v_cvt_pk_bf16_f32 v19, v22, v23
	global_store_dwordx4 v[26:27], v[16:19], off
	global_load_dwordx4 v[16:19], v[36:37], off offset:1024
	global_load_dwordx4 v[20:23], v[84:85], off
	global_load_dwordx4 v[24:27], v[84:85], off offset:16
	global_load_dwordx4 v[28:31], v[86:87], off
	global_load_dwordx4 v[32:35], v[86:87], off offset:16
	s_waitcnt vmcnt(0)
; __device__ __forceinline__ void unpack8(const u32x4 w, float (&f)[8]) { f[0] = bflo(w.x); f[1] = bfhi(w.x); f[2] = bflo(w.y); f[3] = bfhi(w.y); f[4] = bflo(w.z); f[5] = bfhi(w.z); f[6] = bflo(w.w); f[7] = bfhi(w.w); }
; __device__ __forceinline__ u32x4 pack8(const float (&f)[8]) { u32x4 o; o.x = pk2(f[0], f[1]); o.y = pk2(f[2], f[3]); o.z = pk2(f[4], f[5]); o.w = pk2(f[6], f[7]); return o; }
; __device__ __forceinline__ float sigmoidf_(float x) { return __builtin_amdgcn_rcpf(1.0f + __expf(-x)); }
;     __device__ __forceinline__ void operator()(const f32x4 (&acc)[2][2][4][2], const Unit& u, int wr, int wc, int fr, int fq) const {
;     ...
;             for (int m = 0; m < 4; ++m) { const int row = row0 + ai * HALF + m * 16; const size_t off = (size_t)row * 512 + cb; bf16_t* kp = RKV + (size_t)row * 1536 + 512 + cb;
;                 float ks[8], av[8], t[8]; unpack8(*(const u32x4*)kp, ks);
;                 { const f32x4 c0 = *(const f32x4*)(a0 + cb), c1 = *(const f32x4*)(a0 + cb + 4); const f32x4 x0 = acc[ai][0][m][0], x1 = acc[ai][0][m][1];
; #pragma unroll
;                   for (int j = 0; j < 4; ++j) { av[j] = sigmoidf_(c0[j] + x0[j]); av[4 + j] = sigmoidf_(c1[j] + x1[j]); } }
;                 { const f32x4 c0 = *(const f32x4*)(k_a + cb), c1 = *(const f32x4*)(k_a + cb + 4);
; #pragma unroll
;                   for (int j = 0; j < 4; ++j) { t[j] = ks[j] * (1.0f + (av[j] - 1.0f) * c0[j]); t[4 + j] = ks[4 + j] * (1.0f + (av[4 + j] - 1.0f) * c1[j]); } }
;                 *(u32x4*)kp = pack8(t);
;                 { const f32x4 c0 = *(const f32x4*)(k_k + cb), c1 = *(const f32x4*)(k_k + cb + 4); const float ri = rinv[row * 8 + (cb >> 6)];
; #pragma unroll
;                   for (int j = 0; j < 4; ++j) { t[j] = ks[j] * c0[j] * ri; t[4 + j] = ks[4 + j] * c1[j] * ri; } }
;                 *(u32x4*)(KK + off) = pack8(t);
; #pragma unroll
;                 for (int e = 0; e < 8; ++e) t[e] = -t[e] * av[e];
;                 *(u32x4*)(NB + off) = pack8(t);
;                 asm volatile("" ::: "memory"); }
	v_and_b32_e32 v39, 0xffff0000, v16
	v_add_f32_e32 v9, v9, v21
	v_add_f32_e32 v12, v12, v24
	v_add_f32_e32 v13, v13, v25
	v_add_f32_e32 v8, v8, v20
	v_add_f32_e32 v10, v10, v22
	v_mul_f32_e32 v12, 0xbfb8aa3b, v12
	v_mul_f32_e32 v9, 0xbfb8aa3b, v9
	v_mul_f32_e32 v13, 0xbfb8aa3b, v13
	v_add_f32_e32 v14, v14, v26
	v_add_f32_e32 v11, v11, v23
	v_add_f32_e32 v15, v15, v27
	v_mul_f32_e32 v8, 0xbfb8aa3b, v8
	v_mul_f32_e32 v10, 0xbfb8aa3b, v10
	v_exp_f32_e32 v12, v12
	v_exp_f32_e32 v9, v9
	v_exp_f32_e32 v13, v13
	v_mul_f32_e32 v14, 0xbfb8aa3b, v14
	v_mul_f32_e32 v11, 0xbfb8aa3b, v11
	v_mul_f32_e32 v15, 0xbfb8aa3b, v15
	v_exp_f32_e32 v8, v8
	v_exp_f32_e32 v10, v10
	v_exp_f32_e32 v14, v14
	v_exp_f32_e32 v11, v11
	v_exp_f32_e32 v15, v15
	v_add_f32_e32 v12, 1.0, v12
	v_add_f32_e32 v9, 1.0, v9
	v_add_f32_e32 v13, 1.0, v13
	v_add_f32_e32 v8, 1.0, v8
	v_add_f32_e32 v10, 1.0, v10
	v_rcp_f32_e32 v21, v12
	v_rcp_f32_e32 v22, v9
	v_rcp_f32_e32 v23, v13
	v_add_f32_e32 v14, 1.0, v14
	v_add_f32_e32 v11, 1.0, v11
	v_add_f32_e32 v15, 1.0, v15
	v_rcp_f32_e32 v20, v8
	v_rcp_f32_e32 v24, v10
	v_rcp_f32_e32 v25, v14
	v_rcp_f32_e32 v26, v11
	v_rcp_f32_e32 v27, v15
	v_add_f32_e32 v9, -1.0, v21
	v_add_f32_e32 v10, -1.0, v22
	v_add_f32_e32 v11, -1.0, v23
	v_lshlrev_b32_e32 v42, 16, v18
	v_and_b32_e32 v43, 0xffff0000, v18
	v_add_f32_e32 v8, -1.0, v20
	v_add_f32_e32 v12, -1.0, v24
	v_fma_f32 v9, v32, v9, 1.0
	v_fma_f32 v10, v29, v10, 1.0
	v_fma_f32 v11, v33, v11, 1.0
	v_lshlrev_b32_e32 v38, 16, v16
	v_lshlrev_b32_e32 v40, 16, v17
	v_add_f32_e32 v13, -1.0, v25
	v_add_f32_e32 v14, -1.0, v26
	v_add_f32_e32 v15, -1.0, v27
	v_fma_f32 v8, v28, v8, 1.0
	v_fma_f32 v12, v30, v12, 1.0
	v_mul_f32_e32 v16, v9, v42
	v_mul_f32_e32 v9, v10, v39
	v_mul_f32_e32 v10, v11, v43
	v_and_b32_e32 v41, 0xffff0000, v17
	v_lshlrev_b32_e32 v44, 16, v19
	v_and_b32_e32 v45, 0xffff0000, v19
	v_fma_f32 v13, v34, v13, 1.0
	v_fma_f32 v14, v31, v14, 1.0
	v_fma_f32 v15, v35, v15, 1.0
	v_mul_f32_e32 v8, v8, v38
	v_mul_f32_e32 v11, v12, v40
	v_cvt_pk_bf16_f32 v10, v16, v10
	v_lshl_add_u32 v16, v88, 3, s24
	v_mul_f32_e32 v12, v13, v44
	v_mul_f32_e32 v13, v14, v41
	v_mul_f32_e32 v14, v15, v45
	v_cvt_pk_bf16_f32 v8, v8, v9
	v_cvt_pk_bf16_f32 v9, v11, v13
	v_cvt_pk_bf16_f32 v11, v12, v14
	global_store_dwordx4 v[36:37], v[8:11], off offset:1024
	v_ashrrev_i32_e32 v17, 31, v16
	global_load_dwordx4 v[8:11], v[56:57], off
	global_load_dwordx4 v[12:15], v[56:57], off offset:16
	v_lshl_add_u64 v[16:17], v[16:17], 2, s[4:5]
	global_load_dword v30, v[16:17], off
	v_lshlrev_b64 v[18:19], 9, v[88:89]
	v_lshl_add_u64 v[18:19], v[18:19], 0, v[78:79]
	v_mad_i64_i32 v[16:17], s[26:27], v80, s68, v[76:77]
	v_lshlrev_b64 v[18:19], 1, v[18:19]
	v_lshl_add_u64 v[28:29], v[16:17], 0, v[82:83]
	v_lshl_add_u64 v[16:17], s[50:51], 0, v[18:19]
	v_lshl_add_u64 v[18:19], s[62:63], 0, v[18:19]
	s_mov_b64 s[26:27], s[8:9]
	s_waitcnt vmcnt(0)
	v_mul_f32_e32 v8, v8, v38
	v_mul_f32_e32 v12, v12, v42
	v_mul_f32_e32 v9, v9, v39
	v_mul_f32_e32 v13, v13, v43
	v_mul_f32_e32 v10, v10, v40
	v_mul_f32_e32 v14, v14, v44
	v_mul_f32_e32 v11, v11, v41
	v_mul_f32_e32 v15, v15, v45
	v_mul_f32_e32 v31, v8, v30
	v_mul_f32_e32 v12, v30, v12
	v_mul_f32_e32 v32, v9, v30
	v_mul_f32_e32 v13, v30, v13
	v_mul_f32_e32 v33, v10, v30
	v_mul_f32_e32 v14, v30, v14
	v_mul_f32_e32 v34, v11, v30
	v_mul_f32_e32 v15, v30, v15
	v_cvt_pk_bf16_f32 v8, v31, v32
	v_cvt_pk_bf16_f32 v9, v33, v34
	v_cvt_pk_bf16_f32 v10, v12, v13
	v_cvt_pk_bf16_f32 v11, v14, v15
	v_mul_f32_e64 v20, v20, -v31
	v_mul_f32_e64 v22, v22, -v32
	v_mul_f32_e64 v24, v24, -v33
	v_mul_f32_e64 v26, v26, -v34
	v_mul_f32_e64 v12, v21, -v12
	v_mul_f32_e64 v13, v23, -v13
	v_mul_f32_e64 v14, v25, -v14
	v_mul_f32_e64 v15, v27, -v15
	global_store_dwordx4 v[16:17], v[8:11], off
	s_nop 1
	v_cvt_pk_bf16_f32 v8, v20, v22
	v_cvt_pk_bf16_f32 v9, v24, v26
	v_cvt_pk_bf16_f32 v10, v12, v13
	v_cvt_pk_bf16_f32 v11, v14, v15
	global_store_dwordx4 v[18:19], v[8:11], off
	global_load_dwordx4 v[8:11], v[28:29], off offset:1024
	global_load_dwordx4 v[12:15], v[84:85], off
	global_load_dwordx4 v[16:19], v[84:85], off offset:16
	global_load_dwordx4 v[20:23], v[86:87], off
	global_load_dwordx4 v[24:27], v[86:87], off offset:16
	s_waitcnt vmcnt(0)
; __device__ __forceinline__ void unpack8(const u32x4 w, float (&f)[8]) { f[0] = bflo(w.x); f[1] = bfhi(w.x); f[2] = bflo(w.y); f[3] = bfhi(w.y); f[4] = bflo(w.z); f[5] = bfhi(w.z); f[6] = bflo(w.w); f[7] = bfhi(w.w); }
; __device__ __forceinline__ u32x4 pack8(const float (&f)[8]) { u32x4 o; o.x = pk2(f[0], f[1]); o.y = pk2(f[2], f[3]); o.z = pk2(f[4], f[5]); o.w = pk2(f[6], f[7]); return o; }
; __device__ __forceinline__ float sigmoidf_(float x) { return __builtin_amdgcn_rcpf(1.0f + __expf(-x)); }
;     __device__ __forceinline__ void operator()(const f32x4 (&acc)[2][2][4][2], const Unit& u, int wr, int wc, int fr, int fq) const {
;     ...
;             for (int m = 0; m < 4; ++m) { const int row = row0 + ai * HALF + m * 16; const size_t off = (size_t)row * 512 + cb; bf16_t* kp = RKV + (size_t)row * 1536 + 512 + cb;
;                 float ks[8], av[8], t[8]; unpack8(*(const u32x4*)kp, ks);
;                 { const f32x4 c0 = *(const f32x4*)(a0 + cb), c1 = *(const f32x4*)(a0 + cb + 4); const f32x4 x0 = acc[ai][0][m][0], x1 = acc[ai][0][m][1];
; #pragma unroll
;                   for (int j = 0; j < 4; ++j) { av[j] = sigmoidf_(c0[j] + x0[j]); av[4 + j] = sigmoidf_(c1[j] + x1[j]); } }
;                 { const f32x4 c0 = *(const f32x4*)(k_a + cb), c1 = *(const f32x4*)(k_a + cb + 4);
; #pragma unroll
;                   for (int j = 0; j < 4; ++j) { t[j] = ks[j] * (1.0f + (av[j] - 1.0f) * c0[j]); t[4 + j] = ks[4 + j] * (1.0f + (av[4 + j] - 1.0f) * c1[j]); } }
;                 *(u32x4*)kp = pack8(t);
;                 { const f32x4 c0 = *(const f32x4*)(k_k + cb), c1 = *(const f32x4*)(k_k + cb + 4); const float ri = rinv[row * 8 + (cb >> 6)];
; #pragma unroll
;                   for (int j = 0; j < 4; ++j) { t[j] = ks[j] * c0[j] * ri; t[4 + j] = ks[4 + j] * c1[j] * ri; } }
;                 *(u32x4*)(KK + off) = pack8(t);
; #pragma unroll
;                 for (int e = 0; e < 8; ++e) t[e] = -t[e] * av[e];
;                 *(u32x4*)(NB + off) = pack8(t);
;                 asm volatile("" ::: "memory"); }
	v_and_b32_e32 v31, 0xffff0000, v8
	v_add_f32_e32 v1, v1, v13
	v_add_f32_e32 v4, v4, v16
	v_add_f32_e32 v5, v5, v17
	v_add_f32_e32 v0, v0, v12
	v_add_f32_e32 v2, v2, v14
	v_mul_f32_e32 v4, 0xbfb8aa3b, v4
	v_mul_f32_e32 v1, 0xbfb8aa3b, v1
	v_mul_f32_e32 v5, 0xbfb8aa3b, v5
	v_add_f32_e32 v6, v6, v18
	v_add_f32_e32 v3, v3, v15
	v_add_f32_e32 v7, v7, v19
	v_mul_f32_e32 v0, 0xbfb8aa3b, v0
	v_mul_f32_e32 v2, 0xbfb8aa3b, v2
	v_exp_f32_e32 v4, v4
	v_exp_f32_e32 v1, v1
	v_exp_f32_e32 v5, v5
	v_mul_f32_e32 v6, 0xbfb8aa3b, v6
	v_mul_f32_e32 v3, 0xbfb8aa3b, v3
	v_mul_f32_e32 v7, 0xbfb8aa3b, v7
	v_exp_f32_e32 v0, v0
	v_exp_f32_e32 v2, v2
	v_exp_f32_e32 v6, v6
	v_exp_f32_e32 v3, v3
	v_exp_f32_e32 v7, v7
	v_add_f32_e32 v4, 1.0, v4
	v_add_f32_e32 v1, 1.0, v1
	v_add_f32_e32 v5, 1.0, v5
	v_add_f32_e32 v0, 1.0, v0
	v_add_f32_e32 v2, 1.0, v2
	v_rcp_f32_e32 v13, v4
	v_rcp_f32_e32 v14, v1
	v_rcp_f32_e32 v15, v5
	v_add_f32_e32 v6, 1.0, v6
	v_add_f32_e32 v3, 1.0, v3
	v_add_f32_e32 v7, 1.0, v7
	v_rcp_f32_e32 v12, v0
	v_rcp_f32_e32 v16, v2
	v_rcp_f32_e32 v17, v6
	v_rcp_f32_e32 v18, v3
	v_rcp_f32_e32 v19, v7
	v_add_f32_e32 v1, -1.0, v13
	v_add_f32_e32 v2, -1.0, v14
	v_add_f32_e32 v3, -1.0, v15
	v_lshlrev_b32_e32 v34, 16, v10
	v_and_b32_e32 v35, 0xffff0000, v10
	v_add_f32_e32 v0, -1.0, v12
	v_add_f32_e32 v4, -1.0, v16
	v_fma_f32 v1, v24, v1, 1.0
	v_fma_f32 v2, v21, v2, 1.0
	v_fma_f32 v3, v25, v3, 1.0
	v_lshlrev_b32_e32 v30, 16, v8
	v_lshlrev_b32_e32 v32, 16, v9
	v_add_f32_e32 v5, -1.0, v17
	v_add_f32_e32 v6, -1.0, v18
	v_add_f32_e32 v7, -1.0, v19
	v_fma_f32 v0, v20, v0, 1.0
	v_fma_f32 v4, v22, v4, 1.0
	v_mul_f32_e32 v8, v1, v34
	v_mul_f32_e32 v1, v2, v31
	v_mul_f32_e32 v2, v3, v35
	v_and_b32_e32 v33, 0xffff0000, v9
	v_lshlrev_b32_e32 v36, 16, v11
	v_and_b32_e32 v37, 0xffff0000, v11
	v_fma_f32 v5, v26, v5, 1.0
	v_fma_f32 v6, v23, v6, 1.0
	v_fma_f32 v7, v27, v7, 1.0
	v_mul_f32_e32 v0, v0, v30
	v_mul_f32_e32 v3, v4, v32
	v_cvt_pk_bf16_f32 v2, v8, v2
	v_lshl_add_u32 v8, v80, 3, s24
	v_mul_f32_e32 v4, v5, v36
	v_mul_f32_e32 v5, v6, v33
	v_mul_f32_e32 v6, v7, v37
	v_cvt_pk_bf16_f32 v0, v0, v1
	v_cvt_pk_bf16_f32 v1, v3, v5
	v_cvt_pk_bf16_f32 v3, v4, v6
	global_store_dwordx4 v[28:29], v[0:3], off offset:1024
	v_ashrrev_i32_e32 v9, 31, v8
	global_load_dwordx4 v[0:3], v[56:57], off
	global_load_dwordx4 v[4:7], v[56:57], off offset:16
	v_lshl_add_u64 v[8:9], v[8:9], 2, s[4:5]
	global_load_dword v20, v[8:9], off
	v_lshlrev_b64 v[8:9], 9, v[80:81]
	v_lshl_add_u64 v[8:9], v[8:9], 0, v[78:79]
	v_lshlrev_b64 v[8:9], 1, v[8:9]
	v_lshl_add_u64 v[10:11], s[50:51], 0, v[8:9]
	v_lshl_add_u64 v[8:9], s[62:63], 0, v[8:9]
	s_mov_b64 s[24:25], s[0:1]
	s_waitcnt vmcnt(0)
	v_mul_f32_e32 v0, v0, v30
	v_mul_f32_e32 v4, v4, v34
	v_mul_f32_e32 v1, v1, v31
	v_mul_f32_e32 v5, v5, v35
	v_mul_f32_e32 v2, v2, v32
	v_mul_f32_e32 v6, v6, v36
	v_mul_f32_e32 v3, v3, v33
	v_mul_f32_e32 v7, v7, v37
	v_mul_f32_e32 v21, v0, v20
	v_mul_f32_e32 v4, v20, v4
	v_mul_f32_e32 v22, v1, v20
	v_mul_f32_e32 v5, v20, v5
	v_mul_f32_e32 v23, v2, v20
	v_mul_f32_e32 v6, v20, v6
	v_mul_f32_e32 v24, v3, v20
	v_mul_f32_e32 v7, v20, v7
	v_cvt_pk_bf16_f32 v0, v21, v22
	v_cvt_pk_bf16_f32 v1, v23, v24
	v_cvt_pk_bf16_f32 v2, v4, v5
	v_cvt_pk_bf16_f32 v3, v6, v7
	v_mul_f32_e64 v12, v12, -v21
	v_mul_f32_e64 v14, v14, -v22
	v_mul_f32_e64 v16, v16, -v23
	v_mul_f32_e64 v18, v18, -v24
	v_mul_f32_e64 v4, v13, -v4
	v_mul_f32_e64 v5, v15, -v5
	v_mul_f32_e64 v6, v17, -v6
	v_mul_f32_e64 v7, v19, -v7
	global_store_dwordx4 v[10:11], v[0:3], off
	s_nop 1
	v_cvt_pk_bf16_f32 v0, v12, v14
	v_cvt_pk_bf16_f32 v1, v16, v18
	v_cvt_pk_bf16_f32 v2, v4, v5
	v_cvt_pk_bf16_f32 v3, v6, v7
	global_store_dwordx4 v[8:9], v[0:3], off
	s_cbranch_vccz .LBB0_472

; #define PG8_STAGE(bufoff, gbase, voff) do { _Pragma("unroll") for (int _i = 0; _i < 2; ++_i) \
;         __builtin_amdgcn_global_load_lds((const unsigned*)((const char*)(gbase) + (voff)[_i]), (PG8_LAS unsigned*)(lds + (bufoff) + ldsw + _i * 8192), 16, 0, 0); } while (0)
; #define PG8_LDA(dst, b, h) do { _Pragma("unroll") for (int m = 0; m < 4; ++m) _Pragma("unroll") for (int k = 0; k < 2; ++k) dst[m][k] = *(const PG8_LAS bf16x8*)(lds + PG8_SA(b, h) + aoff + m * 2048 + k * 1024); } while (0)
; #define PG8_LDB(dst, b, h) do { _Pragma("unroll") for (int n = 0; n < 2; ++n) _Pragma("unroll") for (int k = 0; k < 2; ++k) dst[n][k] = *(const PG8_LAS bf16x8*)(lds + PG8_SB(b, h) + boff + n * 2048 + k * 1024); } while (0)
; #define PG8_WAIT_V(n) asm volatile("s_waitcnt vmcnt(" #n ")" ::: "memory")
; #define PG8_WAIT_L(n) asm volatile("s_waitcnt lgkmcnt(" #n ")" ::: "memory")
; #define PG8_BAR __builtin_amdgcn_s_barrier()
; #define PG8_SCHED __builtin_amdgcn_sched_barrier(0)
; template <class Epi, class Sched>
; __device__ __forceinline__ void gemm_phase(PG8_LAS unsigned char* lds, const Gemm g, const Sched& S, const Epi& E) {
;     ...
;             PG8_LDB(B0, 0, 0); PG8_SCHED; PG8_LDA(At, 0, 0); PG8_STAGE(PG8_SA(1, 1), a1 + hstep, voffA);
;             PG8_WAIT_L(8); PG8_BAR; PG8_WAIT_L(0); PG8_MMA(0, 0, At, B0); PG8_BAR; PG8_SCHED;
;             PG8_LDB(B1, 0, 1); PG8_STAGE(PG8_SB(0, 0), b2, voffB);
;             PG8_BAR; PG8_WAIT_L(0); PG8_MMA(0, 1, At, B1); PG8_BAR;
;             PG8_LDA(At, 0, 1); PG8_STAGE(PG8_SA(0, 0), a2, voffA);
;             PG8_BAR; PG8_WAIT_L(0); PG8_MMA(1, 0, At, B0); PG8_BAR; PG8_SCHED;
;             PG8_STAGE(PG8_SB(0, 1), b2 + hstep, voffB);
;             PG8_WAIT_V(6); PG8_BAR; PG8_MMA(1, 1, At, B1); PG8_BAR;
;             PG8_LDB(B0, 1, 0); PG8_SCHED; PG8_LDA(At, 1, 0); PG8_STAGE(PG8_SA(0, 1), a2 + hstep, voffA);
;             PG8_WAIT_L(8); PG8_BAR; PG8_WAIT_L(0); PG8_MMA(0, 0, At, B0); PG8_BAR; PG8_SCHED;
;             PG8_LDB(B1, 1, 1); PG8_STAGE(PG8_SB(1, 0), b3, voffB);
;             PG8_BAR; PG8_WAIT_L(0); PG8_MMA(0, 1, At, B1); PG8_BAR;
;             PG8_LDA(At, 1, 1); PG8_STAGE(PG8_SA(1, 0), a3, voffA);
;             PG8_BAR; PG8_WAIT_L(0); PG8_MMA(1, 0, At, B0); PG8_BAR; PG8_SCHED;
;             PG8_STAGE(PG8_SB(1, 1), b3 + hstep, voffB);
;             PG8_WAIT_V(6); PG8_BAR; PG8_MMA(1, 1, At, B1); PG8_BAR;
.LBB0_772:
	ds_read_b128 v[144:147], v151
	ds_read_b128 v[154:157], v151 offset:1024
	ds_read_b128 v[158:161], v151 offset:2048
	ds_read_b128 v[162:165], v151 offset:3072
	s_add_u32 s22, s20, 0xfffc0080
	s_addc_u32 s23, s21, -1
	s_cmp_eq_u32 s61, 12
	s_cselect_b32 s25, s11, s23
	s_cselect_b32 s24, s17, s22
	s_cselect_b32 s23, s5, s60
	s_cselect_b32 s22, s50, s51
	v_lshl_add_u64 v[198:199], s[20:21], 0, v[136:137]
	s_add_i32 m0, s19, 0xc000
	ds_read_b128 v[166:169], v152
	ds_read_b128 v[170:173], v152 offset:1024
	ds_read_b128 v[174:177], v152 offset:2048
	ds_read_b128 v[178:181], v152 offset:3072
	ds_read_b128 v[182:185], v152 offset:4096
	ds_read_b128 v[186:189], v152 offset:5120
	ds_read_b128 v[190:193], v152 offset:6144
	ds_read_b128 v[194:197], v152 offset:7168
	global_load_lds_dwordx4 v[198:199], off
	v_lshl_add_u64 v[198:199], s[20:21], 0, v[138:139]
	s_add_i32 m0, s19, 0xe000
	s_nop 0
	global_load_lds_dwordx4 v[198:199], off
	s_waitcnt lgkmcnt(8)
	s_barrier
	s_waitcnt lgkmcnt(0)
	v_mfma_f32_16x16x32_bf16 v[124:127], v[144:147], v[166:169], v[124:127]
	v_mfma_f32_16x16x32_bf16 v[120:123], v[158:161], v[166:169], v[120:123]
	v_mfma_f32_16x16x32_bf16 v[108:111], v[144:147], v[174:177], v[108:111]
	v_mfma_f32_16x16x32_bf16 v[104:107], v[158:161], v[174:177], v[104:107]
	v_mfma_f32_16x16x32_bf16 v[92:95], v[144:147], v[182:185], v[92:95]
	v_mfma_f32_16x16x32_bf16 v[88:91], v[158:161], v[182:185], v[88:91]
	v_mfma_f32_16x16x32_bf16 v[76:79], v[144:147], v[190:193], v[76:79]
	v_mfma_f32_16x16x32_bf16 v[72:75], v[158:161], v[190:193], v[72:75]
	v_mfma_f32_16x16x32_bf16 v[124:127], v[154:157], v[170:173], v[124:127]
	v_mfma_f32_16x16x32_bf16 v[120:123], v[162:165], v[170:173], v[120:123]
	v_mfma_f32_16x16x32_bf16 v[108:111], v[154:157], v[178:181], v[108:111]
	v_mfma_f32_16x16x32_bf16 v[104:107], v[162:165], v[178:181], v[104:107]
	v_mfma_f32_16x16x32_bf16 v[92:95], v[154:157], v[186:189], v[92:95]
	v_mfma_f32_16x16x32_bf16 v[88:91], v[162:165], v[186:189], v[88:91]
	v_mfma_f32_16x16x32_bf16 v[76:79], v[154:157], v[194:197], v[76:79]
	v_mfma_f32_16x16x32_bf16 v[72:75], v[162:165], v[194:197], v[72:75]
	s_barrier
	s_add_i32 s62, s42, s28
	v_lshl_add_u64 v[214:215], s[22:23], 0, v[130:131]
	s_mov_b32 m0, s62
	ds_read_b128 v[198:201], v153
	ds_read_b128 v[202:205], v153 offset:1024
	ds_read_b128 v[206:209], v153 offset:2048
	ds_read_b128 v[210:213], v153 offset:3072
	global_load_lds_dwordx4 v[214:215], off
	v_lshl_add_u64 v[216:217], s[22:23], 0, v[134:135]
	s_add_i32 m0, s62, 0x2000
	s_nop 0
	global_load_lds_dwordx4 v[216:217], off
	s_barrier
	s_waitcnt lgkmcnt(0)
	v_mfma_f32_16x16x32_bf16 v[116:119], v[198:201], v[166:169], v[116:119]
	v_mfma_f32_16x16x32_bf16 v[112:115], v[206:209], v[166:169], v[112:115]
	v_mfma_f32_16x16x32_bf16 v[100:103], v[198:201], v[174:177], v[100:103]
	v_mfma_f32_16x16x32_bf16 v[96:99], v[206:209], v[174:177], v[96:99]
	v_mfma_f32_16x16x32_bf16 v[84:87], v[198:201], v[182:185], v[84:87]
	v_mfma_f32_16x16x32_bf16 v[80:83], v[206:209], v[182:185], v[80:83]
	v_mfma_f32_16x16x32_bf16 v[68:71], v[198:201], v[190:193], v[68:71]
	v_mfma_f32_16x16x32_bf16 v[64:67], v[206:209], v[190:193], v[64:67]
	v_mfma_f32_16x16x32_bf16 v[116:119], v[202:205], v[170:173], v[116:119]
	v_mfma_f32_16x16x32_bf16 v[112:115], v[210:213], v[170:173], v[112:115]
	v_mfma_f32_16x16x32_bf16 v[100:103], v[202:205], v[178:181], v[100:103]
	v_mfma_f32_16x16x32_bf16 v[96:99], v[210:213], v[178:181], v[96:99]
	v_mfma_f32_16x16x32_bf16 v[84:87], v[202:205], v[186:189], v[84:87]
	v_mfma_f32_16x16x32_bf16 v[80:83], v[210:213], v[186:189], v[80:83]
	v_mfma_f32_16x16x32_bf16 v[68:71], v[202:205], v[194:197], v[68:71]
	v_mfma_f32_16x16x32_bf16 v[64:67], v[210:213], v[194:197], v[64:67]
	s_mov_b32 m0, s19
	v_lshl_add_u64 v[218:219], s[24:25], 0, v[128:129]
	s_barrier
	ds_read_b128 v[166:169], v152 offset:16384
	ds_read_b128 v[170:173], v152 offset:17408
	ds_read_b128 v[174:177], v152 offset:18432
	ds_read_b128 v[178:181], v152 offset:19456
	ds_read_b128 v[182:185], v152 offset:20480
	ds_read_b128 v[186:189], v152 offset:21504
	ds_read_b128 v[190:193], v152 offset:22528
	ds_read_b128 v[194:197], v152 offset:23552
	global_load_lds_dwordx4 v[218:219], off
	v_lshl_add_u64 v[220:221], s[24:25], 0, v[132:133]
	s_mov_b32 m0, s31
	s_nop 0
	global_load_lds_dwordx4 v[220:221], off
	s_barrier
	s_waitcnt lgkmcnt(0)
	v_mfma_f32_16x16x32_bf16 v[60:63], v[144:147], v[166:169], v[60:63]
	v_mfma_f32_16x16x32_bf16 v[56:59], v[158:161], v[166:169], v[56:59]
	v_mfma_f32_16x16x32_bf16 v[44:47], v[144:147], v[174:177], v[44:47]
	v_mfma_f32_16x16x32_bf16 v[40:43], v[158:161], v[174:177], v[40:43]
	v_mfma_f32_16x16x32_bf16 v[28:31], v[144:147], v[182:185], v[28:31]
	v_mfma_f32_16x16x32_bf16 v[24:27], v[158:161], v[182:185], v[24:27]
	v_mfma_f32_16x16x32_bf16 v[12:15], v[144:147], v[190:193], v[12:15]
	v_mfma_f32_16x16x32_bf16 v[8:11], v[158:161], v[190:193], v[8:11]
	v_mfma_f32_16x16x32_bf16 v[60:63], v[154:157], v[170:173], v[60:63]
	v_mfma_f32_16x16x32_bf16 v[56:59], v[162:165], v[170:173], v[56:59]
	v_mfma_f32_16x16x32_bf16 v[44:47], v[154:157], v[178:181], v[44:47]
	v_mfma_f32_16x16x32_bf16 v[40:43], v[162:165], v[178:181], v[40:43]
	v_mfma_f32_16x16x32_bf16 v[28:31], v[154:157], v[186:189], v[28:31]
	v_mfma_f32_16x16x32_bf16 v[24:27], v[162:165], v[186:189], v[24:27]
	v_mfma_f32_16x16x32_bf16 v[12:15], v[154:157], v[194:197], v[12:15]
	v_mfma_f32_16x16x32_bf16 v[8:11], v[162:165], v[194:197], v[8:11]
	s_barrier
; #define PG8_STAGE(bufoff, gbase, voff) do { _Pragma("unroll") for (int _i = 0; _i < 2; ++_i) \
;         __builtin_amdgcn_global_load_lds((const unsigned*)((const char*)(gbase) + (voff)[_i]), (PG8_LAS unsigned*)(lds + (bufoff) + ldsw + _i * 8192), 16, 0, 0); } while (0)
; #define PG8_LDA(dst, b, h) do { _Pragma("unroll") for (int m = 0; m < 4; ++m) _Pragma("unroll") for (int k = 0; k < 2; ++k) dst[m][k] = *(const PG8_LAS bf16x8*)(lds + PG8_SA(b, h) + aoff + m * 2048 + k * 1024); } while (0)
; #define PG8_LDB(dst, b, h) do { _Pragma("unroll") for (int n = 0; n < 2; ++n) _Pragma("unroll") for (int k = 0; k < 2; ++k) dst[n][k] = *(const PG8_LAS bf16x8*)(lds + PG8_SB(b, h) + boff + n * 2048 + k * 1024); } while (0)
; #define PG8_WAIT_V(n) asm volatile("s_waitcnt vmcnt(" #n ")" ::: "memory")
; #define PG8_WAIT_L(n) asm volatile("s_waitcnt lgkmcnt(" #n ")" ::: "memory")
; #define PG8_BAR __builtin_amdgcn_s_barrier()
; #define PG8_SCHED __builtin_amdgcn_sched_barrier(0)
; template <class Epi, class Sched>
; __device__ __forceinline__ void gemm_phase(PG8_LAS unsigned char* lds, const Gemm g, const Sched& S, const Epi& E) {
;     ...
;             PG8_LDB(B0, 0, 0); PG8_SCHED; PG8_LDA(At, 0, 0); PG8_STAGE(PG8_SA(1, 1), a1 + hstep, voffA);
;             PG8_WAIT_L(8); PG8_BAR; PG8_WAIT_L(0); PG8_MMA(0, 0, At, B0); PG8_BAR; PG8_SCHED;
;             PG8_LDB(B1, 0, 1); PG8_STAGE(PG8_SB(0, 0), b2, voffB);
;             PG8_BAR; PG8_WAIT_L(0); PG8_MMA(0, 1, At, B1); PG8_BAR;
;             PG8_LDA(At, 0, 1); PG8_STAGE(PG8_SA(0, 0), a2, voffA);
;             PG8_BAR; PG8_WAIT_L(0); PG8_MMA(1, 0, At, B0); PG8_BAR; PG8_SCHED;
;             PG8_STAGE(PG8_SB(0, 1), b2 + hstep, voffB);
;             PG8_WAIT_V(6); PG8_BAR; PG8_MMA(1, 1, At, B1); PG8_BAR;
;             PG8_LDB(B0, 1, 0); PG8_SCHED; PG8_LDA(At, 1, 0); PG8_STAGE(PG8_SA(0, 1), a2 + hstep, voffA);
;             PG8_WAIT_L(8); PG8_BAR; PG8_WAIT_L(0); PG8_MMA(0, 0, At, B0); PG8_BAR; PG8_SCHED;
;             PG8_LDB(B1, 1, 1); PG8_STAGE(PG8_SB(1, 0), b3, voffB);
;             PG8_BAR; PG8_WAIT_L(0); PG8_MMA(0, 1, At, B1); PG8_BAR;
;             PG8_LDA(At, 1, 1); PG8_STAGE(PG8_SA(1, 0), a3, voffA);
;             PG8_BAR; PG8_WAIT_L(0); PG8_MMA(1, 0, At, B0); PG8_BAR; PG8_SCHED;
;             PG8_STAGE(PG8_SB(1, 1), b3 + hstep, voffB);
;             PG8_WAIT_V(6); PG8_BAR; PG8_MMA(1, 1, At, B1); PG8_BAR;
	s_add_u32 s62, s22, 0x40000
	s_addc_u32 s63, s23, 0
	s_add_i32 s64, s43, s28
	v_lshl_add_u64 v[144:145], s[62:63], 0, v[130:131]
	s_mov_b32 m0, s64
	s_nop 0
	global_load_lds_dwordx4 v[144:145], off
	v_lshl_add_u64 v[144:145], s[62:63], 0, v[134:135]
	s_add_i32 m0, s64, 0x2000
	s_nop 0
	global_load_lds_dwordx4 v[144:145], off
	s_waitcnt vmcnt(6)
	s_barrier
	v_mfma_f32_16x16x32_bf16 v[52:55], v[198:201], v[166:169], v[52:55]
	v_mfma_f32_16x16x32_bf16 v[48:51], v[206:209], v[166:169], v[48:51]
	v_mfma_f32_16x16x32_bf16 v[36:39], v[198:201], v[174:177], v[36:39]
	v_mfma_f32_16x16x32_bf16 v[32:35], v[206:209], v[174:177], v[32:35]
	v_mfma_f32_16x16x32_bf16 v[20:23], v[198:201], v[182:185], v[20:23]
	v_mfma_f32_16x16x32_bf16 v[16:19], v[206:209], v[182:185], v[16:19]
	v_mfma_f32_16x16x32_bf16 v[4:7], v[198:201], v[190:193], v[4:7]
	v_mfma_f32_16x16x32_bf16 v[0:3], v[206:209], v[190:193], v[0:3]
	v_mfma_f32_16x16x32_bf16 v[52:55], v[202:205], v[170:173], v[52:55]
	v_mfma_f32_16x16x32_bf16 v[48:51], v[210:213], v[170:173], v[48:51]
	v_mfma_f32_16x16x32_bf16 v[36:39], v[202:205], v[178:181], v[36:39]
	v_mfma_f32_16x16x32_bf16 v[32:35], v[210:213], v[178:181], v[32:35]
	v_mfma_f32_16x16x32_bf16 v[20:23], v[202:205], v[186:189], v[20:23]
	v_mfma_f32_16x16x32_bf16 v[16:19], v[210:213], v[186:189], v[16:19]
	v_mfma_f32_16x16x32_bf16 v[4:7], v[202:205], v[194:197], v[4:7]
	v_mfma_f32_16x16x32_bf16 v[0:3], v[210:213], v[194:197], v[0:3]
	s_add_i32 s62, 0, 0x18000
	v_add_u32_e32 v162, s62, v149
	s_barrier
	ds_read_b128 v[144:147], v162
	ds_read_b128 v[154:157], v162 offset:1024
	ds_read_b128 v[158:161], v162 offset:2048
	ds_read_b128 v[162:165], v162 offset:3072
	s_add_u32 s24, s24, 0x40000
	s_addc_u32 s25, s25, 0
	s_mov_b32 m0, s34
	v_lshl_add_u64 v[198:199], s[24:25], 0, v[128:129]
	ds_read_b128 v[166:169], v152 offset:32768
	ds_read_b128 v[170:173], v152 offset:33792
	ds_read_b128 v[174:177], v152 offset:34816
	ds_read_b128 v[178:181], v152 offset:35840
	ds_read_b128 v[182:185], v152 offset:36864
	ds_read_b128 v[186:189], v152 offset:37888
	ds_read_b128 v[190:193], v152 offset:38912
	ds_read_b128 v[194:197], v152 offset:39936
	global_load_lds_dwordx4 v[198:199], off
	v_lshl_add_u64 v[198:199], s[24:25], 0, v[132:133]
	s_mov_b32 m0, s35
	s_nop 0
	global_load_lds_dwordx4 v[198:199], off
	s_waitcnt lgkmcnt(8)
	s_barrier
	s_waitcnt lgkmcnt(0)
	v_mfma_f32_16x16x32_bf16 v[124:127], v[144:147], v[166:169], v[124:127]
	v_mfma_f32_16x16x32_bf16 v[120:123], v[158:161], v[166:169], v[120:123]
	v_mfma_f32_16x16x32_bf16 v[108:111], v[144:147], v[174:177], v[108:111]
	v_mfma_f32_16x16x32_bf16 v[104:107], v[158:161], v[174:177], v[104:107]
	v_mfma_f32_16x16x32_bf16 v[92:95], v[144:147], v[182:185], v[92:95]
	v_mfma_f32_16x16x32_bf16 v[88:91], v[158:161], v[182:185], v[88:91]
	v_mfma_f32_16x16x32_bf16 v[76:79], v[144:147], v[190:193], v[76:79]
	v_mfma_f32_16x16x32_bf16 v[72:75], v[158:161], v[190:193], v[72:75]
	v_mfma_f32_16x16x32_bf16 v[124:127], v[154:157], v[170:173], v[124:127]
	v_mfma_f32_16x16x32_bf16 v[120:123], v[162:165], v[170:173], v[120:123]
	v_mfma_f32_16x16x32_bf16 v[108:111], v[154:157], v[178:181], v[108:111]
	v_mfma_f32_16x16x32_bf16 v[104:107], v[162:165], v[178:181], v[104:107]
	v_mfma_f32_16x16x32_bf16 v[92:95], v[154:157], v[186:189], v[92:95]
	v_mfma_f32_16x16x32_bf16 v[88:91], v[162:165], v[186:189], v[88:91]
	v_mfma_f32_16x16x32_bf16 v[76:79], v[154:157], v[194:197], v[76:79]
	v_mfma_f32_16x16x32_bf16 v[72:75], v[162:165], v[194:197], v[72:75]
	s_barrier
	s_add_i32 s24, 0, 0x1c000
	s_add_i32 s25, s62, s28
	v_add_u32_e32 v210, s24, v149
	v_lshl_add_u64 v[214:215], v[214:215], 0, s[0:1]
	s_mov_b32 m0, s25
	ds_read_b128 v[198:201], v210
	ds_read_b128 v[202:205], v210 offset:1024
	ds_read_b128 v[206:209], v210 offset:2048
	ds_read_b128 v[210:213], v210 offset:3072
	global_load_lds_dwordx4 v[214:215], off
	v_lshl_add_u64 v[214:215], v[216:217], 0, s[0:1]
	s_add_i32 m0, s25, 0x2000
	s_nop 0
	global_load_lds_dwordx4 v[214:215], off
	s_barrier
	s_waitcnt lgkmcnt(0)
	v_mfma_f32_16x16x32_bf16 v[116:119], v[198:201], v[166:169], v[116:119]
	v_mfma_f32_16x16x32_bf16 v[112:115], v[206:209], v[166:169], v[112:115]
	v_mfma_f32_16x16x32_bf16 v[100:103], v[198:201], v[174:177], v[100:103]
	v_mfma_f32_16x16x32_bf16 v[96:99], v[206:209], v[174:177], v[96:99]
	v_mfma_f32_16x16x32_bf16 v[84:87], v[198:201], v[182:185], v[84:87]
	v_mfma_f32_16x16x32_bf16 v[80:83], v[206:209], v[182:185], v[80:83]
	v_mfma_f32_16x16x32_bf16 v[68:71], v[198:201], v[190:193], v[68:71]
	v_mfma_f32_16x16x32_bf16 v[64:67], v[206:209], v[190:193], v[64:67]
	v_mfma_f32_16x16x32_bf16 v[116:119], v[202:205], v[170:173], v[116:119]
	v_mfma_f32_16x16x32_bf16 v[112:115], v[210:213], v[170:173], v[112:115]
	v_mfma_f32_16x16x32_bf16 v[100:103], v[202:205], v[178:181], v[100:103]
	v_mfma_f32_16x16x32_bf16 v[96:99], v[210:213], v[178:181], v[96:99]
	v_mfma_f32_16x16x32_bf16 v[84:87], v[202:205], v[186:189], v[84:87]
	v_mfma_f32_16x16x32_bf16 v[80:83], v[210:213], v[186:189], v[80:83]
	v_mfma_f32_16x16x32_bf16 v[68:71], v[202:205], v[194:197], v[68:71]
	v_mfma_f32_16x16x32_bf16 v[64:67], v[210:213], v[194:197], v[64:67]
	s_mov_b32 m0, s37
	v_lshl_add_u64 v[214:215], v[218:219], 0, s[0:1]
	s_barrier
; #define PG8_STAGE(bufoff, gbase, voff) do { _Pragma("unroll") for (int _i = 0; _i < 2; ++_i) \
;         __builtin_amdgcn_global_load_lds((const unsigned*)((const char*)(gbase) + (voff)[_i]), (PG8_LAS unsigned*)(lds + (bufoff) + ldsw + _i * 8192), 16, 0, 0); } while (0)
; #define PG8_WAIT_V(n) asm volatile("s_waitcnt vmcnt(" #n ")" ::: "memory")
; #define PG8_BAR __builtin_amdgcn_s_barrier()
; template <class Epi, class Sched>
; __device__ __forceinline__ void gemm_phase(PG8_LAS unsigned char* lds, const Gemm g, const Sched& S, const Epi& E) {
;     ...
;             PG8_WAIT_V(6); PG8_BAR; PG8_MMA(1, 1, At, B1); PG8_BAR;
;             PG8_LDB(B0, 1, 0); PG8_SCHED; PG8_LDA(At, 1, 0); PG8_STAGE(PG8_SA(0, 1), a2 + hstep, voffA);
;             PG8_WAIT_L(8); PG8_BAR; PG8_WAIT_L(0); PG8_MMA(0, 0, At, B0); PG8_BAR; PG8_SCHED;
;             PG8_LDB(B1, 1, 1); PG8_STAGE(PG8_SB(1, 0), b3, voffB);
;             PG8_BAR; PG8_WAIT_L(0); PG8_MMA(0, 1, At, B1); PG8_BAR;
;             PG8_LDA(At, 1, 1); PG8_STAGE(PG8_SA(1, 0), a3, voffA);
;             PG8_BAR; PG8_WAIT_L(0); PG8_MMA(1, 0, At, B0); PG8_BAR; PG8_SCHED;
;             PG8_STAGE(PG8_SB(1, 1), b3 + hstep, voffB);
;             PG8_WAIT_V(6); PG8_BAR; PG8_MMA(1, 1, At, B1); PG8_BAR;
;         }
;     __device__ __forceinline__ void operator()(const f32x4 (&acc)[2][2][4][2], const Unit& u, int wr, int wc, int fr, int fq) const {
;     ...
;             for (int m = 0; m < 4; ++m) { const int row = row0 + ai * HALF + m * 16; bf16_t* rowp = O + (size_t)row * ldc + col0; float s = 0.f;
; #pragma unroll
;                 for (int bj = 0; bj < 2; ++bj) { const f32x4 v0 = acc[ai][bj][m][0], v1 = acc[ai][bj][m][1]; u32x4 w; w.x = pk2(v0[0], v0[1]); w.y = pk2(v0[2], v0[3]); w.z = pk2(v1[0], v1[1]); w.w = pk2(v1[2], v1[3]);
;                     *(u32x4*)(rowp + bj * HALF) = w; s += ((v0[0] * v0[0] + v0[1] * v0[1]) + (v0[2] * v0[2] + v0[3] * v0[3])) + ((v1[0] * v1[0] + v1[1] * v1[1]) + (v1[2] * v1[2] + v1[3] * v1[3])); }
;                 { auto r16 = __builtin_amdgcn_permlane16_swap(__float_as_uint(s), __float_as_uint(s), false, false); s = __uint_as_float(r16[0]) + __uint_as_float(r16[1]);
;                   auto r32 = __builtin_amdgcn_permlane32_swap(__float_as_uint(s), __float_as_uint(s), false, false); s = __uint_as_float(r32[0]) + __uint_as_float(r32[1]); }
;                 if (fq == 0) atomicAdd(ss + row, s); }
	ds_read_b128 v[166:169], v152 offset:49152
	ds_read_b128 v[170:173], v152 offset:50176
	ds_read_b128 v[174:177], v152 offset:51200
	ds_read_b128 v[178:181], v152 offset:52224
	ds_read_b128 v[182:185], v152 offset:53248
	ds_read_b128 v[186:189], v152 offset:54272
	ds_read_b128 v[190:193], v152 offset:55296
	ds_read_b128 v[194:197], v152 offset:56320
	global_load_lds_dwordx4 v[214:215], off
	v_lshl_add_u64 v[214:215], v[220:221], 0, s[0:1]
	s_mov_b32 m0, s38
	s_nop 0
	global_load_lds_dwordx4 v[214:215], off
	s_barrier
	s_waitcnt lgkmcnt(0)
	v_mfma_f32_16x16x32_bf16 v[60:63], v[144:147], v[166:169], v[60:63]
	v_mfma_f32_16x16x32_bf16 v[56:59], v[158:161], v[166:169], v[56:59]
	v_mfma_f32_16x16x32_bf16 v[44:47], v[144:147], v[174:177], v[44:47]
	v_mfma_f32_16x16x32_bf16 v[40:43], v[158:161], v[174:177], v[40:43]
	v_mfma_f32_16x16x32_bf16 v[28:31], v[144:147], v[182:185], v[28:31]
	v_mfma_f32_16x16x32_bf16 v[24:27], v[158:161], v[182:185], v[24:27]
	v_mfma_f32_16x16x32_bf16 v[12:15], v[144:147], v[190:193], v[12:15]
	v_mfma_f32_16x16x32_bf16 v[8:11], v[158:161], v[190:193], v[8:11]
	v_mfma_f32_16x16x32_bf16 v[60:63], v[154:157], v[170:173], v[60:63]
	v_mfma_f32_16x16x32_bf16 v[56:59], v[162:165], v[170:173], v[56:59]
	v_mfma_f32_16x16x32_bf16 v[44:47], v[154:157], v[178:181], v[44:47]
	v_mfma_f32_16x16x32_bf16 v[40:43], v[162:165], v[178:181], v[40:43]
	v_mfma_f32_16x16x32_bf16 v[28:31], v[154:157], v[186:189], v[28:31]
	v_mfma_f32_16x16x32_bf16 v[24:27], v[162:165], v[186:189], v[24:27]
	v_mfma_f32_16x16x32_bf16 v[12:15], v[154:157], v[194:197], v[12:15]
	v_mfma_f32_16x16x32_bf16 v[8:11], v[162:165], v[194:197], v[8:11]
	s_barrier
	s_add_u32 s22, s22, 0x40080
	s_addc_u32 s23, s23, 0
	s_add_i32 s24, s24, s28
	v_lshl_add_u64 v[144:145], s[22:23], 0, v[130:131]
	s_mov_b32 m0, s24
	s_nop 0
	global_load_lds_dwordx4 v[144:145], off
	v_lshl_add_u64 v[144:145], s[22:23], 0, v[134:135]
	s_add_i32 m0, s24, 0x2000
	s_nop 0
	global_load_lds_dwordx4 v[144:145], off
	s_waitcnt vmcnt(6)
	s_barrier
	v_mfma_f32_16x16x32_bf16 v[52:55], v[198:201], v[166:169], v[52:55]
	v_mfma_f32_16x16x32_bf16 v[48:51], v[206:209], v[166:169], v[48:51]
	v_mfma_f32_16x16x32_bf16 v[36:39], v[198:201], v[174:177], v[36:39]
	v_mfma_f32_16x16x32_bf16 v[32:35], v[206:209], v[174:177], v[32:35]
	v_mfma_f32_16x16x32_bf16 v[20:23], v[198:201], v[182:185], v[20:23]
	v_mfma_f32_16x16x32_bf16 v[16:19], v[206:209], v[182:185], v[16:19]
	v_mfma_f32_16x16x32_bf16 v[4:7], v[198:201], v[190:193], v[4:7]
	v_mfma_f32_16x16x32_bf16 v[0:3], v[206:209], v[190:193], v[0:3]
	v_mfma_f32_16x16x32_bf16 v[52:55], v[202:205], v[170:173], v[52:55]
	v_mfma_f32_16x16x32_bf16 v[48:51], v[210:213], v[170:173], v[48:51]
	v_mfma_f32_16x16x32_bf16 v[36:39], v[202:205], v[178:181], v[36:39]
	v_mfma_f32_16x16x32_bf16 v[32:35], v[210:213], v[178:181], v[32:35]
	v_mfma_f32_16x16x32_bf16 v[20:23], v[202:205], v[186:189], v[20:23]
	v_mfma_f32_16x16x32_bf16 v[16:19], v[210:213], v[186:189], v[16:19]
	v_mfma_f32_16x16x32_bf16 v[4:7], v[202:205], v[194:197], v[4:7]
	v_mfma_f32_16x16x32_bf16 v[0:3], v[210:213], v[194:197], v[0:3]
	s_add_i32 s61, s61, 2
	s_add_u32 s20, s20, 0x100
	s_addc_u32 s21, s21, 0
	s_add_u32 s51, s51, 0x100
	s_addc_u32 s60, s60, 0
	s_cmp_gt_u32 s61, 13
	s_barrier
	s_cbranch_scc0 .LBB0_772
	v_lshl_add_u32 v146, s16, 8, v148
	v_ashrrev_i32_e32 v147, 31, v146
	v_lshl_or_b32 v144, s18, 8, v150
	v_lshlrev_b64 v[154:155], 11, v[146:147]
	v_ashrrev_i32_e32 v145, 31, v144
	v_lshl_add_u64 v[154:155], s[48:49], 0, v[154:155]
	v_lshl_add_u64 v[158:159], v[144:145], 1, v[154:155]
	v_cvt_pk_bf16_f32 v154, v124, v125
	v_cvt_pk_bf16_f32 v156, v120, v121
	v_mul_f32_e32 v125, v125, v125
	v_mul_f32_e32 v121, v121, v121
	v_fmac_f32_e32 v125, v124, v124
	v_mul_f32_e32 v124, v127, v127
	v_fmac_f32_e32 v121, v120, v120
	v_mul_f32_e32 v120, v123, v123
	v_fmac_f32_e32 v124, v126, v126
	v_fmac_f32_e32 v120, v122, v122
	v_add_f32_e32 v124, v125, v124
	v_add_f32_e32 v120, v121, v120
	v_cvt_pk_bf16_f32 v157, v122, v123
	v_add_f32_e32 v124, v124, v120
	v_cvt_pk_bf16_f32 v120, v116, v117
	v_cvt_pk_bf16_f32 v122, v112, v113
	v_mul_f32_e32 v117, v117, v117
	v_mul_f32_e32 v113, v113, v113
	v_fmac_f32_e32 v117, v116, v116
	v_mul_f32_e32 v116, v119, v119
	v_fmac_f32_e32 v113, v112, v112
	v_mul_f32_e32 v112, v115, v115
	v_fmac_f32_e32 v116, v118, v118
	v_fmac_f32_e32 v112, v114, v114
	v_add_f32_e32 v116, v117, v116
	v_add_f32_e32 v112, v113, v112
	v_add_f32_e32 v112, v116, v112
	v_add_f32_e32 v112, v124, v112
	v_mov_b32_e32 v113, v112
	s_nop 1
	v_permlane16_swap_b32_e32 v112, v113
	v_add_f32_e32 v112, v112, v113
	v_mov_b32_e32 v113, v112
	s_nop 1
	v_permlane32_swap_b32_e32 v112, v113
	v_cvt_pk_bf16_f32 v155, v126, v127
	global_store_dwordx4 v[158:159], v[154:157], off
	v_cvt_pk_bf16_f32 v121, v118, v119
	v_cvt_pk_bf16_f32 v123, v114, v115
	global_store_dwordx4 v[158:159], v[120:123], off offset:256
	s_and_saveexec_b64 s[16:17], s[6:7]
	s_cbranch_execz .LBB0_775
	v_lshl_add_u64 v[114:115], v[146:147], 2, s[46:47]
	v_add_f32_e32 v112, v112, v113
	global_atomic_add_f32 v[114:115], v112, off

; #define PG8_STAGE(bufoff, gbase, voff) do { _Pragma("unroll") for (int _i = 0; _i < 2; ++_i) \
;         __builtin_amdgcn_global_load_lds((const unsigned*)((const char*)(gbase) + (voff)[_i]), (PG8_LAS unsigned*)(lds + (bufoff) + ldsw + _i * 8192), 16, 0, 0); } while (0)
; #define PG8_LDA(dst, b, h) do { _Pragma("unroll") for (int m = 0; m < 4; ++m) _Pragma("unroll") for (int k = 0; k < 2; ++k) dst[m][k] = *(const PG8_LAS bf16x8*)(lds + PG8_SA(b, h) + aoff + m * 2048 + k * 1024); } while (0)
; #define PG8_LDB(dst, b, h) do { _Pragma("unroll") for (int n = 0; n < 2; ++n) _Pragma("unroll") for (int k = 0; k < 2; ++k) dst[n][k] = *(const PG8_LAS bf16x8*)(lds + PG8_SB(b, h) + boff + n * 2048 + k * 1024); } while (0)
; #define PG8_WAIT_V(n) asm volatile("s_waitcnt vmcnt(" #n ")" ::: "memory")
; #define PG8_WAIT_L(n) asm volatile("s_waitcnt lgkmcnt(" #n ")" ::: "memory")
; #define PG8_BAR __builtin_amdgcn_s_barrier()
; #define PG8_SCHED __builtin_amdgcn_sched_barrier(0)
; template <class Epi, class Sched>
; __device__ __forceinline__ void gemm_phase(PG8_LAS unsigned char* lds, const Gemm g, const Sched& S, const Epi& E) {
;     ...
;             PG8_LDB(B0, 0, 0); PG8_SCHED; PG8_LDA(At, 0, 0); PG8_STAGE(PG8_SA(1, 1), a1 + hstep, voffA);
;             PG8_WAIT_L(8); PG8_BAR; PG8_WAIT_L(0); PG8_MMA(0, 0, At, B0); PG8_BAR; PG8_SCHED;
;             PG8_LDB(B1, 0, 1); PG8_STAGE(PG8_SB(0, 0), b2, voffB);
;             PG8_BAR; PG8_WAIT_L(0); PG8_MMA(0, 1, At, B1); PG8_BAR;
;             PG8_LDA(At, 0, 1); PG8_STAGE(PG8_SA(0, 0), a2, voffA);
;             PG8_BAR; PG8_WAIT_L(0); PG8_MMA(1, 0, At, B0); PG8_BAR; PG8_SCHED;
;             PG8_STAGE(PG8_SB(0, 1), b2 + hstep, voffB);
;             PG8_WAIT_V(6); PG8_BAR; PG8_MMA(1, 1, At, B1); PG8_BAR;
;             PG8_LDB(B0, 1, 0); PG8_SCHED; PG8_LDA(At, 1, 0); PG8_STAGE(PG8_SA(0, 1), a2 + hstep, voffA);
;             PG8_WAIT_L(8); PG8_BAR; PG8_WAIT_L(0); PG8_MMA(0, 0, At, B0); PG8_BAR; PG8_SCHED;
;             PG8_LDB(B1, 1, 1); PG8_STAGE(PG8_SB(1, 0), b3, voffB);
;             PG8_BAR; PG8_WAIT_L(0); PG8_MMA(0, 1, At, B1); PG8_BAR;
;             PG8_LDA(At, 1, 1); PG8_STAGE(PG8_SA(1, 0), a3, voffA);
;             PG8_BAR; PG8_WAIT_L(0); PG8_MMA(1, 0, At, B0); PG8_BAR; PG8_SCHED;
;             PG8_STAGE(PG8_SB(1, 1), b3 + hstep, voffB);
;             PG8_WAIT_V(6); PG8_BAR; PG8_MMA(1, 1, At, B1); PG8_BAR;
.LBB0_906:
	ds_read_b128 v[152:155], v149
	ds_read_b128 v[156:159], v149 offset:1024
	ds_read_b128 v[160:163], v149 offset:2048
	ds_read_b128 v[164:167], v149 offset:3072
	s_add_u32 s18, s16, 0xfffc0080
	s_addc_u32 s19, s17, -1
	s_cmp_eq_u32 s47, 12
	s_cselect_b32 s21, s9, s19
	s_cselect_b32 s20, s41, s18
	s_cselect_b32 s19, s7, s46
	s_cselect_b32 s18, s42, s43
	v_lshl_add_u64 v[144:145], s[16:17], 0, v[136:137]
	s_add_i32 m0, s15, 0xc000
	ds_read_b128 v[168:171], v150
	ds_read_b128 v[172:175], v150 offset:1024
	ds_read_b128 v[176:179], v150 offset:2048
	ds_read_b128 v[180:183], v150 offset:3072
	ds_read_b128 v[184:187], v150 offset:4096
	ds_read_b128 v[188:191], v150 offset:5120
	ds_read_b128 v[192:195], v150 offset:6144
	ds_read_b128 v[196:199], v150 offset:7168
	global_load_lds_dwordx4 v[144:145], off
	v_lshl_add_u64 v[144:145], s[16:17], 0, v[138:139]
	s_add_i32 m0, s15, 0xe000
	s_nop 0
	global_load_lds_dwordx4 v[144:145], off
	s_waitcnt lgkmcnt(8)
	s_barrier
	s_waitcnt lgkmcnt(0)
	v_mfma_f32_16x16x32_bf16 v[124:127], v[152:155], v[168:171], v[124:127]
	v_mfma_f32_16x16x32_bf16 v[120:123], v[160:163], v[168:171], v[120:123]
	v_mfma_f32_16x16x32_bf16 v[108:111], v[152:155], v[176:179], v[108:111]
	v_mfma_f32_16x16x32_bf16 v[104:107], v[160:163], v[176:179], v[104:107]
	v_mfma_f32_16x16x32_bf16 v[92:95], v[152:155], v[184:187], v[92:95]
	v_mfma_f32_16x16x32_bf16 v[88:91], v[160:163], v[184:187], v[88:91]
	v_mfma_f32_16x16x32_bf16 v[76:79], v[152:155], v[192:195], v[76:79]
	v_mfma_f32_16x16x32_bf16 v[72:75], v[160:163], v[192:195], v[72:75]
	v_mfma_f32_16x16x32_bf16 v[124:127], v[156:159], v[172:175], v[124:127]
	v_mfma_f32_16x16x32_bf16 v[120:123], v[164:167], v[172:175], v[120:123]
	v_mfma_f32_16x16x32_bf16 v[108:111], v[156:159], v[180:183], v[108:111]
	v_mfma_f32_16x16x32_bf16 v[104:107], v[164:167], v[180:183], v[104:107]
	v_mfma_f32_16x16x32_bf16 v[92:95], v[156:159], v[188:191], v[92:95]
	v_mfma_f32_16x16x32_bf16 v[88:91], v[164:167], v[188:191], v[88:91]
	v_mfma_f32_16x16x32_bf16 v[76:79], v[156:159], v[196:199], v[76:79]
	v_mfma_f32_16x16x32_bf16 v[72:75], v[164:167], v[196:199], v[72:75]
	s_barrier
	s_add_i32 s50, s37, s24
	v_lshl_add_u64 v[144:145], s[18:19], 0, v[132:133]
	s_mov_b32 m0, s50
	ds_read_b128 v[200:203], v151
	ds_read_b128 v[204:207], v151 offset:1024
	ds_read_b128 v[208:211], v151 offset:2048
	ds_read_b128 v[212:215], v151 offset:3072
	global_load_lds_dwordx4 v[144:145], off
	v_lshl_add_u64 v[216:217], s[18:19], 0, v[128:129]
	s_add_i32 m0, s50, 0x2000
	s_nop 0
	global_load_lds_dwordx4 v[216:217], off
	s_barrier
	s_waitcnt lgkmcnt(0)
	v_mfma_f32_16x16x32_bf16 v[116:119], v[200:203], v[168:171], v[116:119]
	v_mfma_f32_16x16x32_bf16 v[112:115], v[208:211], v[168:171], v[112:115]
	v_mfma_f32_16x16x32_bf16 v[100:103], v[200:203], v[176:179], v[100:103]
	v_mfma_f32_16x16x32_bf16 v[96:99], v[208:211], v[176:179], v[96:99]
	v_mfma_f32_16x16x32_bf16 v[84:87], v[200:203], v[184:187], v[84:87]
	v_mfma_f32_16x16x32_bf16 v[80:83], v[208:211], v[184:187], v[80:83]
	v_mfma_f32_16x16x32_bf16 v[68:71], v[200:203], v[192:195], v[68:71]
	v_mfma_f32_16x16x32_bf16 v[64:67], v[208:211], v[192:195], v[64:67]
	v_mfma_f32_16x16x32_bf16 v[116:119], v[204:207], v[172:175], v[116:119]
	v_mfma_f32_16x16x32_bf16 v[112:115], v[212:215], v[172:175], v[112:115]
	v_mfma_f32_16x16x32_bf16 v[100:103], v[204:207], v[180:183], v[100:103]
	v_mfma_f32_16x16x32_bf16 v[96:99], v[212:215], v[180:183], v[96:99]
	v_mfma_f32_16x16x32_bf16 v[84:87], v[204:207], v[188:191], v[84:87]
	v_mfma_f32_16x16x32_bf16 v[80:83], v[212:215], v[188:191], v[80:83]
	v_mfma_f32_16x16x32_bf16 v[68:71], v[204:207], v[196:199], v[68:71]
	v_mfma_f32_16x16x32_bf16 v[64:67], v[212:215], v[196:199], v[64:67]
	s_mov_b32 m0, s15
	v_lshl_add_u64 v[218:219], s[20:21], 0, v[134:135]
	s_barrier
	ds_read_b128 v[168:171], v150 offset:16384
	ds_read_b128 v[172:175], v150 offset:17408
	ds_read_b128 v[176:179], v150 offset:18432
	ds_read_b128 v[180:183], v150 offset:19456
	ds_read_b128 v[184:187], v150 offset:20480
	ds_read_b128 v[188:191], v150 offset:21504
	ds_read_b128 v[192:195], v150 offset:22528
	ds_read_b128 v[196:199], v150 offset:23552
	global_load_lds_dwordx4 v[218:219], off
	v_lshl_add_u64 v[220:221], s[20:21], 0, v[130:131]
	s_mov_b32 m0, s27
	s_nop 0
	global_load_lds_dwordx4 v[220:221], off
	s_barrier
	s_waitcnt lgkmcnt(0)
	v_mfma_f32_16x16x32_bf16 v[60:63], v[152:155], v[168:171], v[60:63]
	v_mfma_f32_16x16x32_bf16 v[56:59], v[160:163], v[168:171], v[56:59]
	v_mfma_f32_16x16x32_bf16 v[44:47], v[152:155], v[176:179], v[44:47]
	v_mfma_f32_16x16x32_bf16 v[40:43], v[160:163], v[176:179], v[40:43]
	v_mfma_f32_16x16x32_bf16 v[28:31], v[152:155], v[184:187], v[28:31]
	v_mfma_f32_16x16x32_bf16 v[24:27], v[160:163], v[184:187], v[24:27]
	v_mfma_f32_16x16x32_bf16 v[12:15], v[152:155], v[192:195], v[12:15]
	v_mfma_f32_16x16x32_bf16 v[8:11], v[160:163], v[192:195], v[8:11]
	v_mfma_f32_16x16x32_bf16 v[60:63], v[156:159], v[172:175], v[60:63]
	v_mfma_f32_16x16x32_bf16 v[56:59], v[164:167], v[172:175], v[56:59]
	v_mfma_f32_16x16x32_bf16 v[44:47], v[156:159], v[180:183], v[44:47]
	v_mfma_f32_16x16x32_bf16 v[40:43], v[164:167], v[180:183], v[40:43]
	v_mfma_f32_16x16x32_bf16 v[28:31], v[156:159], v[188:191], v[28:31]
	v_mfma_f32_16x16x32_bf16 v[24:27], v[164:167], v[188:191], v[24:27]
	v_mfma_f32_16x16x32_bf16 v[12:15], v[156:159], v[196:199], v[12:15]
	v_mfma_f32_16x16x32_bf16 v[8:11], v[164:167], v[196:199], v[8:11]
	s_barrier
; #define PG8_STAGE(bufoff, gbase, voff) do { _Pragma("unroll") for (int _i = 0; _i < 2; ++_i) \
;         __builtin_amdgcn_global_load_lds((const unsigned*)((const char*)(gbase) + (voff)[_i]), (PG8_LAS unsigned*)(lds + (bufoff) + ldsw + _i * 8192), 16, 0, 0); } while (0)
; #define PG8_LDA(dst, b, h) do { _Pragma("unroll") for (int m = 0; m < 4; ++m) _Pragma("unroll") for (int k = 0; k < 2; ++k) dst[m][k] = *(const PG8_LAS bf16x8*)(lds + PG8_SA(b, h) + aoff + m * 2048 + k * 1024); } while (0)
; #define PG8_LDB(dst, b, h) do { _Pragma("unroll") for (int n = 0; n < 2; ++n) _Pragma("unroll") for (int k = 0; k < 2; ++k) dst[n][k] = *(const PG8_LAS bf16x8*)(lds + PG8_SB(b, h) + boff + n * 2048 + k * 1024); } while (0)
; #define PG8_WAIT_V(n) asm volatile("s_waitcnt vmcnt(" #n ")" ::: "memory")
; #define PG8_WAIT_L(n) asm volatile("s_waitcnt lgkmcnt(" #n ")" ::: "memory")
; #define PG8_BAR __builtin_amdgcn_s_barrier()
; #define PG8_SCHED __builtin_amdgcn_sched_barrier(0)
; template <class Epi, class Sched>
; __device__ __forceinline__ void gemm_phase(PG8_LAS unsigned char* lds, const Gemm g, const Sched& S, const Epi& E) {
;     ...
;             PG8_LDB(B0, 0, 0); PG8_SCHED; PG8_LDA(At, 0, 0); PG8_STAGE(PG8_SA(1, 1), a1 + hstep, voffA);
;             PG8_WAIT_L(8); PG8_BAR; PG8_WAIT_L(0); PG8_MMA(0, 0, At, B0); PG8_BAR; PG8_SCHED;
;             PG8_LDB(B1, 0, 1); PG8_STAGE(PG8_SB(0, 0), b2, voffB);
;             PG8_BAR; PG8_WAIT_L(0); PG8_MMA(0, 1, At, B1); PG8_BAR;
;             PG8_LDA(At, 0, 1); PG8_STAGE(PG8_SA(0, 0), a2, voffA);
;             PG8_BAR; PG8_WAIT_L(0); PG8_MMA(1, 0, At, B0); PG8_BAR; PG8_SCHED;
;             PG8_STAGE(PG8_SB(0, 1), b2 + hstep, voffB);
;             PG8_WAIT_V(6); PG8_BAR; PG8_MMA(1, 1, At, B1); PG8_BAR;
;             PG8_LDB(B0, 1, 0); PG8_SCHED; PG8_LDA(At, 1, 0); PG8_STAGE(PG8_SA(0, 1), a2 + hstep, voffA);
;             PG8_WAIT_L(8); PG8_BAR; PG8_WAIT_L(0); PG8_MMA(0, 0, At, B0); PG8_BAR; PG8_SCHED;
;             PG8_LDB(B1, 1, 1); PG8_STAGE(PG8_SB(1, 0), b3, voffB);
;             PG8_BAR; PG8_WAIT_L(0); PG8_MMA(0, 1, At, B1); PG8_BAR;
;             PG8_LDA(At, 1, 1); PG8_STAGE(PG8_SA(1, 0), a3, voffA);
;             PG8_BAR; PG8_WAIT_L(0); PG8_MMA(1, 0, At, B0); PG8_BAR; PG8_SCHED;
;             PG8_STAGE(PG8_SB(1, 1), b3 + hstep, voffB);
;             PG8_WAIT_V(6); PG8_BAR; PG8_MMA(1, 1, At, B1); PG8_BAR;
	s_add_u32 s50, s18, 0x40000
	s_addc_u32 s51, s19, 0
	s_add_i32 s60, s38, s24
	v_lshl_add_u64 v[152:153], s[50:51], 0, v[132:133]
	s_mov_b32 m0, s60
	s_nop 0
	global_load_lds_dwordx4 v[152:153], off
	v_lshl_add_u64 v[152:153], s[50:51], 0, v[128:129]
	s_add_i32 m0, s60, 0x2000
	s_nop 0
	global_load_lds_dwordx4 v[152:153], off
	s_waitcnt vmcnt(6)
	s_barrier
	v_mfma_f32_16x16x32_bf16 v[52:55], v[200:203], v[168:171], v[52:55]
	v_mfma_f32_16x16x32_bf16 v[48:51], v[208:211], v[168:171], v[48:51]
	v_mfma_f32_16x16x32_bf16 v[36:39], v[200:203], v[176:179], v[36:39]
	v_mfma_f32_16x16x32_bf16 v[32:35], v[208:211], v[176:179], v[32:35]
	v_mfma_f32_16x16x32_bf16 v[20:23], v[200:203], v[184:187], v[20:23]
	v_mfma_f32_16x16x32_bf16 v[16:19], v[208:211], v[184:187], v[16:19]
	v_mfma_f32_16x16x32_bf16 v[4:7], v[200:203], v[192:195], v[4:7]
	v_mfma_f32_16x16x32_bf16 v[0:3], v[208:211], v[192:195], v[0:3]
	v_mfma_f32_16x16x32_bf16 v[52:55], v[204:207], v[172:175], v[52:55]
	v_mfma_f32_16x16x32_bf16 v[48:51], v[212:215], v[172:175], v[48:51]
	v_mfma_f32_16x16x32_bf16 v[36:39], v[204:207], v[180:183], v[36:39]
	v_mfma_f32_16x16x32_bf16 v[32:35], v[212:215], v[180:183], v[32:35]
	v_mfma_f32_16x16x32_bf16 v[20:23], v[204:207], v[188:191], v[20:23]
	v_mfma_f32_16x16x32_bf16 v[16:19], v[212:215], v[188:191], v[16:19]
	v_mfma_f32_16x16x32_bf16 v[4:7], v[204:207], v[196:199], v[4:7]
	v_mfma_f32_16x16x32_bf16 v[0:3], v[212:215], v[196:199], v[0:3]
	s_add_i32 s50, 0, 0x18000
	v_add_u32_e32 v164, s50, v147
	s_barrier
	ds_read_b128 v[152:155], v164
	ds_read_b128 v[156:159], v164 offset:1024
	ds_read_b128 v[160:163], v164 offset:2048
	ds_read_b128 v[164:167], v164 offset:3072
	s_add_u32 s20, s20, 0x40000
	s_addc_u32 s21, s21, 0
	s_mov_b32 m0, s28
	v_lshl_add_u64 v[200:201], s[20:21], 0, v[134:135]
	ds_read_b128 v[168:171], v150 offset:32768
	ds_read_b128 v[172:175], v150 offset:33792
	ds_read_b128 v[176:179], v150 offset:34816
	ds_read_b128 v[180:183], v150 offset:35840
	ds_read_b128 v[184:187], v150 offset:36864
	ds_read_b128 v[188:191], v150 offset:37888
	ds_read_b128 v[192:195], v150 offset:38912
	ds_read_b128 v[196:199], v150 offset:39936
	global_load_lds_dwordx4 v[200:201], off
	v_lshl_add_u64 v[200:201], s[20:21], 0, v[130:131]
	s_mov_b32 m0, s29
	s_nop 0
	global_load_lds_dwordx4 v[200:201], off
	s_waitcnt lgkmcnt(8)
	s_barrier
	s_waitcnt lgkmcnt(0)
	v_mfma_f32_16x16x32_bf16 v[124:127], v[152:155], v[168:171], v[124:127]
	v_mfma_f32_16x16x32_bf16 v[120:123], v[160:163], v[168:171], v[120:123]
	v_mfma_f32_16x16x32_bf16 v[108:111], v[152:155], v[176:179], v[108:111]
	v_mfma_f32_16x16x32_bf16 v[104:107], v[160:163], v[176:179], v[104:107]
	v_mfma_f32_16x16x32_bf16 v[92:95], v[152:155], v[184:187], v[92:95]
	v_mfma_f32_16x16x32_bf16 v[88:91], v[160:163], v[184:187], v[88:91]
	v_mfma_f32_16x16x32_bf16 v[76:79], v[152:155], v[192:195], v[76:79]
	v_mfma_f32_16x16x32_bf16 v[72:75], v[160:163], v[192:195], v[72:75]
	v_mfma_f32_16x16x32_bf16 v[124:127], v[156:159], v[172:175], v[124:127]
	v_mfma_f32_16x16x32_bf16 v[120:123], v[164:167], v[172:175], v[120:123]
	v_mfma_f32_16x16x32_bf16 v[108:111], v[156:159], v[180:183], v[108:111]
	v_mfma_f32_16x16x32_bf16 v[104:107], v[164:167], v[180:183], v[104:107]
	v_mfma_f32_16x16x32_bf16 v[92:95], v[156:159], v[188:191], v[92:95]
	v_mfma_f32_16x16x32_bf16 v[88:91], v[164:167], v[188:191], v[88:91]
	v_mfma_f32_16x16x32_bf16 v[76:79], v[156:159], v[196:199], v[76:79]
	v_mfma_f32_16x16x32_bf16 v[72:75], v[164:167], v[196:199], v[72:75]
	s_barrier
	s_add_i32 s20, 0, 0x1c000
	s_add_i32 s21, s50, s24
	v_add_u32_e32 v212, s20, v147
	v_lshl_add_u64 v[144:145], v[144:145], 0, s[4:5]
	s_mov_b32 m0, s21
	ds_read_b128 v[200:203], v212
	ds_read_b128 v[204:207], v212 offset:1024
	ds_read_b128 v[208:211], v212 offset:2048
	ds_read_b128 v[212:215], v212 offset:3072
	global_load_lds_dwordx4 v[144:145], off
	v_lshl_add_u64 v[144:145], v[216:217], 0, s[4:5]
	s_add_i32 m0, s21, 0x2000
	s_nop 0
	global_load_lds_dwordx4 v[144:145], off
	s_barrier
	s_waitcnt lgkmcnt(0)
	v_mfma_f32_16x16x32_bf16 v[116:119], v[200:203], v[168:171], v[116:119]
	v_mfma_f32_16x16x32_bf16 v[112:115], v[208:211], v[168:171], v[112:115]
	v_mfma_f32_16x16x32_bf16 v[100:103], v[200:203], v[176:179], v[100:103]
	v_mfma_f32_16x16x32_bf16 v[96:99], v[208:211], v[176:179], v[96:99]
	v_mfma_f32_16x16x32_bf16 v[84:87], v[200:203], v[184:187], v[84:87]
	v_mfma_f32_16x16x32_bf16 v[80:83], v[208:211], v[184:187], v[80:83]
	v_mfma_f32_16x16x32_bf16 v[68:71], v[200:203], v[192:195], v[68:71]
	v_mfma_f32_16x16x32_bf16 v[64:67], v[208:211], v[192:195], v[64:67]
	v_mfma_f32_16x16x32_bf16 v[116:119], v[204:207], v[172:175], v[116:119]
	v_mfma_f32_16x16x32_bf16 v[112:115], v[212:215], v[172:175], v[112:115]
	v_mfma_f32_16x16x32_bf16 v[100:103], v[204:207], v[180:183], v[100:103]
	v_mfma_f32_16x16x32_bf16 v[96:99], v[212:215], v[180:183], v[96:99]
	v_mfma_f32_16x16x32_bf16 v[84:87], v[204:207], v[188:191], v[84:87]
	v_mfma_f32_16x16x32_bf16 v[80:83], v[212:215], v[188:191], v[80:83]
	v_mfma_f32_16x16x32_bf16 v[68:71], v[204:207], v[196:199], v[68:71]
	v_mfma_f32_16x16x32_bf16 v[64:67], v[212:215], v[196:199], v[64:67]
	s_mov_b32 m0, s31
	v_lshl_add_u64 v[144:145], v[218:219], 0, s[4:5]
	s_barrier
	ds_read_b128 v[168:171], v150 offset:49152
	ds_read_b128 v[172:175], v150 offset:50176
	ds_read_b128 v[176:179], v150 offset:51200
	ds_read_b128 v[180:183], v150 offset:52224
	ds_read_b128 v[184:187], v150 offset:53248
	ds_read_b128 v[188:191], v150 offset:54272
	ds_read_b128 v[192:195], v150 offset:55296
	ds_read_b128 v[196:199], v150 offset:56320
	global_load_lds_dwordx4 v[144:145], off
	v_lshl_add_u64 v[144:145], v[220:221], 0, s[4:5]
	s_mov_b32 m0, s34
	s_nop 0
	global_load_lds_dwordx4 v[144:145], off
	s_barrier
; #define PG8_STAGE(bufoff, gbase, voff) do { _Pragma("unroll") for (int _i = 0; _i < 2; ++_i) \
;         __builtin_amdgcn_global_load_lds((const unsigned*)((const char*)(gbase) + (voff)[_i]), (PG8_LAS unsigned*)(lds + (bufoff) + ldsw + _i * 8192), 16, 0, 0); } while (0)
; #define PG8_MMA(ai, bj, At, Bt) do { __builtin_amdgcn_s_setprio(1); _Pragma("unroll") for (int m = 0; m < 4; ++m) _Pragma("unroll") for (int n = 0; n < 2; ++n) _Pragma("unroll") for (int k = 0; k < 2; ++k) \
;         acc[ai][bj][m][n] = __builtin_amdgcn_mfma_f32_16x16x32_bf16(Bt[n][k], At[m][k], acc[ai][bj][m][n], 0, 0, 0); __builtin_amdgcn_s_setprio(0); } while (0)
; #define PG8_WAIT_V(n) asm volatile("s_waitcnt vmcnt(" #n ")" ::: "memory")
; #define PG8_WAIT_L(n) asm volatile("s_waitcnt lgkmcnt(" #n ")" ::: "memory")
; #define PG8_BAR __builtin_amdgcn_s_barrier()
; #define PG8_SCHED __builtin_amdgcn_sched_barrier(0)
; __device__ __forceinline__ unsigned pk2(float lo, float hi) { unsigned r; asm("v_cvt_pk_bf16_f32 %0, %1, %2" : "=v"(r) : "v"(lo), "v"(hi)); return r; }
; __device__ __forceinline__ float siluf_(float x) { return x * __builtin_amdgcn_rcpf(1.0f + __expf(-x)); }
; template <class Epi, class Sched>
; __device__ __forceinline__ void gemm_phase(PG8_LAS unsigned char* lds, const Gemm g, const Sched& S, const Epi& E) {
;     ...
;             PG8_BAR; PG8_WAIT_L(0); PG8_MMA(1, 0, At, B0); PG8_BAR; PG8_SCHED;
;             PG8_STAGE(PG8_SB(1, 1), b3 + hstep, voffB);
;             PG8_WAIT_V(6); PG8_BAR; PG8_MMA(1, 1, At, B1); PG8_BAR;
;     __device__ __forceinline__ void operator()(const f32x4 (&acc)[2][2][4][2], const Unit& u, int wr, int wc, int fr, int fq) const {
;     ...
;         for (int ai = 0; ai < 2; ++ai)
; #pragma unroll
;             for (int m = 0; m < 4; ++m) { bf16_t* rowp = O + (size_t)(row0 + ai * HALF + m * 16) * DFF + col0; float o[8];
; #pragma unroll
;                 for (int n = 0; n < 2; ++n) { const f32x4 g = acc[ai][0][m][n], up = acc[ai][1][m][n];
; #pragma unroll
;                     for (int j = 0; j < 4; ++j) o[4 * n + j] = siluf_(g[j]) * up[j]; }
;                 u32x4 w; w.x = pk2(o[0], o[1]); w.y = pk2(o[2], o[3]); w.z = pk2(o[4], o[5]); w.w = pk2(o[6], o[7]); *(u32x4*)rowp = w; }
	s_waitcnt lgkmcnt(0)
	v_mfma_f32_16x16x32_bf16 v[60:63], v[152:155], v[168:171], v[60:63]
	v_mfma_f32_16x16x32_bf16 v[56:59], v[160:163], v[168:171], v[56:59]
	v_mfma_f32_16x16x32_bf16 v[44:47], v[152:155], v[176:179], v[44:47]
	v_mfma_f32_16x16x32_bf16 v[40:43], v[160:163], v[176:179], v[40:43]
	v_mfma_f32_16x16x32_bf16 v[28:31], v[152:155], v[184:187], v[28:31]
	v_mfma_f32_16x16x32_bf16 v[24:27], v[160:163], v[184:187], v[24:27]
	v_mfma_f32_16x16x32_bf16 v[12:15], v[152:155], v[192:195], v[12:15]
	v_mfma_f32_16x16x32_bf16 v[8:11], v[160:163], v[192:195], v[8:11]
	v_mfma_f32_16x16x32_bf16 v[60:63], v[156:159], v[172:175], v[60:63]
	v_mfma_f32_16x16x32_bf16 v[56:59], v[164:167], v[172:175], v[56:59]
	v_mfma_f32_16x16x32_bf16 v[44:47], v[156:159], v[180:183], v[44:47]
	v_mfma_f32_16x16x32_bf16 v[40:43], v[164:167], v[180:183], v[40:43]
	v_mfma_f32_16x16x32_bf16 v[28:31], v[156:159], v[188:191], v[28:31]
	v_mfma_f32_16x16x32_bf16 v[24:27], v[164:167], v[188:191], v[24:27]
	v_mfma_f32_16x16x32_bf16 v[12:15], v[156:159], v[196:199], v[12:15]
	v_mfma_f32_16x16x32_bf16 v[8:11], v[164:167], v[196:199], v[8:11]
	s_barrier
	s_add_u32 s18, s18, 0x40080
	s_addc_u32 s19, s19, 0
	s_add_i32 s20, s20, s24
	v_lshl_add_u64 v[144:145], s[18:19], 0, v[132:133]
	s_mov_b32 m0, s20
	s_nop 0
	global_load_lds_dwordx4 v[144:145], off
	v_lshl_add_u64 v[144:145], s[18:19], 0, v[128:129]
	s_add_i32 m0, s20, 0x2000
	s_nop 0
	global_load_lds_dwordx4 v[144:145], off
	s_waitcnt vmcnt(6)
	s_barrier
	v_mfma_f32_16x16x32_bf16 v[52:55], v[200:203], v[168:171], v[52:55]
	v_mfma_f32_16x16x32_bf16 v[48:51], v[208:211], v[168:171], v[48:51]
	v_mfma_f32_16x16x32_bf16 v[36:39], v[200:203], v[176:179], v[36:39]
	v_mfma_f32_16x16x32_bf16 v[32:35], v[208:211], v[176:179], v[32:35]
	v_mfma_f32_16x16x32_bf16 v[20:23], v[200:203], v[184:187], v[20:23]
	v_mfma_f32_16x16x32_bf16 v[16:19], v[208:211], v[184:187], v[16:19]
	v_mfma_f32_16x16x32_bf16 v[4:7], v[200:203], v[192:195], v[4:7]
	v_mfma_f32_16x16x32_bf16 v[0:3], v[208:211], v[192:195], v[0:3]
	v_mfma_f32_16x16x32_bf16 v[52:55], v[204:207], v[172:175], v[52:55]
	v_mfma_f32_16x16x32_bf16 v[48:51], v[212:215], v[172:175], v[48:51]
	v_mfma_f32_16x16x32_bf16 v[36:39], v[204:207], v[180:183], v[36:39]
	v_mfma_f32_16x16x32_bf16 v[32:35], v[212:215], v[180:183], v[32:35]
	v_mfma_f32_16x16x32_bf16 v[20:23], v[204:207], v[188:191], v[20:23]
	v_mfma_f32_16x16x32_bf16 v[16:19], v[212:215], v[188:191], v[16:19]
	v_mfma_f32_16x16x32_bf16 v[4:7], v[204:207], v[196:199], v[4:7]
	v_mfma_f32_16x16x32_bf16 v[0:3], v[212:215], v[196:199], v[0:3]
	s_add_i32 s47, s47, 2
	s_add_u32 s16, s16, 0x100
	s_addc_u32 s17, s17, 0
	s_add_u32 s43, s43, 0x100
	s_addc_u32 s46, s46, 0
	s_cmp_gt_u32 s47, 13
	s_barrier
	s_cbranch_scc0 .LBB0_906
	v_mul_f32_e32 v144, 0xbfb8aa3b, v124
	v_exp_f32_e32 v153, v144
	v_mul_f32_e32 v144, 0xbfb8aa3b, v125
	v_exp_f32_e32 v156, v144
	v_lshl_or_b32 v154, s40, 7, v148
	v_add_f32_e32 v153, 1.0, v153
	v_rcp_f32_e32 v153, v153
	v_add_f32_e32 v156, 1.0, v156
	v_rcp_f32_e32 v158, v156
	v_lshl_add_u32 v152, s14, 8, v146
	v_mul_f32_e32 v124, v124, v153
	v_mul_f32_e32 v116, v124, v116
	v_mul_f32_e32 v124, v125, v158
	v_mul_f32_e32 v125, 0xbfb8aa3b, v126
	v_exp_f32_e32 v125, v125
	v_mul_f32_e32 v153, 0xbfb8aa3b, v127
	v_exp_f32_e32 v153, v153
	v_mul_f32_e32 v117, v124, v117
	v_add_f32_e32 v124, 1.0, v125
	v_rcp_f32_e32 v124, v124
	v_add_f32_e32 v125, 1.0, v153
	v_mul_f32_e32 v153, 0xbfb8aa3b, v120
	v_rcp_f32_e32 v125, v125
	v_exp_f32_e32 v153, v153
	v_mul_f32_e32 v124, v126, v124
	v_mul_f32_e32 v124, v124, v118
	v_mul_f32_e32 v118, v127, v125
	v_add_f32_e32 v125, 1.0, v153
	v_rcp_f32_e32 v125, v125
	v_mul_f32_e32 v126, 0xbfb8aa3b, v121
	v_mul_f32_e32 v127, v118, v119
	v_exp_f32_e32 v126, v126
	v_mul_f32_e32 v118, v120, v125
	v_mul_f32_e32 v120, v118, v112
	v_mul_f32_e32 v118, 0xbfb8aa3b, v122
	v_exp_f32_e32 v118, v118
	v_mul_f32_e32 v119, 0xbfb8aa3b, v123
	v_exp_f32_e32 v119, v119
	v_add_f32_e32 v112, 1.0, v126
	v_rcp_f32_e32 v112, v112
	v_add_f32_e32 v118, 1.0, v118
	v_rcp_f32_e32 v118, v118
	v_add_f32_e32 v119, 1.0, v119
	v_rcp_f32_e32 v119, v119
	v_mul_f32_e32 v112, v121, v112
	v_mul_f32_e32 v121, v112, v113
	v_mul_f32_e32 v112, v122, v118
	v_ashrrev_i32_e32 v155, 31, v154
	v_mov_b64_e32 v[144:145], s[52:53]
	v_mul_f32_e32 v122, v112, v114
	v_mul_f32_e32 v112, v123, v119
	v_mad_i64_i32 v[156:157], s[16:17], v152, s39, v[144:145]
	v_mul_f32_e32 v123, v112, v115
	v_lshlrev_b64 v[112:113], 1, v[154:155]
	v_lshl_add_u64 v[118:119], v[156:157], 0, v[112:113]
	v_cvt_pk_bf16_f32 v114, v116, v117
	v_cvt_pk_bf16_f32 v115, v124, v127
	v_cvt_pk_bf16_f32 v116, v120, v121
	v_cvt_pk_bf16_f32 v117, v122, v123
	global_store_dwordx4 v[118:119], v[114:117], off
	s_and_b64 vcc, exec, s[0:1]
	s_mov_b32 s40, s6
	v_mul_f32_e32 v114, 0xbfb8aa3b, v108
	v_exp_f32_e32 v114, v114
	v_mul_f32_e32 v115, 0xbfb8aa3b, v109
	v_exp_f32_e32 v115, v115
	v_or_b32_e32 v116, 16, v152
	v_add_f32_e32 v114, 1.0, v114
	v_rcp_f32_e32 v117, v114
	v_add_f32_e32 v114, 1.0, v115
	v_rcp_f32_e32 v118, v114
	v_mad_i64_i32 v[114:115], s[16:17], v116, s39, v[144:145]
	v_mul_f32_e32 v108, v108, v117
	v_mul_f32_e32 v108, v108, v100
	v_mul_f32_e32 v100, v109, v118
	v_mul_f32_e32 v109, 0xbfb8aa3b, v110
	v_exp_f32_e32 v109, v109
	v_mul_f32_e32 v116, 0xbfb8aa3b, v111
	v_exp_f32_e32 v116, v116
	v_mul_f32_e32 v117, v100, v101
	v_add_f32_e32 v100, 1.0, v109
	v_rcp_f32_e32 v100, v100
	v_add_f32_e32 v101, 1.0, v116
	v_mul_f32_e32 v109, 0xbfb8aa3b, v104
	v_rcp_f32_e32 v101, v101
	v_exp_f32_e32 v109, v109
	v_mul_f32_e32 v100, v110, v100
	v_mul_f32_e32 v102, v100, v102
	v_mul_f32_e32 v100, v111, v101
; __device__ __forceinline__ unsigned pk2(float lo, float hi) { unsigned r; asm("v_cvt_pk_bf16_f32 %0, %1, %2" : "=v"(r) : "v"(lo), "v"(hi)); return r; }
; __device__ __forceinline__ float siluf_(float x) { return x * __builtin_amdgcn_rcpf(1.0f + __expf(-x)); }
;     __device__ __forceinline__ void operator()(const f32x4 (&acc)[2][2][4][2], const Unit& u, int wr, int wc, int fr, int fq) const {
;     ...
;         for (int ai = 0; ai < 2; ++ai)
; #pragma unroll
;             for (int m = 0; m < 4; ++m) { bf16_t* rowp = O + (size_t)(row0 + ai * HALF + m * 16) * DFF + col0; float o[8];
; #pragma unroll
;                 for (int n = 0; n < 2; ++n) { const f32x4 g = acc[ai][0][m][n], up = acc[ai][1][m][n];
; #pragma unroll
;                     for (int j = 0; j < 4; ++j) o[4 * n + j] = siluf_(g[j]) * up[j]; }
;                 u32x4 w; w.x = pk2(o[0], o[1]); w.y = pk2(o[2], o[3]); w.z = pk2(o[4], o[5]); w.w = pk2(o[6], o[7]); *(u32x4*)rowp = w; }
	v_add_f32_e32 v101, 1.0, v109
	v_rcp_f32_e32 v101, v101
	v_mul_f32_e32 v109, 0xbfb8aa3b, v105
	v_mul_f32_e32 v103, v100, v103
	v_exp_f32_e32 v109, v109
	v_mul_f32_e32 v100, v104, v101
	v_mul_f32_e32 v104, v100, v96
	v_mul_f32_e32 v100, 0xbfb8aa3b, v106
	v_exp_f32_e32 v100, v100
	v_mul_f32_e32 v101, 0xbfb8aa3b, v107
	v_exp_f32_e32 v101, v101
	v_add_f32_e32 v96, 1.0, v109
	v_rcp_f32_e32 v96, v96
	v_add_f32_e32 v100, 1.0, v100
	v_rcp_f32_e32 v100, v100
	v_add_f32_e32 v101, 1.0, v101
	v_rcp_f32_e32 v101, v101
	v_mul_f32_e32 v96, v105, v96
	v_mul_f32_e32 v105, v96, v97
	v_mul_f32_e32 v96, v106, v100
	v_mul_f32_e32 v106, v96, v98
	v_mul_f32_e32 v96, v107, v101
	v_mul_f32_e32 v99, v96, v99
	v_lshl_add_u64 v[100:101], v[114:115], 0, v[112:113]
	v_cvt_pk_bf16_f32 v96, v108, v117
	v_cvt_pk_bf16_f32 v97, v102, v103
	v_cvt_pk_bf16_f32 v98, v104, v105
	v_cvt_pk_bf16_f32 v99, v106, v99
	global_store_dwordx4 v[100:101], v[96:99], off
	s_mov_b32 s14, s8
	s_mov_b64 s[18:19], s[12:13]
	v_mul_f32_e32 v96, 0xbfb8aa3b, v92
	v_exp_f32_e32 v96, v96
	v_mul_f32_e32 v97, 0xbfb8aa3b, v93
	v_exp_f32_e32 v97, v97
	v_or_b32_e32 v98, 32, v152
	v_add_f32_e32 v96, 1.0, v96
	v_rcp_f32_e32 v99, v96
	v_add_f32_e32 v96, 1.0, v97
	v_rcp_f32_e32 v100, v96
	v_mad_i64_i32 v[96:97], s[16:17], v98, s39, v[144:145]
	v_mul_f32_e32 v92, v92, v99
	v_mul_f32_e32 v92, v92, v84
	v_mul_f32_e32 v84, v93, v100
	v_mul_f32_e32 v93, 0xbfb8aa3b, v94
	v_exp_f32_e32 v93, v93
	v_mul_f32_e32 v98, 0xbfb8aa3b, v95
	v_exp_f32_e32 v98, v98
	v_mul_f32_e32 v99, v84, v85
	v_add_f32_e32 v84, 1.0, v93
	v_rcp_f32_e32 v84, v84
	v_add_f32_e32 v85, 1.0, v98
	v_mul_f32_e32 v93, 0xbfb8aa3b, v88
	v_rcp_f32_e32 v85, v85
	v_exp_f32_e32 v93, v93
	v_mul_f32_e32 v84, v94, v84
	v_mul_f32_e32 v86, v84, v86
	v_mul_f32_e32 v84, v95, v85
	v_add_f32_e32 v85, 1.0, v93
	v_rcp_f32_e32 v85, v85
	v_mul_f32_e32 v93, 0xbfb8aa3b, v89
	v_mul_f32_e32 v87, v84, v87
	v_exp_f32_e32 v93, v93
	v_mul_f32_e32 v84, v88, v85
	v_mul_f32_e32 v88, v84, v80
	v_mul_f32_e32 v84, 0xbfb8aa3b, v90
	v_exp_f32_e32 v84, v84
	v_mul_f32_e32 v85, 0xbfb8aa3b, v91
	v_exp_f32_e32 v85, v85
	v_add_f32_e32 v80, 1.0, v93
	v_rcp_f32_e32 v80, v80
	v_add_f32_e32 v84, 1.0, v84
	v_rcp_f32_e32 v84, v84
	v_add_f32_e32 v85, 1.0, v85
	v_rcp_f32_e32 v85, v85
	v_mul_f32_e32 v80, v89, v80
	v_mul_f32_e32 v89, v80, v81
	v_mul_f32_e32 v80, v90, v84
	v_mul_f32_e32 v90, v80, v82
	v_mul_f32_e32 v80, v91, v85
	v_mul_f32_e32 v83, v80, v83
	v_lshl_add_u64 v[84:85], v[96:97], 0, v[112:113]
	v_cvt_pk_bf16_f32 v80, v92, v99
	v_cvt_pk_bf16_f32 v81, v86, v87
	v_cvt_pk_bf16_f32 v82, v88, v89
	v_cvt_pk_bf16_f32 v83, v90, v83
	global_store_dwordx4 v[84:85], v[80:83], off
	s_nop 1
	v_mul_f32_e32 v80, 0xbfb8aa3b, v76
	v_exp_f32_e32 v80, v80
	v_mul_f32_e32 v81, 0xbfb8aa3b, v77
	v_exp_f32_e32 v81, v81
	v_or_b32_e32 v82, 48, v152
	v_add_f32_e32 v80, 1.0, v80
	v_rcp_f32_e32 v83, v80
	v_add_f32_e32 v80, 1.0, v81
	v_rcp_f32_e32 v84, v80
	v_mad_i64_i32 v[80:81], s[16:17], v82, s39, v[144:145]
	v_mul_f32_e32 v76, v76, v83
	v_mul_f32_e32 v76, v76, v68
	v_mul_f32_e32 v68, v77, v84
	v_mul_f32_e32 v77, 0xbfb8aa3b, v78
	v_exp_f32_e32 v77, v77
	v_mul_f32_e32 v82, 0xbfb8aa3b, v79
	v_exp_f32_e32 v82, v82
	v_mul_f32_e32 v83, v68, v69
	v_add_f32_e32 v68, 1.0, v77
	v_rcp_f32_e32 v68, v68
	v_add_f32_e32 v69, 1.0, v82
	v_mul_f32_e32 v77, 0xbfb8aa3b, v72
	v_rcp_f32_e32 v69, v69
	v_exp_f32_e32 v77, v77
	v_mul_f32_e32 v68, v78, v68
	v_mul_f32_e32 v70, v68, v70
	v_mul_f32_e32 v68, v79, v69
	v_add_f32_e32 v69, 1.0, v77
	v_rcp_f32_e32 v69, v69
	v_mul_f32_e32 v77, 0xbfb8aa3b, v73
	v_mul_f32_e32 v71, v68, v71
	v_exp_f32_e32 v77, v77
	v_mul_f32_e32 v68, v72, v69
	v_mul_f32_e32 v72, v68, v64
	v_mul_f32_e32 v68, 0xbfb8aa3b, v74
	v_exp_f32_e32 v68, v68
	v_mul_f32_e32 v69, 0xbfb8aa3b, v75
	v_exp_f32_e32 v69, v69
	v_add_f32_e32 v64, 1.0, v77
	v_rcp_f32_e32 v64, v64
	v_add_f32_e32 v68, 1.0, v68
	v_rcp_f32_e32 v68, v68
	v_add_f32_e32 v69, 1.0, v69
	v_rcp_f32_e32 v69, v69
	v_mul_f32_e32 v64, v73, v64
	v_mul_f32_e32 v73, v64, v65
	v_mul_f32_e32 v64, v74, v68
	v_mul_f32_e32 v74, v64, v66
	v_mul_f32_e32 v64, v75, v69
	v_mul_f32_e32 v67, v64, v67
	v_lshl_add_u64 v[68:69], v[80:81], 0, v[112:113]
	v_cvt_pk_bf16_f32 v64, v76, v83
	v_cvt_pk_bf16_f32 v65, v70, v71
	v_cvt_pk_bf16_f32 v66, v72, v73
	v_cvt_pk_bf16_f32 v67, v74, v67
	global_store_dwordx4 v[68:69], v[64:67], off
	s_nop 1
	v_mul_f32_e32 v64, 0xbfb8aa3b, v60
	v_exp_f32_e32 v64, v64
	v_mul_f32_e32 v65, 0xbfb8aa3b, v61
	v_exp_f32_e32 v65, v65
	v_add_u32_e32 v66, 0x80, v152
	v_add_f32_e32 v64, 1.0, v64
	v_rcp_f32_e32 v67, v64
	v_add_f32_e32 v64, 1.0, v65
	v_rcp_f32_e32 v68, v64
	v_mad_i64_i32 v[64:65], s[16:17], v66, s39, v[144:145]
	v_mul_f32_e32 v60, v60, v67
	v_mul_f32_e32 v60, v60, v52
	v_mul_f32_e32 v52, v61, v68
	v_mul_f32_e32 v61, 0xbfb8aa3b, v62
	v_exp_f32_e32 v61, v61
	v_mul_f32_e32 v66, 0xbfb8aa3b, v63
	v_exp_f32_e32 v66, v66
	v_mul_f32_e32 v67, v52, v53
	v_add_f32_e32 v52, 1.0, v61
	v_rcp_f32_e32 v52, v52
	v_add_f32_e32 v53, 1.0, v66
	v_mul_f32_e32 v61, 0xbfb8aa3b, v56
	v_rcp_f32_e32 v53, v53
	v_exp_f32_e32 v61, v61
	v_mul_f32_e32 v52, v62, v52
	v_mul_f32_e32 v54, v52, v54
	v_mul_f32_e32 v52, v63, v53
	v_add_f32_e32 v53, 1.0, v61
	v_rcp_f32_e32 v53, v53
	v_mul_f32_e32 v61, 0xbfb8aa3b, v57
	v_mul_f32_e32 v55, v52, v55
	v_exp_f32_e32 v61, v61
	v_mul_f32_e32 v52, v56, v53
	v_mul_f32_e32 v56, v52, v48
	v_mul_f32_e32 v52, 0xbfb8aa3b, v58
	v_exp_f32_e32 v52, v52
	v_mul_f32_e32 v53, 0xbfb8aa3b, v59
	v_exp_f32_e32 v53, v53
	v_add_f32_e32 v48, 1.0, v61
	v_rcp_f32_e32 v48, v48
	v_add_f32_e32 v52, 1.0, v52
	v_rcp_f32_e32 v52, v52
; __device__ __forceinline__ unsigned pk2(float lo, float hi) { unsigned r; asm("v_cvt_pk_bf16_f32 %0, %1, %2" : "=v"(r) : "v"(lo), "v"(hi)); return r; }
; __device__ __forceinline__ float siluf_(float x) { return x * __builtin_amdgcn_rcpf(1.0f + __expf(-x)); }
;     __device__ __forceinline__ void operator()(const f32x4 (&acc)[2][2][4][2], const Unit& u, int wr, int wc, int fr, int fq) const {
;     ...
;         for (int ai = 0; ai < 2; ++ai)
; #pragma unroll
;             for (int m = 0; m < 4; ++m) { bf16_t* rowp = O + (size_t)(row0 + ai * HALF + m * 16) * DFF + col0; float o[8];
; #pragma unroll
;                 for (int n = 0; n < 2; ++n) { const f32x4 g = acc[ai][0][m][n], up = acc[ai][1][m][n];
; #pragma unroll
;                     for (int j = 0; j < 4; ++j) o[4 * n + j] = siluf_(g[j]) * up[j]; }
;                 u32x4 w; w.x = pk2(o[0], o[1]); w.y = pk2(o[2], o[3]); w.z = pk2(o[4], o[5]); w.w = pk2(o[6], o[7]); *(u32x4*)rowp = w; }
	v_add_f32_e32 v53, 1.0, v53
	v_rcp_f32_e32 v53, v53
	v_mul_f32_e32 v48, v57, v48
	v_mul_f32_e32 v57, v48, v49
	v_mul_f32_e32 v48, v58, v52
	v_mul_f32_e32 v58, v48, v50
	v_mul_f32_e32 v48, v59, v53
	v_mul_f32_e32 v51, v48, v51
	v_lshl_add_u64 v[52:53], v[64:65], 0, v[112:113]
	v_cvt_pk_bf16_f32 v48, v60, v67
	v_cvt_pk_bf16_f32 v49, v54, v55
	v_cvt_pk_bf16_f32 v50, v56, v57
	v_cvt_pk_bf16_f32 v51, v58, v51
	global_store_dwordx4 v[52:53], v[48:51], off
	s_nop 1
	v_mul_f32_e32 v48, 0xbfb8aa3b, v44
	v_exp_f32_e32 v48, v48
	v_mul_f32_e32 v49, 0xbfb8aa3b, v45
	v_exp_f32_e32 v49, v49
	v_add_u32_e32 v50, 0x90, v152
	v_add_f32_e32 v48, 1.0, v48
	v_rcp_f32_e32 v51, v48
	v_add_f32_e32 v48, 1.0, v49
	v_rcp_f32_e32 v52, v48
	v_mad_i64_i32 v[48:49], s[16:17], v50, s39, v[144:145]
	v_mul_f32_e32 v44, v44, v51
	v_mul_f32_e32 v44, v44, v36
	v_mul_f32_e32 v36, v45, v52
	v_mul_f32_e32 v45, 0xbfb8aa3b, v46
	v_exp_f32_e32 v45, v45
	v_mul_f32_e32 v50, 0xbfb8aa3b, v47
	v_exp_f32_e32 v50, v50
	v_mul_f32_e32 v51, v36, v37
	v_add_f32_e32 v36, 1.0, v45
	v_rcp_f32_e32 v36, v36
	v_add_f32_e32 v37, 1.0, v50
	v_mul_f32_e32 v45, 0xbfb8aa3b, v40
	v_rcp_f32_e32 v37, v37
	v_exp_f32_e32 v45, v45
	v_mul_f32_e32 v36, v46, v36
	v_mul_f32_e32 v38, v36, v38
	v_mul_f32_e32 v36, v47, v37
	v_add_f32_e32 v37, 1.0, v45
	v_rcp_f32_e32 v37, v37
	v_mul_f32_e32 v45, 0xbfb8aa3b, v41
	v_mul_f32_e32 v39, v36, v39
	v_exp_f32_e32 v45, v45
	v_mul_f32_e32 v36, v40, v37
	v_mul_f32_e32 v40, v36, v32
	v_mul_f32_e32 v36, 0xbfb8aa3b, v42
	v_exp_f32_e32 v36, v36
	v_mul_f32_e32 v37, 0xbfb8aa3b, v43
	v_exp_f32_e32 v37, v37
	v_add_f32_e32 v32, 1.0, v45
	v_rcp_f32_e32 v32, v32
	v_add_f32_e32 v36, 1.0, v36
	v_rcp_f32_e32 v36, v36
	v_add_f32_e32 v37, 1.0, v37
	v_rcp_f32_e32 v37, v37
	v_mul_f32_e32 v32, v41, v32
	v_mul_f32_e32 v41, v32, v33
	v_mul_f32_e32 v32, v42, v36
	v_mul_f32_e32 v42, v32, v34
	v_mul_f32_e32 v32, v43, v37
	v_mul_f32_e32 v35, v32, v35
	v_lshl_add_u64 v[36:37], v[48:49], 0, v[112:113]
	v_cvt_pk_bf16_f32 v32, v44, v51
	v_cvt_pk_bf16_f32 v33, v38, v39
	v_cvt_pk_bf16_f32 v34, v40, v41
	v_cvt_pk_bf16_f32 v35, v42, v35
	global_store_dwordx4 v[36:37], v[32:35], off
	s_nop 1
	v_mul_f32_e32 v32, 0xbfb8aa3b, v28
	v_exp_f32_e32 v32, v32
	v_mul_f32_e32 v33, 0xbfb8aa3b, v29
	v_exp_f32_e32 v33, v33
	v_add_u32_e32 v34, 0xa0, v152
	v_add_f32_e32 v32, 1.0, v32
	v_rcp_f32_e32 v35, v32
	v_add_f32_e32 v32, 1.0, v33
	v_rcp_f32_e32 v36, v32
	v_mad_i64_i32 v[32:33], s[16:17], v34, s39, v[144:145]
	v_mul_f32_e32 v28, v28, v35
	v_mul_f32_e32 v28, v28, v20
	v_mul_f32_e32 v20, v29, v36
	v_mul_f32_e32 v29, 0xbfb8aa3b, v30
	v_exp_f32_e32 v29, v29
	v_mul_f32_e32 v34, 0xbfb8aa3b, v31
	v_exp_f32_e32 v34, v34
	v_mul_f32_e32 v35, v20, v21
	v_add_f32_e32 v20, 1.0, v29
	v_rcp_f32_e32 v20, v20
	v_add_f32_e32 v21, 1.0, v34
	v_mul_f32_e32 v29, 0xbfb8aa3b, v24
	v_rcp_f32_e32 v21, v21
	v_exp_f32_e32 v29, v29
	v_mul_f32_e32 v20, v30, v20
	v_mul_f32_e32 v22, v20, v22
	v_mul_f32_e32 v20, v31, v21
	v_add_f32_e32 v21, 1.0, v29
	v_rcp_f32_e32 v21, v21
	v_mul_f32_e32 v29, 0xbfb8aa3b, v25
	v_mul_f32_e32 v23, v20, v23
	v_exp_f32_e32 v29, v29
	v_mul_f32_e32 v20, v24, v21
	v_mul_f32_e32 v24, v20, v16
	v_mul_f32_e32 v20, 0xbfb8aa3b, v26
	v_exp_f32_e32 v20, v20
	v_mul_f32_e32 v21, 0xbfb8aa3b, v27
	v_exp_f32_e32 v21, v21
	v_add_f32_e32 v16, 1.0, v29
	v_rcp_f32_e32 v16, v16
	v_add_f32_e32 v20, 1.0, v20
	v_rcp_f32_e32 v20, v20
	v_add_f32_e32 v21, 1.0, v21
	v_rcp_f32_e32 v21, v21
	v_mul_f32_e32 v16, v25, v16
	v_mul_f32_e32 v25, v16, v17
	v_mul_f32_e32 v16, v26, v20
	v_mul_f32_e32 v26, v16, v18
	v_mul_f32_e32 v16, v27, v21
	v_mul_f32_e32 v19, v16, v19
	v_lshl_add_u64 v[20:21], v[32:33], 0, v[112:113]
	v_cvt_pk_bf16_f32 v16, v28, v35
	v_cvt_pk_bf16_f32 v17, v22, v23
	v_cvt_pk_bf16_f32 v18, v24, v25
	v_cvt_pk_bf16_f32 v19, v26, v19
	global_store_dwordx4 v[20:21], v[16:19], off
	s_nop 1
	v_mul_f32_e32 v16, 0xbfb8aa3b, v12
	v_exp_f32_e32 v16, v16
	v_mul_f32_e32 v17, 0xbfb8aa3b, v13
	v_exp_f32_e32 v17, v17
	v_add_u32_e32 v18, 0xb0, v152
	v_add_f32_e32 v16, 1.0, v16
	v_rcp_f32_e32 v19, v16
	v_add_f32_e32 v16, 1.0, v17
	v_rcp_f32_e32 v20, v16
	v_mad_i64_i32 v[16:17], s[16:17], v18, s39, v[144:145]
	v_mul_f32_e32 v12, v12, v19
	v_mul_f32_e32 v12, v12, v4
	v_mul_f32_e32 v4, v13, v20
	v_mul_f32_e32 v13, 0xbfb8aa3b, v14
	v_exp_f32_e32 v13, v13
	v_mul_f32_e32 v18, 0xbfb8aa3b, v15
	v_exp_f32_e32 v18, v18
	v_mul_f32_e32 v19, v4, v5
	v_add_f32_e32 v4, 1.0, v13
	v_rcp_f32_e32 v4, v4
	v_add_f32_e32 v5, 1.0, v18
	v_mul_f32_e32 v13, 0xbfb8aa3b, v8
	v_rcp_f32_e32 v5, v5
	v_exp_f32_e32 v13, v13
	v_mul_f32_e32 v4, v14, v4
	v_mul_f32_e32 v6, v4, v6
	v_mul_f32_e32 v4, v15, v5
	v_add_f32_e32 v5, 1.0, v13
	v_rcp_f32_e32 v5, v5
	v_mul_f32_e32 v13, 0xbfb8aa3b, v9
	v_mul_f32_e32 v7, v4, v7
	v_exp_f32_e32 v13, v13
	v_mul_f32_e32 v4, v8, v5
	v_mul_f32_e32 v8, v4, v0
	v_mul_f32_e32 v4, 0xbfb8aa3b, v10
	v_exp_f32_e32 v4, v4
	v_mul_f32_e32 v5, 0xbfb8aa3b, v11
	v_exp_f32_e32 v5, v5
	v_add_f32_e32 v0, 1.0, v13
	v_rcp_f32_e32 v0, v0
	v_add_f32_e32 v4, 1.0, v4
	v_rcp_f32_e32 v4, v4
	v_add_f32_e32 v5, 1.0, v5
	v_rcp_f32_e32 v5, v5
	v_mul_f32_e32 v0, v9, v0
	v_mul_f32_e32 v9, v0, v1
	v_mul_f32_e32 v0, v10, v4
	v_mul_f32_e32 v10, v0, v2
	v_mul_f32_e32 v0, v11, v5
	v_mul_f32_e32 v3, v0, v3
	v_lshl_add_u64 v[4:5], v[16:17], 0, v[112:113]
	s_mov_b64 s[16:17], s[10:11]
	v_cvt_pk_bf16_f32 v0, v12, v19
	v_cvt_pk_bf16_f32 v1, v6, v7
	v_cvt_pk_bf16_f32 v2, v8, v9
	v_cvt_pk_bf16_f32 v3, v10, v3
	global_store_dwordx4 v[4:5], v[0:3], off
	s_cbranch_vccz .LBB0_903
	s_waitcnt vmcnt(0)
	s_cmpk_gt_u32 s3, 0xff
	s_cbranch_scc1 .LBB0_910
	s_barrier

; #define PG8_STAGE(bufoff, gbase, voff) do { _Pragma("unroll") for (int _i = 0; _i < 2; ++_i) \
;         __builtin_amdgcn_global_load_lds((const unsigned*)((const char*)(gbase) + (voff)[_i]), (PG8_LAS unsigned*)(lds + (bufoff) + ldsw + _i * 8192), 16, 0, 0); } while (0)
; #define PG8_LDA(dst, b, h) do { _Pragma("unroll") for (int m = 0; m < 4; ++m) _Pragma("unroll") for (int k = 0; k < 2; ++k) dst[m][k] = *(const PG8_LAS bf16x8*)(lds + PG8_SA(b, h) + aoff + m * 2048 + k * 1024); } while (0)
; #define PG8_LDB(dst, b, h) do { _Pragma("unroll") for (int n = 0; n < 2; ++n) _Pragma("unroll") for (int k = 0; k < 2; ++k) dst[n][k] = *(const PG8_LAS bf16x8*)(lds + PG8_SB(b, h) + boff + n * 2048 + k * 1024); } while (0)
; #define PG8_WAIT_V(n) asm volatile("s_waitcnt vmcnt(" #n ")" ::: "memory")
; #define PG8_WAIT_L(n) asm volatile("s_waitcnt lgkmcnt(" #n ")" ::: "memory")
; #define PG8_BAR __builtin_amdgcn_s_barrier()
; #define PG8_SCHED __builtin_amdgcn_sched_barrier(0)
; template <class Epi, class Sched>
; __device__ __forceinline__ void gemm_phase(PG8_LAS unsigned char* lds, const Gemm g, const Sched& S, const Epi& E) {
;     ...
;             PG8_LDB(B0, 0, 0); PG8_SCHED; PG8_LDA(At, 0, 0); PG8_STAGE(PG8_SA(1, 1), a1 + hstep, voffA);
;             PG8_WAIT_L(8); PG8_BAR; PG8_WAIT_L(0); PG8_MMA(0, 0, At, B0); PG8_BAR; PG8_SCHED;
;             PG8_LDB(B1, 0, 1); PG8_STAGE(PG8_SB(0, 0), b2, voffB);
;             PG8_BAR; PG8_WAIT_L(0); PG8_MMA(0, 1, At, B1); PG8_BAR;
;             PG8_LDA(At, 0, 1); PG8_STAGE(PG8_SA(0, 0), a2, voffA);
;             PG8_BAR; PG8_WAIT_L(0); PG8_MMA(1, 0, At, B0); PG8_BAR; PG8_SCHED;
;             PG8_STAGE(PG8_SB(0, 1), b2 + hstep, voffB);
;             PG8_WAIT_V(6); PG8_BAR; PG8_MMA(1, 1, At, B1); PG8_BAR;
;             PG8_LDB(B0, 1, 0); PG8_SCHED; PG8_LDA(At, 1, 0); PG8_STAGE(PG8_SA(0, 1), a2 + hstep, voffA);
;             PG8_WAIT_L(8); PG8_BAR; PG8_WAIT_L(0); PG8_MMA(0, 0, At, B0); PG8_BAR; PG8_SCHED;
;             PG8_LDB(B1, 1, 1); PG8_STAGE(PG8_SB(1, 0), b3, voffB);
;             PG8_BAR; PG8_WAIT_L(0); PG8_MMA(0, 1, At, B1); PG8_BAR;
;             PG8_LDA(At, 1, 1); PG8_STAGE(PG8_SA(1, 0), a3, voffA);
;             PG8_BAR; PG8_WAIT_L(0); PG8_MMA(1, 0, At, B0); PG8_BAR; PG8_SCHED;
;             PG8_STAGE(PG8_SB(1, 1), b3 + hstep, voffB);
;             PG8_WAIT_V(6); PG8_BAR; PG8_MMA(1, 1, At, B1); PG8_BAR;
.LBB0_985:
	ds_read_b128 v[144:147], v151
	ds_read_b128 v[154:157], v151 offset:1024
	ds_read_b128 v[158:161], v151 offset:2048
	ds_read_b128 v[162:165], v151 offset:3072
	s_add_u32 s16, s14, 0x100
	s_addc_u32 s17, s15, 0
	s_cmp_eq_u32 s47, 40
	s_cselect_b32 s21, s1, s17
	s_cselect_b32 s20, s0, s16
	s_cselect_b32 s19, s11, s46
	s_cselect_b32 s18, s10, s43
	v_lshl_add_u64 v[198:199], s[14:15], 0, v[136:137]
	s_add_i32 m0, s25, 0xc000
	ds_read_b128 v[166:169], v152
	ds_read_b128 v[170:173], v152 offset:1024
	ds_read_b128 v[174:177], v152 offset:2048
	ds_read_b128 v[178:181], v152 offset:3072
	ds_read_b128 v[182:185], v152 offset:4096
	ds_read_b128 v[186:189], v152 offset:5120
	ds_read_b128 v[190:193], v152 offset:6144
	ds_read_b128 v[194:197], v152 offset:7168
	global_load_lds_dwordx4 v[198:199], off
	v_lshl_add_u64 v[198:199], s[14:15], 0, v[138:139]
	s_add_i32 m0, s25, 0xe000
	s_nop 0
	global_load_lds_dwordx4 v[198:199], off
	s_waitcnt lgkmcnt(8)
	s_barrier
	s_waitcnt lgkmcnt(0)
	v_mfma_f32_16x16x32_bf16 v[124:127], v[144:147], v[166:169], v[124:127]
	v_mfma_f32_16x16x32_bf16 v[120:123], v[158:161], v[166:169], v[120:123]
	v_mfma_f32_16x16x32_bf16 v[108:111], v[144:147], v[174:177], v[108:111]
	v_mfma_f32_16x16x32_bf16 v[104:107], v[158:161], v[174:177], v[104:107]
	v_mfma_f32_16x16x32_bf16 v[92:95], v[144:147], v[182:185], v[92:95]
	v_mfma_f32_16x16x32_bf16 v[88:91], v[158:161], v[182:185], v[88:91]
	v_mfma_f32_16x16x32_bf16 v[76:79], v[144:147], v[190:193], v[76:79]
	v_mfma_f32_16x16x32_bf16 v[72:75], v[158:161], v[190:193], v[72:75]
	v_mfma_f32_16x16x32_bf16 v[124:127], v[154:157], v[170:173], v[124:127]
	v_mfma_f32_16x16x32_bf16 v[120:123], v[162:165], v[170:173], v[120:123]
	v_mfma_f32_16x16x32_bf16 v[108:111], v[154:157], v[178:181], v[108:111]
	v_mfma_f32_16x16x32_bf16 v[104:107], v[162:165], v[178:181], v[104:107]
	v_mfma_f32_16x16x32_bf16 v[92:95], v[154:157], v[186:189], v[92:95]
	v_mfma_f32_16x16x32_bf16 v[88:91], v[162:165], v[186:189], v[88:91]
	v_mfma_f32_16x16x32_bf16 v[76:79], v[154:157], v[194:197], v[76:79]
	v_mfma_f32_16x16x32_bf16 v[72:75], v[162:165], v[194:197], v[72:75]
	s_barrier
	s_add_i32 s14, s37, s24
	v_lshl_add_u64 v[214:215], s[18:19], 0, v[130:131]
	s_mov_b32 m0, s14
	ds_read_b128 v[198:201], v153
	ds_read_b128 v[202:205], v153 offset:1024
	ds_read_b128 v[206:209], v153 offset:2048
	ds_read_b128 v[210:213], v153 offset:3072
	global_load_lds_dwordx4 v[214:215], off
	v_lshl_add_u64 v[216:217], s[18:19], 0, v[134:135]
	s_add_i32 m0, s14, 0x2000
	s_nop 0
	global_load_lds_dwordx4 v[216:217], off
	s_barrier
	s_waitcnt lgkmcnt(0)
	v_mfma_f32_16x16x32_bf16 v[116:119], v[198:201], v[166:169], v[116:119]
	v_mfma_f32_16x16x32_bf16 v[112:115], v[206:209], v[166:169], v[112:115]
	v_mfma_f32_16x16x32_bf16 v[100:103], v[198:201], v[174:177], v[100:103]
	v_mfma_f32_16x16x32_bf16 v[96:99], v[206:209], v[174:177], v[96:99]
	v_mfma_f32_16x16x32_bf16 v[84:87], v[198:201], v[182:185], v[84:87]
	v_mfma_f32_16x16x32_bf16 v[80:83], v[206:209], v[182:185], v[80:83]
	v_mfma_f32_16x16x32_bf16 v[68:71], v[198:201], v[190:193], v[68:71]
	v_mfma_f32_16x16x32_bf16 v[64:67], v[206:209], v[190:193], v[64:67]
	v_mfma_f32_16x16x32_bf16 v[116:119], v[202:205], v[170:173], v[116:119]
	v_mfma_f32_16x16x32_bf16 v[112:115], v[210:213], v[170:173], v[112:115]
	v_mfma_f32_16x16x32_bf16 v[100:103], v[202:205], v[178:181], v[100:103]
	v_mfma_f32_16x16x32_bf16 v[96:99], v[210:213], v[178:181], v[96:99]
	v_mfma_f32_16x16x32_bf16 v[84:87], v[202:205], v[186:189], v[84:87]
	v_mfma_f32_16x16x32_bf16 v[80:83], v[210:213], v[186:189], v[80:83]
	v_mfma_f32_16x16x32_bf16 v[68:71], v[202:205], v[194:197], v[68:71]
	v_mfma_f32_16x16x32_bf16 v[64:67], v[210:213], v[194:197], v[64:67]
	s_mov_b32 m0, s25
	v_lshl_add_u64 v[218:219], s[20:21], 0, v[128:129]
	s_barrier
	ds_read_b128 v[166:169], v152 offset:16384
	ds_read_b128 v[170:173], v152 offset:17408
	ds_read_b128 v[174:177], v152 offset:18432
	ds_read_b128 v[178:181], v152 offset:19456
	ds_read_b128 v[182:185], v152 offset:20480
	ds_read_b128 v[186:189], v152 offset:21504
	ds_read_b128 v[190:193], v152 offset:22528
	ds_read_b128 v[194:197], v152 offset:23552
	global_load_lds_dwordx4 v[218:219], off
	v_lshl_add_u64 v[220:221], s[20:21], 0, v[132:133]
	s_mov_b32 m0, s26
	s_nop 0
	global_load_lds_dwordx4 v[220:221], off
	s_barrier
	s_waitcnt lgkmcnt(0)
	v_mfma_f32_16x16x32_bf16 v[60:63], v[144:147], v[166:169], v[60:63]
	v_mfma_f32_16x16x32_bf16 v[56:59], v[158:161], v[166:169], v[56:59]
	v_mfma_f32_16x16x32_bf16 v[44:47], v[144:147], v[174:177], v[44:47]
	v_mfma_f32_16x16x32_bf16 v[40:43], v[158:161], v[174:177], v[40:43]
	v_mfma_f32_16x16x32_bf16 v[28:31], v[144:147], v[182:185], v[28:31]
	v_mfma_f32_16x16x32_bf16 v[24:27], v[158:161], v[182:185], v[24:27]
	v_mfma_f32_16x16x32_bf16 v[12:15], v[144:147], v[190:193], v[12:15]
	v_mfma_f32_16x16x32_bf16 v[8:11], v[158:161], v[190:193], v[8:11]
	v_mfma_f32_16x16x32_bf16 v[60:63], v[154:157], v[170:173], v[60:63]
	v_mfma_f32_16x16x32_bf16 v[56:59], v[162:165], v[170:173], v[56:59]
	v_mfma_f32_16x16x32_bf16 v[44:47], v[154:157], v[178:181], v[44:47]
	v_mfma_f32_16x16x32_bf16 v[40:43], v[162:165], v[178:181], v[40:43]
	v_mfma_f32_16x16x32_bf16 v[28:31], v[154:157], v[186:189], v[28:31]
	v_mfma_f32_16x16x32_bf16 v[24:27], v[162:165], v[186:189], v[24:27]
	v_mfma_f32_16x16x32_bf16 v[12:15], v[154:157], v[194:197], v[12:15]
	v_mfma_f32_16x16x32_bf16 v[8:11], v[162:165], v[194:197], v[8:11]
	s_barrier
; #define PG8_STAGE(bufoff, gbase, voff) do { _Pragma("unroll") for (int _i = 0; _i < 2; ++_i) \
;         __builtin_amdgcn_global_load_lds((const unsigned*)((const char*)(gbase) + (voff)[_i]), (PG8_LAS unsigned*)(lds + (bufoff) + ldsw + _i * 8192), 16, 0, 0); } while (0)
; #define PG8_LDA(dst, b, h) do { _Pragma("unroll") for (int m = 0; m < 4; ++m) _Pragma("unroll") for (int k = 0; k < 2; ++k) dst[m][k] = *(const PG8_LAS bf16x8*)(lds + PG8_SA(b, h) + aoff + m * 2048 + k * 1024); } while (0)
; #define PG8_LDB(dst, b, h) do { _Pragma("unroll") for (int n = 0; n < 2; ++n) _Pragma("unroll") for (int k = 0; k < 2; ++k) dst[n][k] = *(const PG8_LAS bf16x8*)(lds + PG8_SB(b, h) + boff + n * 2048 + k * 1024); } while (0)
; #define PG8_WAIT_V(n) asm volatile("s_waitcnt vmcnt(" #n ")" ::: "memory")
; #define PG8_WAIT_L(n) asm volatile("s_waitcnt lgkmcnt(" #n ")" ::: "memory")
; #define PG8_BAR __builtin_amdgcn_s_barrier()
; #define PG8_SCHED __builtin_amdgcn_sched_barrier(0)
; template <class Epi, class Sched>
; __device__ __forceinline__ void gemm_phase(PG8_LAS unsigned char* lds, const Gemm g, const Sched& S, const Epi& E) {
;     ...
;             PG8_LDB(B0, 0, 0); PG8_SCHED; PG8_LDA(At, 0, 0); PG8_STAGE(PG8_SA(1, 1), a1 + hstep, voffA);
;             PG8_WAIT_L(8); PG8_BAR; PG8_WAIT_L(0); PG8_MMA(0, 0, At, B0); PG8_BAR; PG8_SCHED;
;             PG8_LDB(B1, 0, 1); PG8_STAGE(PG8_SB(0, 0), b2, voffB);
;             PG8_BAR; PG8_WAIT_L(0); PG8_MMA(0, 1, At, B1); PG8_BAR;
;             PG8_LDA(At, 0, 1); PG8_STAGE(PG8_SA(0, 0), a2, voffA);
;             PG8_BAR; PG8_WAIT_L(0); PG8_MMA(1, 0, At, B0); PG8_BAR; PG8_SCHED;
;             PG8_STAGE(PG8_SB(0, 1), b2 + hstep, voffB);
;             PG8_WAIT_V(6); PG8_BAR; PG8_MMA(1, 1, At, B1); PG8_BAR;
;             PG8_LDB(B0, 1, 0); PG8_SCHED; PG8_LDA(At, 1, 0); PG8_STAGE(PG8_SA(0, 1), a2 + hstep, voffA);
;             PG8_WAIT_L(8); PG8_BAR; PG8_WAIT_L(0); PG8_MMA(0, 0, At, B0); PG8_BAR; PG8_SCHED;
;             PG8_LDB(B1, 1, 1); PG8_STAGE(PG8_SB(1, 0), b3, voffB);
;             PG8_BAR; PG8_WAIT_L(0); PG8_MMA(0, 1, At, B1); PG8_BAR;
;             PG8_LDA(At, 1, 1); PG8_STAGE(PG8_SA(1, 0), a3, voffA);
;             PG8_BAR; PG8_WAIT_L(0); PG8_MMA(1, 0, At, B0); PG8_BAR; PG8_SCHED;
;             PG8_STAGE(PG8_SB(1, 1), b3 + hstep, voffB);
;             PG8_WAIT_V(6); PG8_BAR; PG8_MMA(1, 1, At, B1); PG8_BAR;
	s_add_u32 s14, s18, 0xb0000
	s_addc_u32 s15, s19, 0
	s_add_i32 s50, s38, s24
	v_lshl_add_u64 v[144:145], s[14:15], 0, v[130:131]
	s_mov_b32 m0, s50
	s_nop 0
	global_load_lds_dwordx4 v[144:145], off
	v_lshl_add_u64 v[144:145], s[14:15], 0, v[134:135]
	s_add_i32 m0, s50, 0x2000
	s_nop 0
	global_load_lds_dwordx4 v[144:145], off
	s_waitcnt vmcnt(6)
	s_barrier
	v_mfma_f32_16x16x32_bf16 v[52:55], v[198:201], v[166:169], v[52:55]
	v_mfma_f32_16x16x32_bf16 v[48:51], v[206:209], v[166:169], v[48:51]
	v_mfma_f32_16x16x32_bf16 v[36:39], v[198:201], v[174:177], v[36:39]
	v_mfma_f32_16x16x32_bf16 v[32:35], v[206:209], v[174:177], v[32:35]
	v_mfma_f32_16x16x32_bf16 v[20:23], v[198:201], v[182:185], v[20:23]
	v_mfma_f32_16x16x32_bf16 v[16:19], v[206:209], v[182:185], v[16:19]
	v_mfma_f32_16x16x32_bf16 v[4:7], v[198:201], v[190:193], v[4:7]
	v_mfma_f32_16x16x32_bf16 v[0:3], v[206:209], v[190:193], v[0:3]
	v_mfma_f32_16x16x32_bf16 v[52:55], v[202:205], v[170:173], v[52:55]
	v_mfma_f32_16x16x32_bf16 v[48:51], v[210:213], v[170:173], v[48:51]
	v_mfma_f32_16x16x32_bf16 v[36:39], v[202:205], v[178:181], v[36:39]
	v_mfma_f32_16x16x32_bf16 v[32:35], v[210:213], v[178:181], v[32:35]
	v_mfma_f32_16x16x32_bf16 v[20:23], v[202:205], v[186:189], v[20:23]
	v_mfma_f32_16x16x32_bf16 v[16:19], v[210:213], v[186:189], v[16:19]
	v_mfma_f32_16x16x32_bf16 v[4:7], v[202:205], v[194:197], v[4:7]
	v_mfma_f32_16x16x32_bf16 v[0:3], v[210:213], v[194:197], v[0:3]
	s_add_i32 s50, 0, 0x18000
	v_add_u32_e32 v162, s50, v149
	s_barrier
	ds_read_b128 v[144:147], v162
	ds_read_b128 v[154:157], v162 offset:1024
	ds_read_b128 v[158:161], v162 offset:2048
	ds_read_b128 v[162:165], v162 offset:3072
	s_add_u32 s14, s20, 0xb0000
	s_addc_u32 s15, s21, 0
	s_mov_b32 m0, s27
	v_lshl_add_u64 v[198:199], s[14:15], 0, v[128:129]
	ds_read_b128 v[166:169], v152 offset:32768
	ds_read_b128 v[170:173], v152 offset:33792
	ds_read_b128 v[174:177], v152 offset:34816
	ds_read_b128 v[178:181], v152 offset:35840
	ds_read_b128 v[182:185], v152 offset:36864
	ds_read_b128 v[186:189], v152 offset:37888
	ds_read_b128 v[190:193], v152 offset:38912
	ds_read_b128 v[194:197], v152 offset:39936
	global_load_lds_dwordx4 v[198:199], off
	v_lshl_add_u64 v[198:199], s[14:15], 0, v[132:133]
	s_mov_b32 m0, s28
	s_nop 0
	global_load_lds_dwordx4 v[198:199], off
	s_waitcnt lgkmcnt(8)
	s_barrier
	s_waitcnt lgkmcnt(0)
	v_mfma_f32_16x16x32_bf16 v[124:127], v[144:147], v[166:169], v[124:127]
	v_mfma_f32_16x16x32_bf16 v[120:123], v[158:161], v[166:169], v[120:123]
	v_mfma_f32_16x16x32_bf16 v[108:111], v[144:147], v[174:177], v[108:111]
	v_mfma_f32_16x16x32_bf16 v[104:107], v[158:161], v[174:177], v[104:107]
	v_mfma_f32_16x16x32_bf16 v[92:95], v[144:147], v[182:185], v[92:95]
	v_mfma_f32_16x16x32_bf16 v[88:91], v[158:161], v[182:185], v[88:91]
	v_mfma_f32_16x16x32_bf16 v[76:79], v[144:147], v[190:193], v[76:79]
	v_mfma_f32_16x16x32_bf16 v[72:75], v[158:161], v[190:193], v[72:75]
	v_mfma_f32_16x16x32_bf16 v[124:127], v[154:157], v[170:173], v[124:127]
	v_mfma_f32_16x16x32_bf16 v[120:123], v[162:165], v[170:173], v[120:123]
	v_mfma_f32_16x16x32_bf16 v[108:111], v[154:157], v[178:181], v[108:111]
	v_mfma_f32_16x16x32_bf16 v[104:107], v[162:165], v[178:181], v[104:107]
	v_mfma_f32_16x16x32_bf16 v[92:95], v[154:157], v[186:189], v[92:95]
	v_mfma_f32_16x16x32_bf16 v[88:91], v[162:165], v[186:189], v[88:91]
	v_mfma_f32_16x16x32_bf16 v[76:79], v[154:157], v[194:197], v[76:79]
	v_mfma_f32_16x16x32_bf16 v[72:75], v[162:165], v[194:197], v[72:75]
	s_barrier
	s_add_i32 s20, 0, 0x1c000
	s_add_i32 s14, s50, s24
	v_add_u32_e32 v210, s20, v149
	v_lshl_add_u64 v[214:215], v[214:215], 0, s[12:13]
	s_mov_b32 m0, s14
	ds_read_b128 v[198:201], v210
	ds_read_b128 v[202:205], v210 offset:1024
	ds_read_b128 v[206:209], v210 offset:2048
	ds_read_b128 v[210:213], v210 offset:3072
	global_load_lds_dwordx4 v[214:215], off
	v_lshl_add_u64 v[214:215], v[216:217], 0, s[12:13]
	s_add_i32 m0, s14, 0x2000
	s_nop 0
	global_load_lds_dwordx4 v[214:215], off
	s_barrier
	s_waitcnt lgkmcnt(0)
	v_mfma_f32_16x16x32_bf16 v[116:119], v[198:201], v[166:169], v[116:119]
	v_mfma_f32_16x16x32_bf16 v[112:115], v[206:209], v[166:169], v[112:115]
	v_mfma_f32_16x16x32_bf16 v[100:103], v[198:201], v[174:177], v[100:103]
	v_mfma_f32_16x16x32_bf16 v[96:99], v[206:209], v[174:177], v[96:99]
	v_mfma_f32_16x16x32_bf16 v[84:87], v[198:201], v[182:185], v[84:87]
	v_mfma_f32_16x16x32_bf16 v[80:83], v[206:209], v[182:185], v[80:83]
	v_mfma_f32_16x16x32_bf16 v[68:71], v[198:201], v[190:193], v[68:71]
	v_mfma_f32_16x16x32_bf16 v[64:67], v[206:209], v[190:193], v[64:67]
	v_mfma_f32_16x16x32_bf16 v[116:119], v[202:205], v[170:173], v[116:119]
	v_mfma_f32_16x16x32_bf16 v[112:115], v[210:213], v[170:173], v[112:115]
	v_mfma_f32_16x16x32_bf16 v[100:103], v[202:205], v[178:181], v[100:103]
	v_mfma_f32_16x16x32_bf16 v[96:99], v[210:213], v[178:181], v[96:99]
	v_mfma_f32_16x16x32_bf16 v[84:87], v[202:205], v[186:189], v[84:87]
	v_mfma_f32_16x16x32_bf16 v[80:83], v[210:213], v[186:189], v[80:83]
	v_mfma_f32_16x16x32_bf16 v[68:71], v[202:205], v[194:197], v[68:71]
	v_mfma_f32_16x16x32_bf16 v[64:67], v[210:213], v[194:197], v[64:67]
	s_mov_b32 m0, s30
	v_lshl_add_u64 v[214:215], v[218:219], 0, s[12:13]
	s_barrier
; #define PG8_STAGE(bufoff, gbase, voff) do { _Pragma("unroll") for (int _i = 0; _i < 2; ++_i) \
;         __builtin_amdgcn_global_load_lds((const unsigned*)((const char*)(gbase) + (voff)[_i]), (PG8_LAS unsigned*)(lds + (bufoff) + ldsw + _i * 8192), 16, 0, 0); } while (0)
; #define PG8_LDA(dst, b, h) do { _Pragma("unroll") for (int m = 0; m < 4; ++m) _Pragma("unroll") for (int k = 0; k < 2; ++k) dst[m][k] = *(const PG8_LAS bf16x8*)(lds + PG8_SA(b, h) + aoff + m * 2048 + k * 1024); } while (0)
; #define PG8_WAIT_V(n) asm volatile("s_waitcnt vmcnt(" #n ")" ::: "memory")
; #define PG8_WAIT_L(n) asm volatile("s_waitcnt lgkmcnt(" #n ")" ::: "memory")
; #define PG8_BAR __builtin_amdgcn_s_barrier()
; #define PG8_SCHED __builtin_amdgcn_sched_barrier(0)
; template <class Epi, class Sched>
; __device__ __forceinline__ void gemm_phase(PG8_LAS unsigned char* lds, const Gemm g, const Sched& S, const Epi& E) {
;     ...
;             PG8_LDA(At, 1, 1); PG8_STAGE(PG8_SA(1, 0), a3, voffA);
;             PG8_BAR; PG8_WAIT_L(0); PG8_MMA(1, 0, At, B0); PG8_BAR; PG8_SCHED;
;             PG8_STAGE(PG8_SB(1, 1), b3 + hstep, voffB);
;             PG8_WAIT_V(6); PG8_BAR; PG8_MMA(1, 1, At, B1); PG8_BAR;
;     __device__ __forceinline__ void operator()(const f32x4 (&acc)[2][2][4][2], const Unit& u, int wr, int wc, int fr, int fq) const {
;     ...
;             for (int m = 0; m < 4; ++m) { const int row = row0 + ai * HALF + m * 16; bf16_t* rowp = O + (size_t)row * ldc + col0; float s = 0.f;
; #pragma unroll
;                 for (int bj = 0; bj < 2; ++bj) { const f32x4 v0 = acc[ai][bj][m][0], v1 = acc[ai][bj][m][1]; u32x4 w; w.x = pk2(v0[0], v0[1]); w.y = pk2(v0[2], v0[3]); w.z = pk2(v1[0], v1[1]); w.w = pk2(v1[2], v1[3]);
;                     *(u32x4*)(rowp + bj * HALF) = w; s += ((v0[0] * v0[0] + v0[1] * v0[1]) + (v0[2] * v0[2] + v0[3] * v0[3])) + ((v1[0] * v1[0] + v1[1] * v1[1]) + (v1[2] * v1[2] + v1[3] * v1[3])); }
;                 { auto r16 = __builtin_amdgcn_permlane16_swap(__float_as_uint(s), __float_as_uint(s), false, false); s = __uint_as_float(r16[0]) + __uint_as_float(r16[1]);
;                   auto r32 = __builtin_amdgcn_permlane32_swap(__float_as_uint(s), __float_as_uint(s), false, false); s = __uint_as_float(r32[0]) + __uint_as_float(r32[1]); }
;                 if (fq == 0) atomicAdd(ss + row, s); }
	ds_read_b128 v[166:169], v152 offset:49152
	ds_read_b128 v[170:173], v152 offset:50176
	ds_read_b128 v[174:177], v152 offset:51200
	ds_read_b128 v[178:181], v152 offset:52224
	ds_read_b128 v[182:185], v152 offset:53248
	ds_read_b128 v[186:189], v152 offset:54272
	ds_read_b128 v[190:193], v152 offset:55296
	ds_read_b128 v[194:197], v152 offset:56320
	global_load_lds_dwordx4 v[214:215], off
	v_lshl_add_u64 v[214:215], v[220:221], 0, s[12:13]
	s_mov_b32 m0, s31
	s_nop 0
	global_load_lds_dwordx4 v[214:215], off
	s_barrier
	s_waitcnt lgkmcnt(0)
	v_mfma_f32_16x16x32_bf16 v[60:63], v[144:147], v[166:169], v[60:63]
	v_mfma_f32_16x16x32_bf16 v[56:59], v[158:161], v[166:169], v[56:59]
	v_mfma_f32_16x16x32_bf16 v[44:47], v[144:147], v[174:177], v[44:47]
	v_mfma_f32_16x16x32_bf16 v[40:43], v[158:161], v[174:177], v[40:43]
	v_mfma_f32_16x16x32_bf16 v[28:31], v[144:147], v[182:185], v[28:31]
	v_mfma_f32_16x16x32_bf16 v[24:27], v[158:161], v[182:185], v[24:27]
	v_mfma_f32_16x16x32_bf16 v[12:15], v[144:147], v[190:193], v[12:15]
	v_mfma_f32_16x16x32_bf16 v[8:11], v[158:161], v[190:193], v[8:11]
	v_mfma_f32_16x16x32_bf16 v[60:63], v[154:157], v[170:173], v[60:63]
	v_mfma_f32_16x16x32_bf16 v[56:59], v[162:165], v[170:173], v[56:59]
	v_mfma_f32_16x16x32_bf16 v[44:47], v[154:157], v[178:181], v[44:47]
	v_mfma_f32_16x16x32_bf16 v[40:43], v[162:165], v[178:181], v[40:43]
	v_mfma_f32_16x16x32_bf16 v[28:31], v[154:157], v[186:189], v[28:31]
	v_mfma_f32_16x16x32_bf16 v[24:27], v[162:165], v[186:189], v[24:27]
	v_mfma_f32_16x16x32_bf16 v[12:15], v[154:157], v[194:197], v[12:15]
	v_mfma_f32_16x16x32_bf16 v[8:11], v[162:165], v[194:197], v[8:11]
	s_barrier
	s_add_u32 s14, s18, 0xb0080
	s_addc_u32 s15, s19, 0
	s_add_i32 s18, s20, s24
	v_lshl_add_u64 v[144:145], s[14:15], 0, v[130:131]
	s_mov_b32 m0, s18
	s_nop 0
	global_load_lds_dwordx4 v[144:145], off
	v_lshl_add_u64 v[144:145], s[14:15], 0, v[134:135]
	s_add_i32 m0, s18, 0x2000
	s_nop 0
	global_load_lds_dwordx4 v[144:145], off
	s_waitcnt vmcnt(6)
	s_barrier
	v_mfma_f32_16x16x32_bf16 v[52:55], v[198:201], v[166:169], v[52:55]
	v_mfma_f32_16x16x32_bf16 v[48:51], v[206:209], v[166:169], v[48:51]
	v_mfma_f32_16x16x32_bf16 v[36:39], v[198:201], v[174:177], v[36:39]
	v_mfma_f32_16x16x32_bf16 v[32:35], v[206:209], v[174:177], v[32:35]
	v_mfma_f32_16x16x32_bf16 v[20:23], v[198:201], v[182:185], v[20:23]
	v_mfma_f32_16x16x32_bf16 v[16:19], v[206:209], v[182:185], v[16:19]
	v_mfma_f32_16x16x32_bf16 v[4:7], v[198:201], v[190:193], v[4:7]
	v_mfma_f32_16x16x32_bf16 v[0:3], v[206:209], v[190:193], v[0:3]
	v_mfma_f32_16x16x32_bf16 v[52:55], v[202:205], v[170:173], v[52:55]
	v_mfma_f32_16x16x32_bf16 v[48:51], v[210:213], v[170:173], v[48:51]
	v_mfma_f32_16x16x32_bf16 v[36:39], v[202:205], v[178:181], v[36:39]
	v_mfma_f32_16x16x32_bf16 v[32:35], v[210:213], v[178:181], v[32:35]
	v_mfma_f32_16x16x32_bf16 v[20:23], v[202:205], v[186:189], v[20:23]
	v_mfma_f32_16x16x32_bf16 v[16:19], v[210:213], v[186:189], v[16:19]
	v_mfma_f32_16x16x32_bf16 v[4:7], v[202:205], v[194:197], v[4:7]
	v_mfma_f32_16x16x32_bf16 v[0:3], v[210:213], v[194:197], v[0:3]
	s_add_i32 s47, s47, 2
	s_add_u32 s43, s43, 0x100
	s_addc_u32 s46, s46, 0
	s_cmp_gt_u32 s47, 41
	s_mov_b64 s[14:15], s[16:17]
	s_barrier
	s_cbranch_scc0 .LBB0_985
	v_lshl_add_u32 v146, s42, 8, v148
	v_ashrrev_i32_e32 v147, 31, v146
	v_lshl_or_b32 v144, s41, 8, v150
	v_lshlrev_b64 v[154:155], 11, v[146:147]
	v_ashrrev_i32_e32 v145, 31, v144
	v_lshl_add_u64 v[154:155], s[56:57], 0, v[154:155]
	v_lshl_add_u64 v[158:159], v[144:145], 1, v[154:155]
	v_cvt_pk_bf16_f32 v154, v124, v125
	v_cvt_pk_bf16_f32 v156, v120, v121
	v_mul_f32_e32 v125, v125, v125
	v_mul_f32_e32 v121, v121, v121
	v_fmac_f32_e32 v125, v124, v124
	v_mul_f32_e32 v124, v127, v127
	v_fmac_f32_e32 v121, v120, v120
	v_mul_f32_e32 v120, v123, v123
	v_fmac_f32_e32 v124, v126, v126
	v_fmac_f32_e32 v120, v122, v122
	v_add_f32_e32 v124, v125, v124
	v_add_f32_e32 v120, v121, v120
	v_cvt_pk_bf16_f32 v157, v122, v123
	v_add_f32_e32 v124, v124, v120
	v_cvt_pk_bf16_f32 v120, v116, v117
	v_cvt_pk_bf16_f32 v122, v112, v113
	v_mul_f32_e32 v117, v117, v117
	v_mul_f32_e32 v113, v113, v113
	v_fmac_f32_e32 v117, v116, v116
	v_mul_f32_e32 v116, v119, v119
	v_fmac_f32_e32 v113, v112, v112
	v_mul_f32_e32 v112, v115, v115
	v_fmac_f32_e32 v116, v118, v118
	v_fmac_f32_e32 v112, v114, v114
	v_add_f32_e32 v116, v117, v116
	v_add_f32_e32 v112, v113, v112
	v_add_f32_e32 v112, v116, v112
	v_add_f32_e32 v112, v124, v112
	v_mov_b32_e32 v113, v112
	s_nop 1
	v_permlane16_swap_b32_e32 v112, v113
	v_add_f32_e32 v112, v112, v113
	v_mov_b32_e32 v113, v112
	s_nop 1
	v_permlane32_swap_b32_e32 v112, v113
	v_cvt_pk_bf16_f32 v155, v126, v127
	global_store_dwordx4 v[158:159], v[154:157], off
	v_cvt_pk_bf16_f32 v121, v118, v119
	v_cvt_pk_bf16_f32 v123, v114, v115
	global_store_dwordx4 v[158:159], v[120:123], off offset:256
	s_and_saveexec_b64 s[14:15], s[6:7]
	s_cbranch_execz .LBB0_988
	v_lshl_add_u64 v[114:115], v[146:147], 2, s[4:5]
	v_add_f32_e32 v112, v112, v113
	global_atomic_add_f32 v[114:115], v112, off

; #define PG8_STAGE(bufoff, gbase, voff) do { _Pragma("unroll") for (int _i = 0; _i < 2; ++_i) \
;         __builtin_amdgcn_global_load_lds((const unsigned*)((const char*)(gbase) + (voff)[_i]), (PG8_LAS unsigned*)(lds + (bufoff) + ldsw + _i * 8192), 16, 0, 0); } while (0)
; #define PG8_LDA(dst, b, h) do { _Pragma("unroll") for (int m = 0; m < 4; ++m) _Pragma("unroll") for (int k = 0; k < 2; ++k) dst[m][k] = *(const PG8_LAS bf16x8*)(lds + PG8_SA(b, h) + aoff + m * 2048 + k * 1024); } while (0)
; #define PG8_LDB(dst, b, h) do { _Pragma("unroll") for (int n = 0; n < 2; ++n) _Pragma("unroll") for (int k = 0; k < 2; ++k) dst[n][k] = *(const PG8_LAS bf16x8*)(lds + PG8_SB(b, h) + boff + n * 2048 + k * 1024); } while (0)
; #define PG8_MMA(ai, bj, At, Bt) do { __builtin_amdgcn_s_setprio(1); _Pragma("unroll") for (int m = 0; m < 4; ++m) _Pragma("unroll") for (int n = 0; n < 2; ++n) _Pragma("unroll") for (int k = 0; k < 2; ++k) \
;         acc[ai][bj][m][n] = __builtin_amdgcn_mfma_f32_16x16x32_bf16(Bt[n][k], At[m][k], acc[ai][bj][m][n], 0, 0, 0); __builtin_amdgcn_s_setprio(0); } while (0)
; #define PG8_WAIT_L(n) asm volatile("s_waitcnt lgkmcnt(" #n ")" ::: "memory")
; #define PG8_BAR __builtin_amdgcn_s_barrier()
; #define PG8_SCHED __builtin_amdgcn_sched_barrier(0)
; template <class Epi, class Sched>
; __device__ __forceinline__ void gemm_phase(PG8_LAS unsigned char* lds, const Gemm g, const Sched& S, const Epi& E) {
;     ...
;             const char* a1 = cA + (size_t)(t + 1) * kstep;
;             const char* a2 = last ? nA : cA + (size_t)(t + 2) * kstep; const char* b2 = last ? nB : cB + (size_t)(t + 2) * kstep;
;             const char* a3 = a2 + kstep; const char* b3 = b2 + kstep;
;             if (last && has_next) S.a_ready(nxt);
;             PG8_LDB(B0, 0, 0); PG8_SCHED; PG8_LDA(At, 0, 0); PG8_STAGE(PG8_SA(1, 1), a1 + hstep, voffA);
;             PG8_WAIT_L(8); PG8_BAR; PG8_WAIT_L(0); PG8_MMA(0, 0, At, B0); PG8_BAR; PG8_SCHED;
;             PG8_LDB(B1, 0, 1); PG8_STAGE(PG8_SB(0, 0), b2, voffB);
;             PG8_BAR; PG8_WAIT_L(0); PG8_MMA(0, 1, At, B1); PG8_BAR;
;             PG8_LDA(At, 0, 1); PG8_STAGE(PG8_SA(0, 0), a2, voffA);
;             PG8_BAR; PG8_WAIT_L(0); PG8_MMA(1, 0, At, B0); PG8_BAR; PG8_SCHED;
.LBB0_1020:
	s_add_u32 s35, s26, s34
	s_addc_u32 s43, s27, 0
	s_add_u32 s38, s35, 0x100
	s_addc_u32 s39, s43, 0
	s_and_b64 s[36:37], s[30:31], exec
	s_cselect_b32 s39, s17, s39
	s_cselect_b32 s38, s75, s38
	s_add_u32 s34, s24, s34
	s_addc_u32 s36, s25, 0
	s_add_u32 s34, s34, 0x100
	s_addc_u32 s36, s36, 0
	s_and_b64 s[30:31], s[30:31], exec
	s_cselect_b32 s41, s15, s36
	s_cselect_b32 s40, s76, s34
	s_add_u32 s42, s35, 0x10080
	s_addc_u32 s43, s43, 0
	s_add_i32 s86, s68, s51
	s_add_i32 m0, s23, 0xc000
	s_add_i32 s87, s23, 0xe000
	s_add_i32 s85, s86, 0x2000
	s_add_u32 s36, s40, 0x10000
	s_addc_u32 s37, s41, 0
	s_add_i32 s84, s69, s51
	ds_read_b128 v[148:151], v145
	ds_read_b128 v[152:155], v145 offset:1024
	ds_read_b128 v[156:159], v145 offset:2048
	ds_read_b128 v[160:163], v145 offset:3072
	s_add_i32 s83, s84, 0x2000
	s_add_i32 s82, 0, 0x18000
	s_add_u32 s34, s38, 0x10000
	s_addc_u32 s35, s39, 0
	s_add_i32 s81, s82, s51
	s_add_i32 s80, 0, 0x1c000
	s_add_i32 s79, s81, 0x2000
	s_add_u32 s30, s40, 0x10080
	s_addc_u32 s31, s41, 0
	s_add_i32 s78, s80, s51
	s_add_i32 s77, s78, 0x2000
	v_lshl_add_u64 v[140:141], s[42:43], 0, v[128:129]
	ds_read_b128 v[164:167], v146
	ds_read_b128 v[168:171], v146 offset:1024
	ds_read_b128 v[172:175], v146 offset:2048
	ds_read_b128 v[176:179], v146 offset:3072
	ds_read_b128 v[180:183], v146 offset:4096
	ds_read_b128 v[184:187], v146 offset:5120
	ds_read_b128 v[188:191], v146 offset:6144
	ds_read_b128 v[192:195], v146 offset:7168
	global_load_lds_dwordx4 v[140:141], off
	v_lshl_add_u64 v[140:141], s[42:43], 0, v[132:133]
	s_mov_b32 m0, s87
	s_nop 0
	global_load_lds_dwordx4 v[140:141], off
	s_waitcnt lgkmcnt(8)
	s_barrier
	s_waitcnt lgkmcnt(0)
	v_mfma_f32_16x16x32_bf16 v[124:127], v[148:151], v[164:167], v[124:127]
	v_mfma_f32_16x16x32_bf16 v[120:123], v[156:159], v[164:167], v[120:123]
	v_mfma_f32_16x16x32_bf16 v[112:115], v[148:151], v[172:175], v[112:115]
	v_mfma_f32_16x16x32_bf16 v[104:107], v[156:159], v[172:175], v[104:107]
	v_mfma_f32_16x16x32_bf16 v[96:99], v[148:151], v[180:183], v[96:99]
	v_mfma_f32_16x16x32_bf16 v[88:91], v[156:159], v[180:183], v[88:91]
	v_mfma_f32_16x16x32_bf16 v[80:83], v[148:151], v[188:191], v[80:83]
	v_mfma_f32_16x16x32_bf16 v[72:75], v[156:159], v[188:191], v[72:75]
	v_mfma_f32_16x16x32_bf16 v[124:127], v[152:155], v[168:171], v[124:127]
	v_mfma_f32_16x16x32_bf16 v[120:123], v[160:163], v[168:171], v[120:123]
	v_mfma_f32_16x16x32_bf16 v[112:115], v[152:155], v[176:179], v[112:115]
	v_mfma_f32_16x16x32_bf16 v[104:107], v[160:163], v[176:179], v[104:107]
	v_mfma_f32_16x16x32_bf16 v[96:99], v[152:155], v[184:187], v[96:99]
	v_mfma_f32_16x16x32_bf16 v[88:91], v[160:163], v[184:187], v[88:91]
	v_mfma_f32_16x16x32_bf16 v[80:83], v[152:155], v[192:195], v[80:83]
	v_mfma_f32_16x16x32_bf16 v[72:75], v[160:163], v[192:195], v[72:75]
	s_barrier
	s_mov_b32 m0, s86
	v_lshl_add_u64 v[140:141], s[40:41], 0, v[130:131]
	ds_read_b128 v[196:199], v147
	ds_read_b128 v[200:203], v147 offset:1024
	ds_read_b128 v[204:207], v147 offset:2048
	ds_read_b128 v[208:211], v147 offset:3072
	global_load_lds_dwordx4 v[140:141], off
	v_lshl_add_u64 v[212:213], s[40:41], 0, v[134:135]
	s_mov_b32 m0, s85
	s_nop 0
	global_load_lds_dwordx4 v[212:213], off
	s_barrier
	s_waitcnt lgkmcnt(0)
	v_mfma_f32_16x16x32_bf16 v[116:119], v[196:199], v[164:167], v[116:119]
	v_mfma_f32_16x16x32_bf16 v[108:111], v[204:207], v[164:167], v[108:111]
	v_mfma_f32_16x16x32_bf16 v[100:103], v[196:199], v[172:175], v[100:103]
	v_mfma_f32_16x16x32_bf16 v[92:95], v[204:207], v[172:175], v[92:95]
	v_mfma_f32_16x16x32_bf16 v[84:87], v[196:199], v[180:183], v[84:87]
	v_mfma_f32_16x16x32_bf16 v[76:79], v[204:207], v[180:183], v[76:79]
	v_mfma_f32_16x16x32_bf16 v[68:71], v[196:199], v[188:191], v[68:71]
	v_mfma_f32_16x16x32_bf16 v[64:67], v[204:207], v[188:191], v[64:67]
	v_mfma_f32_16x16x32_bf16 v[116:119], v[200:203], v[168:171], v[116:119]
	v_mfma_f32_16x16x32_bf16 v[108:111], v[208:211], v[168:171], v[108:111]
	v_mfma_f32_16x16x32_bf16 v[100:103], v[200:203], v[176:179], v[100:103]
	v_mfma_f32_16x16x32_bf16 v[92:95], v[208:211], v[176:179], v[92:95]
	v_mfma_f32_16x16x32_bf16 v[84:87], v[200:203], v[184:187], v[84:87]
	v_mfma_f32_16x16x32_bf16 v[76:79], v[208:211], v[184:187], v[76:79]
	v_mfma_f32_16x16x32_bf16 v[68:71], v[200:203], v[192:195], v[68:71]
	v_mfma_f32_16x16x32_bf16 v[64:67], v[208:211], v[192:195], v[64:67]
	s_mov_b32 m0, s23
	v_lshl_add_u64 v[214:215], s[38:39], 0, v[128:129]
	s_barrier
	ds_read_b128 v[164:167], v146 offset:16384
	ds_read_b128 v[168:171], v146 offset:17408
	ds_read_b128 v[172:175], v146 offset:18432
	ds_read_b128 v[176:179], v146 offset:19456
	ds_read_b128 v[180:183], v146 offset:20480
	ds_read_b128 v[184:187], v146 offset:21504
	ds_read_b128 v[188:191], v146 offset:22528
	ds_read_b128 v[192:195], v146 offset:23552
	global_load_lds_dwordx4 v[214:215], off
	v_lshl_add_u64 v[216:217], s[38:39], 0, v[132:133]
	s_mov_b32 m0, s60
	s_nop 0
	global_load_lds_dwordx4 v[216:217], off
	s_barrier
	s_waitcnt lgkmcnt(0)
	v_mfma_f32_16x16x32_bf16 v[60:63], v[148:151], v[164:167], v[60:63]
	v_mfma_f32_16x16x32_bf16 v[56:59], v[156:159], v[164:167], v[56:59]
	v_mfma_f32_16x16x32_bf16 v[52:55], v[148:151], v[172:175], v[52:55]
	v_mfma_f32_16x16x32_bf16 v[44:47], v[156:159], v[172:175], v[44:47]
	v_mfma_f32_16x16x32_bf16 v[36:39], v[148:151], v[180:183], v[36:39]
	v_mfma_f32_16x16x32_bf16 v[28:31], v[156:159], v[180:183], v[28:31]
	v_mfma_f32_16x16x32_bf16 v[20:23], v[148:151], v[188:191], v[20:23]
	v_mfma_f32_16x16x32_bf16 v[12:15], v[156:159], v[188:191], v[12:15]
	v_mfma_f32_16x16x32_bf16 v[60:63], v[152:155], v[168:171], v[60:63]
	v_mfma_f32_16x16x32_bf16 v[56:59], v[160:163], v[168:171], v[56:59]
	v_mfma_f32_16x16x32_bf16 v[52:55], v[152:155], v[176:179], v[52:55]
	v_mfma_f32_16x16x32_bf16 v[44:47], v[160:163], v[176:179], v[44:47]
	v_mfma_f32_16x16x32_bf16 v[36:39], v[152:155], v[184:187], v[36:39]
	v_mfma_f32_16x16x32_bf16 v[28:31], v[160:163], v[184:187], v[28:31]
	v_mfma_f32_16x16x32_bf16 v[20:23], v[152:155], v[192:195], v[20:23]
	v_mfma_f32_16x16x32_bf16 v[12:15], v[160:163], v[192:195], v[12:15]
	s_barrier
; #define PG8_STAGE(bufoff, gbase, voff) do { _Pragma("unroll") for (int _i = 0; _i < 2; ++_i) \
;         __builtin_amdgcn_global_load_lds((const unsigned*)((const char*)(gbase) + (voff)[_i]), (PG8_LAS unsigned*)(lds + (bufoff) + ldsw + _i * 8192), 16, 0, 0); } while (0)
; #define PG8_LDA(dst, b, h) do { _Pragma("unroll") for (int m = 0; m < 4; ++m) _Pragma("unroll") for (int k = 0; k < 2; ++k) dst[m][k] = *(const PG8_LAS bf16x8*)(lds + PG8_SA(b, h) + aoff + m * 2048 + k * 1024); } while (0)
; #define PG8_LDB(dst, b, h) do { _Pragma("unroll") for (int n = 0; n < 2; ++n) _Pragma("unroll") for (int k = 0; k < 2; ++k) dst[n][k] = *(const PG8_LAS bf16x8*)(lds + PG8_SB(b, h) + boff + n * 2048 + k * 1024); } while (0)
; #define PG8_MMA(ai, bj, At, Bt) do { __builtin_amdgcn_s_setprio(1); _Pragma("unroll") for (int m = 0; m < 4; ++m) _Pragma("unroll") for (int n = 0; n < 2; ++n) _Pragma("unroll") for (int k = 0; k < 2; ++k) \
;         acc[ai][bj][m][n] = __builtin_amdgcn_mfma_f32_16x16x32_bf16(Bt[n][k], At[m][k], acc[ai][bj][m][n], 0, 0, 0); __builtin_amdgcn_s_setprio(0); } while (0)
; #define PG8_WAIT_V(n) asm volatile("s_waitcnt vmcnt(" #n ")" ::: "memory")
; #define PG8_WAIT_L(n) asm volatile("s_waitcnt lgkmcnt(" #n ")" ::: "memory")
; #define PG8_BAR __builtin_amdgcn_s_barrier()
; #define PG8_SCHED __builtin_amdgcn_sched_barrier(0)
; template <class Epi, class Sched>
; __device__ __forceinline__ void gemm_phase(PG8_LAS unsigned char* lds, const Gemm g, const Sched& S, const Epi& E) {
;     ...
;             PG8_STAGE(PG8_SB(0, 1), b2 + hstep, voffB);
;             PG8_WAIT_V(6); PG8_BAR; PG8_MMA(1, 1, At, B1); PG8_BAR;
;             PG8_LDB(B0, 1, 0); PG8_SCHED; PG8_LDA(At, 1, 0); PG8_STAGE(PG8_SA(0, 1), a2 + hstep, voffA);
;             PG8_WAIT_L(8); PG8_BAR; PG8_WAIT_L(0); PG8_MMA(0, 0, At, B0); PG8_BAR; PG8_SCHED;
;             PG8_LDB(B1, 1, 1); PG8_STAGE(PG8_SB(1, 0), b3, voffB);
;             PG8_BAR; PG8_WAIT_L(0); PG8_MMA(0, 1, At, B1); PG8_BAR;
;             PG8_LDA(At, 1, 1); PG8_STAGE(PG8_SA(1, 0), a3, voffA);
	s_mov_b32 m0, s84
	v_lshl_add_u64 v[148:149], s[36:37], 0, v[130:131]
	global_load_lds_dwordx4 v[148:149], off
	v_lshl_add_u64 v[148:149], s[36:37], 0, v[134:135]
	s_mov_b32 m0, s83
	s_nop 0
	global_load_lds_dwordx4 v[148:149], off
	s_waitcnt vmcnt(6)
	s_barrier
	v_mfma_f32_16x16x32_bf16 v[48:51], v[196:199], v[164:167], v[48:51]
	v_mfma_f32_16x16x32_bf16 v[40:43], v[204:207], v[164:167], v[40:43]
	v_mfma_f32_16x16x32_bf16 v[32:35], v[196:199], v[172:175], v[32:35]
	v_mfma_f32_16x16x32_bf16 v[24:27], v[204:207], v[172:175], v[24:27]
	v_mfma_f32_16x16x32_bf16 v[16:19], v[196:199], v[180:183], v[16:19]
	v_mfma_f32_16x16x32_bf16 v[8:11], v[204:207], v[180:183], v[8:11]
	v_mfma_f32_16x16x32_bf16 v[4:7], v[196:199], v[188:191], v[4:7]
	v_mfma_f32_16x16x32_bf16 v[0:3], v[204:207], v[188:191], v[0:3]
	v_mfma_f32_16x16x32_bf16 v[48:51], v[200:203], v[168:171], v[48:51]
	v_mfma_f32_16x16x32_bf16 v[40:43], v[208:211], v[168:171], v[40:43]
	v_mfma_f32_16x16x32_bf16 v[32:35], v[200:203], v[176:179], v[32:35]
	v_mfma_f32_16x16x32_bf16 v[24:27], v[208:211], v[176:179], v[24:27]
	v_mfma_f32_16x16x32_bf16 v[16:19], v[200:203], v[184:187], v[16:19]
	v_mfma_f32_16x16x32_bf16 v[8:11], v[208:211], v[184:187], v[8:11]
	v_mfma_f32_16x16x32_bf16 v[4:7], v[200:203], v[192:195], v[4:7]
	v_mfma_f32_16x16x32_bf16 v[0:3], v[208:211], v[192:195], v[0:3]
	v_add_u32_e32 v160, s82, v143
	s_barrier
	ds_read_b128 v[148:151], v160
	ds_read_b128 v[152:155], v160 offset:1024
	ds_read_b128 v[156:159], v160 offset:2048
	ds_read_b128 v[160:163], v160 offset:3072
	s_mov_b32 m0, s61
	v_lshl_add_u64 v[196:197], s[34:35], 0, v[128:129]
	ds_read_b128 v[164:167], v146 offset:32768
	ds_read_b128 v[168:171], v146 offset:33792
	ds_read_b128 v[172:175], v146 offset:34816
	ds_read_b128 v[176:179], v146 offset:35840
	ds_read_b128 v[180:183], v146 offset:36864
	ds_read_b128 v[184:187], v146 offset:37888
	ds_read_b128 v[188:191], v146 offset:38912
	ds_read_b128 v[192:195], v146 offset:39936
	global_load_lds_dwordx4 v[196:197], off
	v_lshl_add_u64 v[196:197], s[34:35], 0, v[132:133]
	s_mov_b32 m0, s62
	s_nop 0
	global_load_lds_dwordx4 v[196:197], off
	s_waitcnt lgkmcnt(8)
	s_barrier
	s_waitcnt lgkmcnt(0)
	v_mfma_f32_16x16x32_bf16 v[124:127], v[148:151], v[164:167], v[124:127]
	v_mfma_f32_16x16x32_bf16 v[120:123], v[156:159], v[164:167], v[120:123]
	v_mfma_f32_16x16x32_bf16 v[112:115], v[148:151], v[172:175], v[112:115]
	v_mfma_f32_16x16x32_bf16 v[104:107], v[156:159], v[172:175], v[104:107]
	v_mfma_f32_16x16x32_bf16 v[96:99], v[148:151], v[180:183], v[96:99]
	v_mfma_f32_16x16x32_bf16 v[88:91], v[156:159], v[180:183], v[88:91]
	v_mfma_f32_16x16x32_bf16 v[80:83], v[148:151], v[188:191], v[80:83]
	v_mfma_f32_16x16x32_bf16 v[72:75], v[156:159], v[188:191], v[72:75]
	v_mfma_f32_16x16x32_bf16 v[124:127], v[152:155], v[168:171], v[124:127]
	v_mfma_f32_16x16x32_bf16 v[120:123], v[160:163], v[168:171], v[120:123]
	v_mfma_f32_16x16x32_bf16 v[112:115], v[152:155], v[176:179], v[112:115]
	v_mfma_f32_16x16x32_bf16 v[104:107], v[160:163], v[176:179], v[104:107]
	v_mfma_f32_16x16x32_bf16 v[96:99], v[152:155], v[184:187], v[96:99]
	v_mfma_f32_16x16x32_bf16 v[88:91], v[160:163], v[184:187], v[88:91]
	v_mfma_f32_16x16x32_bf16 v[80:83], v[152:155], v[192:195], v[80:83]
	v_mfma_f32_16x16x32_bf16 v[72:75], v[160:163], v[192:195], v[72:75]
	s_barrier
	s_mov_b32 m0, s81
	v_add_u32_e32 v208, s80, v143
	v_lshl_add_u64 v[140:141], v[140:141], 0, s[4:5]
	ds_read_b128 v[196:199], v208
	ds_read_b128 v[200:203], v208 offset:1024
	ds_read_b128 v[204:207], v208 offset:2048
	ds_read_b128 v[208:211], v208 offset:3072
	global_load_lds_dwordx4 v[140:141], off
	v_lshl_add_u64 v[140:141], v[212:213], 0, s[4:5]
	s_mov_b32 m0, s79
	s_nop 0
	global_load_lds_dwordx4 v[140:141], off
	s_barrier
	s_waitcnt lgkmcnt(0)
	v_mfma_f32_16x16x32_bf16 v[116:119], v[196:199], v[164:167], v[116:119]
	v_mfma_f32_16x16x32_bf16 v[108:111], v[204:207], v[164:167], v[108:111]
	v_mfma_f32_16x16x32_bf16 v[100:103], v[196:199], v[172:175], v[100:103]
	v_mfma_f32_16x16x32_bf16 v[92:95], v[204:207], v[172:175], v[92:95]
	v_mfma_f32_16x16x32_bf16 v[84:87], v[196:199], v[180:183], v[84:87]
	v_mfma_f32_16x16x32_bf16 v[76:79], v[204:207], v[180:183], v[76:79]
	v_mfma_f32_16x16x32_bf16 v[68:71], v[196:199], v[188:191], v[68:71]
	v_mfma_f32_16x16x32_bf16 v[64:67], v[204:207], v[188:191], v[64:67]
	v_mfma_f32_16x16x32_bf16 v[116:119], v[200:203], v[168:171], v[116:119]
	v_mfma_f32_16x16x32_bf16 v[108:111], v[208:211], v[168:171], v[108:111]
	v_mfma_f32_16x16x32_bf16 v[100:103], v[200:203], v[176:179], v[100:103]
	v_mfma_f32_16x16x32_bf16 v[92:95], v[208:211], v[176:179], v[92:95]
	v_mfma_f32_16x16x32_bf16 v[84:87], v[200:203], v[184:187], v[84:87]
	v_mfma_f32_16x16x32_bf16 v[76:79], v[208:211], v[184:187], v[76:79]
	v_mfma_f32_16x16x32_bf16 v[68:71], v[200:203], v[192:195], v[68:71]
	v_mfma_f32_16x16x32_bf16 v[64:67], v[208:211], v[192:195], v[64:67]
	s_mov_b32 m0, s64
	v_lshl_add_u64 v[140:141], v[214:215], 0, s[4:5]
	s_barrier
	ds_read_b128 v[164:167], v146 offset:49152
	ds_read_b128 v[168:171], v146 offset:50176
	ds_read_b128 v[172:175], v146 offset:51200
	ds_read_b128 v[176:179], v146 offset:52224
	ds_read_b128 v[180:183], v146 offset:53248
	ds_read_b128 v[184:187], v146 offset:54272
	ds_read_b128 v[188:191], v146 offset:55296
	ds_read_b128 v[192:195], v146 offset:56320
	global_load_lds_dwordx4 v[140:141], off
	v_lshl_add_u64 v[140:141], v[216:217], 0, s[4:5]
	s_mov_b32 m0, s65
	s_nop 0
	global_load_lds_dwordx4 v[140:141], off
	s_barrier
; #define PG8_STAGE(bufoff, gbase, voff) do { _Pragma("unroll") for (int _i = 0; _i < 2; ++_i) \
;         __builtin_amdgcn_global_load_lds((const unsigned*)((const char*)(gbase) + (voff)[_i]), (PG8_LAS unsigned*)(lds + (bufoff) + ldsw + _i * 8192), 16, 0, 0); } while (0)
; #define PG8_MMA(ai, bj, At, Bt) do { __builtin_amdgcn_s_setprio(1); _Pragma("unroll") for (int m = 0; m < 4; ++m) _Pragma("unroll") for (int n = 0; n < 2; ++n) _Pragma("unroll") for (int k = 0; k < 2; ++k) \
;         acc[ai][bj][m][n] = __builtin_amdgcn_mfma_f32_16x16x32_bf16(Bt[n][k], At[m][k], acc[ai][bj][m][n], 0, 0, 0); __builtin_amdgcn_s_setprio(0); } while (0)
; #define PG8_WAIT_V(n) asm volatile("s_waitcnt vmcnt(" #n ")" ::: "memory")
; #define PG8_WAIT_L(n) asm volatile("s_waitcnt lgkmcnt(" #n ")" ::: "memory")
; #define PG8_BAR __builtin_amdgcn_s_barrier()
; #define PG8_SCHED __builtin_amdgcn_sched_barrier(0)
; template <class Epi, class Sched>
; __device__ __forceinline__ void gemm_phase(PG8_LAS unsigned char* lds, const Gemm g, const Sched& S, const Epi& E) {
;     ...
;             PG8_BAR; PG8_WAIT_L(0); PG8_MMA(1, 0, At, B0); PG8_BAR; PG8_SCHED;
;             PG8_STAGE(PG8_SB(1, 1), b3 + hstep, voffB);
;             PG8_WAIT_V(6); PG8_BAR; PG8_MMA(1, 1, At, B1); PG8_BAR;
	s_waitcnt lgkmcnt(0)
	v_mfma_f32_16x16x32_bf16 v[60:63], v[148:151], v[164:167], v[60:63]
	v_mfma_f32_16x16x32_bf16 v[56:59], v[156:159], v[164:167], v[56:59]
	v_mfma_f32_16x16x32_bf16 v[52:55], v[148:151], v[172:175], v[52:55]
	v_mfma_f32_16x16x32_bf16 v[44:47], v[156:159], v[172:175], v[44:47]
	v_mfma_f32_16x16x32_bf16 v[36:39], v[148:151], v[180:183], v[36:39]
	v_mfma_f32_16x16x32_bf16 v[28:31], v[156:159], v[180:183], v[28:31]
	v_mfma_f32_16x16x32_bf16 v[20:23], v[148:151], v[188:191], v[20:23]
	v_mfma_f32_16x16x32_bf16 v[12:15], v[156:159], v[188:191], v[12:15]
	v_mfma_f32_16x16x32_bf16 v[60:63], v[152:155], v[168:171], v[60:63]
	v_mfma_f32_16x16x32_bf16 v[56:59], v[160:163], v[168:171], v[56:59]
	v_mfma_f32_16x16x32_bf16 v[52:55], v[152:155], v[176:179], v[52:55]
	v_mfma_f32_16x16x32_bf16 v[44:47], v[160:163], v[176:179], v[44:47]
	v_mfma_f32_16x16x32_bf16 v[36:39], v[152:155], v[184:187], v[36:39]
	v_mfma_f32_16x16x32_bf16 v[28:31], v[160:163], v[184:187], v[28:31]
	v_mfma_f32_16x16x32_bf16 v[20:23], v[152:155], v[192:195], v[20:23]
	v_mfma_f32_16x16x32_bf16 v[12:15], v[160:163], v[192:195], v[12:15]
	s_barrier
	s_mov_b32 m0, s78
	v_lshl_add_u64 v[140:141], s[30:31], 0, v[130:131]
	global_load_lds_dwordx4 v[140:141], off
	v_lshl_add_u64 v[140:141], s[30:31], 0, v[134:135]
	s_mov_b32 m0, s77
	s_nop 0
	global_load_lds_dwordx4 v[140:141], off
	s_waitcnt vmcnt(6)
	s_barrier
	v_mfma_f32_16x16x32_bf16 v[48:51], v[196:199], v[164:167], v[48:51]
	v_mfma_f32_16x16x32_bf16 v[40:43], v[204:207], v[164:167], v[40:43]
	v_mfma_f32_16x16x32_bf16 v[32:35], v[196:199], v[172:175], v[32:35]
	v_mfma_f32_16x16x32_bf16 v[24:27], v[204:207], v[172:175], v[24:27]
	v_mfma_f32_16x16x32_bf16 v[16:19], v[196:199], v[180:183], v[16:19]
	v_mfma_f32_16x16x32_bf16 v[8:11], v[204:207], v[180:183], v[8:11]
	v_mfma_f32_16x16x32_bf16 v[4:7], v[196:199], v[188:191], v[4:7]
	v_mfma_f32_16x16x32_bf16 v[0:3], v[204:207], v[188:191], v[0:3]
	v_mfma_f32_16x16x32_bf16 v[48:51], v[200:203], v[168:171], v[48:51]
	v_mfma_f32_16x16x32_bf16 v[40:43], v[208:211], v[168:171], v[40:43]
	v_mfma_f32_16x16x32_bf16 v[32:35], v[200:203], v[176:179], v[32:35]
	v_mfma_f32_16x16x32_bf16 v[24:27], v[208:211], v[176:179], v[24:27]
	v_mfma_f32_16x16x32_bf16 v[16:19], v[200:203], v[184:187], v[16:19]
	v_mfma_f32_16x16x32_bf16 v[8:11], v[208:211], v[184:187], v[8:11]
	v_mfma_f32_16x16x32_bf16 v[4:7], v[200:203], v[192:195], v[4:7]
	v_mfma_f32_16x16x32_bf16 v[0:3], v[208:211], v[192:195], v[0:3]
	s_movk_i32 s34, 0x100
	s_andn2_b64 vcc, exec, s[28:29]
	s_mov_b64 s[30:31], -1
	s_mov_b64 s[28:29], 0
	s_barrier
	s_cbranch_vccz .LBB0_1020
; __device__ __forceinline__ unsigned pk2(float lo, float hi) { unsigned r; asm("v_cvt_pk_bf16_f32 %0, %1, %2" : "=v"(r) : "v"(lo), "v"(hi)); return r; }
;     __device__ __forceinline__ void operator()(const f32x4 (&acc)[2][2][4][2], const Unit& u, int wr, int wc, int fr, int fq) const {
;         const int row0 = u.pm * BM + wr * 64 + fr, col0 = u.pn * BM + wc * 32 + 8 * fq;
; #pragma unroll
;         for (int ai = 0; ai < 2; ++ai)
; #pragma unroll
;             for (int m = 0; m < 4; ++m) { bf16_t* rowp = O + (size_t)(row0 + ai * HALF + m * 16) * ldc + col0;
; #pragma unroll
;                 for (int bj = 0; bj < 2; ++bj) { const f32x4 v0 = acc[ai][bj][m][0], v1 = acc[ai][bj][m][1]; u32x4 w; w.x = pk2(v0[0], v0[1]); w.y = pk2(v0[2], v0[3]); w.z = pk2(v1[0], v1[1]); w.w = pk2(v1[2], v1[3]);
;                     __builtin_nontemporal_store(w, (u32x4*)(rowp + bj * HALF)); } }
	v_lshl_add_u32 v148, s22, 8, v142
	v_lshl_or_b32 v140, s74, 8, v144
	v_ashrrev_i32_e32 v149, 31, v148
	v_ashrrev_i32_e32 v141, 31, v140
	v_lshlrev_b64 v[150:151], 11, v[148:149]
	v_lshl_add_u64 v[150:151], s[8:9], 0, v[150:151]
	v_lshlrev_b64 v[152:153], 1, v[140:141]
	v_lshl_add_u64 v[140:141], v[150:151], 0, v[152:153]
	v_cvt_pk_bf16_f32 v60, v60, v61
	v_cvt_pk_bf16_f32 v61, v62, v63
	v_cvt_pk_bf16_f32 v62, v56, v57
	v_add_co_u32_e32 v56, vcc, s70, v140
	v_cvt_pk_bf16_f32 v116, v116, v117
	v_cvt_pk_bf16_f32 v117, v118, v119
	v_cvt_pk_bf16_f32 v118, v108, v109
	v_or_b32_e32 v108, 16, v148
	s_nop 0
	v_addc_co_u32_e32 v57, vcc, 0, v141, vcc
	v_cvt_pk_bf16_f32 v48, v48, v49
	v_cvt_pk_bf16_f32 v49, v50, v51
	v_cvt_pk_bf16_f32 v51, v42, v43
	v_cvt_pk_bf16_f32 v42, v44, v45
	v_add_co_u32_e32 v44, vcc, s71, v140
	v_ashrrev_i32_e32 v109, 31, v108
	v_cvt_pk_bf16_f32 v100, v100, v101
	v_cvt_pk_bf16_f32 v101, v102, v103
	v_cvt_pk_bf16_f32 v102, v92, v93
	v_or_b32_e32 v92, 32, v148
	v_addc_co_u32_e32 v45, vcc, 0, v141, vcc
	v_lshlrev_b64 v[108:109], 11, v[108:109]
	v_ashrrev_i32_e32 v93, 31, v92
	v_cvt_pk_bf16_f32 v84, v84, v85
	v_cvt_pk_bf16_f32 v85, v86, v87
	v_cvt_pk_bf16_f32 v86, v76, v77
	v_or_b32_e32 v76, 48, v148
	s_mov_b64 s[24:25], 0x40000
	v_cvt_pk_bf16_f32 v32, v32, v33
	v_cvt_pk_bf16_f32 v33, v34, v35
	v_cvt_pk_bf16_f32 v35, v26, v27
	v_cvt_pk_bf16_f32 v26, v28, v29
	v_add_co_u32_e32 v28, vcc, s72, v140
	v_lshl_add_u64 v[108:109], s[8:9], 0, v[108:109]
	v_lshlrev_b64 v[92:93], 11, v[92:93]
	v_ashrrev_i32_e32 v77, 31, v76
	v_cvt_pk_bf16_f32 v68, v68, v69
	v_cvt_pk_bf16_f32 v69, v70, v71
	v_cvt_pk_bf16_f32 v70, v64, v65
	v_lshl_add_u64 v[64:65], v[140:141], 0, s[24:25]
	v_addc_co_u32_e32 v29, vcc, 0, v141, vcc
	v_cvt_pk_bf16_f32 v119, v110, v111
	global_store_dwordx4 v[140:141], v[116:119], off offset:256 nt
	v_lshl_add_u64 v[92:93], s[8:9], 0, v[92:93]
	v_lshlrev_b64 v[76:77], 11, v[76:77]
	v_lshl_add_u64 v[116:117], v[108:109], 0, v[152:153]
	v_cvt_pk_bf16_f32 v50, v40, v41
	global_store_dwordx4 v[64:65], v[48:51], off offset:256 nt
	v_cvt_pk_bf16_f32 v16, v16, v17
	v_cvt_pk_bf16_f32 v17, v18, v19
	v_cvt_pk_bf16_f32 v19, v10, v11
	v_cvt_pk_bf16_f32 v10, v12, v13
	v_add_co_u32_e32 v12, vcc, s73, v140
	s_nop 0
	v_lshl_add_u64 v[48:49], v[140:141], 0, s[6:7]
	v_cvt_pk_bf16_f32 v103, v94, v95
	global_store_dwordx4 v[116:117], v[100:103], off offset:256 nt
	v_lshl_add_u64 v[76:77], s[8:9], 0, v[76:77]
	v_cvt_pk_bf16_f32 v34, v24, v25
	global_store_dwordx4 v[48:49], v[32:35], off offset:256 nt
	v_lshl_add_u64 v[100:101], v[92:93], 0, v[152:153]
	v_addc_co_u32_e32 v13, vcc, 0, v141, vcc
	v_lshl_add_u64 v[32:33], v[140:141], 0, s[10:11]
	v_cvt_pk_bf16_f32 v87, v78, v79
	global_store_dwordx4 v[100:101], v[84:87], off offset:256 nt
	v_cvt_pk_bf16_f32 v18, v8, v9
	global_store_dwordx4 v[32:33], v[16:19], off offset:256 nt
	s_and_b64 vcc, exec, s[0:1]
	v_lshl_add_u64 v[84:85], v[76:77], 0, v[152:153]
	v_lshl_add_u64 v[16:17], v[140:141], 0, s[12:13]
	s_mov_b32 s74, s14
	s_mov_b32 s22, s16
	s_mov_b64 s[24:25], s[20:21]
	s_mov_b64 s[26:27], s[18:19]
	v_cvt_pk_bf16_f32 v124, v124, v125
	v_cvt_pk_bf16_f32 v125, v126, v127
	v_cvt_pk_bf16_f32 v126, v120, v121
	v_cvt_pk_bf16_f32 v127, v122, v123
	global_store_dwordx4 v[140:141], v[124:127], off nt
	v_cvt_pk_bf16_f32 v108, v112, v113
	v_cvt_pk_bf16_f32 v109, v114, v115
	v_cvt_pk_bf16_f32 v110, v104, v105
	v_cvt_pk_bf16_f32 v111, v106, v107
	global_store_dwordx4 v[116:117], v[108:111], off nt
	v_cvt_pk_bf16_f32 v92, v96, v97
	v_cvt_pk_bf16_f32 v93, v98, v99
	v_cvt_pk_bf16_f32 v94, v88, v89
	v_cvt_pk_bf16_f32 v95, v90, v91
	global_store_dwordx4 v[100:101], v[92:95], off nt
	v_cvt_pk_bf16_f32 v76, v80, v81
	v_cvt_pk_bf16_f32 v77, v82, v83
	v_cvt_pk_bf16_f32 v78, v72, v73
	v_cvt_pk_bf16_f32 v79, v74, v75
	global_store_dwordx4 v[84:85], v[76:79], off nt
	v_cvt_pk_bf16_f32 v71, v66, v67
	global_store_dwordx4 v[84:85], v[68:71], off offset:256 nt
	v_cvt_pk_bf16_f32 v63, v58, v59
	global_store_dwordx4 v[56:57], v[60:63], off nt
	v_cvt_pk_bf16_f32 v40, v52, v53
	v_cvt_pk_bf16_f32 v41, v54, v55
	v_cvt_pk_bf16_f32 v43, v46, v47
	global_store_dwordx4 v[44:45], v[40:43], off nt
	v_cvt_pk_bf16_f32 v24, v36, v37
	v_cvt_pk_bf16_f32 v25, v38, v39
	v_cvt_pk_bf16_f32 v27, v30, v31
	global_store_dwordx4 v[28:29], v[24:27], off nt
	v_cvt_pk_bf16_f32 v8, v20, v21
	v_cvt_pk_bf16_f32 v9, v22, v23
	v_cvt_pk_bf16_f32 v11, v14, v15
	global_store_dwordx4 v[12:13], v[8:11], off nt
	v_cvt_pk_bf16_f32 v4, v4, v5
	v_cvt_pk_bf16_f32 v5, v6, v7
	v_cvt_pk_bf16_f32 v6, v0, v1
	v_cvt_pk_bf16_f32 v7, v2, v3
	global_store_dwordx4 v[16:17], v[4:7], off offset:256 nt
	s_cbranch_vccz .LBB0_1013
	s_waitcnt vmcnt(0)
	s_cmpk_gt_u32 s3, 0xff
	s_cbranch_scc1 .LBB0_1024
	s_barrier

; #define PG8_STAGE(bufoff, gbase, voff) do { _Pragma("unroll") for (int _i = 0; _i < 2; ++_i) \
;         __builtin_amdgcn_global_load_lds((const unsigned*)((const char*)(gbase) + (voff)[_i]), (PG8_LAS unsigned*)(lds + (bufoff) + ldsw + _i * 8192), 16, 0, 0); } while (0)
; #define PG8_LDA(dst, b, h) do { _Pragma("unroll") for (int m = 0; m < 4; ++m) _Pragma("unroll") for (int k = 0; k < 2; ++k) dst[m][k] = *(const PG8_LAS bf16x8*)(lds + PG8_SA(b, h) + aoff + m * 2048 + k * 1024); } while (0)
; #define PG8_LDB(dst, b, h) do { _Pragma("unroll") for (int n = 0; n < 2; ++n) _Pragma("unroll") for (int k = 0; k < 2; ++k) dst[n][k] = *(const PG8_LAS bf16x8*)(lds + PG8_SB(b, h) + boff + n * 2048 + k * 1024); } while (0)
; #define PG8_MMA(ai, bj, At, Bt) do { __builtin_amdgcn_s_setprio(1); _Pragma("unroll") for (int m = 0; m < 4; ++m) _Pragma("unroll") for (int n = 0; n < 2; ++n) _Pragma("unroll") for (int k = 0; k < 2; ++k) \
;         acc[ai][bj][m][n] = __builtin_amdgcn_mfma_f32_16x16x32_bf16(Bt[n][k], At[m][k], acc[ai][bj][m][n], 0, 0, 0); __builtin_amdgcn_s_setprio(0); } while (0)
; #define PG8_WAIT_V(n) asm volatile("s_waitcnt vmcnt(" #n ")" ::: "memory")
; #define PG8_WAIT_L(n) asm volatile("s_waitcnt lgkmcnt(" #n ")" ::: "memory")
; #define PG8_BAR __builtin_amdgcn_s_barrier()
; template <class Epi, class Sched>
; __device__ __forceinline__ void gemm_phase(PG8_LAS unsigned char* lds, const Gemm g, const Sched& S, const Epi& E) {
;     ...
;             const char* a1 = cA + (size_t)(t + 1) * kstep;
;             const char* a2 = last ? nA : cA + (size_t)(t + 2) * kstep; const char* b2 = last ? nB : cB + (size_t)(t + 2) * kstep;
;             const char* a3 = a2 + kstep; const char* b3 = b2 + kstep;
;             if (last && has_next) S.a_ready(nxt);
;             PG8_LDB(B0, 0, 0); PG8_SCHED; PG8_LDA(At, 0, 0); PG8_STAGE(PG8_SA(1, 1), a1 + hstep, voffA);
;             PG8_WAIT_L(8); PG8_BAR; PG8_WAIT_L(0); PG8_MMA(0, 0, At, B0); PG8_BAR; PG8_SCHED;
;             PG8_LDB(B1, 0, 1); PG8_STAGE(PG8_SB(0, 0), b2, voffB);
;             PG8_BAR; PG8_WAIT_L(0); PG8_MMA(0, 1, At, B1); PG8_BAR;
;             PG8_LDA(At, 0, 1); PG8_STAGE(PG8_SA(0, 0), a2, voffA);
;             PG8_BAR; PG8_WAIT_L(0); PG8_MMA(1, 0, At, B0); PG8_BAR; PG8_SCHED;
;             PG8_STAGE(PG8_SB(0, 1), b2 + hstep, voffB);
;             PG8_WAIT_V(6); PG8_BAR; PG8_MMA(1, 1, At, B1); PG8_BAR;
.LBB0_1150:
	ds_read_b128 v[48:51], v167
	ds_read_b128 v[56:59], v167 offset:1024
	ds_read_b128 v[64:67], v167 offset:2048
	ds_read_b128 v[68:71], v167 offset:3072
	s_add_u32 s26, s24, 0xfffc0080
	s_addc_u32 s27, s25, -1
	s_cmp_eq_u32 s53, 12
	s_cselect_b32 s29, s15, s27
	s_cselect_b32 s28, s21, s26
	s_cselect_b32 s27, s13, s52
	s_cselect_b32 s26, s50, s51
	v_lshl_add_u64 v[198:199], s[24:25], 0, v[152:153]
	s_add_i32 m0, s23, 0xc000
	ds_read_b128 v[160:163], v168
	ds_read_b128 v[170:173], v168 offset:1024
	ds_read_b128 v[174:177], v168 offset:2048
	ds_read_b128 v[178:181], v168 offset:3072
	ds_read_b128 v[182:185], v168 offset:4096
	ds_read_b128 v[186:189], v168 offset:5120
	ds_read_b128 v[190:193], v168 offset:6144
	ds_read_b128 v[194:197], v168 offset:7168
	global_load_lds_dwordx4 v[198:199], off
	v_lshl_add_u64 v[198:199], s[24:25], 0, v[154:155]
	s_add_i32 m0, s23, 0xe000
	s_nop 0
	global_load_lds_dwordx4 v[198:199], off
	s_waitcnt lgkmcnt(8)
	s_barrier
	s_waitcnt lgkmcnt(0)
	v_mfma_f32_16x16x32_bf16 v[140:143], v[48:51], v[160:163], v[140:143]
	v_mfma_f32_16x16x32_bf16 v[136:139], v[64:67], v[160:163], v[136:139]
	v_mfma_f32_16x16x32_bf16 v[124:127], v[48:51], v[174:177], v[124:127]
	v_mfma_f32_16x16x32_bf16 v[120:123], v[64:67], v[174:177], v[120:123]
	v_mfma_f32_16x16x32_bf16 v[108:111], v[48:51], v[182:185], v[108:111]
	v_mfma_f32_16x16x32_bf16 v[104:107], v[64:67], v[182:185], v[104:107]
	v_mfma_f32_16x16x32_bf16 v[92:95], v[48:51], v[190:193], v[92:95]
	v_mfma_f32_16x16x32_bf16 v[88:91], v[64:67], v[190:193], v[88:91]
	v_mfma_f32_16x16x32_bf16 v[140:143], v[56:59], v[170:173], v[140:143]
	v_mfma_f32_16x16x32_bf16 v[136:139], v[68:71], v[170:173], v[136:139]
	v_mfma_f32_16x16x32_bf16 v[124:127], v[56:59], v[178:181], v[124:127]
	v_mfma_f32_16x16x32_bf16 v[120:123], v[68:71], v[178:181], v[120:123]
	v_mfma_f32_16x16x32_bf16 v[108:111], v[56:59], v[186:189], v[108:111]
	v_mfma_f32_16x16x32_bf16 v[104:107], v[68:71], v[186:189], v[104:107]
	v_mfma_f32_16x16x32_bf16 v[92:95], v[56:59], v[194:197], v[92:95]
	v_mfma_f32_16x16x32_bf16 v[88:91], v[68:71], v[194:197], v[88:91]
	s_barrier
	s_add_i32 s60, s46, s34
	v_lshl_add_u64 v[214:215], s[26:27], 0, v[146:147]
	s_mov_b32 m0, s60
	ds_read_b128 v[198:201], v169
	ds_read_b128 v[202:205], v169 offset:1024
	ds_read_b128 v[206:209], v169 offset:2048
	ds_read_b128 v[210:213], v169 offset:3072
	global_load_lds_dwordx4 v[214:215], off
	v_lshl_add_u64 v[216:217], s[26:27], 0, v[150:151]
	s_add_i32 m0, s60, 0x2000
	s_nop 0
	global_load_lds_dwordx4 v[216:217], off
	s_barrier
	s_waitcnt lgkmcnt(0)
	v_mfma_f32_16x16x32_bf16 v[132:135], v[198:201], v[160:163], v[132:135]
	v_mfma_f32_16x16x32_bf16 v[128:131], v[206:209], v[160:163], v[128:131]
	v_mfma_f32_16x16x32_bf16 v[116:119], v[198:201], v[174:177], v[116:119]
	v_mfma_f32_16x16x32_bf16 v[112:115], v[206:209], v[174:177], v[112:115]
	v_mfma_f32_16x16x32_bf16 v[100:103], v[198:201], v[182:185], v[100:103]
	v_mfma_f32_16x16x32_bf16 v[96:99], v[206:209], v[182:185], v[96:99]
	v_mfma_f32_16x16x32_bf16 v[84:87], v[198:201], v[190:193], v[84:87]
	v_mfma_f32_16x16x32_bf16 v[80:83], v[206:209], v[190:193], v[80:83]
	v_mfma_f32_16x16x32_bf16 v[132:135], v[202:205], v[170:173], v[132:135]
	v_mfma_f32_16x16x32_bf16 v[128:131], v[210:213], v[170:173], v[128:131]
	v_mfma_f32_16x16x32_bf16 v[116:119], v[202:205], v[178:181], v[116:119]
	v_mfma_f32_16x16x32_bf16 v[112:115], v[210:213], v[178:181], v[112:115]
	v_mfma_f32_16x16x32_bf16 v[100:103], v[202:205], v[186:189], v[100:103]
	v_mfma_f32_16x16x32_bf16 v[96:99], v[210:213], v[186:189], v[96:99]
	v_mfma_f32_16x16x32_bf16 v[84:87], v[202:205], v[194:197], v[84:87]
	v_mfma_f32_16x16x32_bf16 v[80:83], v[210:213], v[194:197], v[80:83]
	s_mov_b32 m0, s23
	v_lshl_add_u64 v[218:219], s[28:29], 0, v[144:145]
	s_barrier
	ds_read_b128 v[160:163], v168 offset:16384
	ds_read_b128 v[170:173], v168 offset:17408
	ds_read_b128 v[174:177], v168 offset:18432
	ds_read_b128 v[178:181], v168 offset:19456
	ds_read_b128 v[182:185], v168 offset:20480
	ds_read_b128 v[186:189], v168 offset:21504
	ds_read_b128 v[190:193], v168 offset:22528
	ds_read_b128 v[194:197], v168 offset:23552
	global_load_lds_dwordx4 v[218:219], off
	v_lshl_add_u64 v[220:221], s[28:29], 0, v[148:149]
	s_mov_b32 m0, s35
	s_nop 0
	global_load_lds_dwordx4 v[220:221], off
	s_barrier
	s_waitcnt lgkmcnt(0)
	v_mfma_f32_16x16x32_bf16 v[76:79], v[48:51], v[160:163], v[76:79]
	v_mfma_f32_16x16x32_bf16 v[72:75], v[64:67], v[160:163], v[72:75]
	v_mfma_f32_16x16x32_bf16 v[44:47], v[48:51], v[174:177], v[44:47]
	v_mfma_f32_16x16x32_bf16 v[40:43], v[64:67], v[174:177], v[40:43]
	v_mfma_f32_16x16x32_bf16 v[28:31], v[48:51], v[182:185], v[28:31]
	v_mfma_f32_16x16x32_bf16 v[24:27], v[64:67], v[182:185], v[24:27]
	v_mfma_f32_16x16x32_bf16 v[12:15], v[48:51], v[190:193], v[12:15]
	v_mfma_f32_16x16x32_bf16 v[8:11], v[64:67], v[190:193], v[8:11]
	v_mfma_f32_16x16x32_bf16 v[76:79], v[56:59], v[170:173], v[76:79]
	v_mfma_f32_16x16x32_bf16 v[72:75], v[68:71], v[170:173], v[72:75]
	v_mfma_f32_16x16x32_bf16 v[44:47], v[56:59], v[178:181], v[44:47]
	v_mfma_f32_16x16x32_bf16 v[40:43], v[68:71], v[178:181], v[40:43]
	v_mfma_f32_16x16x32_bf16 v[28:31], v[56:59], v[186:189], v[28:31]
	v_mfma_f32_16x16x32_bf16 v[24:27], v[68:71], v[186:189], v[24:27]
	v_mfma_f32_16x16x32_bf16 v[12:15], v[56:59], v[194:197], v[12:15]
	v_mfma_f32_16x16x32_bf16 v[8:11], v[68:71], v[194:197], v[8:11]
	s_barrier
	s_add_u32 s60, s26, 0x40000
	s_addc_u32 s61, s27, 0
	s_add_i32 s62, s47, s34
	v_lshl_add_u64 v[48:49], s[60:61], 0, v[146:147]
	s_mov_b32 m0, s62
	s_nop 0
	global_load_lds_dwordx4 v[48:49], off
	v_lshl_add_u64 v[48:49], s[60:61], 0, v[150:151]
	s_add_i32 m0, s62, 0x2000
	s_nop 0
	global_load_lds_dwordx4 v[48:49], off
	s_waitcnt vmcnt(6)
	s_barrier
; #define PG8_STAGE(bufoff, gbase, voff) do { _Pragma("unroll") for (int _i = 0; _i < 2; ++_i) \
;         __builtin_amdgcn_global_load_lds((const unsigned*)((const char*)(gbase) + (voff)[_i]), (PG8_LAS unsigned*)(lds + (bufoff) + ldsw + _i * 8192), 16, 0, 0); } while (0)
; #define PG8_LDA(dst, b, h) do { _Pragma("unroll") for (int m = 0; m < 4; ++m) _Pragma("unroll") for (int k = 0; k < 2; ++k) dst[m][k] = *(const PG8_LAS bf16x8*)(lds + PG8_SA(b, h) + aoff + m * 2048 + k * 1024); } while (0)
; #define PG8_LDB(dst, b, h) do { _Pragma("unroll") for (int n = 0; n < 2; ++n) _Pragma("unroll") for (int k = 0; k < 2; ++k) dst[n][k] = *(const PG8_LAS bf16x8*)(lds + PG8_SB(b, h) + boff + n * 2048 + k * 1024); } while (0)
; #define PG8_MMA(ai, bj, At, Bt) do { __builtin_amdgcn_s_setprio(1); _Pragma("unroll") for (int m = 0; m < 4; ++m) _Pragma("unroll") for (int n = 0; n < 2; ++n) _Pragma("unroll") for (int k = 0; k < 2; ++k) \
;         acc[ai][bj][m][n] = __builtin_amdgcn_mfma_f32_16x16x32_bf16(Bt[n][k], At[m][k], acc[ai][bj][m][n], 0, 0, 0); __builtin_amdgcn_s_setprio(0); } while (0)
; #define PG8_WAIT_V(n) asm volatile("s_waitcnt vmcnt(" #n ")" ::: "memory")
; #define PG8_WAIT_L(n) asm volatile("s_waitcnt lgkmcnt(" #n ")" ::: "memory")
; #define PG8_BAR __builtin_amdgcn_s_barrier()
; #define PG8_SCHED __builtin_amdgcn_sched_barrier(0)
; template <class Epi, class Sched>
; __device__ __forceinline__ void gemm_phase(PG8_LAS unsigned char* lds, const Gemm g, const Sched& S, const Epi& E) {
;     ...
;             PG8_WAIT_V(6); PG8_BAR; PG8_MMA(1, 1, At, B1); PG8_BAR;
;             PG8_LDB(B0, 1, 0); PG8_SCHED; PG8_LDA(At, 1, 0); PG8_STAGE(PG8_SA(0, 1), a2 + hstep, voffA);
;             PG8_WAIT_L(8); PG8_BAR; PG8_WAIT_L(0); PG8_MMA(0, 0, At, B0); PG8_BAR; PG8_SCHED;
;             PG8_LDB(B1, 1, 1); PG8_STAGE(PG8_SB(1, 0), b3, voffB);
;             PG8_BAR; PG8_WAIT_L(0); PG8_MMA(0, 1, At, B1); PG8_BAR;
;             PG8_LDA(At, 1, 1); PG8_STAGE(PG8_SA(1, 0), a3, voffA);
	v_mfma_f32_16x16x32_bf16 v[52:55], v[206:209], v[160:163], v[52:55]
	v_mfma_f32_16x16x32_bf16 v[36:39], v[198:201], v[174:177], v[36:39]
	v_mfma_f32_16x16x32_bf16 v[32:35], v[206:209], v[174:177], v[32:35]
	v_mfma_f32_16x16x32_bf16 v[20:23], v[198:201], v[182:185], v[20:23]
	v_mfma_f32_16x16x32_bf16 v[16:19], v[206:209], v[182:185], v[16:19]
	v_mfma_f32_16x16x32_bf16 v[4:7], v[198:201], v[190:193], v[4:7]
	v_mfma_f32_16x16x32_bf16 v[0:3], v[206:209], v[190:193], v[0:3]
	v_mfma_f32_16x16x32_bf16 v[48:51], v[198:201], v[160:163], v[60:63]
	v_mfma_f32_16x16x32_bf16 v[52:55], v[210:213], v[170:173], v[52:55]
	v_mfma_f32_16x16x32_bf16 v[36:39], v[202:205], v[178:181], v[36:39]
	v_mfma_f32_16x16x32_bf16 v[32:35], v[210:213], v[178:181], v[32:35]
	v_mfma_f32_16x16x32_bf16 v[20:23], v[202:205], v[186:189], v[20:23]
	v_mfma_f32_16x16x32_bf16 v[16:19], v[210:213], v[186:189], v[16:19]
	v_mfma_f32_16x16x32_bf16 v[4:7], v[202:205], v[194:197], v[4:7]
	v_mfma_f32_16x16x32_bf16 v[0:3], v[210:213], v[194:197], v[0:3]
	v_mfma_f32_16x16x32_bf16 v[48:51], v[202:205], v[170:173], v[48:51]
	s_add_i32 s60, 0, 0x18000
	v_add_u32_e32 v68, s60, v165
	s_barrier
	ds_read_b128 v[56:59], v68
	ds_read_b128 v[60:63], v68 offset:1024
	ds_read_b128 v[64:67], v68 offset:2048
	ds_read_b128 v[68:71], v68 offset:3072
	s_add_u32 s28, s28, 0x40000
	s_addc_u32 s29, s29, 0
	s_mov_b32 m0, s36
	v_lshl_add_u64 v[198:199], s[28:29], 0, v[144:145]
	ds_read_b128 v[160:163], v168 offset:32768
	ds_read_b128 v[170:173], v168 offset:33792
	ds_read_b128 v[174:177], v168 offset:34816
	ds_read_b128 v[178:181], v168 offset:35840
	ds_read_b128 v[182:185], v168 offset:36864
	ds_read_b128 v[186:189], v168 offset:37888
	ds_read_b128 v[190:193], v168 offset:38912
	ds_read_b128 v[194:197], v168 offset:39936
	global_load_lds_dwordx4 v[198:199], off
	v_lshl_add_u64 v[198:199], s[28:29], 0, v[148:149]
	s_mov_b32 m0, s37
	s_nop 0
	global_load_lds_dwordx4 v[198:199], off
	s_waitcnt lgkmcnt(8)
	s_barrier
	s_waitcnt lgkmcnt(0)
	v_mfma_f32_16x16x32_bf16 v[140:143], v[56:59], v[160:163], v[140:143]
	v_mfma_f32_16x16x32_bf16 v[136:139], v[64:67], v[160:163], v[136:139]
	v_mfma_f32_16x16x32_bf16 v[124:127], v[56:59], v[174:177], v[124:127]
	v_mfma_f32_16x16x32_bf16 v[120:123], v[64:67], v[174:177], v[120:123]
	v_mfma_f32_16x16x32_bf16 v[108:111], v[56:59], v[182:185], v[108:111]
	v_mfma_f32_16x16x32_bf16 v[104:107], v[64:67], v[182:185], v[104:107]
	v_mfma_f32_16x16x32_bf16 v[92:95], v[56:59], v[190:193], v[92:95]
	v_mfma_f32_16x16x32_bf16 v[88:91], v[64:67], v[190:193], v[88:91]
	v_mfma_f32_16x16x32_bf16 v[140:143], v[60:63], v[170:173], v[140:143]
	v_mfma_f32_16x16x32_bf16 v[136:139], v[68:71], v[170:173], v[136:139]
	v_mfma_f32_16x16x32_bf16 v[124:127], v[60:63], v[178:181], v[124:127]
	v_mfma_f32_16x16x32_bf16 v[120:123], v[68:71], v[178:181], v[120:123]
	v_mfma_f32_16x16x32_bf16 v[108:111], v[60:63], v[186:189], v[108:111]
	v_mfma_f32_16x16x32_bf16 v[104:107], v[68:71], v[186:189], v[104:107]
	v_mfma_f32_16x16x32_bf16 v[92:95], v[60:63], v[194:197], v[92:95]
	v_mfma_f32_16x16x32_bf16 v[88:91], v[68:71], v[194:197], v[88:91]
	s_barrier
	s_add_i32 s28, 0, 0x1c000
	s_add_i32 s29, s60, s34
	v_add_u32_e32 v210, s28, v165
	v_lshl_add_u64 v[214:215], v[214:215], 0, s[10:11]
	s_mov_b32 m0, s29
	ds_read_b128 v[198:201], v210
	ds_read_b128 v[202:205], v210 offset:1024
	ds_read_b128 v[206:209], v210 offset:2048
	ds_read_b128 v[210:213], v210 offset:3072
	global_load_lds_dwordx4 v[214:215], off
	v_lshl_add_u64 v[214:215], v[216:217], 0, s[10:11]
	s_add_i32 m0, s29, 0x2000
	s_nop 0
	global_load_lds_dwordx4 v[214:215], off
	s_barrier
	s_waitcnt lgkmcnt(0)
	v_mfma_f32_16x16x32_bf16 v[132:135], v[198:201], v[160:163], v[132:135]
	v_mfma_f32_16x16x32_bf16 v[128:131], v[206:209], v[160:163], v[128:131]
	v_mfma_f32_16x16x32_bf16 v[116:119], v[198:201], v[174:177], v[116:119]
	v_mfma_f32_16x16x32_bf16 v[112:115], v[206:209], v[174:177], v[112:115]
	v_mfma_f32_16x16x32_bf16 v[100:103], v[198:201], v[182:185], v[100:103]
	v_mfma_f32_16x16x32_bf16 v[96:99], v[206:209], v[182:185], v[96:99]
	v_mfma_f32_16x16x32_bf16 v[84:87], v[198:201], v[190:193], v[84:87]
	v_mfma_f32_16x16x32_bf16 v[80:83], v[206:209], v[190:193], v[80:83]
	v_mfma_f32_16x16x32_bf16 v[132:135], v[202:205], v[170:173], v[132:135]
	v_mfma_f32_16x16x32_bf16 v[128:131], v[210:213], v[170:173], v[128:131]
	v_mfma_f32_16x16x32_bf16 v[116:119], v[202:205], v[178:181], v[116:119]
	v_mfma_f32_16x16x32_bf16 v[112:115], v[210:213], v[178:181], v[112:115]
	v_mfma_f32_16x16x32_bf16 v[100:103], v[202:205], v[186:189], v[100:103]
	v_mfma_f32_16x16x32_bf16 v[96:99], v[210:213], v[186:189], v[96:99]
	v_mfma_f32_16x16x32_bf16 v[84:87], v[202:205], v[194:197], v[84:87]
	v_mfma_f32_16x16x32_bf16 v[80:83], v[210:213], v[194:197], v[80:83]
	s_mov_b32 m0, s39
	v_lshl_add_u64 v[214:215], v[218:219], 0, s[10:11]
	s_barrier
	ds_read_b128 v[160:163], v168 offset:49152
	ds_read_b128 v[170:173], v168 offset:50176
	ds_read_b128 v[174:177], v168 offset:51200
	ds_read_b128 v[178:181], v168 offset:52224
	ds_read_b128 v[182:185], v168 offset:53248
	ds_read_b128 v[186:189], v168 offset:54272
	ds_read_b128 v[190:193], v168 offset:55296
	ds_read_b128 v[194:197], v168 offset:56320
	global_load_lds_dwordx4 v[214:215], off
	v_lshl_add_u64 v[214:215], v[220:221], 0, s[10:11]
	s_mov_b32 m0, s40
	s_nop 0
	global_load_lds_dwordx4 v[214:215], off
	s_barrier
; #define PG8_STAGE(bufoff, gbase, voff) do { _Pragma("unroll") for (int _i = 0; _i < 2; ++_i) \
;         __builtin_amdgcn_global_load_lds((const unsigned*)((const char*)(gbase) + (voff)[_i]), (PG8_LAS unsigned*)(lds + (bufoff) + ldsw + _i * 8192), 16, 0, 0); } while (0)
; #define PG8_MMA(ai, bj, At, Bt) do { __builtin_amdgcn_s_setprio(1); _Pragma("unroll") for (int m = 0; m < 4; ++m) _Pragma("unroll") for (int n = 0; n < 2; ++n) _Pragma("unroll") for (int k = 0; k < 2; ++k) \
;         acc[ai][bj][m][n] = __builtin_amdgcn_mfma_f32_16x16x32_bf16(Bt[n][k], At[m][k], acc[ai][bj][m][n], 0, 0, 0); __builtin_amdgcn_s_setprio(0); } while (0)
; #define PG8_WAIT_V(n) asm volatile("s_waitcnt vmcnt(" #n ")" ::: "memory")
; #define PG8_WAIT_L(n) asm volatile("s_waitcnt lgkmcnt(" #n ")" ::: "memory")
; #define PG8_BAR __builtin_amdgcn_s_barrier()
; #define PG8_SCHED __builtin_amdgcn_sched_barrier(0)
; template <class Epi, class Sched>
; __device__ __forceinline__ void gemm_phase(PG8_LAS unsigned char* lds, const Gemm g, const Sched& S, const Epi& E) {
;     ...
;             PG8_BAR; PG8_WAIT_L(0); PG8_MMA(1, 0, At, B0); PG8_BAR; PG8_SCHED;
;             PG8_STAGE(PG8_SB(1, 1), b3 + hstep, voffB);
;             PG8_WAIT_V(6); PG8_BAR; PG8_MMA(1, 1, At, B1); PG8_BAR;
	s_waitcnt lgkmcnt(0)
	v_mfma_f32_16x16x32_bf16 v[76:79], v[56:59], v[160:163], v[76:79]
	v_mfma_f32_16x16x32_bf16 v[72:75], v[64:67], v[160:163], v[72:75]
	v_mfma_f32_16x16x32_bf16 v[44:47], v[56:59], v[174:177], v[44:47]
	v_mfma_f32_16x16x32_bf16 v[40:43], v[64:67], v[174:177], v[40:43]
	v_mfma_f32_16x16x32_bf16 v[28:31], v[56:59], v[182:185], v[28:31]
	v_mfma_f32_16x16x32_bf16 v[24:27], v[64:67], v[182:185], v[24:27]
	v_mfma_f32_16x16x32_bf16 v[12:15], v[56:59], v[190:193], v[12:15]
	v_mfma_f32_16x16x32_bf16 v[8:11], v[64:67], v[190:193], v[8:11]
	v_mfma_f32_16x16x32_bf16 v[76:79], v[60:63], v[170:173], v[76:79]
	v_mfma_f32_16x16x32_bf16 v[72:75], v[68:71], v[170:173], v[72:75]
	v_mfma_f32_16x16x32_bf16 v[44:47], v[60:63], v[178:181], v[44:47]
	v_mfma_f32_16x16x32_bf16 v[40:43], v[68:71], v[178:181], v[40:43]
	v_mfma_f32_16x16x32_bf16 v[28:31], v[60:63], v[186:189], v[28:31]
	v_mfma_f32_16x16x32_bf16 v[24:27], v[68:71], v[186:189], v[24:27]
	v_mfma_f32_16x16x32_bf16 v[12:15], v[60:63], v[194:197], v[12:15]
	v_mfma_f32_16x16x32_bf16 v[8:11], v[68:71], v[194:197], v[8:11]
	s_barrier
	s_add_u32 s26, s26, 0x40080
	s_addc_u32 s27, s27, 0
	s_add_i32 s28, s28, s34
	v_lshl_add_u64 v[56:57], s[26:27], 0, v[146:147]
	s_mov_b32 m0, s28
	s_nop 0
	global_load_lds_dwordx4 v[56:57], off
	v_lshl_add_u64 v[56:57], s[26:27], 0, v[150:151]
	s_add_i32 m0, s28, 0x2000
	s_nop 0
	global_load_lds_dwordx4 v[56:57], off
	s_waitcnt vmcnt(6)
	s_barrier
	v_mfma_f32_16x16x32_bf16 v[48:51], v[198:201], v[160:163], v[48:51]
	v_mfma_f32_16x16x32_bf16 v[60:63], v[202:205], v[170:173], v[48:51]
	v_mfma_f32_16x16x32_bf16 v[48:51], v[206:209], v[160:163], v[52:55]
	v_mfma_f32_16x16x32_bf16 v[36:39], v[198:201], v[174:177], v[36:39]
	v_mfma_f32_16x16x32_bf16 v[32:35], v[206:209], v[174:177], v[32:35]
	v_mfma_f32_16x16x32_bf16 v[20:23], v[198:201], v[182:185], v[20:23]
	v_mfma_f32_16x16x32_bf16 v[16:19], v[206:209], v[182:185], v[16:19]
	v_mfma_f32_16x16x32_bf16 v[4:7], v[198:201], v[190:193], v[4:7]
	v_mfma_f32_16x16x32_bf16 v[0:3], v[206:209], v[190:193], v[0:3]
	v_mfma_f32_16x16x32_bf16 v[52:55], v[210:213], v[170:173], v[48:51]
	v_mfma_f32_16x16x32_bf16 v[36:39], v[202:205], v[178:181], v[36:39]
	v_mfma_f32_16x16x32_bf16 v[32:35], v[210:213], v[178:181], v[32:35]
	v_mfma_f32_16x16x32_bf16 v[20:23], v[202:205], v[186:189], v[20:23]
	v_mfma_f32_16x16x32_bf16 v[16:19], v[210:213], v[186:189], v[16:19]
	v_mfma_f32_16x16x32_bf16 v[4:7], v[202:205], v[194:197], v[4:7]
	v_mfma_f32_16x16x32_bf16 v[0:3], v[210:213], v[194:197], v[0:3]
	s_add_i32 s53, s53, 2
	s_add_u32 s24, s24, 0x100
	s_addc_u32 s25, s25, 0
	s_add_u32 s51, s51, 0x100
	s_addc_u32 s52, s52, 0
	s_cmp_gt_u32 s53, 13
	s_barrier
	s_cbranch_scc0 .LBB0_1150
; __device__ __forceinline__ void unpack8(const u32x4 w, float (&f)[8]) { f[0] = bflo(w.x); f[1] = bfhi(w.x); f[2] = bflo(w.y); f[3] = bfhi(w.y); f[4] = bflo(w.z); f[5] = bfhi(w.z); f[6] = bflo(w.w); f[7] = bfhi(w.w); }
; __device__ __forceinline__ u32x4 pack8(const float (&f)[8]) { u32x4 o; o.x = pk2(f[0], f[1]); o.y = pk2(f[2], f[3]); o.z = pk2(f[4], f[5]); o.w = pk2(f[6], f[7]); return o; }
; __device__ __forceinline__ float sigmoidf_(float x) { return __builtin_amdgcn_rcpf(1.0f + __expf(-x)); }
;     __device__ __forceinline__ void operator()(const f32x4 (&acc)[2][2][4][2], const Unit& u, int wr, int wc, int fr, int fq) const {
;         const int row0 = u.pm * BM + wr * 64 + fr, col0 = u.pn * BM + wc * 32 + 8 * fq;
;         f32x4 bv[2][2];
; #pragma unroll
;         for (int bj = 0; bj < 2; ++bj)
; #pragma unroll
;             for (int n = 0; n < 2; ++n) bv[bj][n] = *(const f32x4*)(bias + col0 + bj * HALF + 4 * n);
; #pragma unroll
;         for (int ai = 0; ai < 2; ++ai)
; #pragma unroll
;             for (int m = 0; m < 4; ++m) { const int row = row0 + ai * HALF + m * 16; const size_t off = (size_t)row * DM + col0; float s = 0.f;
; #pragma unroll
;                 for (int bj = 0; bj < 2; ++bj) { float e[8], o[8]; unpack8(*(const u32x4*)(E + off + bj * HALF), e);
; #pragma unroll
;                     for (int n = 0; n < 2; ++n) { const f32x4 v = acc[ai][bj][m][n] + bv[bj][n];
; #pragma unroll
;                         for (int j = 0; j < 4; ++j) { o[4 * n + j] = sigmoidf_(v[j]) * e[4 * n + j]; s += o[4 * n + j] * o[4 * n + j]; } }
;                     *(u32x4*)(C + off + bj * HALF) = pack8(o); }
;                 { auto r16 = __builtin_amdgcn_permlane16_swap(__float_as_uint(s), __float_as_uint(s), false, false); s = __uint_as_float(r16[0]) + __uint_as_float(r16[1]);
;                   auto r32 = __builtin_amdgcn_permlane32_swap(__float_as_uint(s), __float_as_uint(s), false, false); s = __uint_as_float(r32[0]) + __uint_as_float(r32[1]); }
;                 if (fq == 0) atomicAdd(ss + row, s); }
	v_lshl_add_u32 v162, s20, 8, v164
	v_lshl_or_b32 v160, s22, 8, v166
	v_ashrrev_i32_e32 v163, 31, v162
	v_ashrrev_i32_e32 v161, 31, v160
	v_lshlrev_b64 v[58:59], 10, v[162:163]
	v_lshl_add_u64 v[58:59], v[58:59], 0, v[160:161]
	v_lshl_add_u64 v[56:57], v[160:161], 2, s[54:55]
	v_lshlrev_b64 v[178:179], 1, v[58:59]
	global_load_dwordx4 v[68:71], v[56:57], off
	global_load_dwordx4 v[64:67], v[56:57], off offset:16
	global_load_dwordx4 v[48:51], v[56:57], off offset:512
	v_lshl_add_u64 v[58:59], s[8:9], 0, v[178:179]
	global_load_dwordx4 v[170:173], v[58:59], off
	global_load_dwordx4 v[174:177], v[58:59], off offset:256
	s_nop 0
	global_load_dwordx4 v[56:59], v[56:57], off offset:528
	v_lshl_add_u64 v[178:179], s[48:49], 0, v[178:179]
	s_waitcnt vmcnt(0)
	v_add_f32_e32 v141, v141, v69
	v_add_f32_e32 v140, v140, v68
	v_mul_f32_e32 v141, 0xbfb8aa3b, v141
	v_add_f32_e32 v142, v142, v70
	v_add_f32_e32 v136, v136, v64
	v_mul_f32_e32 v140, 0xbfb8aa3b, v140
	v_exp_f32_e32 v141, v141
	v_add_f32_e32 v143, v143, v71
	v_add_f32_e32 v137, v137, v65
	v_add_f32_e32 v138, v138, v66
	v_add_f32_e32 v139, v139, v67
	v_mul_f32_e32 v142, 0xbfb8aa3b, v142
	v_mul_f32_e32 v136, 0xbfb8aa3b, v136
	v_exp_f32_e32 v140, v140
	v_add_f32_e32 v128, v128, v56
	v_mul_f32_e32 v143, 0xbfb8aa3b, v143
	v_mul_f32_e32 v137, 0xbfb8aa3b, v137
	v_mul_f32_e32 v138, 0xbfb8aa3b, v138
	v_mul_f32_e32 v139, 0xbfb8aa3b, v139
	v_exp_f32_e32 v142, v142
	v_exp_f32_e32 v136, v136
	v_mul_f32_e32 v128, 0xbfb8aa3b, v128
	v_exp_f32_e32 v143, v143
	v_exp_f32_e32 v137, v137
	v_exp_f32_e32 v138, v138
	v_exp_f32_e32 v139, v139
	v_exp_f32_e32 v128, v128
	v_add_f32_e32 v141, 1.0, v141
	v_add_f32_e32 v140, 1.0, v140
	v_rcp_f32_e32 v141, v141
	v_add_f32_e32 v132, v132, v48
	v_add_f32_e32 v142, 1.0, v142
	v_add_f32_e32 v136, 1.0, v136
	v_rcp_f32_e32 v140, v140
	v_add_f32_e32 v129, v129, v57
	v_add_f32_e32 v133, v133, v49
	v_mul_f32_e32 v132, 0xbfb8aa3b, v132
	v_add_f32_e32 v143, 1.0, v143
	v_add_f32_e32 v137, 1.0, v137
	v_add_f32_e32 v138, 1.0, v138
	v_add_f32_e32 v139, 1.0, v139
	v_rcp_f32_e32 v142, v142
	v_rcp_f32_e32 v136, v136
	v_add_f32_e32 v128, 1.0, v128
	v_mul_f32_e32 v129, 0xbfb8aa3b, v129
	v_mul_f32_e32 v133, 0xbfb8aa3b, v133
	v_exp_f32_e32 v132, v132
	v_lshlrev_b32_e32 v180, 16, v170
	v_and_b32_e32 v170, 0xffff0000, v170
	v_rcp_f32_e32 v143, v143
	v_rcp_f32_e32 v137, v137
	v_rcp_f32_e32 v138, v138
	v_rcp_f32_e32 v139, v139
	v_add_f32_e32 v134, v134, v50
	v_rcp_f32_e32 v128, v128
	v_exp_f32_e32 v129, v129
	v_exp_f32_e32 v133, v133
	v_mul_f32_e32 v141, v141, v170
	v_mul_f32_e32 v134, 0xbfb8aa3b, v134
	v_add_f32_e32 v135, v135, v51
	v_lshlrev_b32_e32 v181, 16, v171
	v_lshlrev_b32_e32 v182, 16, v172
	v_mul_f32_e32 v140, v140, v180
	v_mul_f32_e32 v180, v141, v141
	v_exp_f32_e32 v134, v134
	v_mul_f32_e32 v135, 0xbfb8aa3b, v135
	v_and_b32_e32 v171, 0xffff0000, v171
	v_and_b32_e32 v172, 0xffff0000, v172
	v_lshlrev_b32_e32 v183, 16, v173
	v_and_b32_e32 v173, 0xffff0000, v173
	v_lshlrev_b32_e32 v186, 16, v176
	v_mul_f32_e32 v142, v142, v181
	v_mul_f32_e32 v170, v136, v182
	v_cvt_pk_bf16_f32 v136, v140, v141
	v_fmac_f32_e32 v180, v140, v140
	v_exp_f32_e32 v135, v135
	v_add_f32_e32 v132, 1.0, v132
	v_mul_f32_e32 v143, v143, v171
	v_mul_f32_e32 v171, v137, v172
	v_mul_f32_e32 v172, v138, v183
	v_mul_f32_e32 v173, v139, v173
	v_cvt_pk_bf16_f32 v137, v142, v143
	v_cvt_pk_bf16_f32 v138, v170, v171
	v_cvt_pk_bf16_f32 v139, v172, v173
	global_store_dwordx4 v[178:179], v[136:139], off
	v_fmac_f32_e32 v180, v142, v142
	v_add_f32_e32 v133, 1.0, v133
	v_mul_f32_e32 v136, v128, v186
	v_add_f32_e32 v128, 1.0, v129
	v_add_f32_e32 v129, v130, v58
	v_rcp_f32_e32 v132, v132
	v_fmac_f32_e32 v180, v143, v143
	v_mul_f32_e32 v129, 0xbfb8aa3b, v129
	v_add_f32_e32 v130, v131, v59
	v_rcp_f32_e32 v133, v133
	v_fmac_f32_e32 v180, v170, v170
	v_add_f32_e32 v134, 1.0, v134
	v_rcp_f32_e32 v128, v128
	v_exp_f32_e32 v129, v129
	v_mul_f32_e32 v130, 0xbfb8aa3b, v130
	v_fmac_f32_e32 v180, v171, v171
	v_rcp_f32_e32 v134, v134
	v_add_f32_e32 v135, 1.0, v135
	v_exp_f32_e32 v130, v130
	v_lshlrev_b32_e32 v184, 16, v174
	v_fmac_f32_e32 v180, v172, v172
	v_rcp_f32_e32 v135, v135
	v_and_b32_e32 v174, 0xffff0000, v174
	v_and_b32_e32 v176, 0xffff0000, v176
	v_fmac_f32_e32 v180, v173, v173
	v_mul_f32_e32 v132, v132, v184
	v_lshlrev_b32_e32 v185, 16, v175
	v_fmac_f32_e32 v180, v132, v132
	v_mul_f32_e32 v133, v133, v174
	v_mul_f32_e32 v131, v128, v176
	v_add_f32_e32 v128, 1.0, v129
	v_and_b32_e32 v175, 0xffff0000, v175
	v_fmac_f32_e32 v180, v133, v133
	v_mul_f32_e32 v134, v134, v185
	v_rcp_f32_e32 v128, v128
	v_add_f32_e32 v129, 1.0, v130
	v_fmac_f32_e32 v180, v134, v134
	v_mul_f32_e32 v135, v135, v175
	v_rcp_f32_e32 v129, v129
	v_fmac_f32_e32 v180, v135, v135
	v_lshlrev_b32_e32 v187, 16, v177
	v_fmac_f32_e32 v180, v136, v136
	v_and_b32_e32 v177, 0xffff0000, v177
	v_fmac_f32_e32 v180, v131, v131
	v_mul_f32_e32 v137, v128, v187
	v_fmac_f32_e32 v180, v137, v137
	v_mul_f32_e32 v138, v129, v177
	v_fmac_f32_e32 v180, v138, v138
	v_cvt_pk_bf16_f32 v128, v132, v133
	v_cvt_pk_bf16_f32 v129, v134, v135
	v_cvt_pk_bf16_f32 v130, v136, v131
	v_cvt_pk_bf16_f32 v131, v137, v138
	global_store_dwordx4 v[178:179], v[128:131], off offset:256
	s_nop 1
	v_mov_b32_e32 v128, v180
	s_nop 1
	v_permlane16_swap_b32_e32 v180, v128
	v_add_f32_e32 v128, v180, v128
	v_mov_b32_e32 v129, v128
	s_nop 1
	v_permlane32_swap_b32_e32 v128, v129
	s_and_saveexec_b64 s[20:21], s[4:5]
	s_cbranch_execz .LBB0_1153
	v_lshl_add_u64 v[130:131], v[162:163], 2, s[0:1]
	v_add_f32_e32 v128, v128, v129
	global_atomic_add_f32 v[130:131], v128, off
